# all eight K=1024 GEMM K-loops rewritten: LDS fragment reads software-pipelined (12 quads, counted lgkmcnt), LDS-DMA issue interleaved between MFMAs, m0 from SALU adds
# baseline (speedup 1.0000x reference)
; DEVI f32x4 mfma16(bf16x8 a, bf16x8 b, f32x4 c) { return __builtin_amdgcn_mfma_f32_16x16x32_bf16(a, b, c, 0, 0, 0); }
; template <bool SWAP, class RP>
; DEVI void gemm_main(const int TIDX, const int BIDX, const int GDIM, f32x4 (&acc)[4][4], RP rowoff, const bf16_t* __restrict__ Bt, int ldb, int K, unsigned char* smem) {
;     ...
;   const int nk = K >> 6;
;   const int px = lg ^ (li >> 1);
;   GM_STAGE(0, 0);
;   for (int kt = 0; kt < nk; ++kt) {
;     const int buf = kt & 1;
;     asm volatile("s_waitcnt vmcnt(0)" ::: "memory");
;     __syncthreads();
;     if (kt + 1 < nk) GM_STAGE(kt + 1, buf ^ 1);
;     const unsigned char* A = smem + buf * 32768 + (wr * 64 + li) * 128;
;     const unsigned char* B = smem + buf * 32768 + 16384 + (wc * 64 + li) * 128;
; #pragma unroll
;     for (int ks = 0; ks < 2; ++ks) {
;       const int po = (px ^ (ks * 4)) * 16;
;       bf16x8 af[4], bfr[4];
; #pragma unroll
;       for (int i = 0; i < 4; ++i) {
;         af[i] = *(const bf16x8*)(A + i * 2048 + po);
;         bfr[i] = *(const bf16x8*)(B + i * 2048 + po);
;       }
; #pragma unroll
;       for (int mi = 0; mi < 4; ++mi)
; #pragma unroll
;         for (int ni = 0; ni < 4; ++ni)
;           acc[mi][ni] = SWAP ? mfma16(bfr[ni], af[mi], acc[mi][ni]) : mfma16(af[mi], bfr[ni], acc[mi][ni]);
;     }
.LBB0_47:
	s_and_b32 s25, s24, 0x8000
	s_xor_b32 s26, s25, 0x8000
	v_add_u32_e32 v194, s26, v76
	v_add_u32_e32 v204, s25, v74
	v_or_b32_e32 v205, s25, v78
	v_add_u32_e32 v205, v205, v79
	v_add_u32_e32 v231, v204, v77
	v_add_u32_e32 v232, v205, v77
	v_readfirstlane_b32 s101, v194
	v_add_u32_e32 v204, v204, v75
	v_add_u32_e32 v205, v205, v75
	s_waitcnt vmcnt(0)
	s_barrier
	ds_read_b128 v[80:83], v231
	ds_read_b128 v[96:99], v232 offset:16384
	ds_read_b128 v[100:103], v232 offset:18432
	ds_read_b128 v[104:107], v232 offset:20480
	ds_read_b128 v[108:111], v232 offset:22528
	ds_read_b128 v[84:87], v231 offset:2048
	ds_read_b128 v[88:91], v231 offset:4096
	ds_read_b128 v[92:95], v231 offset:6144
	ds_read_b128 v[190:193], v205 offset:16384
	ds_read_b128 v[196:199], v205 offset:18432
	ds_read_b128 v[200:203], v205 offset:20480
	ds_read_b128 v[208:211], v205 offset:22528
	s_mov_b32 m0, s101
	v_lshl_add_u64 v[112:113], v[64:65], 0, s[0:1]
	global_load_lds_dwordx4 v[112:113], off
	s_add_i32 m0, s101, 0x1000
	v_lshl_add_u64 v[112:113], v[66:67], 0, s[0:1]
	global_load_lds_dwordx4 v[112:113], off
	s_waitcnt lgkmcnt(7)
	v_mfma_f32_16x16x32_bf16 v[60:63], v[96:99], v[80:83], v[60:63]
	v_mfma_f32_16x16x32_bf16 v[56:59], v[100:103], v[80:83], v[56:59]
	s_add_i32 m0, s101, 0x2000
	v_lshl_add_u64 v[112:113], v[68:69], 0, s[0:1]
	global_load_lds_dwordx4 v[112:113], off
	v_mfma_f32_16x16x32_bf16 v[52:55], v[104:107], v[80:83], v[52:55]
	v_mfma_f32_16x16x32_bf16 v[48:51], v[108:111], v[80:83], v[48:51]
	ds_read_b128 v[80:83], v204
	s_add_i32 m0, s101, 0x3000
	v_lshl_add_u64 v[112:113], v[70:71], 0, s[0:1]
	global_load_lds_dwordx4 v[112:113], off
	s_waitcnt lgkmcnt(7)
	v_mfma_f32_16x16x32_bf16 v[44:47], v[96:99], v[84:87], v[44:47]
	v_mfma_f32_16x16x32_bf16 v[40:43], v[100:103], v[84:87], v[40:43]
	s_add_i32 m0, s101, 0x4000
	v_lshl_add_u64 v[112:113], v[72:73], 0, s[0:1]
	v_lshl_add_u64 v[112:113], v[112:113], 0, s[28:29]
	global_load_lds_dwordx4 v[112:113], off
	v_mfma_f32_16x16x32_bf16 v[36:39], v[104:107], v[84:87], v[36:39]
	v_mfma_f32_16x16x32_bf16 v[32:35], v[108:111], v[84:87], v[32:35]
	ds_read_b128 v[84:87], v204 offset:2048
	s_add_i32 m0, s101, 0x5000
	v_lshl_add_u64 v[112:113], v[72:73], 0, s[0:1]
	v_lshl_add_u64 v[112:113], v[112:113], 0, s[72:73]
	global_load_lds_dwordx4 v[112:113], off
	s_waitcnt lgkmcnt(7)
	v_mfma_f32_16x16x32_bf16 v[28:31], v[96:99], v[88:91], v[28:31]
	v_mfma_f32_16x16x32_bf16 v[24:27], v[100:103], v[88:91], v[24:27]
	s_add_i32 m0, s101, 0x6000
	v_lshl_add_u64 v[112:113], v[72:73], 0, s[0:1]
	v_lshl_add_u64 v[112:113], v[112:113], 0, s[78:79]
	global_load_lds_dwordx4 v[112:113], off
	v_mfma_f32_16x16x32_bf16 v[20:23], v[104:107], v[88:91], v[20:23]
	v_mfma_f32_16x16x32_bf16 v[16:19], v[108:111], v[88:91], v[16:19]
	ds_read_b128 v[88:91], v204 offset:4096
	s_add_i32 m0, s101, 0x7000
	v_lshl_add_u64 v[112:113], v[72:73], 0, s[0:1]
	v_lshl_add_u64 v[112:113], v[112:113], 0, s[80:81]
	global_load_lds_dwordx4 v[112:113], off
	s_waitcnt lgkmcnt(7)
	v_mfma_f32_16x16x32_bf16 v[12:15], v[96:99], v[92:95], v[12:15]
	v_mfma_f32_16x16x32_bf16 v[8:11], v[100:103], v[92:95], v[8:11]
	v_mfma_f32_16x16x32_bf16 v[4:7], v[104:107], v[92:95], v[4:7]
	v_mfma_f32_16x16x32_bf16 v[0:3], v[108:111], v[92:95], v[0:3]
	ds_read_b128 v[92:95], v204 offset:6144
	s_waitcnt lgkmcnt(3)
	v_mfma_f32_16x16x32_bf16 v[60:63], v[190:193], v[80:83], v[60:63]
	v_mfma_f32_16x16x32_bf16 v[56:59], v[196:199], v[80:83], v[56:59]
	v_mfma_f32_16x16x32_bf16 v[52:55], v[200:203], v[80:83], v[52:55]
	v_mfma_f32_16x16x32_bf16 v[48:51], v[208:211], v[80:83], v[48:51]
	s_waitcnt lgkmcnt(2)
	v_mfma_f32_16x16x32_bf16 v[44:47], v[190:193], v[84:87], v[44:47]
	v_mfma_f32_16x16x32_bf16 v[40:43], v[196:199], v[84:87], v[40:43]
	v_mfma_f32_16x16x32_bf16 v[36:39], v[200:203], v[84:87], v[36:39]
	v_mfma_f32_16x16x32_bf16 v[32:35], v[208:211], v[84:87], v[32:35]
	s_waitcnt lgkmcnt(1)
	v_mfma_f32_16x16x32_bf16 v[28:31], v[190:193], v[88:91], v[28:31]
	v_mfma_f32_16x16x32_bf16 v[24:27], v[196:199], v[88:91], v[24:27]
	v_mfma_f32_16x16x32_bf16 v[20:23], v[200:203], v[88:91], v[20:23]
	v_mfma_f32_16x16x32_bf16 v[16:19], v[208:211], v[88:91], v[16:19]
	s_waitcnt lgkmcnt(0)
	s_add_u32 s0, s0, 0x80
	s_addc_u32 s1, s1, 0
	s_add_i32 s24, s24, 0x8000
	s_cmpk_lg_i32 s0, 0x780
	v_mfma_f32_16x16x32_bf16 v[12:15], v[190:193], v[92:95], v[12:15]
	v_mfma_f32_16x16x32_bf16 v[8:11], v[196:199], v[92:95], v[8:11]
	v_mfma_f32_16x16x32_bf16 v[4:7], v[200:203], v[92:95], v[4:7]
	v_mfma_f32_16x16x32_bf16 v[0:3], v[208:211], v[92:95], v[0:3]
	s_cbranch_scc1 .LBB0_47
; DEVI f32x4 mfma16(bf16x8 a, bf16x8 b, f32x4 c) { return __builtin_amdgcn_mfma_f32_16x16x32_bf16(a, b, c, 0, 0, 0); }
; template <bool SWAP, class RP>
; DEVI void gemm_main(const int TIDX, const int BIDX, const int GDIM, f32x4 (&acc)[4][4], RP rowoff, const bf16_t* __restrict__ Bt, int ldb, int K, unsigned char* smem) {
;     ...
;     const unsigned char* A = smem + buf * 32768 + (wr * 64 + li) * 128;
;     const unsigned char* B = smem + buf * 32768 + 16384 + (wc * 64 + li) * 128;
; #pragma unroll
;     for (int ks = 0; ks < 2; ++ks) {
;       const int po = (px ^ (ks * 4)) * 16;
;       bf16x8 af[4], bfr[4];
; #pragma unroll
;       for (int i = 0; i < 4; ++i) {
;         af[i] = *(const bf16x8*)(A + i * 2048 + po);
;         bfr[i] = *(const bf16x8*)(B + i * 2048 + po);
;       }
; #pragma unroll
;       for (int mi = 0; mi < 4; ++mi)
; #pragma unroll
;         for (int ni = 0; ni < 4; ++ni)
;           acc[mi][ni] = SWAP ? mfma16(bfr[ni], af[mi], acc[mi][ni]) : mfma16(af[mi], bfr[ni], acc[mi][ni]);
;     }
;   }
;   __syncthreads();
	v_add_u32_e32 v72, v78, v79
	v_add_u32_e32 v73, v72, v77
	s_waitcnt vmcnt(0)
	s_waitcnt vmcnt(0)
	s_barrier
	ds_read_b128 v[64:67], v73 offset:49152
	v_add_u32_e32 v88, v74, v77
	ds_read_b128 v[76:79], v73 offset:51200
	ds_read_b128 v[80:83], v73 offset:53248
	ds_read_b128 v[84:87], v73 offset:55296
	ds_read_b128 v[68:71], v88 offset:32768
	s_waitcnt lgkmcnt(0)
	v_mfma_f32_16x16x32_bf16 v[60:63], v[64:67], v[68:71], v[60:63]
	v_add_u32_e32 v72, v72, v75
	v_mfma_f32_16x16x32_bf16 v[56:59], v[76:79], v[68:71], v[56:59]
	v_mfma_f32_16x16x32_bf16 v[52:55], v[80:83], v[68:71], v[52:55]
	v_mfma_f32_16x16x32_bf16 v[48:51], v[84:87], v[68:71], v[48:51]
	ds_read_b128 v[68:71], v88 offset:34816
	s_waitcnt lgkmcnt(0)
	v_mfma_f32_16x16x32_bf16 v[44:47], v[64:67], v[68:71], v[44:47]
	v_mfma_f32_16x16x32_bf16 v[40:43], v[76:79], v[68:71], v[40:43]
	v_mfma_f32_16x16x32_bf16 v[36:39], v[80:83], v[68:71], v[36:39]
	v_mfma_f32_16x16x32_bf16 v[32:35], v[84:87], v[68:71], v[32:35]
	ds_read_b128 v[68:71], v88 offset:36864
	s_waitcnt lgkmcnt(0)
	v_mfma_f32_16x16x32_bf16 v[28:31], v[64:67], v[68:71], v[28:31]
	v_mfma_f32_16x16x32_bf16 v[24:27], v[76:79], v[68:71], v[24:27]
	v_mfma_f32_16x16x32_bf16 v[20:23], v[80:83], v[68:71], v[20:23]
	v_mfma_f32_16x16x32_bf16 v[16:19], v[84:87], v[68:71], v[16:19]
	ds_read_b128 v[68:71], v88 offset:38912
	s_waitcnt lgkmcnt(0)
	v_mfma_f32_16x16x32_bf16 v[12:15], v[64:67], v[68:71], v[12:15]
	v_mfma_f32_16x16x32_bf16 v[64:67], v[80:83], v[68:71], v[4:7]
	s_nop 2
	ds_read_b128 v[4:7], v72 offset:49152
	v_mfma_f32_16x16x32_bf16 v[8:11], v[76:79], v[68:71], v[8:11]
	v_mfma_f32_16x16x32_bf16 v[140:143], v[84:87], v[68:71], v[0:3]
	v_add_u32_e32 v68, v74, v75
	s_nop 1
	ds_read_b128 v[0:3], v68 offset:32768
	s_waitcnt lgkmcnt(0)
	v_mfma_f32_16x16x32_bf16 v[124:127], v[4:7], v[0:3], v[60:63]
	s_nop 2
	ds_read_b128 v[60:63], v72 offset:51200
	s_waitcnt lgkmcnt(0)
	v_mfma_f32_16x16x32_bf16 v[120:123], v[60:63], v[0:3], v[56:59]
	s_nop 2
	ds_read_b128 v[56:59], v72 offset:53248
	s_waitcnt lgkmcnt(0)
	v_mfma_f32_16x16x32_bf16 v[116:119], v[56:59], v[0:3], v[52:55]
	s_nop 2
	ds_read_b128 v[52:55], v72 offset:55296
	s_waitcnt lgkmcnt(0)
	v_mfma_f32_16x16x32_bf16 v[112:115], v[52:55], v[0:3], v[48:51]
	ds_read_b128 v[0:3], v68 offset:34816
	s_waitcnt lgkmcnt(0)
	v_mfma_f32_16x16x32_bf16 v[108:111], v[4:7], v[0:3], v[44:47]
	v_mfma_f32_16x16x32_bf16 v[104:107], v[60:63], v[0:3], v[40:43]
	v_mfma_f32_16x16x32_bf16 v[100:103], v[56:59], v[0:3], v[36:39]
	v_mfma_f32_16x16x32_bf16 v[96:99], v[52:55], v[0:3], v[32:35]
	ds_read_b128 v[0:3], v68 offset:36864
	s_waitcnt lgkmcnt(0)
	v_mfma_f32_16x16x32_bf16 v[84:87], v[56:59], v[0:3], v[20:23]
	s_nop 2
	ds_read_b128 v[20:23], v68 offset:38912
	s_waitcnt lgkmcnt(0)
	v_mfma_f32_16x16x32_bf16 v[92:95], v[4:7], v[0:3], v[28:31]
	s_barrier
	v_mfma_f32_16x16x32_bf16 v[88:91], v[60:63], v[0:3], v[24:27]
	v_mfma_f32_16x16x32_bf16 v[80:83], v[52:55], v[0:3], v[16:19]
	v_mov_b32_e32 v0, v129
	v_mfma_f32_16x16x32_bf16 v[76:79], v[4:7], v[20:23], v[12:15]
	v_mov_b32_e32 v5, v130
	v_mov_b32_e32 v6, 0x8100000
	v_mfma_f32_16x16x32_bf16 v[72:75], v[60:63], v[20:23], v[8:11]
	v_ashrrev_i32_e32 v1, 6, v5
	v_bfe_u32 v4, v5, 3, 3
	v_mov_b32_e32 v7, 0x8100000
	v_mfma_f32_16x16x32_bf16 v[68:71], v[56:59], v[20:23], v[64:67]
	v_lshl_or_b32 v10, v1, 3, v4
	v_add_u32_e32 v2, s21, v10
	v_cmp_lt_i32_e32 vcc, v2, v138
	v_mfma_f32_16x16x32_bf16 v[64:67], v[52:55], v[20:23], v[140:143]
	s_and_saveexec_b64 s[0:1], vcc
	s_cbranch_execz .LBB0_50
	v_ashrrev_i32_e32 v3, 31, v2
	v_lshl_add_u64 v[2:3], v[2:3], 2, v[136:137]
	global_load_dword v2, v[2:3], off
	s_waitcnt vmcnt(0)
	v_lshlrev_b32_e32 v2, 10, v2
	v_and_b32_e32 v7, 0xfffff800, v2

; DEVI f32x4 mfma16(bf16x8 a, bf16x8 b, f32x4 c) { return __builtin_amdgcn_mfma_f32_16x16x32_bf16(a, b, c, 0, 0, 0); }
; template <bool SWAP, class RP>
; DEVI void gemm_main(const int TIDX, const int BIDX, const int GDIM, f32x4 (&acc)[4][4], RP rowoff, const bf16_t* __restrict__ Bt, int ldb, int K, unsigned char* smem) {
;     ...
;   const int nk = K >> 6;
;   const int px = lg ^ (li >> 1);
;   GM_STAGE(0, 0);
;   for (int kt = 0; kt < nk; ++kt) {
;     const int buf = kt & 1;
;     asm volatile("s_waitcnt vmcnt(0)" ::: "memory");
;     __syncthreads();
;     if (kt + 1 < nk) GM_STAGE(kt + 1, buf ^ 1);
;     const unsigned char* A = smem + buf * 32768 + (wr * 64 + li) * 128;
;     const unsigned char* B = smem + buf * 32768 + 16384 + (wc * 64 + li) * 128;
; #pragma unroll
;     for (int ks = 0; ks < 2; ++ks) {
;       const int po = (px ^ (ks * 4)) * 16;
;       bf16x8 af[4], bfr[4];
; #pragma unroll
;       for (int i = 0; i < 4; ++i) {
;         af[i] = *(const bf16x8*)(A + i * 2048 + po);
;         bfr[i] = *(const bf16x8*)(B + i * 2048 + po);
;       }
; #pragma unroll
;       for (int mi = 0; mi < 4; ++mi)
; #pragma unroll
;         for (int ni = 0; ni < 4; ++ni)
;           acc[mi][ni] = SWAP ? mfma16(bfr[ni], af[mi], acc[mi][ni]) : mfma16(af[mi], bfr[ni], acc[mi][ni]);
;     }
.LBB0_57:
	s_and_b32 s20, s19, 0x8000
	s_xor_b32 s21, s20, 0x8000
	v_add_u32_e32 v128, s21, v150
	v_add_u32_e32 v151, s20, v146
	v_or_b32_e32 v160, s20, v147
	v_add_u32_e32 v160, v160, v149
	v_add_u32_e32 v194, v151, v148
	v_add_u32_e32 v231, v160, v148
	v_readfirstlane_b32 s101, v128
	v_add_u32_e32 v151, v151, v145
	v_add_u32_e32 v160, v160, v145
	s_waitcnt vmcnt(0)
	s_barrier
	ds_read_b128 v[152:155], v194
	ds_read_b128 v[170:173], v231 offset:16384
	ds_read_b128 v[174:177], v231 offset:18432
	ds_read_b128 v[178:181], v231 offset:20480
	ds_read_b128 v[182:185], v231 offset:22528
	ds_read_b128 v[156:159], v194 offset:2048
	ds_read_b128 v[162:165], v194 offset:4096
	ds_read_b128 v[166:169], v194 offset:6144
	ds_read_b128 v[190:193], v160 offset:16384
	ds_read_b128 v[196:199], v160 offset:18432
	ds_read_b128 v[200:203], v160 offset:20480
	ds_read_b128 v[208:211], v160 offset:22528
	s_mov_b32 m0, s101
	v_lshl_add_u64 v[204:205], v[134:135], 0, s[0:1]
	global_load_lds_dwordx4 v[204:205], off
	s_add_i32 m0, s101, 0x1000
	v_lshl_add_u64 v[204:205], v[136:137], 0, s[0:1]
	global_load_lds_dwordx4 v[204:205], off
	s_waitcnt lgkmcnt(7)
	v_mfma_f32_16x16x32_bf16 v[60:63], v[170:173], v[152:155], v[60:63]
	v_mfma_f32_16x16x32_bf16 v[56:59], v[174:177], v[152:155], v[56:59]
	s_add_i32 m0, s101, 0x2000
	v_lshl_add_u64 v[204:205], v[138:139], 0, s[0:1]
	global_load_lds_dwordx4 v[204:205], off
	v_mfma_f32_16x16x32_bf16 v[52:55], v[178:181], v[152:155], v[52:55]
	v_mfma_f32_16x16x32_bf16 v[48:51], v[182:185], v[152:155], v[48:51]
	ds_read_b128 v[152:155], v151
	s_add_i32 m0, s101, 0x3000
	v_lshl_add_u64 v[204:205], v[140:141], 0, s[0:1]
	global_load_lds_dwordx4 v[204:205], off
	s_waitcnt lgkmcnt(7)
	v_mfma_f32_16x16x32_bf16 v[44:47], v[170:173], v[156:159], v[44:47]
	v_mfma_f32_16x16x32_bf16 v[40:43], v[174:177], v[156:159], v[40:43]
	s_add_i32 m0, s101, 0x4000
	v_lshl_add_u64 v[204:205], v[142:143], 0, s[0:1]
	v_lshl_add_u64 v[204:205], v[204:205], 0, s[22:23]
	global_load_lds_dwordx4 v[204:205], off
	v_mfma_f32_16x16x32_bf16 v[36:39], v[178:181], v[156:159], v[36:39]
	v_mfma_f32_16x16x32_bf16 v[32:35], v[182:185], v[156:159], v[32:35]
	ds_read_b128 v[156:159], v151 offset:2048
	s_add_i32 m0, s101, 0x5000
	v_lshl_add_u64 v[204:205], v[142:143], 0, s[0:1]
	v_lshl_add_u64 v[204:205], v[204:205], 0, s[72:73]
	global_load_lds_dwordx4 v[204:205], off
	s_waitcnt lgkmcnt(7)
	v_mfma_f32_16x16x32_bf16 v[28:31], v[170:173], v[162:165], v[28:31]
	v_mfma_f32_16x16x32_bf16 v[24:27], v[174:177], v[162:165], v[24:27]
	s_add_i32 m0, s101, 0x6000
	v_lshl_add_u64 v[204:205], v[142:143], 0, s[0:1]
	v_lshl_add_u64 v[204:205], v[204:205], 0, s[78:79]
	global_load_lds_dwordx4 v[204:205], off
	v_mfma_f32_16x16x32_bf16 v[20:23], v[178:181], v[162:165], v[20:23]
	v_mfma_f32_16x16x32_bf16 v[16:19], v[182:185], v[162:165], v[16:19]
	ds_read_b128 v[162:165], v151 offset:4096
	s_add_i32 m0, s101, 0x7000
	v_lshl_add_u64 v[204:205], v[142:143], 0, s[0:1]
	v_lshl_add_u64 v[204:205], v[204:205], 0, s[80:81]
	global_load_lds_dwordx4 v[204:205], off
	s_waitcnt lgkmcnt(7)
	v_mfma_f32_16x16x32_bf16 v[12:15], v[170:173], v[166:169], v[12:15]
	v_mfma_f32_16x16x32_bf16 v[8:11], v[174:177], v[166:169], v[8:11]
	v_mfma_f32_16x16x32_bf16 v[4:7], v[178:181], v[166:169], v[4:7]
	v_mfma_f32_16x16x32_bf16 v[0:3], v[182:185], v[166:169], v[0:3]
	ds_read_b128 v[166:169], v151 offset:6144
	s_waitcnt lgkmcnt(3)
	v_mfma_f32_16x16x32_bf16 v[60:63], v[190:193], v[152:155], v[60:63]
	v_mfma_f32_16x16x32_bf16 v[56:59], v[196:199], v[152:155], v[56:59]
	v_mfma_f32_16x16x32_bf16 v[52:55], v[200:203], v[152:155], v[52:55]
	v_mfma_f32_16x16x32_bf16 v[48:51], v[208:211], v[152:155], v[48:51]
	s_waitcnt lgkmcnt(2)
	v_mfma_f32_16x16x32_bf16 v[44:47], v[190:193], v[156:159], v[44:47]
	v_mfma_f32_16x16x32_bf16 v[40:43], v[196:199], v[156:159], v[40:43]
	v_mfma_f32_16x16x32_bf16 v[36:39], v[200:203], v[156:159], v[36:39]
	v_mfma_f32_16x16x32_bf16 v[32:35], v[208:211], v[156:159], v[32:35]
	s_waitcnt lgkmcnt(1)
	v_mfma_f32_16x16x32_bf16 v[28:31], v[190:193], v[162:165], v[28:31]
	v_mfma_f32_16x16x32_bf16 v[24:27], v[196:199], v[162:165], v[24:27]
	v_mfma_f32_16x16x32_bf16 v[20:23], v[200:203], v[162:165], v[20:23]
	v_mfma_f32_16x16x32_bf16 v[16:19], v[208:211], v[162:165], v[16:19]
	s_waitcnt lgkmcnt(0)
	s_add_u32 s0, s0, 0x80
	s_addc_u32 s1, s1, 0
	s_add_i32 s19, s19, 0x8000
	s_cmpk_lg_i32 s0, 0x780
	v_mfma_f32_16x16x32_bf16 v[12:15], v[190:193], v[166:169], v[12:15]
	v_mfma_f32_16x16x32_bf16 v[8:11], v[196:199], v[166:169], v[8:11]
	v_mfma_f32_16x16x32_bf16 v[4:7], v[200:203], v[166:169], v[4:7]
	v_mfma_f32_16x16x32_bf16 v[0:3], v[208:211], v[166:169], v[0:3]
	s_cbranch_scc1 .LBB0_57
	v_mul_f32_e32 v128, 0xbfb8aa3b, v124
	v_exp_f32_e32 v134, v128
	v_mul_f32_e32 v128, 0xbfb8aa3b, v125
	v_exp_f32_e32 v135, v128
	s_waitcnt vmcnt(0)
	s_waitcnt vmcnt(0)
	s_barrier
; DEVI uint32_t pack2(float lo, float hi) { f32x2_t v = {lo, hi}; bf16x2_t b = __builtin_convertvector(v, bf16x2_t); return __builtin_bit_cast(uint32_t, b); }
; DEVI float siluf_(float x) { return x / (1.f + __expf(-x)); }
; DEVI void phase_p8(const int TIDX, const int BIDX, const int GDIM, KAP KA, unsigned char* WSB, float* OUTB, int l, unsigned char* smem) {
;     ...
; #pragma unroll
;     for (int i = 0; i < 4; ++i)
; #pragma unroll
;       for (int j = 0; j < 4; ++j) sg[i][j] = make_uint2(pack2(siluf_(acc[i][j][0]), siluf_(acc[i][j][1])), pack2(siluf_(acc[i][j][2]), siluf_(acc[i][j][3])));
	v_pk_add_f32 v[134:135], v[134:135], 1.0 op_sel_hi:[1,0]
	s_nop 0
	v_div_scale_f32 v128, s[0:1], v135, v135, v125
	v_rcp_f32_e32 v136, v128
	s_nop 0
	v_fma_f32 v137, -v128, v136, 1.0
	v_fmac_f32_e32 v136, v137, v136
	v_div_scale_f32 v137, vcc, v125, v135, v125
	v_mul_f32_e32 v138, v137, v136
	v_fma_f32 v139, -v128, v138, v137
	v_fmac_f32_e32 v138, v139, v136
	v_fma_f32 v128, -v128, v138, v137
	v_div_fmas_f32 v128, v128, v136, v138
	v_div_fixup_f32 v125, v128, v135, v125
	v_div_scale_f32 v128, s[0:1], v134, v134, v124
	v_rcp_f32_e32 v135, v128
	s_nop 0
	v_fma_f32 v136, -v128, v135, 1.0
	v_fmac_f32_e32 v135, v136, v135
	v_div_scale_f32 v136, vcc, v124, v134, v124
	v_mul_f32_e32 v137, v136, v135
	v_fma_f32 v138, -v128, v137, v136
	v_fmac_f32_e32 v137, v138, v135
	v_fma_f32 v128, -v128, v137, v136
	v_div_fmas_f32 v128, v128, v135, v137
	v_div_fixup_f32 v124, v128, v134, v124
	v_cvt_pk_bf16_f32 v124, v124, v125
	v_mul_f32_e32 v125, 0xbfb8aa3b, v126
	v_exp_f32_e32 v134, v125
	v_mul_f32_e32 v125, 0xbfb8aa3b, v127
	v_exp_f32_e32 v135, v125
	s_nop 0
	v_pk_add_f32 v[134:135], v[134:135], 1.0 op_sel_hi:[1,0]
	s_nop 0
	v_div_scale_f32 v125, s[0:1], v135, v135, v127
	v_rcp_f32_e32 v128, v125
	s_nop 0
	v_fma_f32 v136, -v125, v128, 1.0
	v_fmac_f32_e32 v128, v136, v128
	v_div_scale_f32 v136, vcc, v127, v135, v127
	v_mul_f32_e32 v137, v136, v128
	v_fma_f32 v138, -v125, v137, v136
	v_fmac_f32_e32 v137, v138, v128
	v_fma_f32 v125, -v125, v137, v136
	v_div_fmas_f32 v125, v125, v128, v137
	v_div_fixup_f32 v125, v125, v135, v127
	v_div_scale_f32 v127, s[0:1], v134, v134, v126
	v_rcp_f32_e32 v128, v127
	s_nop 0
	v_fma_f32 v135, -v127, v128, 1.0
	v_fmac_f32_e32 v128, v135, v128
	v_div_scale_f32 v135, vcc, v126, v134, v126
	v_mul_f32_e32 v136, v135, v128
	v_fma_f32 v137, -v127, v136, v135
	v_fmac_f32_e32 v136, v137, v128
	v_fma_f32 v127, -v127, v136, v135
	v_div_fmas_f32 v127, v127, v128, v136
	v_div_fixup_f32 v126, v127, v134, v126
	v_cvt_pk_bf16_f32 v125, v126, v125
	v_mul_f32_e32 v126, 0xbfb8aa3b, v120
	v_mul_f32_e32 v127, 0xbfb8aa3b, v121
	v_exp_f32_e32 v126, v126
	v_exp_f32_e32 v127, v127
	s_nop 0
	v_pk_add_f32 v[126:127], v[126:127], 1.0 op_sel_hi:[1,0]
	s_nop 0
	v_div_scale_f32 v128, s[0:1], v127, v127, v121
	v_rcp_f32_e32 v134, v128
	s_nop 0
	v_fma_f32 v135, -v128, v134, 1.0
	v_fmac_f32_e32 v134, v135, v134
	v_div_scale_f32 v135, vcc, v121, v127, v121
	v_mul_f32_e32 v136, v135, v134
	v_fma_f32 v137, -v128, v136, v135
	v_fmac_f32_e32 v136, v137, v134
	v_fma_f32 v128, -v128, v136, v135
	v_div_fmas_f32 v128, v128, v134, v136
	v_div_fixup_f32 v121, v128, v127, v121
	v_div_scale_f32 v127, s[0:1], v126, v126, v120
	v_rcp_f32_e32 v128, v127
	s_nop 0
	v_fma_f32 v134, -v127, v128, 1.0
	v_fmac_f32_e32 v128, v134, v128
	v_div_scale_f32 v134, vcc, v120, v126, v120
	v_mul_f32_e32 v135, v134, v128
	v_fma_f32 v136, -v127, v135, v134
	v_fmac_f32_e32 v135, v136, v128
	v_fma_f32 v127, -v127, v135, v134
	v_div_fmas_f32 v127, v127, v128, v135
	v_div_fixup_f32 v120, v127, v126, v120
	v_cvt_pk_bf16_f32 v120, v120, v121
	v_mul_f32_e32 v121, 0xbfb8aa3b, v122
	v_exp_f32_e32 v126, v121
	v_mul_f32_e32 v121, 0xbfb8aa3b, v123
	v_exp_f32_e32 v127, v121
	s_nop 0
	v_pk_add_f32 v[126:127], v[126:127], 1.0 op_sel_hi:[1,0]
	s_nop 0
	v_div_scale_f32 v121, s[0:1], v127, v127, v123
	v_rcp_f32_e32 v128, v121
	s_nop 0
	v_fma_f32 v134, -v121, v128, 1.0
	v_fmac_f32_e32 v128, v134, v128
	v_div_scale_f32 v134, vcc, v123, v127, v123
	v_mul_f32_e32 v135, v134, v128
	v_fma_f32 v136, -v121, v135, v134
	v_fmac_f32_e32 v135, v136, v128
	v_fma_f32 v121, -v121, v135, v134
	v_div_fmas_f32 v121, v121, v128, v135
	v_div_fixup_f32 v121, v121, v127, v123
	v_div_scale_f32 v123, s[0:1], v126, v126, v122
	v_rcp_f32_e32 v127, v123
	s_nop 0
	v_fma_f32 v128, -v123, v127, 1.0
	v_fmac_f32_e32 v127, v128, v127
	v_div_scale_f32 v128, vcc, v122, v126, v122
	v_mul_f32_e32 v134, v128, v127
	v_fma_f32 v135, -v123, v134, v128
	v_fmac_f32_e32 v134, v135, v127
	v_fma_f32 v123, -v123, v134, v128
	v_div_fmas_f32 v123, v123, v127, v134
	v_div_fixup_f32 v122, v123, v126, v122
	v_cvt_pk_bf16_f32 v121, v122, v121
	v_mul_f32_e32 v122, 0xbfb8aa3b, v116
	v_mul_f32_e32 v123, 0xbfb8aa3b, v117
	v_exp_f32_e32 v122, v122
	v_exp_f32_e32 v123, v123
	s_nop 0
	v_pk_add_f32 v[122:123], v[122:123], 1.0 op_sel_hi:[1,0]
	s_nop 0
	v_div_scale_f32 v126, s[0:1], v123, v123, v117
	v_rcp_f32_e32 v127, v126
	s_nop 0
	v_fma_f32 v128, -v126, v127, 1.0
	v_fmac_f32_e32 v127, v128, v127
	v_div_scale_f32 v128, vcc, v117, v123, v117
	v_mul_f32_e32 v134, v128, v127
	v_fma_f32 v135, -v126, v134, v128
	v_fmac_f32_e32 v134, v135, v127
	v_fma_f32 v126, -v126, v134, v128
	v_div_fmas_f32 v126, v126, v127, v134
	v_div_fixup_f32 v117, v126, v123, v117
	v_div_scale_f32 v123, s[0:1], v122, v122, v116
	v_rcp_f32_e32 v126, v123
	s_nop 0
	v_fma_f32 v127, -v123, v126, 1.0
	v_fmac_f32_e32 v126, v127, v126
	v_div_scale_f32 v127, vcc, v116, v122, v116
	v_mul_f32_e32 v128, v127, v126
	v_fma_f32 v134, -v123, v128, v127
	v_fmac_f32_e32 v128, v134, v126
	v_fma_f32 v123, -v123, v128, v127
	v_div_fmas_f32 v123, v123, v126, v128
	v_div_fixup_f32 v116, v123, v122, v116
	v_cvt_pk_bf16_f32 v116, v116, v117
	v_mul_f32_e32 v117, 0xbfb8aa3b, v118
	v_exp_f32_e32 v122, v117
	v_mul_f32_e32 v117, 0xbfb8aa3b, v119
	v_exp_f32_e32 v123, v117
	s_nop 0
	v_pk_add_f32 v[122:123], v[122:123], 1.0 op_sel_hi:[1,0]
	s_nop 0
	v_div_scale_f32 v117, s[0:1], v123, v123, v119
	v_rcp_f32_e32 v126, v117
	s_nop 0
	v_fma_f32 v127, -v117, v126, 1.0
	v_fmac_f32_e32 v126, v127, v126
	v_div_scale_f32 v127, vcc, v119, v123, v119
	v_mul_f32_e32 v128, v127, v126
	v_fma_f32 v134, -v117, v128, v127
	v_fmac_f32_e32 v128, v134, v126
; DEVI uint32_t pack2(float lo, float hi) { f32x2_t v = {lo, hi}; bf16x2_t b = __builtin_convertvector(v, bf16x2_t); return __builtin_bit_cast(uint32_t, b); }
; DEVI float siluf_(float x) { return x / (1.f + __expf(-x)); }
; DEVI void phase_p8(const int TIDX, const int BIDX, const int GDIM, KAP KA, unsigned char* WSB, float* OUTB, int l, unsigned char* smem) {
;     ...
; #pragma unroll
;     for (int i = 0; i < 4; ++i)
; #pragma unroll
;       for (int j = 0; j < 4; ++j) sg[i][j] = make_uint2(pack2(siluf_(acc[i][j][0]), siluf_(acc[i][j][1])), pack2(siluf_(acc[i][j][2]), siluf_(acc[i][j][3])));
	v_fma_f32 v117, -v117, v128, v127
	v_div_fmas_f32 v117, v117, v126, v128
	v_div_fixup_f32 v117, v117, v123, v119
	v_div_scale_f32 v119, s[0:1], v122, v122, v118
	v_rcp_f32_e32 v123, v119
	s_nop 0
	v_fma_f32 v126, -v119, v123, 1.0
	v_fmac_f32_e32 v123, v126, v123
	v_div_scale_f32 v126, vcc, v118, v122, v118
	v_mul_f32_e32 v127, v126, v123
	v_fma_f32 v128, -v119, v127, v126
	v_fmac_f32_e32 v127, v128, v123
	v_fma_f32 v119, -v119, v127, v126
	v_div_fmas_f32 v119, v119, v123, v127
	v_div_fixup_f32 v118, v119, v122, v118
	v_cvt_pk_bf16_f32 v117, v118, v117
	v_mul_f32_e32 v118, 0xbfb8aa3b, v112
	v_mul_f32_e32 v119, 0xbfb8aa3b, v113
	v_exp_f32_e32 v118, v118
	v_exp_f32_e32 v119, v119
	s_nop 0
	v_pk_add_f32 v[118:119], v[118:119], 1.0 op_sel_hi:[1,0]
	s_nop 0
	v_div_scale_f32 v122, s[0:1], v119, v119, v113
	v_rcp_f32_e32 v123, v122
	s_nop 0
	v_fma_f32 v126, -v122, v123, 1.0
	v_fmac_f32_e32 v123, v126, v123
	v_div_scale_f32 v126, vcc, v113, v119, v113
	v_mul_f32_e32 v127, v126, v123
	v_fma_f32 v128, -v122, v127, v126
	v_fmac_f32_e32 v127, v128, v123
	v_fma_f32 v122, -v122, v127, v126
	v_div_fmas_f32 v122, v122, v123, v127
	v_div_fixup_f32 v113, v122, v119, v113
	v_div_scale_f32 v119, s[0:1], v118, v118, v112
	v_rcp_f32_e32 v122, v119
	s_nop 0
	v_fma_f32 v123, -v119, v122, 1.0
	v_fmac_f32_e32 v122, v123, v122
	v_div_scale_f32 v123, vcc, v112, v118, v112
	v_mul_f32_e32 v126, v123, v122
	v_fma_f32 v127, -v119, v126, v123
	v_fmac_f32_e32 v126, v127, v122
	v_fma_f32 v119, -v119, v126, v123
	v_div_fmas_f32 v119, v119, v122, v126
	v_div_fixup_f32 v112, v119, v118, v112
	v_cvt_pk_bf16_f32 v112, v112, v113
	v_mul_f32_e32 v113, 0xbfb8aa3b, v114
	v_exp_f32_e32 v118, v113
	v_mul_f32_e32 v113, 0xbfb8aa3b, v115
	v_exp_f32_e32 v119, v113
	s_nop 0
	v_pk_add_f32 v[118:119], v[118:119], 1.0 op_sel_hi:[1,0]
	s_nop 0
	v_div_scale_f32 v113, s[0:1], v119, v119, v115
	v_rcp_f32_e32 v122, v113
	s_nop 0
	v_fma_f32 v123, -v113, v122, 1.0
	v_fmac_f32_e32 v122, v123, v122
	v_div_scale_f32 v123, vcc, v115, v119, v115
	v_mul_f32_e32 v126, v123, v122
	v_fma_f32 v127, -v113, v126, v123
	v_fmac_f32_e32 v126, v127, v122
	v_fma_f32 v113, -v113, v126, v123
	v_div_fmas_f32 v113, v113, v122, v126
	v_div_fixup_f32 v113, v113, v119, v115
	v_div_scale_f32 v115, s[0:1], v118, v118, v114
	v_rcp_f32_e32 v119, v115
	s_nop 0
	v_fma_f32 v122, -v115, v119, 1.0
	v_fmac_f32_e32 v119, v122, v119
	v_div_scale_f32 v122, vcc, v114, v118, v114
	v_mul_f32_e32 v123, v122, v119
	v_fma_f32 v126, -v115, v123, v122
	v_fmac_f32_e32 v123, v126, v119
	v_fma_f32 v115, -v115, v123, v122
	v_div_fmas_f32 v115, v115, v119, v123
	v_div_fixup_f32 v114, v115, v118, v114
	v_cvt_pk_bf16_f32 v113, v114, v113
	v_mul_f32_e32 v114, 0xbfb8aa3b, v108
	v_mul_f32_e32 v115, 0xbfb8aa3b, v109
	v_exp_f32_e32 v114, v114
	v_exp_f32_e32 v115, v115
	s_nop 0
	v_pk_add_f32 v[114:115], v[114:115], 1.0 op_sel_hi:[1,0]
	s_nop 0
	v_div_scale_f32 v118, s[0:1], v115, v115, v109
	v_rcp_f32_e32 v119, v118
	s_nop 0
	v_fma_f32 v122, -v118, v119, 1.0
	v_fmac_f32_e32 v119, v122, v119
	v_div_scale_f32 v122, vcc, v109, v115, v109
	v_mul_f32_e32 v123, v122, v119
	v_fma_f32 v126, -v118, v123, v122
	v_fmac_f32_e32 v123, v126, v119
	v_fma_f32 v118, -v118, v123, v122
	v_div_fmas_f32 v118, v118, v119, v123
	v_div_fixup_f32 v109, v118, v115, v109
	v_div_scale_f32 v115, s[0:1], v114, v114, v108
	v_rcp_f32_e32 v118, v115
	s_nop 0
	v_fma_f32 v119, -v115, v118, 1.0
	v_fmac_f32_e32 v118, v119, v118
	v_div_scale_f32 v119, vcc, v108, v114, v108
	v_mul_f32_e32 v122, v119, v118
	v_fma_f32 v123, -v115, v122, v119
	v_fmac_f32_e32 v122, v123, v118
	v_fma_f32 v115, -v115, v122, v119
	v_div_fmas_f32 v115, v115, v118, v122
	v_div_fixup_f32 v108, v115, v114, v108
	v_cvt_pk_bf16_f32 v108, v108, v109
	v_mul_f32_e32 v109, 0xbfb8aa3b, v110
	v_exp_f32_e32 v114, v109
	v_mul_f32_e32 v109, 0xbfb8aa3b, v111
	v_exp_f32_e32 v115, v109
	s_nop 0
	v_pk_add_f32 v[114:115], v[114:115], 1.0 op_sel_hi:[1,0]
	s_nop 0
	v_div_scale_f32 v109, s[0:1], v115, v115, v111
	v_rcp_f32_e32 v118, v109
	s_nop 0
	v_fma_f32 v119, -v109, v118, 1.0
	v_fmac_f32_e32 v118, v119, v118
	v_div_scale_f32 v119, vcc, v111, v115, v111
	v_mul_f32_e32 v122, v119, v118
	v_fma_f32 v123, -v109, v122, v119
	v_fmac_f32_e32 v122, v123, v118
	v_fma_f32 v109, -v109, v122, v119
	v_div_fmas_f32 v109, v109, v118, v122
	v_div_fixup_f32 v109, v109, v115, v111
	v_div_scale_f32 v111, s[0:1], v114, v114, v110
	v_rcp_f32_e32 v115, v111
	s_nop 0
	v_fma_f32 v118, -v111, v115, 1.0
	v_fmac_f32_e32 v115, v118, v115
	v_div_scale_f32 v118, vcc, v110, v114, v110
	v_mul_f32_e32 v119, v118, v115
	v_fma_f32 v122, -v111, v119, v118
	v_fmac_f32_e32 v119, v122, v115
	v_fma_f32 v111, -v111, v119, v118
	v_div_fmas_f32 v111, v111, v115, v119
	v_div_fixup_f32 v110, v111, v114, v110
	v_cvt_pk_bf16_f32 v109, v110, v109
	v_mul_f32_e32 v110, 0xbfb8aa3b, v104
	v_mul_f32_e32 v111, 0xbfb8aa3b, v105
	v_exp_f32_e32 v110, v110
	v_exp_f32_e32 v111, v111
	s_nop 0
	v_pk_add_f32 v[110:111], v[110:111], 1.0 op_sel_hi:[1,0]
	s_nop 0
	v_div_scale_f32 v114, s[0:1], v111, v111, v105
	v_rcp_f32_e32 v115, v114
	s_nop 0
	v_fma_f32 v118, -v114, v115, 1.0
	v_fmac_f32_e32 v115, v118, v115
	v_div_scale_f32 v118, vcc, v105, v111, v105
	v_mul_f32_e32 v119, v118, v115
	v_fma_f32 v122, -v114, v119, v118
	v_fmac_f32_e32 v119, v122, v115
	v_fma_f32 v114, -v114, v119, v118
	v_div_fmas_f32 v114, v114, v115, v119
	v_div_fixup_f32 v105, v114, v111, v105
	v_div_scale_f32 v111, s[0:1], v110, v110, v104
	v_rcp_f32_e32 v114, v111
	s_nop 0
	v_fma_f32 v115, -v111, v114, 1.0
	v_fmac_f32_e32 v114, v115, v114
	v_div_scale_f32 v115, vcc, v104, v110, v104
	v_mul_f32_e32 v118, v115, v114
; DEVI uint32_t pack2(float lo, float hi) { f32x2_t v = {lo, hi}; bf16x2_t b = __builtin_convertvector(v, bf16x2_t); return __builtin_bit_cast(uint32_t, b); }
; DEVI float siluf_(float x) { return x / (1.f + __expf(-x)); }
; DEVI void phase_p8(const int TIDX, const int BIDX, const int GDIM, KAP KA, unsigned char* WSB, float* OUTB, int l, unsigned char* smem) {
;     ...
; #pragma unroll
;     for (int i = 0; i < 4; ++i)
; #pragma unroll
;       for (int j = 0; j < 4; ++j) sg[i][j] = make_uint2(pack2(siluf_(acc[i][j][0]), siluf_(acc[i][j][1])), pack2(siluf_(acc[i][j][2]), siluf_(acc[i][j][3])));
	v_fma_f32 v119, -v111, v118, v115
	v_fmac_f32_e32 v118, v119, v114
	v_fma_f32 v111, -v111, v118, v115
	v_div_fmas_f32 v111, v111, v114, v118
	v_div_fixup_f32 v104, v111, v110, v104
	v_cvt_pk_bf16_f32 v104, v104, v105
	v_mul_f32_e32 v105, 0xbfb8aa3b, v106
	v_exp_f32_e32 v110, v105
	v_mul_f32_e32 v105, 0xbfb8aa3b, v107
	v_exp_f32_e32 v111, v105
	s_nop 0
	v_pk_add_f32 v[110:111], v[110:111], 1.0 op_sel_hi:[1,0]
	s_nop 0
	v_div_scale_f32 v105, s[0:1], v111, v111, v107
	v_rcp_f32_e32 v114, v105
	s_nop 0
	v_fma_f32 v115, -v105, v114, 1.0
	v_fmac_f32_e32 v114, v115, v114
	v_div_scale_f32 v115, vcc, v107, v111, v107
	v_mul_f32_e32 v118, v115, v114
	v_fma_f32 v119, -v105, v118, v115
	v_fmac_f32_e32 v118, v119, v114
	v_fma_f32 v105, -v105, v118, v115
	v_div_fmas_f32 v105, v105, v114, v118
	v_div_fixup_f32 v105, v105, v111, v107
	v_div_scale_f32 v107, s[0:1], v110, v110, v106
	v_rcp_f32_e32 v111, v107
	s_nop 0
	v_fma_f32 v114, -v107, v111, 1.0
	v_fmac_f32_e32 v111, v114, v111
	v_div_scale_f32 v114, vcc, v106, v110, v106
	v_mul_f32_e32 v115, v114, v111
	v_fma_f32 v118, -v107, v115, v114
	v_fmac_f32_e32 v115, v118, v111
	v_fma_f32 v107, -v107, v115, v114
	v_div_fmas_f32 v107, v107, v111, v115
	v_div_fixup_f32 v106, v107, v110, v106
	v_cvt_pk_bf16_f32 v105, v106, v105
	v_mul_f32_e32 v106, 0xbfb8aa3b, v100
	v_mul_f32_e32 v107, 0xbfb8aa3b, v101
	v_exp_f32_e32 v106, v106
	v_exp_f32_e32 v107, v107
	s_nop 0
	v_pk_add_f32 v[106:107], v[106:107], 1.0 op_sel_hi:[1,0]
	s_nop 0
	v_div_scale_f32 v110, s[0:1], v107, v107, v101
	v_rcp_f32_e32 v111, v110
	s_nop 0
	v_fma_f32 v114, -v110, v111, 1.0
	v_fmac_f32_e32 v111, v114, v111
	v_div_scale_f32 v114, vcc, v101, v107, v101
	v_mul_f32_e32 v115, v114, v111
	v_fma_f32 v118, -v110, v115, v114
	v_fmac_f32_e32 v115, v118, v111
	v_fma_f32 v110, -v110, v115, v114
	v_div_fmas_f32 v110, v110, v111, v115
	v_div_fixup_f32 v101, v110, v107, v101
	v_div_scale_f32 v107, s[0:1], v106, v106, v100
	v_rcp_f32_e32 v110, v107
	s_nop 0
	v_fma_f32 v111, -v107, v110, 1.0
	v_fmac_f32_e32 v110, v111, v110
	v_div_scale_f32 v111, vcc, v100, v106, v100
	v_mul_f32_e32 v114, v111, v110
	v_fma_f32 v115, -v107, v114, v111
	v_fmac_f32_e32 v114, v115, v110
	v_fma_f32 v107, -v107, v114, v111
	v_div_fmas_f32 v107, v107, v110, v114
	v_div_fixup_f32 v100, v107, v106, v100
	v_cvt_pk_bf16_f32 v100, v100, v101
	v_mul_f32_e32 v101, 0xbfb8aa3b, v102
	v_exp_f32_e32 v106, v101
	v_mul_f32_e32 v101, 0xbfb8aa3b, v103
	v_exp_f32_e32 v107, v101
	s_nop 0
	v_pk_add_f32 v[106:107], v[106:107], 1.0 op_sel_hi:[1,0]
	s_nop 0
	v_div_scale_f32 v101, s[0:1], v107, v107, v103
	v_rcp_f32_e32 v110, v101
	s_nop 0
	v_fma_f32 v111, -v101, v110, 1.0
	v_fmac_f32_e32 v110, v111, v110
	v_div_scale_f32 v111, vcc, v103, v107, v103
	v_mul_f32_e32 v114, v111, v110
	v_fma_f32 v115, -v101, v114, v111
	v_fmac_f32_e32 v114, v115, v110
	v_fma_f32 v101, -v101, v114, v111
	v_div_fmas_f32 v101, v101, v110, v114
	v_div_fixup_f32 v101, v101, v107, v103
	v_div_scale_f32 v103, s[0:1], v106, v106, v102
	v_rcp_f32_e32 v107, v103
	s_nop 0
	v_fma_f32 v110, -v103, v107, 1.0
	v_fmac_f32_e32 v107, v110, v107
	v_div_scale_f32 v110, vcc, v102, v106, v102
	v_mul_f32_e32 v111, v110, v107
	v_fma_f32 v114, -v103, v111, v110
	v_fmac_f32_e32 v111, v114, v107
	v_fma_f32 v103, -v103, v111, v110
	v_div_fmas_f32 v103, v103, v107, v111
	v_div_fixup_f32 v102, v103, v106, v102
	v_cvt_pk_bf16_f32 v101, v102, v101
	v_mul_f32_e32 v102, 0xbfb8aa3b, v96
	v_mul_f32_e32 v103, 0xbfb8aa3b, v97
	v_exp_f32_e32 v102, v102
	v_exp_f32_e32 v103, v103
	s_nop 0
	v_pk_add_f32 v[102:103], v[102:103], 1.0 op_sel_hi:[1,0]
	s_nop 0
	v_div_scale_f32 v106, s[0:1], v103, v103, v97
	v_rcp_f32_e32 v107, v106
	s_nop 0
	v_fma_f32 v110, -v106, v107, 1.0
	v_fmac_f32_e32 v107, v110, v107
	v_div_scale_f32 v110, vcc, v97, v103, v97
	v_mul_f32_e32 v111, v110, v107
	v_fma_f32 v114, -v106, v111, v110
	v_fmac_f32_e32 v111, v114, v107
	v_fma_f32 v106, -v106, v111, v110
	v_div_fmas_f32 v106, v106, v107, v111
	v_div_fixup_f32 v97, v106, v103, v97
	v_div_scale_f32 v103, s[0:1], v102, v102, v96
	v_rcp_f32_e32 v106, v103
	s_nop 0
	v_fma_f32 v107, -v103, v106, 1.0
	v_fmac_f32_e32 v106, v107, v106
	v_div_scale_f32 v107, vcc, v96, v102, v96
	v_mul_f32_e32 v110, v107, v106
	v_fma_f32 v111, -v103, v110, v107
	v_fmac_f32_e32 v110, v111, v106
	v_fma_f32 v103, -v103, v110, v107
	v_div_fmas_f32 v103, v103, v106, v110
	v_div_fixup_f32 v96, v103, v102, v96
	v_cvt_pk_bf16_f32 v96, v96, v97
	v_mul_f32_e32 v97, 0xbfb8aa3b, v98
	v_exp_f32_e32 v102, v97
	v_mul_f32_e32 v97, 0xbfb8aa3b, v99
	v_exp_f32_e32 v103, v97
	s_nop 0
	v_pk_add_f32 v[102:103], v[102:103], 1.0 op_sel_hi:[1,0]
	s_nop 0
	v_div_scale_f32 v97, s[0:1], v103, v103, v99
	v_rcp_f32_e32 v106, v97
	s_nop 0
	v_fma_f32 v107, -v97, v106, 1.0
	v_fmac_f32_e32 v106, v107, v106
	v_div_scale_f32 v107, vcc, v99, v103, v99
	v_mul_f32_e32 v110, v107, v106
	v_fma_f32 v111, -v97, v110, v107
	v_fmac_f32_e32 v110, v111, v106
	v_fma_f32 v97, -v97, v110, v107
	v_div_fmas_f32 v97, v97, v106, v110
	v_div_fixup_f32 v97, v97, v103, v99
	v_div_scale_f32 v99, s[0:1], v102, v102, v98
	v_rcp_f32_e32 v103, v99
	s_nop 0
	v_fma_f32 v106, -v99, v103, 1.0
	v_fmac_f32_e32 v103, v106, v103
	v_div_scale_f32 v106, vcc, v98, v102, v98
	v_mul_f32_e32 v107, v106, v103
	v_fma_f32 v110, -v99, v107, v106
	v_fmac_f32_e32 v107, v110, v103
	v_fma_f32 v99, -v99, v107, v106
	v_div_fmas_f32 v99, v99, v103, v107
	v_div_fixup_f32 v98, v99, v102, v98
	v_cvt_pk_bf16_f32 v97, v98, v97
	v_mul_f32_e32 v98, 0xbfb8aa3b, v92
	v_mul_f32_e32 v99, 0xbfb8aa3b, v93
	v_exp_f32_e32 v98, v98
	v_exp_f32_e32 v99, v99
	s_nop 0
	v_pk_add_f32 v[98:99], v[98:99], 1.0 op_sel_hi:[1,0]
; DEVI uint32_t pack2(float lo, float hi) { f32x2_t v = {lo, hi}; bf16x2_t b = __builtin_convertvector(v, bf16x2_t); return __builtin_bit_cast(uint32_t, b); }
; DEVI float siluf_(float x) { return x / (1.f + __expf(-x)); }
; DEVI void phase_p8(const int TIDX, const int BIDX, const int GDIM, KAP KA, unsigned char* WSB, float* OUTB, int l, unsigned char* smem) {
;     ...
; #pragma unroll
;     for (int i = 0; i < 4; ++i)
; #pragma unroll
;       for (int j = 0; j < 4; ++j) sg[i][j] = make_uint2(pack2(siluf_(acc[i][j][0]), siluf_(acc[i][j][1])), pack2(siluf_(acc[i][j][2]), siluf_(acc[i][j][3])));
	s_nop 0
	v_div_scale_f32 v102, s[0:1], v99, v99, v93
	v_rcp_f32_e32 v103, v102
	s_nop 0
	v_fma_f32 v106, -v102, v103, 1.0
	v_fmac_f32_e32 v103, v106, v103
	v_div_scale_f32 v106, vcc, v93, v99, v93
	v_mul_f32_e32 v107, v106, v103
	v_fma_f32 v110, -v102, v107, v106
	v_fmac_f32_e32 v107, v110, v103
	v_fma_f32 v102, -v102, v107, v106
	v_div_fmas_f32 v102, v102, v103, v107
	v_div_fixup_f32 v93, v102, v99, v93
	v_div_scale_f32 v99, s[0:1], v98, v98, v92
	v_rcp_f32_e32 v102, v99
	s_nop 0
	v_fma_f32 v103, -v99, v102, 1.0
	v_fmac_f32_e32 v102, v103, v102
	v_div_scale_f32 v103, vcc, v92, v98, v92
	v_mul_f32_e32 v106, v103, v102
	v_fma_f32 v107, -v99, v106, v103
	v_fmac_f32_e32 v106, v107, v102
	v_fma_f32 v99, -v99, v106, v103
	v_div_fmas_f32 v99, v99, v102, v106
	v_div_fixup_f32 v92, v99, v98, v92
	v_cvt_pk_bf16_f32 v92, v92, v93
	v_mul_f32_e32 v93, 0xbfb8aa3b, v94
	v_exp_f32_e32 v98, v93
	v_mul_f32_e32 v93, 0xbfb8aa3b, v95
	v_exp_f32_e32 v99, v93
	s_nop 0
	v_pk_add_f32 v[98:99], v[98:99], 1.0 op_sel_hi:[1,0]
	s_nop 0
	v_div_scale_f32 v93, s[0:1], v99, v99, v95
	v_rcp_f32_e32 v102, v93
	s_nop 0
	v_fma_f32 v103, -v93, v102, 1.0
	v_fmac_f32_e32 v102, v103, v102
	v_div_scale_f32 v103, vcc, v95, v99, v95
	v_mul_f32_e32 v106, v103, v102
	v_fma_f32 v107, -v93, v106, v103
	v_fmac_f32_e32 v106, v107, v102
	v_fma_f32 v93, -v93, v106, v103
	v_div_fmas_f32 v93, v93, v102, v106
	v_div_fixup_f32 v93, v93, v99, v95
	v_div_scale_f32 v95, s[0:1], v98, v98, v94
	v_rcp_f32_e32 v99, v95
	s_nop 0
	v_fma_f32 v102, -v95, v99, 1.0
	v_fmac_f32_e32 v99, v102, v99
	v_div_scale_f32 v102, vcc, v94, v98, v94
	v_mul_f32_e32 v103, v102, v99
	v_fma_f32 v106, -v95, v103, v102
	v_fmac_f32_e32 v103, v106, v99
	v_fma_f32 v95, -v95, v103, v102
	v_div_fmas_f32 v95, v95, v99, v103
	v_div_fixup_f32 v94, v95, v98, v94
	v_cvt_pk_bf16_f32 v93, v94, v93
	v_mul_f32_e32 v94, 0xbfb8aa3b, v88
	v_mul_f32_e32 v95, 0xbfb8aa3b, v89
	v_exp_f32_e32 v94, v94
	v_exp_f32_e32 v95, v95
	s_nop 0
	v_pk_add_f32 v[94:95], v[94:95], 1.0 op_sel_hi:[1,0]
	s_nop 0
	v_div_scale_f32 v98, s[0:1], v95, v95, v89
	v_rcp_f32_e32 v99, v98
	s_nop 0
	v_fma_f32 v102, -v98, v99, 1.0
	v_fmac_f32_e32 v99, v102, v99
	v_div_scale_f32 v102, vcc, v89, v95, v89
	v_mul_f32_e32 v103, v102, v99
	v_fma_f32 v106, -v98, v103, v102
	v_fmac_f32_e32 v103, v106, v99
	v_fma_f32 v98, -v98, v103, v102
	v_div_fmas_f32 v98, v98, v99, v103
	v_div_fixup_f32 v89, v98, v95, v89
	v_div_scale_f32 v95, s[0:1], v94, v94, v88
	v_rcp_f32_e32 v98, v95
	s_nop 0
	v_fma_f32 v99, -v95, v98, 1.0
	v_fmac_f32_e32 v98, v99, v98
	v_div_scale_f32 v99, vcc, v88, v94, v88
	v_mul_f32_e32 v102, v99, v98
	v_fma_f32 v103, -v95, v102, v99
	v_fmac_f32_e32 v102, v103, v98
	v_fma_f32 v95, -v95, v102, v99
	v_div_fmas_f32 v95, v95, v98, v102
	v_div_fixup_f32 v88, v95, v94, v88
	v_cvt_pk_bf16_f32 v88, v88, v89
	v_mul_f32_e32 v89, 0xbfb8aa3b, v90
	v_exp_f32_e32 v94, v89
	v_mul_f32_e32 v89, 0xbfb8aa3b, v91
	v_exp_f32_e32 v95, v89
	s_nop 0
	v_pk_add_f32 v[94:95], v[94:95], 1.0 op_sel_hi:[1,0]
	s_nop 0
	v_div_scale_f32 v89, s[0:1], v95, v95, v91
	v_rcp_f32_e32 v98, v89
	s_nop 0
	v_fma_f32 v99, -v89, v98, 1.0
	v_fmac_f32_e32 v98, v99, v98
	v_div_scale_f32 v99, vcc, v91, v95, v91
	v_mul_f32_e32 v102, v99, v98
	v_fma_f32 v103, -v89, v102, v99
	v_fmac_f32_e32 v102, v103, v98
	v_fma_f32 v89, -v89, v102, v99
	v_div_fmas_f32 v89, v89, v98, v102
	v_div_fixup_f32 v89, v89, v95, v91
	v_div_scale_f32 v91, s[0:1], v94, v94, v90
	v_rcp_f32_e32 v95, v91
	s_nop 0
	v_fma_f32 v98, -v91, v95, 1.0
	v_fmac_f32_e32 v95, v98, v95
	v_div_scale_f32 v98, vcc, v90, v94, v90
	v_mul_f32_e32 v99, v98, v95
	v_fma_f32 v102, -v91, v99, v98
	v_fmac_f32_e32 v99, v102, v95
	v_fma_f32 v91, -v91, v99, v98
	v_div_fmas_f32 v91, v91, v95, v99
	v_div_fixup_f32 v90, v91, v94, v90
	v_cvt_pk_bf16_f32 v89, v90, v89
	v_mul_f32_e32 v90, 0xbfb8aa3b, v84
	v_mul_f32_e32 v91, 0xbfb8aa3b, v85
	v_exp_f32_e32 v90, v90
	v_exp_f32_e32 v91, v91
	s_nop 0
	v_pk_add_f32 v[90:91], v[90:91], 1.0 op_sel_hi:[1,0]
	s_nop 0
	v_div_scale_f32 v94, s[0:1], v91, v91, v85
	v_rcp_f32_e32 v95, v94
	s_nop 0
	v_fma_f32 v98, -v94, v95, 1.0
	v_fmac_f32_e32 v95, v98, v95
	v_div_scale_f32 v98, vcc, v85, v91, v85
	v_mul_f32_e32 v99, v98, v95
	v_fma_f32 v102, -v94, v99, v98
	v_fmac_f32_e32 v99, v102, v95
	v_fma_f32 v94, -v94, v99, v98
	v_div_fmas_f32 v94, v94, v95, v99
	v_div_fixup_f32 v85, v94, v91, v85
	v_div_scale_f32 v91, s[0:1], v90, v90, v84
	v_rcp_f32_e32 v94, v91
	s_nop 0
	v_fma_f32 v95, -v91, v94, 1.0
	v_fmac_f32_e32 v94, v95, v94
	v_div_scale_f32 v95, vcc, v84, v90, v84
	v_mul_f32_e32 v98, v95, v94
	v_fma_f32 v99, -v91, v98, v95
	v_fmac_f32_e32 v98, v99, v94
	v_fma_f32 v91, -v91, v98, v95
	v_div_fmas_f32 v91, v91, v94, v98
	v_div_fixup_f32 v84, v91, v90, v84
	v_cvt_pk_bf16_f32 v84, v84, v85
	v_mul_f32_e32 v85, 0xbfb8aa3b, v86
	v_exp_f32_e32 v90, v85
	v_mul_f32_e32 v85, 0xbfb8aa3b, v87
	v_exp_f32_e32 v91, v85
	s_nop 0
	v_pk_add_f32 v[90:91], v[90:91], 1.0 op_sel_hi:[1,0]
	s_nop 0
	v_div_scale_f32 v85, s[0:1], v91, v91, v87
	v_rcp_f32_e32 v94, v85
	s_nop 0
	v_fma_f32 v95, -v85, v94, 1.0
	v_fmac_f32_e32 v94, v95, v94
	v_div_scale_f32 v95, vcc, v87, v91, v87
	v_mul_f32_e32 v98, v95, v94
	v_fma_f32 v99, -v85, v98, v95
	v_fmac_f32_e32 v98, v99, v94
	v_fma_f32 v85, -v85, v98, v95
	v_div_fmas_f32 v85, v85, v94, v98
	v_div_fixup_f32 v85, v85, v91, v87
	v_div_scale_f32 v87, s[0:1], v90, v90, v86
	v_rcp_f32_e32 v91, v87
	s_nop 0
	v_fma_f32 v94, -v87, v91, 1.0
	v_fmac_f32_e32 v91, v94, v91
	v_div_scale_f32 v94, vcc, v86, v90, v86
	v_mul_f32_e32 v95, v94, v91
	v_fma_f32 v98, -v87, v95, v94
	v_fmac_f32_e32 v95, v98, v91
	v_fma_f32 v87, -v87, v95, v94
; DEVI uint32_t pack2(float lo, float hi) { f32x2_t v = {lo, hi}; bf16x2_t b = __builtin_convertvector(v, bf16x2_t); return __builtin_bit_cast(uint32_t, b); }
; DEVI float siluf_(float x) { return x / (1.f + __expf(-x)); }
; DEVI void phase_p8(const int TIDX, const int BIDX, const int GDIM, KAP KA, unsigned char* WSB, float* OUTB, int l, unsigned char* smem) {
;     ...
; #pragma unroll
;     for (int i = 0; i < 4; ++i)
; #pragma unroll
;       for (int j = 0; j < 4; ++j) sg[i][j] = make_uint2(pack2(siluf_(acc[i][j][0]), siluf_(acc[i][j][1])), pack2(siluf_(acc[i][j][2]), siluf_(acc[i][j][3])));
	v_div_fmas_f32 v87, v87, v91, v95
	v_div_fixup_f32 v86, v87, v90, v86
	v_cvt_pk_bf16_f32 v85, v86, v85
	v_mul_f32_e32 v86, 0xbfb8aa3b, v80
	v_mul_f32_e32 v87, 0xbfb8aa3b, v81
	v_exp_f32_e32 v86, v86
	v_exp_f32_e32 v87, v87
	s_nop 0
	v_pk_add_f32 v[86:87], v[86:87], 1.0 op_sel_hi:[1,0]
	s_nop 0
	v_div_scale_f32 v90, s[0:1], v87, v87, v81
	v_rcp_f32_e32 v91, v90
	s_nop 0
	v_fma_f32 v94, -v90, v91, 1.0
	v_fmac_f32_e32 v91, v94, v91
	v_div_scale_f32 v94, vcc, v81, v87, v81
	v_mul_f32_e32 v95, v94, v91
	v_fma_f32 v98, -v90, v95, v94
	v_fmac_f32_e32 v95, v98, v91
	v_fma_f32 v90, -v90, v95, v94
	v_div_fmas_f32 v90, v90, v91, v95
	v_div_fixup_f32 v81, v90, v87, v81
	v_div_scale_f32 v87, s[0:1], v86, v86, v80
	v_rcp_f32_e32 v90, v87
	s_nop 0
	v_fma_f32 v91, -v87, v90, 1.0
	v_fmac_f32_e32 v90, v91, v90
	v_div_scale_f32 v91, vcc, v80, v86, v80
	v_mul_f32_e32 v94, v91, v90
	v_fma_f32 v95, -v87, v94, v91
	v_fmac_f32_e32 v94, v95, v90
	v_fma_f32 v87, -v87, v94, v91
	v_div_fmas_f32 v87, v87, v90, v94
	v_div_fixup_f32 v80, v87, v86, v80
	v_cvt_pk_bf16_f32 v80, v80, v81
	v_mul_f32_e32 v81, 0xbfb8aa3b, v82
	v_exp_f32_e32 v86, v81
	v_mul_f32_e32 v81, 0xbfb8aa3b, v83
	v_exp_f32_e32 v87, v81
	s_nop 0
	v_pk_add_f32 v[86:87], v[86:87], 1.0 op_sel_hi:[1,0]
	s_nop 0
	v_div_scale_f32 v81, s[0:1], v87, v87, v83
	v_rcp_f32_e32 v90, v81
	s_nop 0
	v_fma_f32 v91, -v81, v90, 1.0
	v_fmac_f32_e32 v90, v91, v90
	v_div_scale_f32 v91, vcc, v83, v87, v83
	v_mul_f32_e32 v94, v91, v90
	v_fma_f32 v95, -v81, v94, v91
	v_fmac_f32_e32 v94, v95, v90
	v_fma_f32 v81, -v81, v94, v91
	v_div_fmas_f32 v81, v81, v90, v94
	v_div_fixup_f32 v81, v81, v87, v83
	v_div_scale_f32 v83, s[0:1], v86, v86, v82
	v_rcp_f32_e32 v87, v83
	s_nop 0
	v_fma_f32 v90, -v83, v87, 1.0
	v_fmac_f32_e32 v87, v90, v87
	v_div_scale_f32 v90, vcc, v82, v86, v82
	v_mul_f32_e32 v91, v90, v87
	v_fma_f32 v94, -v83, v91, v90
	v_fmac_f32_e32 v91, v94, v87
	v_fma_f32 v83, -v83, v91, v90
	v_div_fmas_f32 v83, v83, v87, v91
	v_div_fixup_f32 v82, v83, v86, v82
	v_cvt_pk_bf16_f32 v81, v82, v81
	v_mul_f32_e32 v82, 0xbfb8aa3b, v76
	v_mul_f32_e32 v83, 0xbfb8aa3b, v77
	v_exp_f32_e32 v82, v82
	v_exp_f32_e32 v83, v83
	s_nop 0
	v_pk_add_f32 v[82:83], v[82:83], 1.0 op_sel_hi:[1,0]
	s_nop 0
	v_div_scale_f32 v86, s[0:1], v83, v83, v77
	v_rcp_f32_e32 v87, v86
	s_nop 0
	v_fma_f32 v90, -v86, v87, 1.0
	v_fmac_f32_e32 v87, v90, v87
	v_div_scale_f32 v90, vcc, v77, v83, v77
	v_mul_f32_e32 v91, v90, v87
	v_fma_f32 v94, -v86, v91, v90
	v_fmac_f32_e32 v91, v94, v87
	v_fma_f32 v86, -v86, v91, v90
	v_div_fmas_f32 v86, v86, v87, v91
	v_div_fixup_f32 v77, v86, v83, v77
	v_div_scale_f32 v83, s[0:1], v82, v82, v76
	v_rcp_f32_e32 v86, v83
	s_nop 0
	v_fma_f32 v87, -v83, v86, 1.0
	v_fmac_f32_e32 v86, v87, v86
	v_div_scale_f32 v87, vcc, v76, v82, v76
	v_mul_f32_e32 v90, v87, v86
	v_fma_f32 v91, -v83, v90, v87
	v_fmac_f32_e32 v90, v91, v86
	v_fma_f32 v83, -v83, v90, v87
	v_div_fmas_f32 v83, v83, v86, v90
	v_div_fixup_f32 v76, v83, v82, v76
	v_cvt_pk_bf16_f32 v76, v76, v77
	v_mul_f32_e32 v77, 0xbfb8aa3b, v78
	v_exp_f32_e32 v82, v77
	v_mul_f32_e32 v77, 0xbfb8aa3b, v79
	v_exp_f32_e32 v83, v77
	s_nop 0
	v_pk_add_f32 v[82:83], v[82:83], 1.0 op_sel_hi:[1,0]
	s_nop 0
	v_div_scale_f32 v77, s[0:1], v83, v83, v79
	v_rcp_f32_e32 v86, v77
	s_nop 0
	v_fma_f32 v87, -v77, v86, 1.0
	v_fmac_f32_e32 v86, v87, v86
	v_div_scale_f32 v87, vcc, v79, v83, v79
	v_mul_f32_e32 v90, v87, v86
	v_fma_f32 v91, -v77, v90, v87
	v_fmac_f32_e32 v90, v91, v86
	v_fma_f32 v77, -v77, v90, v87
	v_div_fmas_f32 v77, v77, v86, v90
	v_div_fixup_f32 v77, v77, v83, v79
	v_div_scale_f32 v79, s[0:1], v82, v82, v78
	v_rcp_f32_e32 v83, v79
	s_nop 0
	v_fma_f32 v86, -v79, v83, 1.0
	v_fmac_f32_e32 v83, v86, v83
	v_div_scale_f32 v86, vcc, v78, v82, v78
	v_mul_f32_e32 v87, v86, v83
	v_fma_f32 v90, -v79, v87, v86
	v_fmac_f32_e32 v87, v90, v83
	v_fma_f32 v79, -v79, v87, v86
	v_div_fmas_f32 v79, v79, v83, v87
	v_div_fixup_f32 v78, v79, v82, v78
	v_cvt_pk_bf16_f32 v77, v78, v77
	v_mul_f32_e32 v78, 0xbfb8aa3b, v72
	v_mul_f32_e32 v79, 0xbfb8aa3b, v73
	v_exp_f32_e32 v78, v78
	v_exp_f32_e32 v79, v79
	s_nop 0
	v_pk_add_f32 v[78:79], v[78:79], 1.0 op_sel_hi:[1,0]
	s_nop 0
	v_div_scale_f32 v82, s[0:1], v79, v79, v73
	v_rcp_f32_e32 v83, v82
	s_nop 0
	v_fma_f32 v86, -v82, v83, 1.0
	v_fmac_f32_e32 v83, v86, v83
	v_div_scale_f32 v86, vcc, v73, v79, v73
	v_mul_f32_e32 v87, v86, v83
	v_fma_f32 v90, -v82, v87, v86
	v_fmac_f32_e32 v87, v90, v83
	v_fma_f32 v82, -v82, v87, v86
	v_div_fmas_f32 v82, v82, v83, v87
	v_div_fixup_f32 v73, v82, v79, v73
	v_div_scale_f32 v79, s[0:1], v78, v78, v72
	v_rcp_f32_e32 v82, v79
	s_nop 0
	v_fma_f32 v83, -v79, v82, 1.0
	v_fmac_f32_e32 v82, v83, v82
	v_div_scale_f32 v83, vcc, v72, v78, v72
	v_mul_f32_e32 v86, v83, v82
	v_fma_f32 v87, -v79, v86, v83
	v_fmac_f32_e32 v86, v87, v82
	v_fma_f32 v79, -v79, v86, v83
	v_div_fmas_f32 v79, v79, v82, v86
	v_div_fixup_f32 v72, v79, v78, v72
	v_cvt_pk_bf16_f32 v72, v72, v73
	v_mul_f32_e32 v73, 0xbfb8aa3b, v74
	v_exp_f32_e32 v78, v73
	v_mul_f32_e32 v73, 0xbfb8aa3b, v75
	v_exp_f32_e32 v79, v73
	s_nop 0
	v_pk_add_f32 v[78:79], v[78:79], 1.0 op_sel_hi:[1,0]
	s_nop 0
	v_div_scale_f32 v73, s[0:1], v79, v79, v75
	v_rcp_f32_e32 v82, v73
	s_nop 0
	v_fma_f32 v83, -v73, v82, 1.0
	v_fmac_f32_e32 v82, v83, v82
	v_div_scale_f32 v83, vcc, v75, v79, v75
	v_mul_f32_e32 v86, v83, v82
	v_fma_f32 v87, -v73, v86, v83
	v_fmac_f32_e32 v86, v87, v82
	v_fma_f32 v73, -v73, v86, v83
	v_div_fmas_f32 v73, v73, v82, v86
	v_div_fixup_f32 v73, v73, v79, v75
	v_div_scale_f32 v75, s[0:1], v78, v78, v74
	v_rcp_f32_e32 v79, v75
	s_nop 0
	v_fma_f32 v82, -v75, v79, 1.0
	v_fmac_f32_e32 v79, v82, v79
; DEVI uint32_t pack2(float lo, float hi) { f32x2_t v = {lo, hi}; bf16x2_t b = __builtin_convertvector(v, bf16x2_t); return __builtin_bit_cast(uint32_t, b); }
; DEVI float siluf_(float x) { return x / (1.f + __expf(-x)); }
; DEVI f32x4 mfma16(bf16x8 a, bf16x8 b, f32x4 c) { return __builtin_amdgcn_mfma_f32_16x16x32_bf16(a, b, c, 0, 0, 0); }
; template <bool SWAP, class RP>
; DEVI void gemm_main(const int TIDX, const int BIDX, const int GDIM, f32x4 (&acc)[4][4], RP rowoff, const bf16_t* __restrict__ Bt, int ldb, int K, unsigned char* smem) {
;     ...
;     const unsigned char* A = smem + buf * 32768 + (wr * 64 + li) * 128;
;     const unsigned char* B = smem + buf * 32768 + 16384 + (wc * 64 + li) * 128;
; #pragma unroll
;     for (int ks = 0; ks < 2; ++ks) {
;       const int po = (px ^ (ks * 4)) * 16;
;       bf16x8 af[4], bfr[4];
; #pragma unroll
;       for (int i = 0; i < 4; ++i) {
;         af[i] = *(const bf16x8*)(A + i * 2048 + po);
;         bfr[i] = *(const bf16x8*)(B + i * 2048 + po);
;       }
; #pragma unroll
;       for (int mi = 0; mi < 4; ++mi)
; #pragma unroll
;         for (int ni = 0; ni < 4; ++ni)
;           acc[mi][ni] = SWAP ? mfma16(bfr[ni], af[mi], acc[mi][ni]) : mfma16(af[mi], bfr[ni], acc[mi][ni]);
;     }
;   }
;   __syncthreads();
; DEVI void phase_p8(const int TIDX, const int BIDX, const int GDIM, KAP KA, unsigned char* WSB, float* OUTB, int l, unsigned char* smem) {
;     ...
; #pragma unroll
;     for (int i = 0; i < 4; ++i)
; #pragma unroll
;       for (int j = 0; j < 4; ++j) sg[i][j] = make_uint2(pack2(siluf_(acc[i][j][0]), siluf_(acc[i][j][1])), pack2(siluf_(acc[i][j][2]), siluf_(acc[i][j][3])));
;     zero_acc(acc);
;     gemm_main<true>(TIDX, BIDX, GDIM, acc, rg, WE + ((size_t)(32 + e) * 512 + nt * 128) * 1024, 1024, 1024, smem);
	v_div_scale_f32 v82, vcc, v74, v78, v74
	v_mul_f32_e32 v83, v82, v79
	v_fma_f32 v86, -v75, v83, v82
	v_fmac_f32_e32 v83, v86, v79
	v_fma_f32 v75, -v75, v83, v82
	v_div_fmas_f32 v75, v75, v79, v83
	v_div_fixup_f32 v74, v75, v78, v74
	v_cvt_pk_bf16_f32 v73, v74, v73
	v_mul_f32_e32 v74, 0xbfb8aa3b, v68
	v_mul_f32_e32 v75, 0xbfb8aa3b, v69
	v_exp_f32_e32 v74, v74
	v_exp_f32_e32 v75, v75
	s_nop 0
	v_pk_add_f32 v[74:75], v[74:75], 1.0 op_sel_hi:[1,0]
	s_nop 0
	v_div_scale_f32 v78, s[0:1], v75, v75, v69
	v_rcp_f32_e32 v79, v78
	s_nop 0
	v_fma_f32 v82, -v78, v79, 1.0
	v_fmac_f32_e32 v79, v82, v79
	v_div_scale_f32 v82, vcc, v69, v75, v69
	v_mul_f32_e32 v83, v82, v79
	v_fma_f32 v86, -v78, v83, v82
	v_fmac_f32_e32 v83, v86, v79
	v_fma_f32 v78, -v78, v83, v82
	v_div_fmas_f32 v78, v78, v79, v83
	v_div_fixup_f32 v69, v78, v75, v69
	v_div_scale_f32 v75, s[0:1], v74, v74, v68
	v_rcp_f32_e32 v78, v75
	s_nop 0
	v_fma_f32 v79, -v75, v78, 1.0
	v_fmac_f32_e32 v78, v79, v78
	v_div_scale_f32 v79, vcc, v68, v74, v68
	v_mul_f32_e32 v82, v79, v78
	v_fma_f32 v83, -v75, v82, v79
	v_fmac_f32_e32 v82, v83, v78
	v_fma_f32 v75, -v75, v82, v79
	v_div_fmas_f32 v75, v75, v78, v82
	v_div_fixup_f32 v68, v75, v74, v68
	v_cvt_pk_bf16_f32 v68, v68, v69
	v_mul_f32_e32 v69, 0xbfb8aa3b, v70
	v_exp_f32_e32 v74, v69
	v_mul_f32_e32 v69, 0xbfb8aa3b, v71
	v_exp_f32_e32 v75, v69
	s_nop 0
	v_pk_add_f32 v[74:75], v[74:75], 1.0 op_sel_hi:[1,0]
	s_nop 0
	v_div_scale_f32 v69, s[0:1], v75, v75, v71
	v_rcp_f32_e32 v78, v69
	s_nop 0
	v_fma_f32 v79, -v69, v78, 1.0
	v_fmac_f32_e32 v78, v79, v78
	v_div_scale_f32 v79, vcc, v71, v75, v71
	v_mul_f32_e32 v82, v79, v78
	v_fma_f32 v83, -v69, v82, v79
	v_fmac_f32_e32 v82, v83, v78
	v_fma_f32 v69, -v69, v82, v79
	v_div_fmas_f32 v69, v69, v78, v82
	v_div_fixup_f32 v69, v69, v75, v71
	v_div_scale_f32 v71, s[0:1], v74, v74, v70
	v_rcp_f32_e32 v75, v71
	s_nop 0
	v_fma_f32 v78, -v71, v75, 1.0
	v_fmac_f32_e32 v75, v78, v75
	v_div_scale_f32 v78, vcc, v70, v74, v70
	v_mul_f32_e32 v79, v78, v75
	v_fma_f32 v82, -v71, v79, v78
	v_fmac_f32_e32 v79, v82, v75
	v_fma_f32 v71, -v71, v79, v78
	v_div_fmas_f32 v71, v71, v75, v79
	v_div_fixup_f32 v70, v71, v74, v70
	v_cvt_pk_bf16_f32 v69, v70, v69
	v_mul_f32_e32 v70, 0xbfb8aa3b, v64
	v_mul_f32_e32 v71, 0xbfb8aa3b, v65
	v_exp_f32_e32 v70, v70
	v_exp_f32_e32 v71, v71
	s_nop 0
	v_pk_add_f32 v[70:71], v[70:71], 1.0 op_sel_hi:[1,0]
	s_nop 0
	v_div_scale_f32 v74, s[0:1], v71, v71, v65
	v_rcp_f32_e32 v75, v74
	s_nop 0
	v_fma_f32 v78, -v74, v75, 1.0
	v_fmac_f32_e32 v75, v78, v75
	v_div_scale_f32 v78, vcc, v65, v71, v65
	v_mul_f32_e32 v79, v78, v75
	v_fma_f32 v82, -v74, v79, v78
	v_fmac_f32_e32 v79, v82, v75
	v_fma_f32 v74, -v74, v79, v78
	v_div_fmas_f32 v74, v74, v75, v79
	v_div_fixup_f32 v65, v74, v71, v65
	v_div_scale_f32 v71, s[0:1], v70, v70, v64
	v_rcp_f32_e32 v74, v71
	s_nop 0
	v_fma_f32 v75, -v71, v74, 1.0
	v_fmac_f32_e32 v74, v75, v74
	v_div_scale_f32 v75, vcc, v64, v70, v64
	v_mul_f32_e32 v78, v75, v74
	v_fma_f32 v79, -v71, v78, v75
	v_fmac_f32_e32 v78, v79, v74
	v_fma_f32 v71, -v71, v78, v75
	v_div_fmas_f32 v71, v71, v74, v78
	v_div_fixup_f32 v64, v71, v70, v64
	v_cvt_pk_bf16_f32 v64, v64, v65
	v_mul_f32_e32 v65, 0xbfb8aa3b, v66
	v_exp_f32_e32 v70, v65
	v_mul_f32_e32 v65, 0xbfb8aa3b, v67
	v_exp_f32_e32 v71, v65
	s_nop 0
	v_pk_add_f32 v[70:71], v[70:71], 1.0 op_sel_hi:[1,0]
	s_nop 0
	v_div_scale_f32 v65, s[0:1], v71, v71, v67
	v_rcp_f32_e32 v74, v65
	s_nop 0
	v_fma_f32 v75, -v65, v74, 1.0
	v_fmac_f32_e32 v74, v75, v74
	v_div_scale_f32 v75, vcc, v67, v71, v67
	v_mul_f32_e32 v78, v75, v74
	v_fma_f32 v79, -v65, v78, v75
	v_fmac_f32_e32 v78, v79, v74
	v_fma_f32 v65, -v65, v78, v75
	v_div_fmas_f32 v65, v65, v74, v78
	v_div_fixup_f32 v65, v65, v71, v67
	v_div_scale_f32 v67, s[0:1], v70, v70, v66
	v_rcp_f32_e32 v71, v67
	s_nop 0
	v_fma_f32 v74, -v67, v71, 1.0
	v_fmac_f32_e32 v71, v74, v71
	v_div_scale_f32 v74, vcc, v66, v70, v66
	v_mul_f32_e32 v75, v74, v71
	v_fma_f32 v78, -v67, v75, v74
	v_fmac_f32_e32 v75, v78, v71
	v_fma_f32 v67, -v67, v75, v74
	v_div_fmas_f32 v67, v67, v71, v75
	v_div_fixup_f32 v66, v67, v70, v66
	v_cvt_pk_bf16_f32 v65, v66, v65
	v_add_u32_e32 v66, v147, v149
	v_add_u32_e32 v67, v66, v148
	v_add_u32_e32 v70, v146, v148
	ds_read_b128 v[134:137], v67 offset:55296
	ds_read_b128 v[138:141], v70 offset:38912
	ds_read_b128 v[148:151], v67 offset:53248
	ds_read_b128 v[152:155], v70 offset:36864
	ds_read_b128 v[156:159], v67 offset:51200
	ds_read_b128 v[162:165], v70 offset:34816
	ds_read_b128 v[166:169], v67 offset:49152
	ds_read_b128 v[170:173], v70 offset:32768
	s_waitcnt lgkmcnt(0)
	v_mfma_f32_16x16x32_bf16 v[60:63], v[166:169], v[170:173], v[60:63]
	v_add_u32_e32 v67, v146, v145
	v_add_u32_e32 v66, v66, v145
	v_lshlrev_b32_e32 v74, 16, v124
	v_mfma_f32_16x16x32_bf16 v[56:59], v[156:159], v[170:173], v[56:59]
	v_and_b32_e32 v75, 0xffff0000, v124
	v_or_b32_e32 v78, s18, v144
	v_lshlrev_b32_e32 v128, 1, v78
	v_mfma_f32_16x16x32_bf16 v[52:55], v[148:151], v[170:173], v[52:55]
	v_mfma_f32_16x16x32_bf16 v[48:51], v[134:137], v[170:173], v[48:51]
	v_mfma_f32_16x16x32_bf16 v[44:47], v[166:169], v[162:165], v[44:47]
	v_mfma_f32_16x16x32_bf16 v[40:43], v[156:159], v[162:165], v[40:43]
	v_mfma_f32_16x16x32_bf16 v[36:39], v[148:151], v[162:165], v[36:39]
	v_mfma_f32_16x16x32_bf16 v[32:35], v[134:137], v[162:165], v[32:35]
	v_mfma_f32_16x16x32_bf16 v[28:31], v[166:169], v[152:155], v[28:31]
	v_mfma_f32_16x16x32_bf16 v[24:27], v[156:159], v[152:155], v[24:27]
	v_mfma_f32_16x16x32_bf16 v[20:23], v[148:151], v[152:155], v[20:23]
	v_mfma_f32_16x16x32_bf16 v[16:19], v[134:137], v[152:155], v[16:19]
	v_mfma_f32_16x16x32_bf16 v[12:15], v[166:169], v[138:141], v[12:15]
	v_mfma_f32_16x16x32_bf16 v[8:11], v[156:159], v[138:141], v[8:11]
	v_mfma_f32_16x16x32_bf16 v[4:7], v[148:151], v[138:141], v[4:7]
	v_mfma_f32_16x16x32_bf16 v[134:137], v[134:137], v[138:141], v[0:3]
	s_nop 2
	ds_read_b128 v[0:3], v67 offset:32768
	ds_read_b128 v[138:141], v66 offset:49152
	ds_read_b128 v[146:149], v67 offset:34816
	ds_read_b128 v[150:153], v66 offset:51200
	ds_read_b128 v[154:157], v67 offset:36864
	ds_read_b128 v[162:165], v66 offset:53248
	ds_read_b128 v[166:169], v67 offset:38912
	ds_read_b128 v[170:173], v66 offset:55296
	v_lshl_add_u32 v66, s17, 7, v131
	v_ashrrev_i32_e32 v67, 31, v66
	s_waitcnt lgkmcnt(6)
	v_mfma_f32_16x16x32_bf16 v[60:63], v[138:141], v[0:3], v[60:63]
	v_lshlrev_b64 v[70:71], 10, v[66:67]
	v_lshl_add_u64 v[70:71], s[8:9], 0, v[70:71]
	s_waitcnt lgkmcnt(0)
	v_mfma_f32_16x16x32_bf16 v[56:59], v[150:153], v[0:3], v[56:59]
	s_barrier
; DEVI uint32_t pack2(float lo, float hi) { f32x2_t v = {lo, hi}; bf16x2_t b = __builtin_convertvector(v, bf16x2_t); return __builtin_bit_cast(uint32_t, b); }
; DEVI float lo2f(uint32_t u) { return __uint_as_float(u << 16); }
; DEVI float hi2f(uint32_t u) { return __uint_as_float(u & 0xffff0000u); }
; #define EPI_END } __builtin_amdgcn_sched_barrier(0); } }
; DEVI void phase_p8(const int TIDX, const int BIDX, const int GDIM, KAP KA, unsigned char* WSB, float* OUTB, int l, unsigned char* smem) {
;     ...
;     EPI_SWAP_BEGIN(mt * 128, nt * 128)
;       const f32x4 a = acc[mi][ni];
;       const uint2 g = sg[mi][ni];
;       *(uint2*)(H + (size_t)row * 512 + col) = make_uint2(pack2(a[0] * lo2f(g.x), a[1] * hi2f(g.x)), pack2(a[2] * lo2f(g.y), a[3] * hi2f(g.y)));
;     EPI_END
	s_nop 2
	v_pk_mul_f32 v[60:61], v[60:61], v[74:75]
	v_lshlrev_b32_e32 v74, 16, v125
	v_and_b32_e32 v75, 0xffff0000, v125
	v_pk_mul_f32 v[62:63], v[62:63], v[74:75]
	v_cvt_pk_bf16_f32 v60, v60, v61
	v_cvt_pk_bf16_f32 v61, v62, v63
	v_lshl_add_u64 v[62:63], v[70:71], 0, v[128:129]
	global_store_dwordx2 v[62:63], v[60:61], off
	v_lshlrev_b32_e32 v60, 16, v120
	v_and_b32_e32 v61, 0xffff0000, v120
	v_mfma_f32_16x16x32_bf16 v[52:55], v[162:165], v[0:3], v[52:55]
	v_mul_f32_e64 v56, v56, v60
	v_mul_f32_e64 v57, v57, v61
	v_lshlrev_b32_e32 v60, 16, v121
	v_and_b32_e32 v61, 0xffff0000, v121
	v_pk_mul_f32 v[58:59], v[58:59], v[60:61]
	v_cvt_pk_bf16_f32 v56, v56, v57
	v_cvt_pk_bf16_f32 v57, v58, v59
	global_store_dwordx2 v[62:63], v[56:57], off offset:32
	v_lshlrev_b32_e32 v56, 16, v116
	v_and_b32_e32 v57, 0xffff0000, v116
	v_mfma_f32_16x16x32_bf16 v[48:51], v[170:173], v[0:3], v[48:51]
	v_mul_f32_e64 v52, v52, v56
	v_mul_f32_e64 v53, v53, v57
	v_lshlrev_b32_e32 v56, 16, v117
	v_and_b32_e32 v57, 0xffff0000, v117
	v_pk_mul_f32 v[54:55], v[54:55], v[56:57]
	v_cvt_pk_bf16_f32 v52, v52, v53
	v_cvt_pk_bf16_f32 v53, v54, v55
	global_store_dwordx2 v[62:63], v[52:53], off offset:64
	v_lshlrev_b32_e32 v52, 16, v112
	v_and_b32_e32 v53, 0xffff0000, v112
	v_pk_mul_f32 v[48:49], v[48:49], v[52:53]
	v_lshlrev_b32_e32 v52, 16, v113
	v_and_b32_e32 v53, 0xffff0000, v113
	v_pk_mul_f32 v[50:51], v[50:51], v[52:53]
	v_cvt_pk_bf16_f32 v48, v48, v49
	v_cvt_pk_bf16_f32 v49, v50, v51
	v_mfma_f32_16x16x32_bf16 v[44:47], v[138:141], v[146:149], v[44:47]
	global_store_dwordx2 v[62:63], v[48:49], off offset:96
	v_mfma_f32_16x16x32_bf16 v[40:43], v[150:153], v[146:149], v[40:43]
	v_mfma_f32_16x16x32_bf16 v[36:39], v[162:165], v[146:149], v[36:39]
	v_mfma_f32_16x16x32_bf16 v[32:35], v[170:173], v[146:149], v[32:35]
	v_mfma_f32_16x16x32_bf16 v[28:31], v[138:141], v[154:157], v[28:31]
	v_mfma_f32_16x16x32_bf16 v[24:27], v[150:153], v[154:157], v[24:27]
	v_mfma_f32_16x16x32_bf16 v[20:23], v[162:165], v[154:157], v[20:23]
	v_mfma_f32_16x16x32_bf16 v[16:19], v[170:173], v[154:157], v[16:19]
	v_mfma_f32_16x16x32_bf16 v[12:15], v[138:141], v[166:169], v[12:15]
	v_mfma_f32_16x16x32_bf16 v[8:11], v[150:153], v[166:169], v[8:11]
	v_mfma_f32_16x16x32_bf16 v[0:3], v[162:165], v[166:169], v[4:7]
	v_mfma_f32_16x16x32_bf16 v[4:7], v[170:173], v[166:169], v[134:137]
	v_or_b32_e32 v48, 16, v66
	v_ashrrev_i32_e32 v49, 31, v48
	v_lshlrev_b32_e32 v50, 16, v108
	v_and_b32_e32 v51, 0xffff0000, v108
	v_lshlrev_b64 v[48:49], 10, v[48:49]
	v_pk_mul_f32 v[44:45], v[44:45], v[50:51]
	v_lshlrev_b32_e32 v50, 16, v109
	v_and_b32_e32 v51, 0xffff0000, v109
	v_lshl_add_u64 v[48:49], s[8:9], 0, v[48:49]
	v_pk_mul_f32 v[46:47], v[46:47], v[50:51]
	v_cvt_pk_bf16_f32 v44, v44, v45
	v_cvt_pk_bf16_f32 v45, v46, v47
	v_lshl_add_u64 v[46:47], v[48:49], 0, v[128:129]
	global_store_dwordx2 v[46:47], v[44:45], off
	v_lshlrev_b32_e32 v44, 16, v104
	v_and_b32_e32 v45, 0xffff0000, v104
	v_pk_mul_f32 v[40:41], v[40:41], v[44:45]
	v_lshlrev_b32_e32 v44, 16, v105
	v_and_b32_e32 v45, 0xffff0000, v105
	v_pk_mul_f32 v[42:43], v[42:43], v[44:45]
	v_cvt_pk_bf16_f32 v40, v40, v41
	v_cvt_pk_bf16_f32 v41, v42, v43
	global_store_dwordx2 v[46:47], v[40:41], off offset:32
	v_lshlrev_b32_e32 v40, 16, v100
	v_and_b32_e32 v41, 0xffff0000, v100
	v_pk_mul_f32 v[36:37], v[36:37], v[40:41]
	v_lshlrev_b32_e32 v40, 16, v101
	v_and_b32_e32 v41, 0xffff0000, v101
	v_pk_mul_f32 v[38:39], v[38:39], v[40:41]
	v_cvt_pk_bf16_f32 v36, v36, v37
	v_cvt_pk_bf16_f32 v37, v38, v39
; DEVI uint32_t pack2(float lo, float hi) { f32x2_t v = {lo, hi}; bf16x2_t b = __builtin_convertvector(v, bf16x2_t); return __builtin_bit_cast(uint32_t, b); }
; DEVI float lo2f(uint32_t u) { return __uint_as_float(u << 16); }
; DEVI float hi2f(uint32_t u) { return __uint_as_float(u & 0xffff0000u); }
; #define EPI_END } __builtin_amdgcn_sched_barrier(0); } }
; DEVI void phase_p8(const int TIDX, const int BIDX, const int GDIM, KAP KA, unsigned char* WSB, float* OUTB, int l, unsigned char* smem) {
;     ...
;   for (int item = (BIDX & 7) * (GDIM >> 3) + (BIDX >> 3); item < NT * 4; item += GDIM) {
;     ...
;     EPI_SWAP_BEGIN(mt * 128, nt * 128)
;       const f32x4 a = acc[mi][ni];
;       const uint2 g = sg[mi][ni];
;       *(uint2*)(H + (size_t)row * 512 + col) = make_uint2(pack2(a[0] * lo2f(g.x), a[1] * hi2f(g.x)), pack2(a[2] * lo2f(g.y), a[3] * hi2f(g.y)));
;     EPI_END
	global_store_dwordx2 v[46:47], v[36:37], off offset:64
	v_lshlrev_b32_e32 v36, 16, v96
	v_and_b32_e32 v37, 0xffff0000, v96
	v_pk_mul_f32 v[32:33], v[32:33], v[36:37]
	v_lshlrev_b32_e32 v36, 16, v97
	v_and_b32_e32 v37, 0xffff0000, v97
	v_pk_mul_f32 v[34:35], v[34:35], v[36:37]
	v_cvt_pk_bf16_f32 v32, v32, v33
	v_cvt_pk_bf16_f32 v33, v34, v35
	global_store_dwordx2 v[46:47], v[32:33], off offset:96
	v_or_b32_e32 v32, 32, v66
	v_ashrrev_i32_e32 v33, 31, v32
	v_lshlrev_b32_e32 v34, 16, v92
	v_and_b32_e32 v35, 0xffff0000, v92
	v_lshlrev_b64 v[32:33], 10, v[32:33]
	v_pk_mul_f32 v[28:29], v[28:29], v[34:35]
	v_lshlrev_b32_e32 v34, 16, v93
	v_and_b32_e32 v35, 0xffff0000, v93
	v_lshl_add_u64 v[32:33], s[8:9], 0, v[32:33]
	v_pk_mul_f32 v[30:31], v[30:31], v[34:35]
	v_cvt_pk_bf16_f32 v28, v28, v29
	v_cvt_pk_bf16_f32 v29, v30, v31
	v_lshl_add_u64 v[30:31], v[32:33], 0, v[128:129]
	global_store_dwordx2 v[30:31], v[28:29], off
	v_lshlrev_b32_e32 v28, 16, v88
	v_and_b32_e32 v29, 0xffff0000, v88
	v_pk_mul_f32 v[24:25], v[24:25], v[28:29]
	v_lshlrev_b32_e32 v28, 16, v89
	v_and_b32_e32 v29, 0xffff0000, v89
	v_pk_mul_f32 v[26:27], v[26:27], v[28:29]
	v_cvt_pk_bf16_f32 v24, v24, v25
	v_cvt_pk_bf16_f32 v25, v26, v27
	global_store_dwordx2 v[30:31], v[24:25], off offset:32
	v_lshlrev_b32_e32 v24, 16, v84
	v_and_b32_e32 v25, 0xffff0000, v84
	v_pk_mul_f32 v[20:21], v[20:21], v[24:25]
	v_lshlrev_b32_e32 v24, 16, v85
	v_and_b32_e32 v25, 0xffff0000, v85
	v_pk_mul_f32 v[22:23], v[22:23], v[24:25]
	v_cvt_pk_bf16_f32 v20, v20, v21
	v_cvt_pk_bf16_f32 v21, v22, v23
	global_store_dwordx2 v[30:31], v[20:21], off offset:64
	v_lshlrev_b32_e32 v20, 16, v80
	v_and_b32_e32 v21, 0xffff0000, v80
	v_pk_mul_f32 v[16:17], v[16:17], v[20:21]
	v_lshlrev_b32_e32 v20, 16, v81
	v_and_b32_e32 v21, 0xffff0000, v81
	v_pk_mul_f32 v[18:19], v[18:19], v[20:21]
	v_cvt_pk_bf16_f32 v16, v16, v17
	v_cvt_pk_bf16_f32 v17, v18, v19
	global_store_dwordx2 v[30:31], v[16:17], off offset:96
	v_or_b32_e32 v16, 48, v66
	v_ashrrev_i32_e32 v17, 31, v16
	v_lshlrev_b32_e32 v18, 16, v76
	v_and_b32_e32 v19, 0xffff0000, v76
	v_lshlrev_b64 v[16:17], 10, v[16:17]
	v_pk_mul_f32 v[12:13], v[12:13], v[18:19]
	v_lshlrev_b32_e32 v18, 16, v77
	v_and_b32_e32 v19, 0xffff0000, v77
	v_lshl_add_u64 v[16:17], s[8:9], 0, v[16:17]
	v_pk_mul_f32 v[14:15], v[14:15], v[18:19]
	v_cvt_pk_bf16_f32 v12, v12, v13
	v_cvt_pk_bf16_f32 v13, v14, v15
	v_lshl_add_u64 v[14:15], v[16:17], 0, v[128:129]
	global_store_dwordx2 v[14:15], v[12:13], off
	v_lshlrev_b32_e32 v12, 16, v72
	v_and_b32_e32 v13, 0xffff0000, v72
	v_pk_mul_f32 v[8:9], v[8:9], v[12:13]
	v_lshlrev_b32_e32 v12, 16, v73
	v_and_b32_e32 v13, 0xffff0000, v73
	v_pk_mul_f32 v[10:11], v[10:11], v[12:13]
	v_cvt_pk_bf16_f32 v8, v8, v9
	v_cvt_pk_bf16_f32 v9, v10, v11
	global_store_dwordx2 v[14:15], v[8:9], off offset:32
	v_lshlrev_b32_e32 v8, 16, v68
	v_and_b32_e32 v9, 0xffff0000, v68
	v_pk_mul_f32 v[0:1], v[0:1], v[8:9]
	v_lshlrev_b32_e32 v8, 16, v69
	v_and_b32_e32 v9, 0xffff0000, v69
	v_pk_mul_f32 v[2:3], v[2:3], v[8:9]
	v_cvt_pk_bf16_f32 v0, v0, v1
	v_cvt_pk_bf16_f32 v1, v2, v3
	global_store_dwordx2 v[14:15], v[0:1], off offset:64
	v_lshlrev_b32_e32 v0, 16, v64
	v_and_b32_e32 v1, 0xffff0000, v64
	v_lshlrev_b32_e32 v2, 16, v65
	v_and_b32_e32 v3, 0xffff0000, v65
	v_pk_mul_f32 v[0:1], v[4:5], v[0:1]
	v_pk_mul_f32 v[2:3], v[6:7], v[2:3]
	v_cvt_pk_bf16_f32 v0, v0, v1
	v_cvt_pk_bf16_f32 v1, v2, v3
	global_store_dwordx2 v[14:15], v[0:1], off offset:96
	s_add_i32 s16, s16, s84
	s_add_i32 s14, s14, s15
	s_cmp_ge_i32 s16, s3
	s_cbranch_scc0 .LBB0_38

; DEVI f32x4 mfma16(bf16x8 a, bf16x8 b, f32x4 c) { return __builtin_amdgcn_mfma_f32_16x16x32_bf16(a, b, c, 0, 0, 0); }
; template <bool SWAP, class RP>
; DEVI void gemm_main(const int TIDX, const int BIDX, const int GDIM, f32x4 (&acc)[4][4], RP rowoff, const bf16_t* __restrict__ Bt, int ldb, int K, unsigned char* smem) {
;     ...
;   const int nk = K >> 6;
;   const int px = lg ^ (li >> 1);
;   GM_STAGE(0, 0);
;   for (int kt = 0; kt < nk; ++kt) {
;     const int buf = kt & 1;
;     asm volatile("s_waitcnt vmcnt(0)" ::: "memory");
;     __syncthreads();
;     if (kt + 1 < nk) GM_STAGE(kt + 1, buf ^ 1);
;     const unsigned char* A = smem + buf * 32768 + (wr * 64 + li) * 128;
;     const unsigned char* B = smem + buf * 32768 + 16384 + (wc * 64 + li) * 128;
; #pragma unroll
;     for (int ks = 0; ks < 2; ++ks) {
;       const int po = (px ^ (ks * 4)) * 16;
;       bf16x8 af[4], bfr[4];
; #pragma unroll
;       for (int i = 0; i < 4; ++i) {
;         af[i] = *(const bf16x8*)(A + i * 2048 + po);
;         bfr[i] = *(const bf16x8*)(B + i * 2048 + po);
;       }
; #pragma unroll
;       for (int mi = 0; mi < 4; ++mi)
; #pragma unroll
;         for (int ni = 0; ni < 4; ++ni)
;           acc[mi][ni] = SWAP ? mfma16(bfr[ni], af[mi], acc[mi][ni]) : mfma16(af[mi], bfr[ni], acc[mi][ni]);
;     }
.LBB0_62:
	s_and_b32 s25, s24, 0x8000
	s_xor_b32 s26, s25, 0x8000
	v_add_u32_e32 v194, s26, v78
	v_add_u32_e32 v204, s25, v77
	v_or_b32_e32 v205, s25, v80
	v_add_u32_e32 v205, v205, v81
	v_add_u32_e32 v231, v204, v79
	v_add_u32_e32 v232, v205, v79
	v_readfirstlane_b32 s101, v194
	v_add_u32_e32 v204, v204, v76
	v_add_u32_e32 v205, v205, v76
	s_waitcnt vmcnt(0)
	s_barrier
	ds_read_b128 v[82:85], v231
	ds_read_b128 v[98:101], v232 offset:16384
	ds_read_b128 v[102:105], v232 offset:18432
	ds_read_b128 v[106:109], v232 offset:20480
	ds_read_b128 v[110:113], v232 offset:22528
	ds_read_b128 v[86:89], v231 offset:2048
	ds_read_b128 v[90:93], v231 offset:4096
	ds_read_b128 v[94:97], v231 offset:6144
	ds_read_b128 v[190:193], v205 offset:16384
	ds_read_b128 v[196:199], v205 offset:18432
	ds_read_b128 v[200:203], v205 offset:20480
	ds_read_b128 v[208:211], v205 offset:22528
	s_mov_b32 m0, s101
	v_lshl_add_u64 v[114:115], v[64:65], 0, s[0:1]
	global_load_lds_dwordx4 v[114:115], off
	s_add_i32 m0, s101, 0x1000
	v_lshl_add_u64 v[114:115], v[66:67], 0, s[0:1]
	global_load_lds_dwordx4 v[114:115], off
	s_waitcnt lgkmcnt(7)
	v_mfma_f32_16x16x32_bf16 v[60:63], v[98:101], v[82:85], v[60:63]
	v_mfma_f32_16x16x32_bf16 v[56:59], v[102:105], v[82:85], v[56:59]
	s_add_i32 m0, s101, 0x2000
	v_lshl_add_u64 v[114:115], v[68:69], 0, s[0:1]
	global_load_lds_dwordx4 v[114:115], off
	v_mfma_f32_16x16x32_bf16 v[52:55], v[106:109], v[82:85], v[52:55]
	v_mfma_f32_16x16x32_bf16 v[48:51], v[110:113], v[82:85], v[48:51]
	ds_read_b128 v[82:85], v204
	s_add_i32 m0, s101, 0x3000
	v_lshl_add_u64 v[114:115], v[70:71], 0, s[0:1]
	global_load_lds_dwordx4 v[114:115], off
	s_waitcnt lgkmcnt(7)
	v_mfma_f32_16x16x32_bf16 v[44:47], v[98:101], v[86:89], v[44:47]
	v_mfma_f32_16x16x32_bf16 v[40:43], v[102:105], v[86:89], v[40:43]
	s_add_i32 m0, s101, 0x4000
	s_mov_b64 s[26:27], 0xe90080
	v_lshl_add_u64 v[114:115], v[72:73], 0, s[0:1]
	v_lshl_add_u64 v[114:115], v[114:115], 0, s[26:27]
	global_load_lds_dwordx4 v[114:115], off
	v_mfma_f32_16x16x32_bf16 v[36:39], v[106:109], v[86:89], v[36:39]
	v_mfma_f32_16x16x32_bf16 v[32:35], v[110:113], v[86:89], v[32:35]
	ds_read_b128 v[86:89], v204 offset:2048
	s_add_i32 m0, s101, 0x5000
	s_mov_b64 s[26:27], 0xea0080
	v_lshl_add_u64 v[114:115], v[72:73], 0, s[0:1]
	v_lshl_add_u64 v[114:115], v[114:115], 0, s[26:27]
	global_load_lds_dwordx4 v[114:115], off
	s_waitcnt lgkmcnt(7)
	v_mfma_f32_16x16x32_bf16 v[28:31], v[98:101], v[90:93], v[28:31]
	v_mfma_f32_16x16x32_bf16 v[24:27], v[102:105], v[90:93], v[24:27]
	s_add_i32 m0, s101, 0x6000
	s_mov_b64 s[26:27], 0xeb0080
	v_lshl_add_u64 v[114:115], v[72:73], 0, s[0:1]
	v_lshl_add_u64 v[114:115], v[114:115], 0, s[26:27]
	global_load_lds_dwordx4 v[114:115], off
	v_mfma_f32_16x16x32_bf16 v[20:23], v[106:109], v[90:93], v[20:23]
	v_mfma_f32_16x16x32_bf16 v[16:19], v[110:113], v[90:93], v[16:19]
	ds_read_b128 v[90:93], v204 offset:4096
	s_add_i32 m0, s101, 0x7000
	s_mov_b64 s[26:27], 0xec0080
	v_lshl_add_u64 v[114:115], v[72:73], 0, s[0:1]
	v_lshl_add_u64 v[114:115], v[114:115], 0, s[26:27]
	global_load_lds_dwordx4 v[114:115], off
	s_waitcnt lgkmcnt(7)
	v_mfma_f32_16x16x32_bf16 v[12:15], v[98:101], v[94:97], v[12:15]
	v_mfma_f32_16x16x32_bf16 v[8:11], v[102:105], v[94:97], v[8:11]
	v_mfma_f32_16x16x32_bf16 v[4:7], v[106:109], v[94:97], v[4:7]
	v_mfma_f32_16x16x32_bf16 v[0:3], v[110:113], v[94:97], v[0:3]
	ds_read_b128 v[94:97], v204 offset:6144
	s_waitcnt lgkmcnt(3)
	v_mfma_f32_16x16x32_bf16 v[60:63], v[190:193], v[82:85], v[60:63]
	v_mfma_f32_16x16x32_bf16 v[56:59], v[196:199], v[82:85], v[56:59]
	v_mfma_f32_16x16x32_bf16 v[52:55], v[200:203], v[82:85], v[52:55]
	v_mfma_f32_16x16x32_bf16 v[48:51], v[208:211], v[82:85], v[48:51]
	s_waitcnt lgkmcnt(2)
	v_mfma_f32_16x16x32_bf16 v[44:47], v[190:193], v[86:89], v[44:47]
	v_mfma_f32_16x16x32_bf16 v[40:43], v[196:199], v[86:89], v[40:43]
	v_mfma_f32_16x16x32_bf16 v[36:39], v[200:203], v[86:89], v[36:39]
	v_mfma_f32_16x16x32_bf16 v[32:35], v[208:211], v[86:89], v[32:35]
	s_waitcnt lgkmcnt(1)
	v_mfma_f32_16x16x32_bf16 v[28:31], v[190:193], v[90:93], v[28:31]
	v_mfma_f32_16x16x32_bf16 v[24:27], v[196:199], v[90:93], v[24:27]
	v_mfma_f32_16x16x32_bf16 v[20:23], v[200:203], v[90:93], v[20:23]
	v_mfma_f32_16x16x32_bf16 v[16:19], v[208:211], v[90:93], v[16:19]
	s_waitcnt lgkmcnt(0)
	s_add_u32 s0, s0, 0x80
	s_addc_u32 s1, s1, 0
	s_add_i32 s24, s24, 0x8000
	s_cmpk_eq_i32 s0, 0x780
	v_mfma_f32_16x16x32_bf16 v[12:15], v[190:193], v[94:97], v[12:15]
	v_mfma_f32_16x16x32_bf16 v[8:11], v[196:199], v[94:97], v[8:11]
	v_mfma_f32_16x16x32_bf16 v[4:7], v[200:203], v[94:97], v[4:7]
	v_mfma_f32_16x16x32_bf16 v[0:3], v[208:211], v[94:97], v[0:3]
	s_cbranch_scc0 .LBB0_62
	v_add_u32_e32 v72, v80, v81
	v_add_u32_e32 v73, v77, v79
	v_add_u32_e32 v98, v72, v79
	s_waitcnt vmcnt(0)
	s_waitcnt vmcnt(0)
	s_barrier
; DEVI uint32_t pack2(float lo, float hi) { f32x2_t v = {lo, hi}; bf16x2_t b = __builtin_convertvector(v, bf16x2_t); return __builtin_bit_cast(uint32_t, b); }
; DEVI float sigmoidf_(float x) { return 1.f / (1.f + __expf(-x)); }
; DEVI f32x4 mfma16(bf16x8 a, bf16x8 b, f32x4 c) { return __builtin_amdgcn_mfma_f32_16x16x32_bf16(a, b, c, 0, 0, 0); }
; template <bool SWAP, class RP>
; DEVI void gemm_main(const int TIDX, const int BIDX, const int GDIM, f32x4 (&acc)[4][4], RP rowoff, const bf16_t* __restrict__ Bt, int ldb, int K, unsigned char* smem) {
;     ...
;     const unsigned char* A = smem + buf * 32768 + (wr * 64 + li) * 128;
;     const unsigned char* B = smem + buf * 32768 + 16384 + (wc * 64 + li) * 128;
; #pragma unroll
;     for (int ks = 0; ks < 2; ++ks) {
;       const int po = (px ^ (ks * 4)) * 16;
;       bf16x8 af[4], bfr[4];
; #pragma unroll
;       for (int i = 0; i < 4; ++i) {
;         af[i] = *(const bf16x8*)(A + i * 2048 + po);
;         bfr[i] = *(const bf16x8*)(B + i * 2048 + po);
;       }
; #pragma unroll
;       for (int mi = 0; mi < 4; ++mi)
; #pragma unroll
;         for (int ni = 0; ni < 4; ++ni)
;           acc[mi][ni] = SWAP ? mfma16(bfr[ni], af[mi], acc[mi][ni]) : mfma16(af[mi], bfr[ni], acc[mi][ni]);
;     }
;   }
;   __syncthreads();
; DEVI void phase_p8(const int TIDX, const int BIDX, const int GDIM, KAP KA, unsigned char* WSB, float* OUTB, int l, unsigned char* smem) {
;     ...
; #pragma unroll
;       for (int i = 0; i < 4; ++i)
; #pragma unroll
;         for (int j = 0; j < 4; ++j) gp[i][j] = make_uint2(pack2(sigmoidf_(acc[i][j][0]), sigmoidf_(acc[i][j][1])), pack2(sigmoidf_(acc[i][j][2]), sigmoidf_(acc[i][j][3])));
	ds_read_b128 v[64:67], v73 offset:32768
	ds_read_b128 v[68:71], v98 offset:49152
	ds_read_b128 v[78:81], v73 offset:34816
	ds_read_b128 v[82:85], v98 offset:51200
	ds_read_b128 v[86:89], v73 offset:36864
	ds_read_b128 v[90:93], v98 offset:53248
	ds_read_b128 v[94:97], v73 offset:38912
	ds_read_b128 v[98:101], v98 offset:55296
	s_waitcnt lgkmcnt(6)
	v_mfma_f32_16x16x32_bf16 v[60:63], v[68:71], v[64:67], v[60:63]
	v_add_u32_e32 v73, v77, v76
	v_add_u32_e32 v72, v72, v76
	s_mov_b32 s39, 0x1ffffc0
	s_waitcnt lgkmcnt(4)
	v_mfma_f32_16x16x32_bf16 v[56:59], v[82:85], v[64:67], v[56:59]
	s_mov_b64 s[26:27], 0x4080
	s_mov_b64 s[40:41], 0x8080
	s_waitcnt lgkmcnt(2)
	v_mfma_f32_16x16x32_bf16 v[52:55], v[90:93], v[64:67], v[52:55]
	s_waitcnt lgkmcnt(0)
	v_mfma_f32_16x16x32_bf16 v[48:51], v[98:101], v[64:67], v[48:51]
	v_mfma_f32_16x16x32_bf16 v[44:47], v[68:71], v[78:81], v[44:47]
	v_mfma_f32_16x16x32_bf16 v[40:43], v[82:85], v[78:81], v[40:43]
	v_mfma_f32_16x16x32_bf16 v[36:39], v[90:93], v[78:81], v[36:39]
	v_mfma_f32_16x16x32_bf16 v[32:35], v[98:101], v[78:81], v[32:35]
	v_mfma_f32_16x16x32_bf16 v[28:31], v[68:71], v[86:89], v[28:31]
	v_mfma_f32_16x16x32_bf16 v[24:27], v[82:85], v[86:89], v[24:27]
	v_mfma_f32_16x16x32_bf16 v[20:23], v[90:93], v[86:89], v[20:23]
	v_mfma_f32_16x16x32_bf16 v[16:19], v[98:101], v[86:89], v[16:19]
	v_mfma_f32_16x16x32_bf16 v[12:15], v[68:71], v[94:97], v[12:15]
	v_mfma_f32_16x16x32_bf16 v[8:11], v[82:85], v[94:97], v[8:11]
	v_mfma_f32_16x16x32_bf16 v[4:7], v[90:93], v[94:97], v[4:7]
	v_mfma_f32_16x16x32_bf16 v[0:3], v[98:101], v[94:97], v[0:3]
	ds_read_b128 v[64:67], v73 offset:32768
	ds_read_b128 v[68:71], v72 offset:49152
	ds_read_b128 v[76:79], v73 offset:34816
	ds_read_b128 v[80:83], v72 offset:51200
	ds_read_b128 v[84:87], v73 offset:36864
	ds_read_b128 v[88:91], v72 offset:53248
	ds_read_b128 v[92:95], v73 offset:38912
	ds_read_b128 v[96:99], v72 offset:55296
	s_waitcnt lgkmcnt(0)
	s_barrier
	v_mfma_f32_16x16x32_bf16 v[60:63], v[68:71], v[64:67], v[60:63]
	v_mfma_f32_16x16x32_bf16 v[56:59], v[80:83], v[64:67], v[56:59]
	v_mfma_f32_16x16x32_bf16 v[52:55], v[88:91], v[64:67], v[52:55]
	s_nop 5
	v_mul_f32_e32 v60, 0xbfb8aa3b, v60
	v_mul_f32_e32 v61, 0xbfb8aa3b, v61
	v_exp_f32_e32 v60, v60
	v_exp_f32_e32 v61, v61
	v_mfma_f32_16x16x32_bf16 v[48:51], v[96:99], v[64:67], v[48:51]
	v_mul_f32_e32 v56, 0xbfb8aa3b, v56
	v_mul_f32_e32 v57, 0xbfb8aa3b, v57
	v_pk_add_f32 v[60:61], v[60:61], 1.0 op_sel_hi:[1,0]
	v_mfma_f32_16x16x32_bf16 v[44:47], v[68:71], v[76:79], v[44:47]
	v_div_scale_f32 v64, s[0:1], v61, v61, 1.0
	v_rcp_f32_e32 v65, v64
	v_mfma_f32_16x16x32_bf16 v[28:31], v[68:71], v[84:87], v[28:31]
	v_exp_f32_e32 v56, v56
	v_exp_f32_e32 v57, v57
	v_fma_f32 v66, -v64, v65, 1.0
	v_fmac_f32_e32 v65, v66, v65
	v_div_scale_f32 v66, vcc, 1.0, v61, 1.0
	v_mul_f32_e32 v67, v66, v65
	v_mfma_f32_16x16x32_bf16 v[12:15], v[68:71], v[92:95], v[12:15]
	v_fma_f32 v68, -v64, v67, v66
	v_fmac_f32_e32 v67, v68, v65
	v_fma_f32 v64, -v64, v67, v66
	v_div_fmas_f32 v64, v64, v65, v67
	v_div_fixup_f32 v61, v64, v61, 1.0
	v_div_scale_f32 v64, s[0:1], v60, v60, 1.0
	v_rcp_f32_e32 v65, v64
	v_mfma_f32_16x16x32_bf16 v[40:43], v[80:83], v[76:79], v[40:43]
	v_add_f32_e64 v56, v56, 1.0
	v_add_f32_e64 v57, v57, 1.0
	v_mul_f32_e32 v52, 0xbfb8aa3b, v52
	v_fma_f32 v66, -v64, v65, 1.0
	v_fmac_f32_e32 v65, v66, v65
	v_div_scale_f32 v66, vcc, 1.0, v60, 1.0
	v_mul_f32_e32 v67, v66, v65
	v_fma_f32 v68, -v64, v67, v66
	v_fmac_f32_e32 v67, v68, v65
	v_fma_f32 v64, -v64, v67, v66
	v_div_fmas_f32 v64, v64, v65, v67
	v_div_fixup_f32 v60, v64, v60, 1.0
	v_mfma_f32_16x16x32_bf16 v[36:39], v[88:91], v[76:79], v[36:39]
	v_mul_f32_e32 v53, 0xbfb8aa3b, v53
	v_exp_f32_e32 v52, v52
	v_exp_f32_e32 v53, v53
	v_mfma_f32_16x16x32_bf16 v[32:35], v[96:99], v[76:79], v[32:35]
	v_cvt_pk_bf16_f32 v76, v60, v61
	v_mul_f32_e32 v60, 0xbfb8aa3b, v62
	v_mul_f32_e32 v61, 0xbfb8aa3b, v63
	v_exp_f32_e32 v60, v60
	v_exp_f32_e32 v61, v61
	v_pk_add_f32 v[52:53], v[52:53], 1.0 op_sel_hi:[1,0]
	v_mfma_f32_16x16x32_bf16 v[24:27], v[80:83], v[84:87], v[24:27]
	v_mul_f32_e32 v48, 0xbfb8aa3b, v48
	v_pk_add_f32 v[60:61], v[60:61], 1.0 op_sel_hi:[1,0]
	v_mul_f32_e32 v49, 0xbfb8aa3b, v49
	v_div_scale_f32 v62, s[0:1], v61, v61, 1.0
	v_rcp_f32_e32 v63, v62
	v_mfma_f32_16x16x32_bf16 v[8:11], v[80:83], v[92:95], v[8:11]
	v_exp_f32_e32 v48, v48
	v_exp_f32_e32 v49, v49
	v_fma_f32 v64, -v62, v63, 1.0
	v_fmac_f32_e32 v63, v64, v63
	v_div_scale_f32 v64, vcc, 1.0, v61, 1.0
	v_mul_f32_e32 v65, v64, v63
	v_fma_f32 v66, -v62, v65, v64
	v_fmac_f32_e32 v65, v66, v63
	v_fma_f32 v62, -v62, v65, v64
	v_div_fmas_f32 v62, v62, v63, v65
	v_div_fixup_f32 v61, v62, v61, 1.0
	v_div_scale_f32 v62, s[0:1], v60, v60, 1.0
	v_rcp_f32_e32 v63, v62
	v_pk_add_f32 v[48:49], v[48:49], 1.0 op_sel_hi:[1,0]
	v_mul_f32_e32 v44, 0xbfb8aa3b, v44
	v_mul_f32_e32 v45, 0xbfb8aa3b, v45
	v_fma_f32 v64, -v62, v63, 1.0
	v_fmac_f32_e32 v63, v64, v63
	v_div_scale_f32 v64, vcc, 1.0, v60, 1.0
	v_mul_f32_e32 v65, v64, v63
	v_fma_f32 v66, -v62, v65, v64
	v_fmac_f32_e32 v65, v66, v63
	v_fma_f32 v62, -v62, v65, v64
	v_div_fmas_f32 v62, v62, v63, v65
	v_div_fixup_f32 v60, v62, v60, 1.0
	v_cvt_pk_bf16_f32 v77, v60, v61
	v_div_scale_f32 v60, s[0:1], v57, v57, 1.0
	v_rcp_f32_e32 v61, v60
	v_exp_f32_e32 v44, v44
	v_exp_f32_e32 v45, v45
	v_mfma_f32_16x16x32_bf16 v[20:23], v[88:91], v[84:87], v[20:23]
	v_fma_f32 v62, -v60, v61, 1.0
	v_fmac_f32_e32 v61, v62, v61
	v_div_scale_f32 v62, vcc, 1.0, v57, 1.0
	v_mul_f32_e32 v63, v62, v61
	v_fma_f32 v64, -v60, v63, v62
	v_fmac_f32_e32 v63, v64, v61
	v_fma_f32 v60, -v60, v63, v62
	v_div_fmas_f32 v60, v60, v61, v63
; DEVI uint32_t pack2(float lo, float hi) { f32x2_t v = {lo, hi}; bf16x2_t b = __builtin_convertvector(v, bf16x2_t); return __builtin_bit_cast(uint32_t, b); }
; DEVI float sigmoidf_(float x) { return 1.f / (1.f + __expf(-x)); }
; DEVI void phase_p8(const int TIDX, const int BIDX, const int GDIM, KAP KA, unsigned char* WSB, float* OUTB, int l, unsigned char* smem) {
;     ...
; #pragma unroll
;       for (int i = 0; i < 4; ++i)
; #pragma unroll
;         for (int j = 0; j < 4; ++j) gp[i][j] = make_uint2(pack2(sigmoidf_(acc[i][j][0]), sigmoidf_(acc[i][j][1])), pack2(sigmoidf_(acc[i][j][2]), sigmoidf_(acc[i][j][3])));
	v_div_fixup_f32 v57, v60, v57, 1.0
	v_div_scale_f32 v60, s[0:1], v56, v56, 1.0
	v_rcp_f32_e32 v61, v60
	v_pk_add_f32 v[44:45], v[44:45], 1.0 op_sel_hi:[1,0]
	v_mfma_f32_16x16x32_bf16 v[16:19], v[96:99], v[84:87], v[16:19]
	v_mul_f32_e32 v40, 0xbfb8aa3b, v40
	v_fma_f32 v62, -v60, v61, 1.0
	v_fmac_f32_e32 v61, v62, v61
	v_div_scale_f32 v62, vcc, 1.0, v56, 1.0
	v_mul_f32_e32 v63, v62, v61
	v_fma_f32 v64, -v60, v63, v62
	v_fmac_f32_e32 v63, v64, v61
	v_fma_f32 v60, -v60, v63, v62
	v_div_fmas_f32 v60, v60, v61, v63
	v_div_fixup_f32 v56, v60, v56, 1.0
	v_cvt_pk_bf16_f32 v78, v56, v57
	v_mul_f32_e32 v56, 0xbfb8aa3b, v58
	v_mul_f32_e32 v57, 0xbfb8aa3b, v59
	v_exp_f32_e32 v56, v56
	v_exp_f32_e32 v57, v57
	v_mul_f32_e32 v41, 0xbfb8aa3b, v41
	v_exp_f32_e32 v40, v40
	v_exp_f32_e32 v41, v41
	v_pk_add_f32 v[56:57], v[56:57], 1.0 op_sel_hi:[1,0]
	v_mul_f32_e32 v36, 0xbfb8aa3b, v36
	v_div_scale_f32 v58, s[0:1], v57, v57, 1.0
	v_rcp_f32_e32 v59, v58
	v_pk_add_f32 v[40:41], v[40:41], 1.0 op_sel_hi:[1,0]
	v_mul_f32_e32 v37, 0xbfb8aa3b, v37
	v_exp_f32_e32 v36, v36
	v_fma_f32 v60, -v58, v59, 1.0
	v_fmac_f32_e32 v59, v60, v59
	v_div_scale_f32 v60, vcc, 1.0, v57, 1.0
	v_mul_f32_e32 v61, v60, v59
	v_fma_f32 v62, -v58, v61, v60
	v_fmac_f32_e32 v61, v62, v59
	v_fma_f32 v58, -v58, v61, v60
	v_div_fmas_f32 v58, v58, v59, v61
	v_div_fixup_f32 v57, v58, v57, 1.0
	v_div_scale_f32 v58, s[0:1], v56, v56, 1.0
	v_rcp_f32_e32 v59, v58
	v_exp_f32_e32 v37, v37
	v_mfma_f32_16x16x32_bf16 v[4:7], v[88:91], v[92:95], v[4:7]
	v_mul_f32_e32 v32, 0xbfb8aa3b, v32
	v_fma_f32 v60, -v58, v59, 1.0
	v_fmac_f32_e32 v59, v60, v59
	v_div_scale_f32 v60, vcc, 1.0, v56, 1.0
	v_mul_f32_e32 v61, v60, v59
	v_fma_f32 v62, -v58, v61, v60
	v_fmac_f32_e32 v61, v62, v59
	v_fma_f32 v58, -v58, v61, v60
	v_div_fmas_f32 v58, v58, v59, v61
	v_div_fixup_f32 v56, v58, v56, 1.0
	v_cvt_pk_bf16_f32 v79, v56, v57
	v_div_scale_f32 v56, s[0:1], v53, v53, 1.0
	v_rcp_f32_e32 v57, v56
	v_pk_add_f32 v[36:37], v[36:37], 1.0 op_sel_hi:[1,0]
	v_mul_f32_e32 v33, 0xbfb8aa3b, v33
	v_exp_f32_e32 v32, v32
	v_fma_f32 v58, -v56, v57, 1.0
	v_fmac_f32_e32 v57, v58, v57
	v_div_scale_f32 v58, vcc, 1.0, v53, 1.0
	v_mul_f32_e32 v59, v58, v57
	v_fma_f32 v60, -v56, v59, v58
	v_fmac_f32_e32 v59, v60, v57
	v_fma_f32 v56, -v56, v59, v58
	v_div_fmas_f32 v56, v56, v57, v59
	v_div_fixup_f32 v53, v56, v53, 1.0
	v_div_scale_f32 v56, s[0:1], v52, v52, 1.0
	v_rcp_f32_e32 v57, v56
	v_exp_f32_e32 v33, v33
	v_mul_f32_e32 v28, 0xbfb8aa3b, v28
	v_mul_f32_e32 v29, 0xbfb8aa3b, v29
	v_fma_f32 v58, -v56, v57, 1.0
	v_fmac_f32_e32 v57, v58, v57
	v_div_scale_f32 v58, vcc, 1.0, v52, 1.0
	v_mul_f32_e32 v59, v58, v57
	v_fma_f32 v60, -v56, v59, v58
	v_fmac_f32_e32 v59, v60, v57
	v_fma_f32 v56, -v56, v59, v58
	v_div_fmas_f32 v56, v56, v57, v59
	v_div_fixup_f32 v52, v56, v52, 1.0
	v_cvt_pk_bf16_f32 v80, v52, v53
	v_mul_f32_e32 v52, 0xbfb8aa3b, v54
	v_mul_f32_e32 v53, 0xbfb8aa3b, v55
	v_exp_f32_e32 v52, v52
	v_exp_f32_e32 v53, v53
	v_pk_add_f32 v[32:33], v[32:33], 1.0 op_sel_hi:[1,0]
	v_exp_f32_e32 v28, v28
	v_exp_f32_e32 v29, v29
	v_pk_add_f32 v[52:53], v[52:53], 1.0 op_sel_hi:[1,0]
	v_mfma_f32_16x16x32_bf16 v[0:3], v[96:99], v[92:95], v[0:3]
	v_div_scale_f32 v54, s[0:1], v53, v53, 1.0
	v_rcp_f32_e32 v55, v54
	v_pk_add_f32 v[28:29], v[28:29], 1.0 op_sel_hi:[1,0]
	v_mul_f32_e32 v24, 0xbfb8aa3b, v24
	v_mul_f32_e32 v25, 0xbfb8aa3b, v25
	v_fma_f32 v56, -v54, v55, 1.0
	v_fmac_f32_e32 v55, v56, v55
	v_div_scale_f32 v56, vcc, 1.0, v53, 1.0
	v_mul_f32_e32 v57, v56, v55
	v_fma_f32 v58, -v54, v57, v56
	v_fmac_f32_e32 v57, v58, v55
	v_fma_f32 v54, -v54, v57, v56
	v_div_fmas_f32 v54, v54, v55, v57
	v_div_fixup_f32 v53, v54, v53, 1.0
	v_div_scale_f32 v54, s[0:1], v52, v52, 1.0
	v_rcp_f32_e32 v55, v54
	v_exp_f32_e32 v24, v24
	v_exp_f32_e32 v25, v25
	v_mul_f32_e32 v20, 0xbfb8aa3b, v20
	v_fma_f32 v56, -v54, v55, 1.0
	v_fmac_f32_e32 v55, v56, v55
	v_div_scale_f32 v56, vcc, 1.0, v52, 1.0
	v_mul_f32_e32 v57, v56, v55
	v_fma_f32 v58, -v54, v57, v56
	v_fmac_f32_e32 v57, v58, v55
	v_fma_f32 v54, -v54, v57, v56
	v_div_fmas_f32 v54, v54, v55, v57
	v_div_fixup_f32 v52, v54, v52, 1.0
	v_cvt_pk_bf16_f32 v81, v52, v53
	v_div_scale_f32 v52, s[0:1], v49, v49, 1.0
	v_rcp_f32_e32 v53, v52
	v_pk_add_f32 v[24:25], v[24:25], 1.0 op_sel_hi:[1,0]
	v_mul_f32_e32 v21, 0xbfb8aa3b, v21
	v_exp_f32_e32 v20, v20
	v_fma_f32 v54, -v52, v53, 1.0
	v_fmac_f32_e32 v53, v54, v53
	v_div_scale_f32 v54, vcc, 1.0, v49, 1.0
	v_mul_f32_e32 v55, v54, v53
	v_fma_f32 v56, -v52, v55, v54
	v_fmac_f32_e32 v55, v56, v53
	v_fma_f32 v52, -v52, v55, v54
	v_div_fmas_f32 v52, v52, v53, v55
	v_div_fixup_f32 v49, v52, v49, 1.0
	v_div_scale_f32 v52, s[0:1], v48, v48, 1.0
	v_rcp_f32_e32 v53, v52
	v_exp_f32_e32 v21, v21
	v_mul_f32_e32 v16, 0xbfb8aa3b, v16
	v_mul_f32_e32 v17, 0xbfb8aa3b, v17
	v_fma_f32 v54, -v52, v53, 1.0
	v_fmac_f32_e32 v53, v54, v53
	v_div_scale_f32 v54, vcc, 1.0, v48, 1.0
	v_mul_f32_e32 v55, v54, v53
	v_fma_f32 v56, -v52, v55, v54
	v_fmac_f32_e32 v55, v56, v53
	v_fma_f32 v52, -v52, v55, v54
	v_div_fmas_f32 v52, v52, v53, v55
	v_div_fixup_f32 v48, v52, v48, 1.0
	v_cvt_pk_bf16_f32 v82, v48, v49
	v_mul_f32_e32 v48, 0xbfb8aa3b, v50
	v_mul_f32_e32 v49, 0xbfb8aa3b, v51
	v_exp_f32_e32 v48, v48
	v_exp_f32_e32 v49, v49
	v_pk_add_f32 v[20:21], v[20:21], 1.0 op_sel_hi:[1,0]
	v_exp_f32_e32 v16, v16
	v_exp_f32_e32 v17, v17
	v_pk_add_f32 v[48:49], v[48:49], 1.0 op_sel_hi:[1,0]
	v_mul_f32_e32 v12, 0xbfb8aa3b, v12
	v_div_scale_f32 v50, s[0:1], v49, v49, 1.0
	v_rcp_f32_e32 v51, v50
	v_pk_add_f32 v[16:17], v[16:17], 1.0 op_sel_hi:[1,0]
	v_mul_f32_e32 v13, 0xbfb8aa3b, v13
	v_exp_f32_e32 v12, v12
	v_fma_f32 v52, -v50, v51, 1.0
; DEVI uint32_t pack2(float lo, float hi) { f32x2_t v = {lo, hi}; bf16x2_t b = __builtin_convertvector(v, bf16x2_t); return __builtin_bit_cast(uint32_t, b); }
; DEVI float sigmoidf_(float x) { return 1.f / (1.f + __expf(-x)); }
; DEVI void phase_p8(const int TIDX, const int BIDX, const int GDIM, KAP KA, unsigned char* WSB, float* OUTB, int l, unsigned char* smem) {
;     ...
; #pragma unroll
;       for (int i = 0; i < 4; ++i)
; #pragma unroll
;         for (int j = 0; j < 4; ++j) gp[i][j] = make_uint2(pack2(sigmoidf_(acc[i][j][0]), sigmoidf_(acc[i][j][1])), pack2(sigmoidf_(acc[i][j][2]), sigmoidf_(acc[i][j][3])));
	v_fmac_f32_e32 v51, v52, v51
	v_div_scale_f32 v52, vcc, 1.0, v49, 1.0
	v_mul_f32_e32 v53, v52, v51
	v_fma_f32 v54, -v50, v53, v52
	v_fmac_f32_e32 v53, v54, v51
	v_fma_f32 v50, -v50, v53, v52
	v_div_fmas_f32 v50, v50, v51, v53
	v_div_fixup_f32 v49, v50, v49, 1.0
	v_div_scale_f32 v50, s[0:1], v48, v48, 1.0
	v_rcp_f32_e32 v51, v50
	v_exp_f32_e32 v13, v13
	v_mul_f32_e32 v8, 0xbfb8aa3b, v8
	v_mul_f32_e32 v9, 0xbfb8aa3b, v9
	v_fma_f32 v52, -v50, v51, 1.0
	v_fmac_f32_e32 v51, v52, v51
	v_div_scale_f32 v52, vcc, 1.0, v48, 1.0
	v_mul_f32_e32 v53, v52, v51
	v_fma_f32 v54, -v50, v53, v52
	v_fmac_f32_e32 v53, v54, v51
	v_fma_f32 v50, -v50, v53, v52
	v_div_fmas_f32 v50, v50, v51, v53
	v_div_fixup_f32 v48, v50, v48, 1.0
	v_cvt_pk_bf16_f32 v83, v48, v49
	v_div_scale_f32 v48, s[0:1], v45, v45, 1.0
	v_rcp_f32_e32 v49, v48
	v_pk_add_f32 v[12:13], v[12:13], 1.0 op_sel_hi:[1,0]
	v_exp_f32_e32 v8, v8
	v_exp_f32_e32 v9, v9
	v_fma_f32 v50, -v48, v49, 1.0
	v_fmac_f32_e32 v49, v50, v49
	v_div_scale_f32 v50, vcc, 1.0, v45, 1.0
	v_mul_f32_e32 v51, v50, v49
	v_fma_f32 v52, -v48, v51, v50
	v_fmac_f32_e32 v51, v52, v49
	v_fma_f32 v48, -v48, v51, v50
	v_div_fmas_f32 v48, v48, v49, v51
	v_div_fixup_f32 v45, v48, v45, 1.0
	v_div_scale_f32 v48, s[0:1], v44, v44, 1.0
	v_rcp_f32_e32 v49, v48
	v_pk_add_f32 v[8:9], v[8:9], 1.0 op_sel_hi:[1,0]
	v_mul_f32_e32 v4, 0xbfb8aa3b, v4
	v_mul_f32_e32 v5, 0xbfb8aa3b, v5
	v_fma_f32 v50, -v48, v49, 1.0
	v_fmac_f32_e32 v49, v50, v49
	v_div_scale_f32 v50, vcc, 1.0, v44, 1.0
	v_mul_f32_e32 v51, v50, v49
	v_fma_f32 v52, -v48, v51, v50
	v_fmac_f32_e32 v51, v52, v49
	v_fma_f32 v48, -v48, v51, v50
	v_div_fmas_f32 v48, v48, v49, v51
	v_div_fixup_f32 v44, v48, v44, 1.0
	v_cvt_pk_bf16_f32 v84, v44, v45
	v_mul_f32_e32 v44, 0xbfb8aa3b, v46
	v_mul_f32_e32 v45, 0xbfb8aa3b, v47
	v_exp_f32_e32 v44, v44
	v_exp_f32_e32 v45, v45
	v_exp_f32_e32 v4, v4
	v_exp_f32_e32 v5, v5
	v_mul_f32_e32 v0, 0xbfb8aa3b, v0
	v_pk_add_f32 v[44:45], v[44:45], 1.0 op_sel_hi:[1,0]
	v_mul_f32_e32 v1, 0xbfb8aa3b, v1
	v_div_scale_f32 v46, s[0:1], v45, v45, 1.0
	v_rcp_f32_e32 v47, v46
	v_pk_add_f32 v[4:5], v[4:5], 1.0 op_sel_hi:[1,0]
	v_exp_f32_e32 v0, v0
	v_exp_f32_e32 v1, v1
	v_fma_f32 v48, -v46, v47, 1.0
	v_fmac_f32_e32 v47, v48, v47
	v_div_scale_f32 v48, vcc, 1.0, v45, 1.0
	v_mul_f32_e32 v49, v48, v47
	v_fma_f32 v50, -v46, v49, v48
	v_fmac_f32_e32 v49, v50, v47
	v_fma_f32 v46, -v46, v49, v48
	v_div_fmas_f32 v46, v46, v47, v49
	v_div_fixup_f32 v45, v46, v45, 1.0
	v_div_scale_f32 v46, s[0:1], v44, v44, 1.0
	v_rcp_f32_e32 v47, v46
	v_pk_add_f32 v[0:1], v[0:1], 1.0 op_sel_hi:[1,0]
	v_fma_f32 v48, -v46, v47, 1.0
	v_fmac_f32_e32 v47, v48, v47
	v_div_scale_f32 v48, vcc, 1.0, v44, 1.0
	v_mul_f32_e32 v49, v48, v47
	v_fma_f32 v50, -v46, v49, v48
	v_fmac_f32_e32 v49, v50, v47
	v_fma_f32 v46, -v46, v49, v48
	v_div_fmas_f32 v46, v46, v47, v49
	v_div_fixup_f32 v44, v46, v44, 1.0
	v_cvt_pk_bf16_f32 v85, v44, v45
	v_div_scale_f32 v44, s[0:1], v41, v41, 1.0
	v_rcp_f32_e32 v45, v44
	s_nop 0
	v_fma_f32 v46, -v44, v45, 1.0
	v_fmac_f32_e32 v45, v46, v45
	v_div_scale_f32 v46, vcc, 1.0, v41, 1.0
	v_mul_f32_e32 v47, v46, v45
	v_fma_f32 v48, -v44, v47, v46
	v_fmac_f32_e32 v47, v48, v45
	v_fma_f32 v44, -v44, v47, v46
	v_div_fmas_f32 v44, v44, v45, v47
	v_div_fixup_f32 v41, v44, v41, 1.0
	v_div_scale_f32 v44, s[0:1], v40, v40, 1.0
	v_rcp_f32_e32 v45, v44
	s_nop 0
	v_fma_f32 v46, -v44, v45, 1.0
	v_fmac_f32_e32 v45, v46, v45
	v_div_scale_f32 v46, vcc, 1.0, v40, 1.0
	v_mul_f32_e32 v47, v46, v45
	v_fma_f32 v48, -v44, v47, v46
	v_fmac_f32_e32 v47, v48, v45
	v_fma_f32 v44, -v44, v47, v46
	v_div_fmas_f32 v44, v44, v45, v47
	v_div_fixup_f32 v40, v44, v40, 1.0
	v_cvt_pk_bf16_f32 v86, v40, v41
	v_mul_f32_e32 v40, 0xbfb8aa3b, v42
	v_mul_f32_e32 v41, 0xbfb8aa3b, v43
	v_exp_f32_e32 v40, v40
	v_exp_f32_e32 v41, v41
	s_nop 0
	v_pk_add_f32 v[40:41], v[40:41], 1.0 op_sel_hi:[1,0]
	s_nop 0
	v_div_scale_f32 v42, s[0:1], v41, v41, 1.0
	v_rcp_f32_e32 v43, v42
	s_nop 0
	v_fma_f32 v44, -v42, v43, 1.0
	v_fmac_f32_e32 v43, v44, v43
	v_div_scale_f32 v44, vcc, 1.0, v41, 1.0
	v_mul_f32_e32 v45, v44, v43
	v_fma_f32 v46, -v42, v45, v44
	v_fmac_f32_e32 v45, v46, v43
	v_fma_f32 v42, -v42, v45, v44
	v_div_fmas_f32 v42, v42, v43, v45
	v_div_fixup_f32 v41, v42, v41, 1.0
	v_div_scale_f32 v42, s[0:1], v40, v40, 1.0
	v_rcp_f32_e32 v43, v42
	s_nop 0
	v_fma_f32 v44, -v42, v43, 1.0
	v_fmac_f32_e32 v43, v44, v43
	v_div_scale_f32 v44, vcc, 1.0, v40, 1.0
	v_mul_f32_e32 v45, v44, v43
	v_fma_f32 v46, -v42, v45, v44
	v_fmac_f32_e32 v45, v46, v43
	v_fma_f32 v42, -v42, v45, v44
	v_div_fmas_f32 v42, v42, v43, v45
	v_div_fixup_f32 v40, v42, v40, 1.0
	v_cvt_pk_bf16_f32 v87, v40, v41
	v_div_scale_f32 v40, s[0:1], v37, v37, 1.0
	v_rcp_f32_e32 v41, v40
	s_nop 0
	v_fma_f32 v42, -v40, v41, 1.0
	v_fmac_f32_e32 v41, v42, v41
	v_div_scale_f32 v42, vcc, 1.0, v37, 1.0
	v_mul_f32_e32 v43, v42, v41
	v_fma_f32 v44, -v40, v43, v42
	v_fmac_f32_e32 v43, v44, v41
	v_fma_f32 v40, -v40, v43, v42
	v_div_fmas_f32 v40, v40, v41, v43
	v_div_fixup_f32 v37, v40, v37, 1.0
	v_div_scale_f32 v40, s[0:1], v36, v36, 1.0
	v_rcp_f32_e32 v41, v40
	s_nop 0
	v_fma_f32 v42, -v40, v41, 1.0
	v_fmac_f32_e32 v41, v42, v41
	v_div_scale_f32 v42, vcc, 1.0, v36, 1.0
	v_mul_f32_e32 v43, v42, v41
	v_fma_f32 v44, -v40, v43, v42
	v_fmac_f32_e32 v43, v44, v41
	v_fma_f32 v40, -v40, v43, v42
	v_div_fmas_f32 v40, v40, v41, v43
	v_div_fixup_f32 v36, v40, v36, 1.0
	v_cvt_pk_bf16_f32 v88, v36, v37
	v_mul_f32_e32 v36, 0xbfb8aa3b, v38
	v_mul_f32_e32 v37, 0xbfb8aa3b, v39
	v_exp_f32_e32 v36, v36
	v_exp_f32_e32 v37, v37
	s_nop 0
	v_pk_add_f32 v[36:37], v[36:37], 1.0 op_sel_hi:[1,0]
	s_nop 0
; DEVI uint32_t pack2(float lo, float hi) { f32x2_t v = {lo, hi}; bf16x2_t b = __builtin_convertvector(v, bf16x2_t); return __builtin_bit_cast(uint32_t, b); }
; DEVI float sigmoidf_(float x) { return 1.f / (1.f + __expf(-x)); }
; DEVI void phase_p8(const int TIDX, const int BIDX, const int GDIM, KAP KA, unsigned char* WSB, float* OUTB, int l, unsigned char* smem) {
;     ...
; #pragma unroll
;       for (int i = 0; i < 4; ++i)
; #pragma unroll
;         for (int j = 0; j < 4; ++j) gp[i][j] = make_uint2(pack2(sigmoidf_(acc[i][j][0]), sigmoidf_(acc[i][j][1])), pack2(sigmoidf_(acc[i][j][2]), sigmoidf_(acc[i][j][3])));
	v_div_scale_f32 v38, s[0:1], v37, v37, 1.0
	v_rcp_f32_e32 v39, v38
	s_nop 0
	v_fma_f32 v40, -v38, v39, 1.0
	v_fmac_f32_e32 v39, v40, v39
	v_div_scale_f32 v40, vcc, 1.0, v37, 1.0
	v_mul_f32_e32 v41, v40, v39
	v_fma_f32 v42, -v38, v41, v40
	v_fmac_f32_e32 v41, v42, v39
	v_fma_f32 v38, -v38, v41, v40
	v_div_fmas_f32 v38, v38, v39, v41
	v_div_fixup_f32 v37, v38, v37, 1.0
	v_div_scale_f32 v38, s[0:1], v36, v36, 1.0
	v_rcp_f32_e32 v39, v38
	s_nop 0
	v_fma_f32 v40, -v38, v39, 1.0
	v_fmac_f32_e32 v39, v40, v39
	v_div_scale_f32 v40, vcc, 1.0, v36, 1.0
	v_mul_f32_e32 v41, v40, v39
	v_fma_f32 v42, -v38, v41, v40
	v_fmac_f32_e32 v41, v42, v39
	v_fma_f32 v38, -v38, v41, v40
	v_div_fmas_f32 v38, v38, v39, v41
	v_div_fixup_f32 v36, v38, v36, 1.0
	v_cvt_pk_bf16_f32 v89, v36, v37
	v_div_scale_f32 v36, s[0:1], v33, v33, 1.0
	v_rcp_f32_e32 v37, v36
	s_nop 0
	v_fma_f32 v38, -v36, v37, 1.0
	v_fmac_f32_e32 v37, v38, v37
	v_div_scale_f32 v38, vcc, 1.0, v33, 1.0
	v_mul_f32_e32 v39, v38, v37
	v_fma_f32 v40, -v36, v39, v38
	v_fmac_f32_e32 v39, v40, v37
	v_fma_f32 v36, -v36, v39, v38
	v_div_fmas_f32 v36, v36, v37, v39
	v_div_fixup_f32 v33, v36, v33, 1.0
	v_div_scale_f32 v36, s[0:1], v32, v32, 1.0
	v_rcp_f32_e32 v37, v36
	s_nop 0
	v_fma_f32 v38, -v36, v37, 1.0
	v_fmac_f32_e32 v37, v38, v37
	v_div_scale_f32 v38, vcc, 1.0, v32, 1.0
	v_mul_f32_e32 v39, v38, v37
	v_fma_f32 v40, -v36, v39, v38
	v_fmac_f32_e32 v39, v40, v37
	v_fma_f32 v36, -v36, v39, v38
	v_div_fmas_f32 v36, v36, v37, v39
	v_div_fixup_f32 v32, v36, v32, 1.0
	v_cvt_pk_bf16_f32 v90, v32, v33
	v_mul_f32_e32 v32, 0xbfb8aa3b, v34
	v_mul_f32_e32 v33, 0xbfb8aa3b, v35
	v_exp_f32_e32 v32, v32
	v_exp_f32_e32 v33, v33
	s_nop 0
	v_pk_add_f32 v[32:33], v[32:33], 1.0 op_sel_hi:[1,0]
	s_nop 0
	v_div_scale_f32 v34, s[0:1], v33, v33, 1.0
	v_rcp_f32_e32 v35, v34
	s_nop 0
	v_fma_f32 v36, -v34, v35, 1.0
	v_fmac_f32_e32 v35, v36, v35
	v_div_scale_f32 v36, vcc, 1.0, v33, 1.0
	v_mul_f32_e32 v37, v36, v35
	v_fma_f32 v38, -v34, v37, v36
	v_fmac_f32_e32 v37, v38, v35
	v_fma_f32 v34, -v34, v37, v36
	v_div_fmas_f32 v34, v34, v35, v37
	v_div_fixup_f32 v33, v34, v33, 1.0
	v_div_scale_f32 v34, s[0:1], v32, v32, 1.0
	v_rcp_f32_e32 v35, v34
	s_nop 0
	v_fma_f32 v36, -v34, v35, 1.0
	v_fmac_f32_e32 v35, v36, v35
	v_div_scale_f32 v36, vcc, 1.0, v32, 1.0
	v_mul_f32_e32 v37, v36, v35
	v_fma_f32 v38, -v34, v37, v36
	v_fmac_f32_e32 v37, v38, v35
	v_fma_f32 v34, -v34, v37, v36
	v_div_fmas_f32 v34, v34, v35, v37
	v_div_fixup_f32 v32, v34, v32, 1.0
	v_cvt_pk_bf16_f32 v91, v32, v33
	v_div_scale_f32 v32, s[0:1], v29, v29, 1.0
	v_rcp_f32_e32 v33, v32
	s_nop 0
	v_fma_f32 v34, -v32, v33, 1.0
	v_fmac_f32_e32 v33, v34, v33
	v_div_scale_f32 v34, vcc, 1.0, v29, 1.0
	v_mul_f32_e32 v35, v34, v33
	v_fma_f32 v36, -v32, v35, v34
	v_fmac_f32_e32 v35, v36, v33
	v_fma_f32 v32, -v32, v35, v34
	v_div_fmas_f32 v32, v32, v33, v35
	v_div_fixup_f32 v29, v32, v29, 1.0
	v_div_scale_f32 v32, s[0:1], v28, v28, 1.0
	v_rcp_f32_e32 v33, v32
	s_nop 0
	v_fma_f32 v34, -v32, v33, 1.0
	v_fmac_f32_e32 v33, v34, v33
	v_div_scale_f32 v34, vcc, 1.0, v28, 1.0
	v_mul_f32_e32 v35, v34, v33
	v_fma_f32 v36, -v32, v35, v34
	v_fmac_f32_e32 v35, v36, v33
	v_fma_f32 v32, -v32, v35, v34
	v_div_fmas_f32 v32, v32, v33, v35
	v_div_fixup_f32 v28, v32, v28, 1.0
	v_cvt_pk_bf16_f32 v92, v28, v29
	v_mul_f32_e32 v28, 0xbfb8aa3b, v30
	v_mul_f32_e32 v29, 0xbfb8aa3b, v31
	v_exp_f32_e32 v28, v28
	v_exp_f32_e32 v29, v29
	s_nop 0
	v_pk_add_f32 v[28:29], v[28:29], 1.0 op_sel_hi:[1,0]
	s_nop 0
	v_div_scale_f32 v30, s[0:1], v29, v29, 1.0
	v_rcp_f32_e32 v31, v30
	s_nop 0
	v_fma_f32 v32, -v30, v31, 1.0
	v_fmac_f32_e32 v31, v32, v31
	v_div_scale_f32 v32, vcc, 1.0, v29, 1.0
	v_mul_f32_e32 v33, v32, v31
	v_fma_f32 v34, -v30, v33, v32
	v_fmac_f32_e32 v33, v34, v31
	v_fma_f32 v30, -v30, v33, v32
	v_div_fmas_f32 v30, v30, v31, v33
	v_div_fixup_f32 v29, v30, v29, 1.0
	v_div_scale_f32 v30, s[0:1], v28, v28, 1.0
	v_rcp_f32_e32 v31, v30
	s_nop 0
	v_fma_f32 v32, -v30, v31, 1.0
	v_fmac_f32_e32 v31, v32, v31
	v_div_scale_f32 v32, vcc, 1.0, v28, 1.0
	v_mul_f32_e32 v33, v32, v31
	v_fma_f32 v34, -v30, v33, v32
	v_fmac_f32_e32 v33, v34, v31
	v_fma_f32 v30, -v30, v33, v32
	v_div_fmas_f32 v30, v30, v31, v33
	v_div_fixup_f32 v28, v30, v28, 1.0
	v_cvt_pk_bf16_f32 v93, v28, v29
	v_div_scale_f32 v28, s[0:1], v25, v25, 1.0
	v_rcp_f32_e32 v29, v28
	s_nop 0
	v_fma_f32 v30, -v28, v29, 1.0
	v_fmac_f32_e32 v29, v30, v29
	v_div_scale_f32 v30, vcc, 1.0, v25, 1.0
	v_mul_f32_e32 v31, v30, v29
	v_fma_f32 v32, -v28, v31, v30
	v_fmac_f32_e32 v31, v32, v29
	v_fma_f32 v28, -v28, v31, v30
	v_div_fmas_f32 v28, v28, v29, v31
	v_div_fixup_f32 v25, v28, v25, 1.0
	v_div_scale_f32 v28, s[0:1], v24, v24, 1.0
	v_rcp_f32_e32 v29, v28
	s_nop 0
	v_fma_f32 v30, -v28, v29, 1.0
	v_fmac_f32_e32 v29, v30, v29
	v_div_scale_f32 v30, vcc, 1.0, v24, 1.0
	v_mul_f32_e32 v31, v30, v29
	v_fma_f32 v32, -v28, v31, v30
	v_fmac_f32_e32 v31, v32, v29
	v_fma_f32 v28, -v28, v31, v30
	v_div_fmas_f32 v28, v28, v29, v31
	v_div_fixup_f32 v24, v28, v24, 1.0
	v_cvt_pk_bf16_f32 v94, v24, v25
	v_mul_f32_e32 v24, 0xbfb8aa3b, v26
	v_mul_f32_e32 v25, 0xbfb8aa3b, v27
	v_exp_f32_e32 v24, v24
	v_exp_f32_e32 v25, v25
	s_nop 0
	v_pk_add_f32 v[24:25], v[24:25], 1.0 op_sel_hi:[1,0]
	s_nop 0
	v_div_scale_f32 v26, s[0:1], v25, v25, 1.0
	v_rcp_f32_e32 v27, v26
	s_nop 0
	v_fma_f32 v28, -v26, v27, 1.0
	v_fmac_f32_e32 v27, v28, v27
	v_div_scale_f32 v28, vcc, 1.0, v25, 1.0
	v_mul_f32_e32 v29, v28, v27
	v_fma_f32 v30, -v26, v29, v28
	v_fmac_f32_e32 v29, v30, v27
	v_fma_f32 v26, -v26, v29, v28
	v_div_fmas_f32 v26, v26, v27, v29
	v_div_fixup_f32 v25, v26, v25, 1.0
	v_div_scale_f32 v26, s[0:1], v24, v24, 1.0
; DEVI uint32_t pack2(float lo, float hi) { f32x2_t v = {lo, hi}; bf16x2_t b = __builtin_convertvector(v, bf16x2_t); return __builtin_bit_cast(uint32_t, b); }
; DEVI float sigmoidf_(float x) { return 1.f / (1.f + __expf(-x)); }
; DEVI void phase_p8(const int TIDX, const int BIDX, const int GDIM, KAP KA, unsigned char* WSB, float* OUTB, int l, unsigned char* smem) {
;     ...
; #pragma unroll
;       for (int i = 0; i < 4; ++i)
; #pragma unroll
;         for (int j = 0; j < 4; ++j) gp[i][j] = make_uint2(pack2(sigmoidf_(acc[i][j][0]), sigmoidf_(acc[i][j][1])), pack2(sigmoidf_(acc[i][j][2]), sigmoidf_(acc[i][j][3])));
	v_rcp_f32_e32 v27, v26
	s_nop 0
	v_fma_f32 v28, -v26, v27, 1.0
	v_fmac_f32_e32 v27, v28, v27
	v_div_scale_f32 v28, vcc, 1.0, v24, 1.0
	v_mul_f32_e32 v29, v28, v27
	v_fma_f32 v30, -v26, v29, v28
	v_fmac_f32_e32 v29, v30, v27
	v_fma_f32 v26, -v26, v29, v28
	v_div_fmas_f32 v26, v26, v27, v29
	v_div_fixup_f32 v24, v26, v24, 1.0
	v_cvt_pk_bf16_f32 v95, v24, v25
	v_div_scale_f32 v24, s[0:1], v21, v21, 1.0
	v_rcp_f32_e32 v25, v24
	s_nop 0
	v_fma_f32 v26, -v24, v25, 1.0
	v_fmac_f32_e32 v25, v26, v25
	v_div_scale_f32 v26, vcc, 1.0, v21, 1.0
	v_mul_f32_e32 v27, v26, v25
	v_fma_f32 v28, -v24, v27, v26
	v_fmac_f32_e32 v27, v28, v25
	v_fma_f32 v24, -v24, v27, v26
	v_div_fmas_f32 v24, v24, v25, v27
	v_div_fixup_f32 v21, v24, v21, 1.0
	v_div_scale_f32 v24, s[0:1], v20, v20, 1.0
	v_rcp_f32_e32 v25, v24
	s_nop 0
	v_fma_f32 v26, -v24, v25, 1.0
	v_fmac_f32_e32 v25, v26, v25
	v_div_scale_f32 v26, vcc, 1.0, v20, 1.0
	v_mul_f32_e32 v27, v26, v25
	v_fma_f32 v28, -v24, v27, v26
	v_fmac_f32_e32 v27, v28, v25
	v_fma_f32 v24, -v24, v27, v26
	v_div_fmas_f32 v24, v24, v25, v27
	v_div_fixup_f32 v20, v24, v20, 1.0
	v_cvt_pk_bf16_f32 v96, v20, v21
	v_mul_f32_e32 v20, 0xbfb8aa3b, v22
	v_mul_f32_e32 v21, 0xbfb8aa3b, v23
	v_exp_f32_e32 v20, v20
	v_exp_f32_e32 v21, v21
	s_nop 0
	v_pk_add_f32 v[20:21], v[20:21], 1.0 op_sel_hi:[1,0]
	s_nop 0
	v_div_scale_f32 v22, s[0:1], v21, v21, 1.0
	v_rcp_f32_e32 v23, v22
	s_nop 0
	v_fma_f32 v24, -v22, v23, 1.0
	v_fmac_f32_e32 v23, v24, v23
	v_div_scale_f32 v24, vcc, 1.0, v21, 1.0
	v_mul_f32_e32 v25, v24, v23
	v_fma_f32 v26, -v22, v25, v24
	v_fmac_f32_e32 v25, v26, v23
	v_fma_f32 v22, -v22, v25, v24
	v_div_fmas_f32 v22, v22, v23, v25
	v_div_fixup_f32 v21, v22, v21, 1.0
	v_div_scale_f32 v22, s[0:1], v20, v20, 1.0
	v_rcp_f32_e32 v23, v22
	s_nop 0
	v_fma_f32 v24, -v22, v23, 1.0
	v_fmac_f32_e32 v23, v24, v23
	v_div_scale_f32 v24, vcc, 1.0, v20, 1.0
	v_mul_f32_e32 v25, v24, v23
	v_fma_f32 v26, -v22, v25, v24
	v_fmac_f32_e32 v25, v26, v23
	v_fma_f32 v22, -v22, v25, v24
	v_div_fmas_f32 v22, v22, v23, v25
	v_div_fixup_f32 v20, v22, v20, 1.0
	v_cvt_pk_bf16_f32 v97, v20, v21
	v_div_scale_f32 v20, s[0:1], v17, v17, 1.0
	v_rcp_f32_e32 v21, v20
	s_nop 0
	v_fma_f32 v22, -v20, v21, 1.0
	v_fmac_f32_e32 v21, v22, v21
	v_div_scale_f32 v22, vcc, 1.0, v17, 1.0
	v_mul_f32_e32 v23, v22, v21
	v_fma_f32 v24, -v20, v23, v22
	v_fmac_f32_e32 v23, v24, v21
	v_fma_f32 v20, -v20, v23, v22
	v_div_fmas_f32 v20, v20, v21, v23
	v_div_fixup_f32 v17, v20, v17, 1.0
	v_div_scale_f32 v20, s[0:1], v16, v16, 1.0
	v_rcp_f32_e32 v21, v20
	s_nop 0
	v_fma_f32 v22, -v20, v21, 1.0
	v_fmac_f32_e32 v21, v22, v21
	v_div_scale_f32 v22, vcc, 1.0, v16, 1.0
	v_mul_f32_e32 v23, v22, v21
	v_fma_f32 v24, -v20, v23, v22
	v_fmac_f32_e32 v23, v24, v21
	v_fma_f32 v20, -v20, v23, v22
	v_div_fmas_f32 v20, v20, v21, v23
	v_div_fixup_f32 v16, v20, v16, 1.0
	v_cvt_pk_bf16_f32 v98, v16, v17
	v_mul_f32_e32 v16, 0xbfb8aa3b, v18
	v_mul_f32_e32 v17, 0xbfb8aa3b, v19
	v_exp_f32_e32 v16, v16
	v_exp_f32_e32 v17, v17
	s_nop 0
	v_pk_add_f32 v[16:17], v[16:17], 1.0 op_sel_hi:[1,0]
	s_nop 0
	v_div_scale_f32 v18, s[0:1], v17, v17, 1.0
	v_rcp_f32_e32 v19, v18
	s_nop 0
	v_fma_f32 v20, -v18, v19, 1.0
	v_fmac_f32_e32 v19, v20, v19
	v_div_scale_f32 v20, vcc, 1.0, v17, 1.0
	v_mul_f32_e32 v21, v20, v19
	v_fma_f32 v22, -v18, v21, v20
	v_fmac_f32_e32 v21, v22, v19
	v_fma_f32 v18, -v18, v21, v20
	v_div_fmas_f32 v18, v18, v19, v21
	v_div_fixup_f32 v17, v18, v17, 1.0
	v_div_scale_f32 v18, s[0:1], v16, v16, 1.0
	v_rcp_f32_e32 v19, v18
	s_nop 0
	v_fma_f32 v20, -v18, v19, 1.0
	v_fmac_f32_e32 v19, v20, v19
	v_div_scale_f32 v20, vcc, 1.0, v16, 1.0
	v_mul_f32_e32 v21, v20, v19
	v_fma_f32 v22, -v18, v21, v20
	v_fmac_f32_e32 v21, v22, v19
	v_fma_f32 v18, -v18, v21, v20
	v_div_fmas_f32 v18, v18, v19, v21
	v_div_fixup_f32 v16, v18, v16, 1.0
	v_cvt_pk_bf16_f32 v99, v16, v17
	v_div_scale_f32 v16, s[0:1], v13, v13, 1.0
	v_rcp_f32_e32 v17, v16
	s_nop 0
	v_fma_f32 v18, -v16, v17, 1.0
	v_fmac_f32_e32 v17, v18, v17
	v_div_scale_f32 v18, vcc, 1.0, v13, 1.0
	v_mul_f32_e32 v19, v18, v17
	v_fma_f32 v20, -v16, v19, v18
	v_fmac_f32_e32 v19, v20, v17
	v_fma_f32 v16, -v16, v19, v18
	v_div_fmas_f32 v16, v16, v17, v19
	v_div_fixup_f32 v13, v16, v13, 1.0
	v_div_scale_f32 v16, s[0:1], v12, v12, 1.0
	v_rcp_f32_e32 v17, v16
	s_nop 0
	v_fma_f32 v18, -v16, v17, 1.0
	v_fmac_f32_e32 v17, v18, v17
	v_div_scale_f32 v18, vcc, 1.0, v12, 1.0
	v_mul_f32_e32 v19, v18, v17
	v_fma_f32 v20, -v16, v19, v18
	v_fmac_f32_e32 v19, v20, v17
	v_fma_f32 v16, -v16, v19, v18
	v_div_fmas_f32 v16, v16, v17, v19
	v_div_fixup_f32 v12, v16, v12, 1.0
	v_cvt_pk_bf16_f32 v100, v12, v13
	v_mul_f32_e32 v12, 0xbfb8aa3b, v14
	v_mul_f32_e32 v13, 0xbfb8aa3b, v15
	v_exp_f32_e32 v12, v12
	v_exp_f32_e32 v13, v13
	s_nop 0
	v_pk_add_f32 v[12:13], v[12:13], 1.0 op_sel_hi:[1,0]
	s_nop 0
	v_div_scale_f32 v14, s[0:1], v13, v13, 1.0
	v_rcp_f32_e32 v15, v14
	s_nop 0
	v_fma_f32 v16, -v14, v15, 1.0
	v_fmac_f32_e32 v15, v16, v15
	v_div_scale_f32 v16, vcc, 1.0, v13, 1.0
	v_mul_f32_e32 v17, v16, v15
	v_fma_f32 v18, -v14, v17, v16
	v_fmac_f32_e32 v17, v18, v15
	v_fma_f32 v14, -v14, v17, v16
	v_div_fmas_f32 v14, v14, v15, v17
	v_div_fixup_f32 v13, v14, v13, 1.0
	v_div_scale_f32 v14, s[0:1], v12, v12, 1.0
	v_rcp_f32_e32 v15, v14
	s_nop 0
	v_fma_f32 v16, -v14, v15, 1.0
	v_fmac_f32_e32 v15, v16, v15
	v_div_scale_f32 v16, vcc, 1.0, v12, 1.0
	v_mul_f32_e32 v17, v16, v15
	v_fma_f32 v18, -v14, v17, v16
	v_fmac_f32_e32 v17, v18, v15
	v_fma_f32 v14, -v14, v17, v16
	v_div_fmas_f32 v14, v14, v15, v17
	v_div_fixup_f32 v12, v14, v12, 1.0
	v_cvt_pk_bf16_f32 v101, v12, v13
	v_div_scale_f32 v12, s[0:1], v9, v9, 1.0
; DEVI uint32_t pack2(float lo, float hi) { f32x2_t v = {lo, hi}; bf16x2_t b = __builtin_convertvector(v, bf16x2_t); return __builtin_bit_cast(uint32_t, b); }
; DEVI float sigmoidf_(float x) { return 1.f / (1.f + __expf(-x)); }
; template <bool SWAP, class RP>
; DEVI void gemm_main(const int TIDX, const int BIDX, const int GDIM, f32x4 (&acc)[4][4], RP rowoff, const bf16_t* __restrict__ Bt, int ldb, int K, unsigned char* smem) {
;     ...
;   const int lane = tid & 63, w = tid >> 6, wr = w >> 1, wc = w & 1, li = lane & 15, lg = lane >> 4;
;   const unsigned char* abase = rowoff.base;
;   const unsigned char* bbase = (const unsigned char*)Bt;
;   const uint32_t schunk = (uint32_t)((lane & 7) ^ (((lane >> 4) + 4 * (w & 1)) & 7)) * 16u;
;   uint32_t ao0, ao1, ao2, ao3;
;   const int rsub = w * 8 + (lane >> 3);
;   ao0 = rowoff(rsub) + schunk; ao1 = rowoff(rsub + 32) + schunk; ao2 = rowoff(rsub + 64) + schunk; ao3 = rowoff(rsub + 96) + schunk;
;   const uint32_t bo = (uint32_t)(rsub * ldb) * 2u + schunk, bstep = (uint32_t)(32 * ldb) * 2u;
;   unsigned char* sbase = smem + w * 1024;
; DEVI void phase_p8(const int TIDX, const int BIDX, const int GDIM, KAP KA, unsigned char* WSB, float* OUTB, int l, unsigned char* smem) {
;     ...
; #pragma unroll
;       for (int i = 0; i < 4; ++i)
; #pragma unroll
;         for (int j = 0; j < 4; ++j) gp[i][j] = make_uint2(pack2(sigmoidf_(acc[i][j][0]), sigmoidf_(acc[i][j][1])), pack2(sigmoidf_(acc[i][j][2]), sigmoidf_(acc[i][j][3])));
;       zero_acc(acc);
;       RowLin rpl{(const unsigned char*)((const bf16_t*)(WSB + O_YM) + (size_t)m0 * 256), 512};
;       gemm_main<true>(TIDX, BIDX, GDIM, acc, rpl, W + WO_PLE + (size_t)n0 * 256, 256, 256, smem);
	v_rcp_f32_e32 v13, v12
	s_nop 0
	v_fma_f32 v14, -v12, v13, 1.0
	v_fmac_f32_e32 v13, v14, v13
	v_div_scale_f32 v14, vcc, 1.0, v9, 1.0
	v_mul_f32_e32 v15, v14, v13
	v_fma_f32 v16, -v12, v15, v14
	v_fmac_f32_e32 v15, v16, v13
	v_fma_f32 v12, -v12, v15, v14
	v_div_fmas_f32 v12, v12, v13, v15
	v_div_fixup_f32 v9, v12, v9, 1.0
	v_div_scale_f32 v12, s[0:1], v8, v8, 1.0
	v_rcp_f32_e32 v13, v12
	s_nop 0
	v_fma_f32 v14, -v12, v13, 1.0
	v_fmac_f32_e32 v13, v14, v13
	v_div_scale_f32 v14, vcc, 1.0, v8, 1.0
	v_mul_f32_e32 v15, v14, v13
	v_fma_f32 v16, -v12, v15, v14
	v_fmac_f32_e32 v15, v16, v13
	v_fma_f32 v12, -v12, v15, v14
	v_div_fmas_f32 v12, v12, v13, v15
	v_div_fixup_f32 v8, v12, v8, 1.0
	v_cvt_pk_bf16_f32 v102, v8, v9
	v_mul_f32_e32 v8, 0xbfb8aa3b, v10
	v_mul_f32_e32 v9, 0xbfb8aa3b, v11
	v_exp_f32_e32 v8, v8
	v_exp_f32_e32 v9, v9
	s_nop 0
	v_pk_add_f32 v[8:9], v[8:9], 1.0 op_sel_hi:[1,0]
	s_nop 0
	v_div_scale_f32 v10, s[0:1], v9, v9, 1.0
	v_rcp_f32_e32 v11, v10
	s_nop 0
	v_fma_f32 v12, -v10, v11, 1.0
	v_fmac_f32_e32 v11, v12, v11
	v_div_scale_f32 v12, vcc, 1.0, v9, 1.0
	v_mul_f32_e32 v13, v12, v11
	v_fma_f32 v14, -v10, v13, v12
	v_fmac_f32_e32 v13, v14, v11
	v_fma_f32 v10, -v10, v13, v12
	v_div_fmas_f32 v10, v10, v11, v13
	v_div_fixup_f32 v9, v10, v9, 1.0
	v_div_scale_f32 v10, s[0:1], v8, v8, 1.0
	v_rcp_f32_e32 v11, v10
	s_nop 0
	v_fma_f32 v12, -v10, v11, 1.0
	v_fmac_f32_e32 v11, v12, v11
	v_div_scale_f32 v12, vcc, 1.0, v8, 1.0
	v_mul_f32_e32 v13, v12, v11
	v_fma_f32 v14, -v10, v13, v12
	v_fmac_f32_e32 v13, v14, v11
	v_fma_f32 v10, -v10, v13, v12
	v_div_fmas_f32 v10, v10, v11, v13
	v_div_fixup_f32 v8, v10, v8, 1.0
	v_cvt_pk_bf16_f32 v103, v8, v9
	v_div_scale_f32 v8, s[0:1], v5, v5, 1.0
	v_rcp_f32_e32 v9, v8
	s_nop 0
	v_fma_f32 v10, -v8, v9, 1.0
	v_fmac_f32_e32 v9, v10, v9
	v_div_scale_f32 v10, vcc, 1.0, v5, 1.0
	v_mul_f32_e32 v11, v10, v9
	v_fma_f32 v12, -v8, v11, v10
	v_fmac_f32_e32 v11, v12, v9
	v_fma_f32 v8, -v8, v11, v10
	v_div_fmas_f32 v8, v8, v9, v11
	v_div_fixup_f32 v5, v8, v5, 1.0
	v_div_scale_f32 v8, s[0:1], v4, v4, 1.0
	v_rcp_f32_e32 v9, v8
	s_nop 0
	v_fma_f32 v10, -v8, v9, 1.0
	v_fmac_f32_e32 v9, v10, v9
	v_div_scale_f32 v10, vcc, 1.0, v4, 1.0
	v_mul_f32_e32 v11, v10, v9
	v_fma_f32 v12, -v8, v11, v10
	v_fmac_f32_e32 v11, v12, v9
	v_fma_f32 v8, -v8, v11, v10
	v_div_fmas_f32 v8, v8, v9, v11
	v_div_fixup_f32 v4, v8, v4, 1.0
	v_cvt_pk_bf16_f32 v104, v4, v5
	v_mul_f32_e32 v4, 0xbfb8aa3b, v6
	v_mul_f32_e32 v5, 0xbfb8aa3b, v7
	v_exp_f32_e32 v4, v4
	v_exp_f32_e32 v5, v5
	s_nop 0
	v_pk_add_f32 v[4:5], v[4:5], 1.0 op_sel_hi:[1,0]
	s_nop 0
	v_div_scale_f32 v6, s[0:1], v5, v5, 1.0
	v_rcp_f32_e32 v7, v6
	s_nop 0
	v_fma_f32 v8, -v6, v7, 1.0
	v_fmac_f32_e32 v7, v8, v7
	v_div_scale_f32 v8, vcc, 1.0, v5, 1.0
	v_mul_f32_e32 v9, v8, v7
	v_fma_f32 v10, -v6, v9, v8
	v_fmac_f32_e32 v9, v10, v7
	v_fma_f32 v6, -v6, v9, v8
	v_div_fmas_f32 v6, v6, v7, v9
	v_div_fixup_f32 v5, v6, v5, 1.0
	v_div_scale_f32 v6, s[0:1], v4, v4, 1.0
	v_rcp_f32_e32 v7, v6
	s_nop 0
	v_fma_f32 v8, -v6, v7, 1.0
	v_fmac_f32_e32 v7, v8, v7
	v_div_scale_f32 v8, vcc, 1.0, v4, 1.0
	v_mul_f32_e32 v9, v8, v7
	v_fma_f32 v10, -v6, v9, v8
	v_fmac_f32_e32 v9, v10, v7
	v_fma_f32 v6, -v6, v9, v8
	v_div_fmas_f32 v6, v6, v7, v9
	v_div_fixup_f32 v4, v6, v4, 1.0
	v_cvt_pk_bf16_f32 v105, v4, v5
	v_div_scale_f32 v4, s[0:1], v1, v1, 1.0
	v_rcp_f32_e32 v5, v4
	v_mov_b32_e32 v10, v130
	v_mov_b32_e32 v9, v129
	v_fma_f32 v6, -v4, v5, 1.0
	v_fmac_f32_e32 v5, v6, v5
	v_div_scale_f32 v6, vcc, 1.0, v1, 1.0
	v_mul_f32_e32 v7, v6, v5
	v_fma_f32 v8, -v4, v7, v6
	v_fmac_f32_e32 v7, v8, v5
	v_fma_f32 v4, -v4, v7, v6
	v_div_fmas_f32 v4, v4, v5, v7
	v_div_fixup_f32 v1, v4, v1, 1.0
	v_div_scale_f32 v4, s[0:1], v0, v0, 1.0
	v_rcp_f32_e32 v5, v4
	s_nop 0
	v_fma_f32 v6, -v4, v5, 1.0
	v_fmac_f32_e32 v5, v6, v5
	v_div_scale_f32 v6, vcc, 1.0, v0, 1.0
	v_mul_f32_e32 v7, v6, v5
	v_fma_f32 v8, -v4, v7, v6
	v_fmac_f32_e32 v7, v8, v5
	v_fma_f32 v4, -v4, v7, v6
	v_div_fmas_f32 v4, v4, v5, v7
	v_div_fixup_f32 v0, v4, v0, 1.0
	v_cvt_pk_bf16_f32 v106, v0, v1
	v_mul_f32_e32 v0, 0xbfb8aa3b, v2
	v_mul_f32_e32 v1, 0xbfb8aa3b, v3
	v_exp_f32_e32 v0, v0
	v_exp_f32_e32 v1, v1
	s_nop 0
	v_pk_add_f32 v[0:1], v[0:1], 1.0 op_sel_hi:[1,0]
	s_nop 0
	v_div_scale_f32 v2, s[0:1], v1, v1, 1.0
	v_rcp_f32_e32 v3, v2
	s_nop 0
	v_fma_f32 v4, -v2, v3, 1.0
	v_fmac_f32_e32 v3, v4, v3
	v_div_scale_f32 v4, vcc, 1.0, v1, 1.0
	v_mul_f32_e32 v5, v4, v3
	v_fma_f32 v6, -v2, v5, v4
	v_fmac_f32_e32 v5, v6, v3
	v_fma_f32 v2, -v2, v5, v4
	v_div_fmas_f32 v2, v2, v3, v5
	v_div_fixup_f32 v1, v2, v1, 1.0
	v_div_scale_f32 v2, s[0:1], v0, v0, 1.0
	v_rcp_f32_e32 v3, v2
	s_lshl_b64 s[0:1], s[8:9], 9
	s_add_u32 s0, s13, s0
	s_addc_u32 s1, s14, s1
	v_fma_f32 v4, -v2, v3, 1.0
	v_fmac_f32_e32 v3, v4, v3
	v_div_scale_f32 v4, vcc, 1.0, v0, 1.0
	v_mul_f32_e32 v5, v4, v3
	v_fma_f32 v6, -v2, v5, v4
	v_fmac_f32_e32 v5, v6, v3
	v_fma_f32 v2, -v2, v5, v4
	v_div_fmas_f32 v2, v2, v3, v5
	v_div_fixup_f32 v0, v2, v0, 1.0
	v_cvt_pk_bf16_f32 v107, v0, v1
	v_mov_b32_e32 v0, v129
	s_lshl_b32 s9, s23, 9
	v_ashrrev_i32_e32 v5, 6, v10
	v_and_b32_e32 v11, 1, v5
	v_bfe_u32 v4, v10, 4, 2
	v_and_b32_e32 v6, 7, v10
	v_lshlrev_b32_e32 v7, 2, v11
	s_add_u32 s24, s15, s9
	v_bitop3_b32 v4, v7, v6, v4 bitop3:0x36
	v_lshlrev_b32_e32 v6, 12, v5
	v_lshlrev_b32_e32 v7, 6, v10
	s_movk_i32 s9, 0xe00
	v_and_or_b32 v6, v7, s9, v6
	v_lshl_or_b32 v128, v4, 4, v6
	v_add_u32_e32 v4, 0x4000, v128
	v_lshlrev_b32_e32 v13, 10, v5
	v_mov_b32_e32 v5, v129
	v_readfirstlane_b32 s29, v13
	v_lshl_add_u64 v[68:69], s[0:1], 0, v[4:5]
	v_add_u32_e32 v5, 0x1000, v13
	s_mov_b32 m0, s29
	v_readfirstlane_b32 s30, v5
; DEVI f32x4 mfma16(bf16x8 a, bf16x8 b, f32x4 c) { return __builtin_amdgcn_mfma_f32_16x16x32_bf16(a, b, c, 0, 0, 0); }
; template <bool SWAP, class RP>
; DEVI void gemm_main(const int TIDX, const int BIDX, const int GDIM, f32x4 (&acc)[4][4], RP rowoff, const bf16_t* __restrict__ Bt, int ldb, int K, unsigned char* smem) {
;     ...
;   const int nk = K >> 6;
;   const int px = lg ^ (li >> 1);
;   GM_STAGE(0, 0);
;   for (int kt = 0; kt < nk; ++kt) {
;     const int buf = kt & 1;
;     asm volatile("s_waitcnt vmcnt(0)" ::: "memory");
;     __syncthreads();
;     if (kt + 1 < nk) GM_STAGE(kt + 1, buf ^ 1);
;     const unsigned char* A = smem + buf * 32768 + (wr * 64 + li) * 128;
;     const unsigned char* B = smem + buf * 32768 + 16384 + (wc * 64 + li) * 128;
; #pragma unroll
;     for (int ks = 0; ks < 2; ++ks) {
;       const int po = (px ^ (ks * 4)) * 16;
;       bf16x8 af[4], bfr[4];
; #pragma unroll
;       for (int i = 0; i < 4; ++i) {
;         af[i] = *(const bf16x8*)(A + i * 2048 + po);
;         bfr[i] = *(const bf16x8*)(B + i * 2048 + po);
;       }
; #pragma unroll
;       for (int mi = 0; mi < 4; ++mi)
; #pragma unroll
;         for (int ni = 0; ni < 4; ++ni)
;           acc[mi][ni] = SWAP ? mfma16(bfr[ni], af[mi], acc[mi][ni]) : mfma16(af[mi], bfr[ni], acc[mi][ni]);
	global_load_lds_dwordx4 v128, s[0:1]
	s_mov_b32 m0, s30
	v_add_u32_e32 v6, 0x8000, v128
	global_load_lds_dwordx4 v4, s[0:1]
	v_add_u32_e32 v4, 0x2000, v13
	v_add_u32_e32 v14, 0x4000, v13
	v_readfirstlane_b32 s31, v4
	v_add_u32_e32 v4, 0x3000, v13
	v_mov_b32_e32 v7, v129
	s_mov_b32 m0, s31
	v_readfirstlane_b32 s34, v4
	s_addc_u32 s25, s16, 0
	v_add_u32_e32 v8, 0xc000, v128
	v_lshl_add_u64 v[70:71], s[0:1], 0, v[6:7]
	global_load_lds_dwordx4 v6, s[0:1]
	s_mov_b32 m0, s34
	v_readfirstlane_b32 s35, v14
	v_add_u32_e32 v6, 0x5000, v13
	v_lshl_add_u64 v[64:65], s[0:1], 0, v[128:129]
	v_lshl_add_u64 v[72:73], s[0:1], 0, v[8:9]
	global_load_lds_dwordx4 v8, s[0:1]
	v_lshl_add_u64 v[66:67], s[24:25], 0, v[128:129]
	s_mov_b32 m0, s35
	s_mov_b64 s[0:1], 0x4000
	v_readfirstlane_b32 s36, v6
	v_add_u32_e32 v6, 0x6000, v13
	global_load_lds_dwordx4 v128, s[24:25]
	v_lshl_add_u64 v[4:5], v[66:67], 0, s[0:1]
	s_mov_b32 m0, s36
	v_readfirstlane_b32 s37, v6
	v_add_u32_e32 v6, 0x7000, v13
	global_load_lds_dwordx4 v[4:5], off
	v_lshl_add_u64 v[4:5], v[66:67], 0, s[58:59]
	s_mov_b32 m0, s37
	s_mov_b64 s[0:1], 0xc000
	v_readfirstlane_b32 s38, v6
	global_load_lds_dwordx4 v[4:5], off
	v_lshl_add_u64 v[4:5], v[66:67], 0, s[0:1]
	s_mov_b32 m0, s38
	v_lshrrev_b32_e32 v6, 1, v10
	global_load_lds_dwordx4 v[4:5], off
	v_and_b32_e32 v4, 15, v10
	v_lshrrev_b32_e32 v12, 4, v10
	v_bfe_u32 v5, v10, 1, 3
	v_and_or_b32 v6, v6, s39, v4
	v_add_u32_e32 v7, 0x8000, v13
	v_lshlrev_b32_e32 v44, 7, v6
	v_lshlrev_b32_e32 v6, 7, v4
	v_bitop3_b32 v4, v5, v12, 3 bitop3:0x78
	v_readfirstlane_b32 s0, v7
	v_add_u32_e32 v7, 0x9000, v13
	v_lshlrev_b32_e32 v45, 4, v4
	v_lshl_add_u64 v[4:5], v[64:65], 0, s[66:67]
	s_mov_b32 m0, s0
	v_readfirstlane_b32 s1, v7
	v_add_u32_e32 v7, 0xa000, v13
	s_waitcnt vmcnt(0)
	s_waitcnt vmcnt(0) lgkmcnt(0)
	s_barrier
	global_load_lds_dwordx4 v[4:5], off
	v_lshl_add_u64 v[4:5], v[68:69], 0, s[66:67]
	s_mov_b32 m0, s1
	v_readfirstlane_b32 s9, v7
	v_add_u32_e32 v7, 0xb000, v13
	v_add_u32_e32 v8, 0xc000, v13
	global_load_lds_dwordx4 v[4:5], off
	v_lshl_add_u64 v[4:5], v[70:71], 0, s[66:67]
	s_mov_b32 m0, s9
	v_readfirstlane_b32 s24, v7
	global_load_lds_dwordx4 v[4:5], off
	v_lshl_add_u64 v[4:5], v[72:73], 0, s[66:67]
	s_mov_b32 m0, s24
	v_readfirstlane_b32 s25, v8
	global_load_lds_dwordx4 v[4:5], off
	v_lshl_add_u64 v[4:5], v[66:67], 0, s[66:67]
	s_mov_b32 m0, s25
	v_add_u32_e32 v7, 0xd000, v13
	global_load_lds_dwordx4 v[4:5], off
	v_lshl_add_u64 v[4:5], v[66:67], 0, s[26:27]
	v_readfirstlane_b32 s26, v7
	v_add_u32_e32 v7, 0xe000, v13
	s_mov_b32 m0, s26
	v_readfirstlane_b32 s27, v7
	v_add_u32_e32 v7, 0xf000, v13
	global_load_lds_dwordx4 v[4:5], off
	v_lshl_add_u64 v[4:5], v[66:67], 0, s[40:41]
	s_mov_b32 m0, s27
	s_mov_b64 s[40:41], 0xc080
	v_readfirstlane_b32 s28, v7
	global_load_lds_dwordx4 v[4:5], off
	v_lshl_add_u64 v[4:5], v[66:67], 0, s[40:41]
	s_mov_b32 m0, s28
	v_lshl_or_b32 v47, v11, 13, v6
	global_load_lds_dwordx4 v[4:5], off
	v_or_b32_e32 v109, v44, v45
	v_or_b32_e32 v111, v47, v45
	ds_read_b128 v[4:7], v109
	ds_read_b128 v[8:11], v111 offset:16384
	ds_read_b128 v[12:15], v109 offset:2048
	ds_read_b128 v[16:19], v111 offset:18432
	ds_read_b128 v[20:23], v109 offset:4096
	ds_read_b128 v[24:27], v111 offset:20480
	ds_read_b128 v[28:31], v109 offset:6144
	ds_read_b128 v[32:35], v111 offset:22528
	v_mov_b32_e32 v1, v0
	v_mov_b32_e32 v2, v0
	v_mov_b32_e32 v3, v0
	v_xor_b32_e32 v46, 64, v45
	v_bitop3_b32 v108, v44, v45, 64 bitop3:0xf6
	s_waitcnt lgkmcnt(0)
	v_mfma_f32_16x16x32_bf16 v[48:51], v[24:27], v[4:7], v[0:3]
	v_or_b32_e32 v110, v47, v46
	s_mov_b64 s[40:41], 0x100
	s_mov_b32 m0, s29
	v_mfma_f32_16x16x32_bf16 v[56:59], v[16:19], v[12:15], v[0:3]
	v_mfma_f32_16x16x32_bf16 v[36:39], v[8:11], v[4:7], v[0:3]
	v_mfma_f32_16x16x32_bf16 v[40:43], v[16:19], v[4:7], v[0:3]
	v_mfma_f32_16x16x32_bf16 v[4:7], v[32:35], v[4:7], v[0:3]
	v_mfma_f32_16x16x32_bf16 v[52:55], v[8:11], v[12:15], v[0:3]
	v_mfma_f32_16x16x32_bf16 v[60:63], v[24:27], v[12:15], v[0:3]
	v_mfma_f32_16x16x32_bf16 v[12:15], v[32:35], v[12:15], v[0:3]
	v_mfma_f32_16x16x32_bf16 v[112:115], v[8:11], v[20:23], v[0:3]
	v_mfma_f32_16x16x32_bf16 v[116:119], v[16:19], v[20:23], v[0:3]
	v_mfma_f32_16x16x32_bf16 v[120:123], v[24:27], v[20:23], v[0:3]
	v_mfma_f32_16x16x32_bf16 v[20:23], v[32:35], v[20:23], v[0:3]
	v_mfma_f32_16x16x32_bf16 v[124:127], v[8:11], v[28:31], v[0:3]
	v_mfma_f32_16x16x32_bf16 v[132:135], v[16:19], v[28:31], v[0:3]
	v_mfma_f32_16x16x32_bf16 v[136:139], v[24:27], v[28:31], v[0:3]
	v_mfma_f32_16x16x32_bf16 v[140:143], v[32:35], v[28:31], v[0:3]
	s_nop 2
	ds_read_b128 v[0:3], v108
	ds_read_b128 v[24:27], v110 offset:16384
	ds_read_b128 v[8:11], v108 offset:2048
	ds_read_b128 v[144:147], v110 offset:18432
	ds_read_b128 v[148:151], v108 offset:4096
	ds_read_b128 v[152:155], v110 offset:20480
	ds_read_b128 v[156:159], v108 offset:6144
	ds_read_b128 v[162:165], v110 offset:22528
	s_waitcnt vmcnt(0)
	s_waitcnt vmcnt(0) lgkmcnt(0)
	v_mfma_f32_16x16x32_bf16 v[170:173], v[152:155], v[0:3], v[48:51]
	s_barrier
; DEVI f32x4 mfma16(bf16x8 a, bf16x8 b, f32x4 c) { return __builtin_amdgcn_mfma_f32_16x16x32_bf16(a, b, c, 0, 0, 0); }
; template <bool SWAP, class RP>
; DEVI void gemm_main(const int TIDX, const int BIDX, const int GDIM, f32x4 (&acc)[4][4], RP rowoff, const bf16_t* __restrict__ Bt, int ldb, int K, unsigned char* smem) {
;     ...
;   for (int kt = 0; kt < nk; ++kt) {
;     const int buf = kt & 1;
;     asm volatile("s_waitcnt vmcnt(0)" ::: "memory");
;     __syncthreads();
;     if (kt + 1 < nk) GM_STAGE(kt + 1, buf ^ 1);
;     const unsigned char* A = smem + buf * 32768 + (wr * 64 + li) * 128;
;     const unsigned char* B = smem + buf * 32768 + 16384 + (wc * 64 + li) * 128;
; #pragma unroll
;     for (int ks = 0; ks < 2; ++ks) {
;       const int po = (px ^ (ks * 4)) * 16;
;       bf16x8 af[4], bfr[4];
; #pragma unroll
;       for (int i = 0; i < 4; ++i) {
;         af[i] = *(const bf16x8*)(A + i * 2048 + po);
;         bfr[i] = *(const bf16x8*)(B + i * 2048 + po);
;       }
; #pragma unroll
;       for (int mi = 0; mi < 4; ++mi)
; #pragma unroll
;         for (int ni = 0; ni < 4; ++ni)
;           acc[mi][ni] = SWAP ? mfma16(bfr[ni], af[mi], acc[mi][ni]) : mfma16(af[mi], bfr[ni], acc[mi][ni]);
	v_mfma_f32_16x16x32_bf16 v[48:51], v[144:147], v[8:11], v[56:59]
	s_nop 2
	v_lshl_add_u64 v[56:57], v[64:65], 0, s[40:41]
	global_load_lds_dwordx4 v[56:57], off
	v_lshl_add_u64 v[56:57], v[68:69], 0, s[40:41]
	s_mov_b32 m0, s30
	v_mfma_f32_16x16x32_bf16 v[166:169], v[24:27], v[0:3], v[36:39]
	global_load_lds_dwordx4 v[56:57], off
	v_lshl_add_u64 v[56:57], v[70:71], 0, s[40:41]
	s_mov_b32 m0, s31
	s_mov_b64 s[30:31], 0x4100
	global_load_lds_dwordx4 v[56:57], off
	v_lshl_add_u64 v[56:57], v[72:73], 0, s[40:41]
	s_mov_b32 m0, s34
	v_mfma_f32_16x16x32_bf16 v[44:47], v[144:147], v[0:3], v[40:43]
	global_load_lds_dwordx4 v[56:57], off
	v_lshl_add_u64 v[56:57], v[66:67], 0, s[40:41]
	s_mov_b32 m0, s35
	v_mfma_f32_16x16x32_bf16 v[28:31], v[162:165], v[0:3], v[4:7]
	global_load_lds_dwordx4 v[56:57], off
	v_lshl_add_u64 v[56:57], v[66:67], 0, s[30:31]
	s_mov_b32 m0, s36
	s_mov_b64 s[30:31], 0x8100
	global_load_lds_dwordx4 v[56:57], off
	v_lshl_add_u64 v[56:57], v[66:67], 0, s[30:31]
	s_mov_b32 m0, s37
	s_mov_b64 s[30:31], 0xc100
	global_load_lds_dwordx4 v[56:57], off
	v_lshl_add_u64 v[56:57], v[66:67], 0, s[30:31]
	s_mov_b32 m0, s38
	v_mfma_f32_16x16x32_bf16 v[52:55], v[24:27], v[8:11], v[52:55]
	global_load_lds_dwordx4 v[56:57], off
	s_mov_b64 s[30:31], 0x180
	v_mfma_f32_16x16x32_bf16 v[32:35], v[152:155], v[8:11], v[60:63]
	v_lshl_add_u64 v[64:65], v[64:65], 0, s[30:31]
	s_mov_b32 m0, s0
	v_mfma_f32_16x16x32_bf16 v[36:39], v[162:165], v[8:11], v[12:15]
	v_mfma_f32_16x16x32_bf16 v[8:11], v[24:27], v[148:151], v[112:115]
	v_mfma_f32_16x16x32_bf16 v[40:43], v[144:147], v[148:151], v[116:119]
	v_mfma_f32_16x16x32_bf16 v[16:19], v[152:155], v[148:151], v[120:123]
	v_mfma_f32_16x16x32_bf16 v[24:27], v[24:27], v[156:159], v[124:127]
	v_mfma_f32_16x16x32_bf16 v[12:15], v[144:147], v[156:159], v[132:135]
	v_mfma_f32_16x16x32_bf16 v[0:3], v[152:155], v[156:159], v[136:139]
	ds_read_b128 v[56:59], v109 offset:32768
	ds_read_b128 v[60:63], v111 offset:49152
	ds_read_b128 v[112:115], v109 offset:34816
	ds_read_b128 v[116:119], v111 offset:51200
	ds_read_b128 v[120:123], v109 offset:36864
	ds_read_b128 v[124:127], v111 offset:53248
	ds_read_b128 v[132:135], v109 offset:38912
	ds_read_b128 v[136:139], v111 offset:55296
	v_mfma_f32_16x16x32_bf16 v[20:23], v[162:165], v[148:151], v[20:23]
	v_mfma_f32_16x16x32_bf16 v[4:7], v[162:165], v[156:159], v[140:143]
	s_waitcnt lgkmcnt(0)
	v_mfma_f32_16x16x32_bf16 v[140:143], v[60:63], v[56:59], v[166:169]
	v_mfma_f32_16x16x32_bf16 v[44:47], v[116:119], v[56:59], v[44:47]
	v_mfma_f32_16x16x32_bf16 v[144:147], v[124:127], v[56:59], v[170:173]
	v_mfma_f32_16x16x32_bf16 v[28:31], v[136:139], v[56:59], v[28:31]
	v_mfma_f32_16x16x32_bf16 v[52:55], v[60:63], v[112:115], v[52:55]
	v_mfma_f32_16x16x32_bf16 v[56:59], v[116:119], v[112:115], v[48:51]
	v_mfma_f32_16x16x32_bf16 v[148:151], v[124:127], v[112:115], v[32:35]
	v_mfma_f32_16x16x32_bf16 v[112:115], v[136:139], v[112:115], v[36:39]
	v_mfma_f32_16x16x32_bf16 v[8:11], v[60:63], v[120:123], v[8:11]
	v_mfma_f32_16x16x32_bf16 v[152:155], v[116:119], v[120:123], v[40:43]
	v_mfma_f32_16x16x32_bf16 v[16:19], v[124:127], v[120:123], v[16:19]
	v_mfma_f32_16x16x32_bf16 v[120:123], v[136:139], v[120:123], v[20:23]
	v_mfma_f32_16x16x32_bf16 v[156:159], v[60:63], v[132:135], v[24:27]
	v_mfma_f32_16x16x32_bf16 v[116:119], v[116:119], v[132:135], v[12:15]
	v_mfma_f32_16x16x32_bf16 v[124:127], v[124:127], v[132:135], v[0:3]
	v_mfma_f32_16x16x32_bf16 v[132:135], v[136:139], v[132:135], v[4:7]
	s_nop 1
	ds_read_b128 v[0:3], v108 offset:32768
	ds_read_b128 v[136:139], v110 offset:49152
	ds_read_b128 v[4:7], v108 offset:34816
	ds_read_b128 v[162:165], v110 offset:51200
	ds_read_b128 v[166:169], v108 offset:36864
	ds_read_b128 v[170:173], v110 offset:53248
	ds_read_b128 v[174:177], v108 offset:38912
	ds_read_b128 v[178:181], v110 offset:55296
	s_waitcnt vmcnt(0)
	s_waitcnt vmcnt(0) lgkmcnt(0)
	s_barrier
	global_load_lds_dwordx4 v[64:65], off
	v_lshl_add_u64 v[64:65], v[68:69], 0, s[30:31]
	s_mov_b32 m0, s1
	s_mov_b64 s[0:1], 0x4180
	global_load_lds_dwordx4 v[64:65], off
	v_lshl_add_u64 v[64:65], v[70:71], 0, s[30:31]
	s_mov_b32 m0, s9
	v_mfma_f32_16x16x32_bf16 v[60:63], v[136:139], v[0:3], v[140:143]
	global_load_lds_dwordx4 v[64:65], off
	v_lshl_add_u64 v[64:65], v[72:73], 0, s[30:31]
	s_mov_b32 m0, s24
	v_mfma_f32_16x16x32_bf16 v[44:47], v[162:165], v[0:3], v[44:47]
	global_load_lds_dwordx4 v[64:65], off
	v_lshl_add_u64 v[64:65], v[66:67], 0, s[30:31]
	s_mov_b32 m0, s25
	v_mfma_f32_16x16x32_bf16 v[32:35], v[170:173], v[0:3], v[144:147]
	global_load_lds_dwordx4 v[64:65], off
	v_lshl_add_u64 v[64:65], v[66:67], 0, s[0:1]
	s_mov_b32 m0, s26
	s_mov_b64 s[0:1], 0x8180
	global_load_lds_dwordx4 v[64:65], off
	v_lshl_add_u64 v[64:65], v[66:67], 0, s[0:1]
	s_mov_b32 m0, s27
	s_mov_b64 s[0:1], 0xc180
	global_load_lds_dwordx4 v[64:65], off
	v_lshl_add_u64 v[64:65], v[66:67], 0, s[0:1]
	s_mov_b32 m0, s28
	v_mfma_f32_16x16x32_bf16 v[24:27], v[178:181], v[0:3], v[28:31]
	global_load_lds_dwordx4 v[64:65], off
	v_mfma_f32_16x16x32_bf16 v[48:51], v[136:139], v[4:7], v[52:55]
	v_mfma_f32_16x16x32_bf16 v[28:31], v[162:165], v[4:7], v[56:59]
	v_mfma_f32_16x16x32_bf16 v[36:39], v[170:173], v[4:7], v[148:151]
	v_mfma_f32_16x16x32_bf16 v[40:43], v[178:181], v[4:7], v[112:115]
	v_mfma_f32_16x16x32_bf16 v[20:23], v[136:139], v[166:169], v[8:11]
	v_mfma_f32_16x16x32_bf16 v[0:3], v[170:173], v[166:169], v[16:19]
	v_mfma_f32_16x16x32_bf16 v[4:7], v[178:181], v[166:169], v[120:123]
	v_mfma_f32_16x16x32_bf16 v[8:11], v[136:139], v[174:177], v[156:159]
	v_mfma_f32_16x16x32_bf16 v[16:19], v[162:165], v[174:177], v[116:119]
	v_mfma_f32_16x16x32_bf16 v[52:55], v[170:173], v[174:177], v[124:127]
	v_mfma_f32_16x16x32_bf16 v[56:59], v[178:181], v[174:177], v[132:135]
	ds_read_b128 v[64:67], v109
	ds_read_b128 v[68:71], v111 offset:16384
	ds_read_b128 v[112:115], v109 offset:2048
	ds_read_b128 v[116:119], v111 offset:18432
	ds_read_b128 v[120:123], v109 offset:4096
	ds_read_b128 v[124:127], v111 offset:20480
	ds_read_b128 v[132:135], v109 offset:6144
	ds_read_b128 v[136:139], v111 offset:22528
	v_mfma_f32_16x16x32_bf16 v[12:15], v[162:165], v[166:169], v[152:155]
	s_waitcnt lgkmcnt(0)
; DEVI f32x4 mfma16(bf16x8 a, bf16x8 b, f32x4 c) { return __builtin_amdgcn_mfma_f32_16x16x32_bf16(a, b, c, 0, 0, 0); }
; template <bool SWAP, class RP>
; DEVI void gemm_main(const int TIDX, const int BIDX, const int GDIM, f32x4 (&acc)[4][4], RP rowoff, const bf16_t* __restrict__ Bt, int ldb, int K, unsigned char* smem) {
;     ...
;   for (int kt = 0; kt < nk; ++kt) {
;     const int buf = kt & 1;
;     asm volatile("s_waitcnt vmcnt(0)" ::: "memory");
;     __syncthreads();
;     if (kt + 1 < nk) GM_STAGE(kt + 1, buf ^ 1);
;     const unsigned char* A = smem + buf * 32768 + (wr * 64 + li) * 128;
;     const unsigned char* B = smem + buf * 32768 + 16384 + (wc * 64 + li) * 128;
; #pragma unroll
;     for (int ks = 0; ks < 2; ++ks) {
;       const int po = (px ^ (ks * 4)) * 16;
;       bf16x8 af[4], bfr[4];
; #pragma unroll
;       for (int i = 0; i < 4; ++i) {
;         af[i] = *(const bf16x8*)(A + i * 2048 + po);
;         bfr[i] = *(const bf16x8*)(B + i * 2048 + po);
;       }
; #pragma unroll
;       for (int mi = 0; mi < 4; ++mi)
; #pragma unroll
;         for (int ni = 0; ni < 4; ++ni)
;           acc[mi][ni] = SWAP ? mfma16(bfr[ni], af[mi], acc[mi][ni]) : mfma16(af[mi], bfr[ni], acc[mi][ni]);
;     }
;   }
;   __syncthreads();
	v_mfma_f32_16x16x32_bf16 v[60:63], v[68:71], v[64:67], v[60:63]
	v_mfma_f32_16x16x32_bf16 v[44:47], v[116:119], v[64:67], v[44:47]
	v_mfma_f32_16x16x32_bf16 v[32:35], v[124:127], v[64:67], v[32:35]
	v_mfma_f32_16x16x32_bf16 v[24:27], v[136:139], v[64:67], v[24:27]
	v_mfma_f32_16x16x32_bf16 v[48:51], v[68:71], v[112:115], v[48:51]
	v_mfma_f32_16x16x32_bf16 v[28:31], v[116:119], v[112:115], v[28:31]
	v_mfma_f32_16x16x32_bf16 v[36:39], v[124:127], v[112:115], v[36:39]
	v_mfma_f32_16x16x32_bf16 v[40:43], v[136:139], v[112:115], v[40:43]
	v_mfma_f32_16x16x32_bf16 v[20:23], v[68:71], v[120:123], v[20:23]
	v_mfma_f32_16x16x32_bf16 v[12:15], v[116:119], v[120:123], v[12:15]
	v_mfma_f32_16x16x32_bf16 v[0:3], v[124:127], v[120:123], v[0:3]
	v_mfma_f32_16x16x32_bf16 v[4:7], v[136:139], v[120:123], v[4:7]
	v_mfma_f32_16x16x32_bf16 v[8:11], v[68:71], v[132:135], v[8:11]
	v_mfma_f32_16x16x32_bf16 v[16:19], v[116:119], v[132:135], v[16:19]
	v_mfma_f32_16x16x32_bf16 v[52:55], v[124:127], v[132:135], v[52:55]
	v_mfma_f32_16x16x32_bf16 v[56:59], v[136:139], v[132:135], v[56:59]
	ds_read_b128 v[64:67], v108
	ds_read_b128 v[68:71], v110 offset:16384
	ds_read_b128 v[112:115], v108 offset:2048
	ds_read_b128 v[116:119], v110 offset:18432
	ds_read_b128 v[120:123], v108 offset:4096
	ds_read_b128 v[124:127], v110 offset:20480
	ds_read_b128 v[132:135], v108 offset:6144
	ds_read_b128 v[136:139], v110 offset:22528
	s_waitcnt vmcnt(0)
	s_waitcnt vmcnt(0) lgkmcnt(0)
	v_mfma_f32_16x16x32_bf16 v[60:63], v[68:71], v[64:67], v[60:63]
	s_barrier
	v_mfma_f32_16x16x32_bf16 v[44:47], v[116:119], v[64:67], v[44:47]
	v_mfma_f32_16x16x32_bf16 v[32:35], v[124:127], v[64:67], v[32:35]
	v_mfma_f32_16x16x32_bf16 v[24:27], v[136:139], v[64:67], v[24:27]
	v_mfma_f32_16x16x32_bf16 v[48:51], v[68:71], v[112:115], v[48:51]
	v_mfma_f32_16x16x32_bf16 v[28:31], v[116:119], v[112:115], v[28:31]
	v_mfma_f32_16x16x32_bf16 v[36:39], v[124:127], v[112:115], v[36:39]
	v_mfma_f32_16x16x32_bf16 v[40:43], v[136:139], v[112:115], v[40:43]
	v_mfma_f32_16x16x32_bf16 v[20:23], v[68:71], v[120:123], v[20:23]
	v_mfma_f32_16x16x32_bf16 v[12:15], v[116:119], v[120:123], v[12:15]
	v_mfma_f32_16x16x32_bf16 v[0:3], v[124:127], v[120:123], v[0:3]
	v_mfma_f32_16x16x32_bf16 v[4:7], v[136:139], v[120:123], v[4:7]
	v_mfma_f32_16x16x32_bf16 v[8:11], v[68:71], v[132:135], v[8:11]
	v_mfma_f32_16x16x32_bf16 v[16:19], v[116:119], v[132:135], v[16:19]
	v_mfma_f32_16x16x32_bf16 v[52:55], v[124:127], v[132:135], v[52:55]
	v_mfma_f32_16x16x32_bf16 v[56:59], v[136:139], v[132:135], v[56:59]
	ds_read_b128 v[64:67], v109 offset:32768
	ds_read_b128 v[68:71], v111 offset:49152
	ds_read_b128 v[112:115], v109 offset:34816
	ds_read_b128 v[116:119], v111 offset:51200
	ds_read_b128 v[120:123], v109 offset:36864
	ds_read_b128 v[124:127], v111 offset:53248
	ds_read_b128 v[132:135], v109 offset:38912
	ds_read_b128 v[136:139], v111 offset:55296
	s_waitcnt lgkmcnt(6)
	v_mfma_f32_16x16x32_bf16 v[60:63], v[68:71], v[64:67], v[60:63]
	s_waitcnt lgkmcnt(4)
	v_mfma_f32_16x16x32_bf16 v[44:47], v[116:119], v[64:67], v[44:47]
	s_waitcnt lgkmcnt(2)
	v_mfma_f32_16x16x32_bf16 v[32:35], v[124:127], v[64:67], v[32:35]
	s_waitcnt lgkmcnt(0)
	v_mfma_f32_16x16x32_bf16 v[24:27], v[136:139], v[64:67], v[24:27]
	v_mfma_f32_16x16x32_bf16 v[48:51], v[68:71], v[112:115], v[48:51]
	v_mfma_f32_16x16x32_bf16 v[28:31], v[116:119], v[112:115], v[28:31]
	v_mfma_f32_16x16x32_bf16 v[36:39], v[124:127], v[112:115], v[36:39]
	v_mfma_f32_16x16x32_bf16 v[40:43], v[136:139], v[112:115], v[40:43]
	v_mfma_f32_16x16x32_bf16 v[20:23], v[68:71], v[120:123], v[20:23]
	v_mfma_f32_16x16x32_bf16 v[12:15], v[116:119], v[120:123], v[12:15]
	v_mfma_f32_16x16x32_bf16 v[0:3], v[124:127], v[120:123], v[0:3]
	v_mfma_f32_16x16x32_bf16 v[4:7], v[136:139], v[120:123], v[4:7]
	v_mfma_f32_16x16x32_bf16 v[8:11], v[68:71], v[132:135], v[8:11]
	v_mfma_f32_16x16x32_bf16 v[64:67], v[116:119], v[132:135], v[16:19]
	v_mfma_f32_16x16x32_bf16 v[52:55], v[124:127], v[132:135], v[52:55]
	v_mfma_f32_16x16x32_bf16 v[56:59], v[136:139], v[132:135], v[56:59]
	s_nop 0
	ds_read_b128 v[16:19], v108 offset:32768
	ds_read_b128 v[68:71], v110 offset:49152
	ds_read_b128 v[112:115], v108 offset:34816
	ds_read_b128 v[116:119], v110 offset:51200
	ds_read_b128 v[120:123], v108 offset:36864
	ds_read_b128 v[124:127], v110 offset:53248
	ds_read_b128 v[132:135], v108 offset:38912
	ds_read_b128 v[108:111], v110 offset:55296
	s_waitcnt lgkmcnt(0)
	s_barrier
; DEVI uint32_t pack2(float lo, float hi) { f32x2_t v = {lo, hi}; bf16x2_t b = __builtin_convertvector(v, bf16x2_t); return __builtin_bit_cast(uint32_t, b); }
; DEVI float lo2f(uint32_t u) { return __uint_as_float(u << 16); }
; DEVI float hi2f(uint32_t u) { return __uint_as_float(u & 0xffff0000u); }
; #define EPI_END } __builtin_amdgcn_sched_barrier(0); } }
; DEVI void phase_p8(const int TIDX, const int BIDX, const int GDIM, KAP KA, unsigned char* WSB, float* OUTB, int l, unsigned char* smem) {
;     ...
;       EPI_SWAP_BEGIN(m0, n0)
;         const f32x4 a = acc[mi][ni];
;         const uint2 g = gp[mi][ni];
;         *(uint2*)((bf16_t*)PRE + (size_t)row * 1024 + col) = make_uint2(pack2(a[0] * lo2f(g.x), a[1] * hi2f(g.x)), pack2(a[2] * lo2f(g.y), a[3] * hi2f(g.y)));
;       EPI_END
	v_mfma_f32_16x16x32_bf16 v[60:63], v[68:71], v[16:19], v[60:63]
	v_mfma_f32_16x16x32_bf16 v[140:143], v[116:119], v[112:115], v[28:31]
	v_mfma_f32_16x16x32_bf16 v[28:31], v[68:71], v[120:123], v[20:23]
	v_mfma_f32_16x16x32_bf16 v[20:23], v[124:127], v[120:123], v[0:3]
	v_mfma_f32_16x16x32_bf16 v[0:3], v[124:127], v[132:135], v[52:55]
	s_nop 2
	v_add_u32_e32 v52, s8, v74
	v_ashrrev_i32_e32 v53, 31, v52
	v_mfma_f32_16x16x32_bf16 v[44:47], v[116:119], v[16:19], v[44:47]
	v_lshlrev_b64 v[54:55], 11, v[52:53]
	v_lshl_add_u64 v[54:55], s[6:7], 0, v[54:55]
	v_mfma_f32_16x16x32_bf16 v[32:35], v[124:127], v[16:19], v[32:35]
	v_mfma_f32_16x16x32_bf16 v[136:139], v[108:111], v[16:19], v[24:27]
	v_mfma_f32_16x16x32_bf16 v[24:27], v[116:119], v[120:123], v[12:15]
	v_mfma_f32_16x16x32_bf16 v[16:19], v[108:111], v[120:123], v[4:7]
	v_mfma_f32_16x16x32_bf16 v[12:15], v[68:71], v[132:135], v[8:11]
	v_mfma_f32_16x16x32_bf16 v[8:11], v[116:119], v[132:135], v[64:67]
	v_mfma_f32_16x16x32_bf16 v[4:7], v[108:111], v[132:135], v[56:59]
	s_nop 1
	v_or_b32_e32 v64, s23, v75
	v_lshlrev_b32_e32 v128, 1, v64
	v_lshl_add_u64 v[54:55], v[54:55], 0, v[128:129]
	v_lshlrev_b32_e32 v56, 16, v76
	v_and_b32_e32 v57, 0xffff0000, v76
	v_lshlrev_b32_e32 v58, 16, v77
	v_and_b32_e32 v59, 0xffff0000, v77
	v_pk_mul_f32 v[56:57], v[60:61], v[56:57]
	v_pk_mul_f32 v[58:59], v[62:63], v[58:59]
	v_cvt_pk_bf16_f32 v56, v56, v57
	v_cvt_pk_bf16_f32 v57, v58, v59
	global_store_dwordx2 v[54:55], v[56:57], off
	v_lshlrev_b32_e32 v56, 16, v78
	v_and_b32_e32 v57, 0xffff0000, v78
	v_pk_mul_f32 v[44:45], v[44:45], v[56:57]
	v_lshlrev_b32_e32 v56, 16, v79
	v_and_b32_e32 v57, 0xffff0000, v79
	v_pk_mul_f32 v[46:47], v[46:47], v[56:57]
	v_cvt_pk_bf16_f32 v44, v44, v45
	v_cvt_pk_bf16_f32 v45, v46, v47
	global_store_dwordx2 v[54:55], v[44:45], off offset:32
	v_lshlrev_b32_e32 v44, 16, v80
	v_and_b32_e32 v45, 0xffff0000, v80
	v_pk_mul_f32 v[32:33], v[32:33], v[44:45]
	v_lshlrev_b32_e32 v44, 16, v81
	v_and_b32_e32 v45, 0xffff0000, v81
	v_pk_mul_f32 v[34:35], v[34:35], v[44:45]
	v_cvt_pk_bf16_f32 v32, v32, v33
	v_cvt_pk_bf16_f32 v33, v34, v35
	global_store_dwordx2 v[54:55], v[32:33], off offset:64
	v_lshlrev_b32_e32 v32, 16, v82
	v_and_b32_e32 v33, 0xffff0000, v82
	v_lshlrev_b32_e32 v34, 16, v83
	v_and_b32_e32 v35, 0xffff0000, v83
	v_pk_mul_f32 v[32:33], v[136:137], v[32:33]
	v_pk_mul_f32 v[34:35], v[138:139], v[34:35]
	v_cvt_pk_bf16_f32 v32, v32, v33
	v_cvt_pk_bf16_f32 v33, v34, v35
	v_mfma_f32_16x16x32_bf16 v[48:51], v[68:71], v[112:115], v[48:51]
	global_store_dwordx2 v[54:55], v[32:33], off offset:96
	v_mfma_f32_16x16x32_bf16 v[36:39], v[124:127], v[112:115], v[36:39]
	v_mfma_f32_16x16x32_bf16 v[40:43], v[108:111], v[112:115], v[40:43]
	v_or_b32_e32 v32, 16, v52
	v_ashrrev_i32_e32 v33, 31, v32
	v_lshlrev_b64 v[32:33], 11, v[32:33]
	v_lshlrev_b32_e32 v34, 16, v84
	v_and_b32_e32 v35, 0xffff0000, v84
	v_lshlrev_b32_e32 v44, 16, v85
	v_and_b32_e32 v45, 0xffff0000, v85
	v_lshl_add_u64 v[32:33], s[6:7], 0, v[32:33]
	v_pk_mul_f32 v[34:35], v[48:49], v[34:35]
	v_pk_mul_f32 v[44:45], v[50:51], v[44:45]
	v_cvt_pk_bf16_f32 v34, v34, v35
	v_cvt_pk_bf16_f32 v35, v44, v45
	v_lshl_add_u64 v[32:33], v[32:33], 0, v[128:129]
	global_store_dwordx2 v[32:33], v[34:35], off
	v_lshlrev_b32_e32 v34, 16, v86
	v_and_b32_e32 v35, 0xffff0000, v86
	v_lshlrev_b32_e32 v44, 16, v87
	v_and_b32_e32 v45, 0xffff0000, v87
	v_pk_mul_f32 v[34:35], v[140:141], v[34:35]
	v_pk_mul_f32 v[44:45], v[142:143], v[44:45]
	v_cvt_pk_bf16_f32 v34, v34, v35
	v_cvt_pk_bf16_f32 v35, v44, v45
	global_store_dwordx2 v[32:33], v[34:35], off offset:32
	v_lshlrev_b32_e32 v34, 16, v88
	v_and_b32_e32 v35, 0xffff0000, v88
	v_pk_mul_f32 v[34:35], v[36:37], v[34:35]
	v_lshlrev_b32_e32 v36, 16, v89
; DEVI uint32_t pack2(float lo, float hi) { f32x2_t v = {lo, hi}; bf16x2_t b = __builtin_convertvector(v, bf16x2_t); return __builtin_bit_cast(uint32_t, b); }
; DEVI float lo2f(uint32_t u) { return __uint_as_float(u << 16); }
; DEVI float hi2f(uint32_t u) { return __uint_as_float(u & 0xffff0000u); }
; DEVI float sigmoidf_(float x) { return 1.f / (1.f + __expf(-x)); }
; #define EPI_END } __builtin_amdgcn_sched_barrier(0); } }
; DEVI void phase_p8(const int TIDX, const int BIDX, const int GDIM, KAP KA, unsigned char* WSB, float* OUTB, int l, unsigned char* smem) {
;     ...
;     for (int item = (BIDX & 7) * (GDIM >> 3) + (BIDX >> 3); item < 516 * 8; item += GDIM) {
;       const int mt = item >> 3, nt = item & 7, m0 = mt * 128, n0 = nt * 128;
;       f32x4 acc[4][4];
;       uint2 gp[4][4];
;       zero_acc(acc);
;       RowLin rx{(const unsigned char*)(XB + (size_t)m0 * 1024), 2048};
;       gemm_main<true>(TIDX, BIDX, GDIM, acc, rx, W + WO_PG + (size_t)n0 * 1024, 1024, 1024, smem);
; #pragma unroll
;       for (int i = 0; i < 4; ++i)
; #pragma unroll
;         for (int j = 0; j < 4; ++j) gp[i][j] = make_uint2(pack2(sigmoidf_(acc[i][j][0]), sigmoidf_(acc[i][j][1])), pack2(sigmoidf_(acc[i][j][2]), sigmoidf_(acc[i][j][3])));
;       zero_acc(acc);
;       RowLin rpl{(const unsigned char*)((const bf16_t*)(WSB + O_YM) + (size_t)m0 * 256), 512};
;       gemm_main<true>(TIDX, BIDX, GDIM, acc, rpl, W + WO_PLE + (size_t)n0 * 256, 256, 256, smem);
;       EPI_SWAP_BEGIN(m0, n0)
;         const f32x4 a = acc[mi][ni];
;         const uint2 g = gp[mi][ni];
;         *(uint2*)((bf16_t*)PRE + (size_t)row * 1024 + col) = make_uint2(pack2(a[0] * lo2f(g.x), a[1] * hi2f(g.x)), pack2(a[2] * lo2f(g.y), a[3] * hi2f(g.y)));
;       EPI_END
;     }
	v_and_b32_e32 v37, 0xffff0000, v89
	v_pk_mul_f32 v[36:37], v[38:39], v[36:37]
	v_cvt_pk_bf16_f32 v34, v34, v35
	v_cvt_pk_bf16_f32 v35, v36, v37
	global_store_dwordx2 v[32:33], v[34:35], off offset:64
	v_lshlrev_b32_e32 v34, 16, v90
	v_and_b32_e32 v35, 0xffff0000, v90
	v_lshlrev_b32_e32 v36, 16, v91
	v_and_b32_e32 v37, 0xffff0000, v91
	v_pk_mul_f32 v[34:35], v[40:41], v[34:35]
	v_pk_mul_f32 v[36:37], v[42:43], v[36:37]
	v_cvt_pk_bf16_f32 v34, v34, v35
	v_cvt_pk_bf16_f32 v35, v36, v37
	global_store_dwordx2 v[32:33], v[34:35], off offset:96
	v_or_b32_e32 v32, 32, v52
	v_ashrrev_i32_e32 v33, 31, v32
	v_lshlrev_b32_e32 v34, 16, v92
	v_and_b32_e32 v35, 0xffff0000, v92
	v_lshlrev_b64 v[32:33], 11, v[32:33]
	v_pk_mul_f32 v[28:29], v[28:29], v[34:35]
	v_lshlrev_b32_e32 v34, 16, v93
	v_and_b32_e32 v35, 0xffff0000, v93
	v_lshl_add_u64 v[32:33], s[6:7], 0, v[32:33]
	v_pk_mul_f32 v[30:31], v[30:31], v[34:35]
	v_cvt_pk_bf16_f32 v28, v28, v29
	v_cvt_pk_bf16_f32 v29, v30, v31
	v_lshl_add_u64 v[30:31], v[32:33], 0, v[128:129]
	global_store_dwordx2 v[30:31], v[28:29], off
	v_lshlrev_b32_e32 v28, 16, v94
	v_and_b32_e32 v29, 0xffff0000, v94
	v_pk_mul_f32 v[24:25], v[24:25], v[28:29]
	v_lshlrev_b32_e32 v28, 16, v95
	v_and_b32_e32 v29, 0xffff0000, v95
	v_pk_mul_f32 v[26:27], v[26:27], v[28:29]
	v_cvt_pk_bf16_f32 v24, v24, v25
	v_cvt_pk_bf16_f32 v25, v26, v27
	global_store_dwordx2 v[30:31], v[24:25], off offset:32
	v_lshlrev_b32_e32 v24, 16, v96
	v_and_b32_e32 v25, 0xffff0000, v96
	v_pk_mul_f32 v[20:21], v[20:21], v[24:25]
	v_lshlrev_b32_e32 v24, 16, v97
	v_and_b32_e32 v25, 0xffff0000, v97
	v_pk_mul_f32 v[22:23], v[22:23], v[24:25]
	v_cvt_pk_bf16_f32 v20, v20, v21
	v_cvt_pk_bf16_f32 v21, v22, v23
	global_store_dwordx2 v[30:31], v[20:21], off offset:64
	v_lshlrev_b32_e32 v20, 16, v98
	v_and_b32_e32 v21, 0xffff0000, v98
	v_pk_mul_f32 v[16:17], v[16:17], v[20:21]
	v_lshlrev_b32_e32 v20, 16, v99
	v_and_b32_e32 v21, 0xffff0000, v99
	v_pk_mul_f32 v[18:19], v[18:19], v[20:21]
	v_cvt_pk_bf16_f32 v16, v16, v17
	v_cvt_pk_bf16_f32 v17, v18, v19
	global_store_dwordx2 v[30:31], v[16:17], off offset:96
	v_or_b32_e32 v16, 48, v52
	v_ashrrev_i32_e32 v17, 31, v16
	v_lshlrev_b32_e32 v18, 16, v100
	v_and_b32_e32 v19, 0xffff0000, v100
	v_lshlrev_b64 v[16:17], 11, v[16:17]
	v_pk_mul_f32 v[12:13], v[12:13], v[18:19]
	v_lshlrev_b32_e32 v18, 16, v101
	v_and_b32_e32 v19, 0xffff0000, v101
	v_lshl_add_u64 v[16:17], s[6:7], 0, v[16:17]
	v_pk_mul_f32 v[14:15], v[14:15], v[18:19]
	v_cvt_pk_bf16_f32 v12, v12, v13
	v_cvt_pk_bf16_f32 v13, v14, v15
	v_lshl_add_u64 v[14:15], v[16:17], 0, v[128:129]
	global_store_dwordx2 v[14:15], v[12:13], off
	v_lshlrev_b32_e32 v12, 16, v102
	v_and_b32_e32 v13, 0xffff0000, v102
	v_pk_mul_f32 v[8:9], v[8:9], v[12:13]
	v_lshlrev_b32_e32 v12, 16, v103
	v_and_b32_e32 v13, 0xffff0000, v103
	v_pk_mul_f32 v[10:11], v[10:11], v[12:13]
	v_cvt_pk_bf16_f32 v8, v8, v9
	v_cvt_pk_bf16_f32 v9, v10, v11
	global_store_dwordx2 v[14:15], v[8:9], off offset:32
	v_lshlrev_b32_e32 v8, 16, v104
	v_and_b32_e32 v9, 0xffff0000, v104
	v_pk_mul_f32 v[0:1], v[0:1], v[8:9]
	v_lshlrev_b32_e32 v8, 16, v105
	v_and_b32_e32 v9, 0xffff0000, v105
	v_pk_mul_f32 v[2:3], v[2:3], v[8:9]
	v_cvt_pk_bf16_f32 v0, v0, v1
	v_cvt_pk_bf16_f32 v1, v2, v3
	global_store_dwordx2 v[14:15], v[0:1], off offset:64
	v_lshlrev_b32_e32 v0, 16, v106
	v_and_b32_e32 v1, 0xffff0000, v106
	v_lshlrev_b32_e32 v2, 16, v107
	v_and_b32_e32 v3, 0xffff0000, v107
	v_pk_mul_f32 v[0:1], v[4:5], v[0:1]
	v_pk_mul_f32 v[2:3], v[6:7], v[2:3]
	v_cvt_pk_bf16_f32 v0, v0, v1
	v_cvt_pk_bf16_f32 v1, v2, v3
	global_store_dwordx2 v[14:15], v[0:1], off offset:96
	s_add_i32 s2, s2, s84
	s_add_i32 s19, s19, s20
	s_add_i32 s21, s21, s22
	s_cmpk_gt_i32 s2, 0x101f
	s_cbranch_scc0 .LBB0_61

; DEVI f32x4 mfma16(bf16x8 a, bf16x8 b, f32x4 c) { return __builtin_amdgcn_mfma_f32_16x16x32_bf16(a, b, c, 0, 0, 0); }
; template <bool SWAP, class RP>
; DEVI void gemm_main(const int TIDX, const int BIDX, const int GDIM, f32x4 (&acc)[4][4], RP rowoff, const bf16_t* __restrict__ Bt, int ldb, int K, unsigned char* smem) {
;     ...
;   for (int kt = 0; kt < nk; ++kt) {
;     const int buf = kt & 1;
;     asm volatile("s_waitcnt vmcnt(0)" ::: "memory");
;     __syncthreads();
;     if (kt + 1 < nk) GM_STAGE(kt + 1, buf ^ 1);
;     const unsigned char* A = smem + buf * 32768 + (wr * 64 + li) * 128;
;     const unsigned char* B = smem + buf * 32768 + 16384 + (wc * 64 + li) * 128;
; #pragma unroll
;     for (int ks = 0; ks < 2; ++ks) {
;       const int po = (px ^ (ks * 4)) * 16;
;       bf16x8 af[4], bfr[4];
; #pragma unroll
;       for (int i = 0; i < 4; ++i) {
;         af[i] = *(const bf16x8*)(A + i * 2048 + po);
;         bfr[i] = *(const bf16x8*)(B + i * 2048 + po);
;       }
; #pragma unroll
;       for (int mi = 0; mi < 4; ++mi)
; #pragma unroll
;         for (int ni = 0; ni < 4; ++ni)
;           acc[mi][ni] = SWAP ? mfma16(bfr[ni], af[mi], acc[mi][ni]) : mfma16(af[mi], bfr[ni], acc[mi][ni]);
.LBB0_105:
	s_and_b32 s5, s26, 0x8000
	s_xor_b32 s27, s5, 0x8000
	v_add_u32_e32 v194, s27, v84
	v_add_u32_e32 v204, s5, v65
	v_or_b32_e32 v205, s5, v86
	v_add_u32_e32 v205, v205, v87
	v_add_u32_e32 v231, v204, v85
	v_add_u32_e32 v232, v205, v85
	v_readfirstlane_b32 s101, v194
	v_add_u32_e32 v204, v204, v83
	v_add_u32_e32 v205, v205, v83
	s_waitcnt vmcnt(0)
	s_barrier
	ds_read_b128 v[88:91], v231
	ds_read_b128 v[104:107], v232 offset:16384
	ds_read_b128 v[108:111], v232 offset:18432
	ds_read_b128 v[112:115], v232 offset:20480
	ds_read_b128 v[116:119], v232 offset:22528
	ds_read_b128 v[92:95], v231 offset:2048
	ds_read_b128 v[96:99], v231 offset:4096
	ds_read_b128 v[100:103], v231 offset:6144
	ds_read_b128 v[190:193], v205 offset:16384
	ds_read_b128 v[196:199], v205 offset:18432
	ds_read_b128 v[200:203], v205 offset:20480
	ds_read_b128 v[208:211], v205 offset:22528
	s_mov_b32 m0, s101
	v_lshl_add_u64 v[120:121], v[66:67], 0, s[6:7]
	global_load_lds_dwordx4 v[120:121], off
	s_add_i32 m0, s101, 0x1000
	v_lshl_add_u64 v[120:121], v[68:69], 0, s[6:7]
	global_load_lds_dwordx4 v[120:121], off
	s_waitcnt lgkmcnt(7)
	v_mfma_f32_16x16x32_bf16 v[60:63], v[104:107], v[88:91], v[60:63]
	v_mfma_f32_16x16x32_bf16 v[56:59], v[108:111], v[88:91], v[56:59]
	s_add_i32 m0, s101, 0x2000
	v_lshl_add_u64 v[120:121], v[70:71], 0, s[6:7]
	global_load_lds_dwordx4 v[120:121], off
	v_mfma_f32_16x16x32_bf16 v[52:55], v[112:115], v[88:91], v[52:55]
	v_mfma_f32_16x16x32_bf16 v[48:51], v[116:119], v[88:91], v[48:51]
	ds_read_b128 v[88:91], v204
	s_add_i32 m0, s101, 0x3000
	v_lshl_add_u64 v[120:121], v[72:73], 0, s[6:7]
	global_load_lds_dwordx4 v[120:121], off
	s_waitcnt lgkmcnt(7)
	v_mfma_f32_16x16x32_bf16 v[44:47], v[104:107], v[92:95], v[44:47]
	v_mfma_f32_16x16x32_bf16 v[40:43], v[108:111], v[92:95], v[40:43]
	s_add_i32 m0, s101, 0x4000
	s_mov_b64 s[28:29], 0xc90080
	v_lshl_add_u64 v[120:121], v[74:75], 0, s[6:7]
	v_lshl_add_u64 v[120:121], v[120:121], 0, s[28:29]
	global_load_lds_dwordx4 v[120:121], off
	v_mfma_f32_16x16x32_bf16 v[36:39], v[112:115], v[92:95], v[36:39]
	v_mfma_f32_16x16x32_bf16 v[32:35], v[116:119], v[92:95], v[32:35]
	ds_read_b128 v[92:95], v204 offset:2048
	s_add_i32 m0, s101, 0x5000
	s_mov_b64 s[28:29], 0xca0080
	v_lshl_add_u64 v[120:121], v[74:75], 0, s[6:7]
	v_lshl_add_u64 v[120:121], v[120:121], 0, s[28:29]
	global_load_lds_dwordx4 v[120:121], off
	s_waitcnt lgkmcnt(7)
	v_mfma_f32_16x16x32_bf16 v[28:31], v[104:107], v[96:99], v[28:31]
	v_mfma_f32_16x16x32_bf16 v[24:27], v[108:111], v[96:99], v[24:27]
	s_add_i32 m0, s101, 0x6000
	s_mov_b64 s[28:29], 0xcb0080
	v_lshl_add_u64 v[120:121], v[74:75], 0, s[6:7]
	v_lshl_add_u64 v[120:121], v[120:121], 0, s[28:29]
	global_load_lds_dwordx4 v[120:121], off
	v_mfma_f32_16x16x32_bf16 v[20:23], v[112:115], v[96:99], v[20:23]
	v_mfma_f32_16x16x32_bf16 v[16:19], v[116:119], v[96:99], v[16:19]
	ds_read_b128 v[96:99], v204 offset:4096
	s_add_i32 m0, s101, 0x7000
	s_mov_b64 s[28:29], 0xcc0080
	v_lshl_add_u64 v[120:121], v[74:75], 0, s[6:7]
	v_lshl_add_u64 v[120:121], v[120:121], 0, s[28:29]
	global_load_lds_dwordx4 v[120:121], off
	s_waitcnt lgkmcnt(7)
	v_mfma_f32_16x16x32_bf16 v[12:15], v[104:107], v[100:103], v[12:15]
	v_mfma_f32_16x16x32_bf16 v[8:11], v[108:111], v[100:103], v[8:11]
	v_mfma_f32_16x16x32_bf16 v[4:7], v[112:115], v[100:103], v[4:7]
	v_mfma_f32_16x16x32_bf16 v[0:3], v[116:119], v[100:103], v[0:3]
	ds_read_b128 v[100:103], v204 offset:6144
	s_waitcnt lgkmcnt(3)
	v_mfma_f32_16x16x32_bf16 v[60:63], v[190:193], v[88:91], v[60:63]
	v_mfma_f32_16x16x32_bf16 v[56:59], v[196:199], v[88:91], v[56:59]
	v_mfma_f32_16x16x32_bf16 v[52:55], v[200:203], v[88:91], v[52:55]
	v_mfma_f32_16x16x32_bf16 v[48:51], v[208:211], v[88:91], v[48:51]
	s_waitcnt lgkmcnt(2)
	v_mfma_f32_16x16x32_bf16 v[44:47], v[190:193], v[92:95], v[44:47]
	v_mfma_f32_16x16x32_bf16 v[40:43], v[196:199], v[92:95], v[40:43]
	v_mfma_f32_16x16x32_bf16 v[36:39], v[200:203], v[92:95], v[36:39]
	v_mfma_f32_16x16x32_bf16 v[32:35], v[208:211], v[92:95], v[32:35]
	s_waitcnt lgkmcnt(1)
	v_mfma_f32_16x16x32_bf16 v[28:31], v[190:193], v[96:99], v[28:31]
	v_mfma_f32_16x16x32_bf16 v[24:27], v[196:199], v[96:99], v[24:27]
	v_mfma_f32_16x16x32_bf16 v[20:23], v[200:203], v[96:99], v[20:23]
	v_mfma_f32_16x16x32_bf16 v[16:19], v[208:211], v[96:99], v[16:19]
	s_waitcnt lgkmcnt(0)
	s_add_u32 s6, s6, 0x80
	s_addc_u32 s7, s7, 0
	s_add_i32 s26, s26, 0x8000
	s_cmpk_eq_i32 s6, 0x780
	v_mfma_f32_16x16x32_bf16 v[12:15], v[190:193], v[100:103], v[12:15]
	v_mfma_f32_16x16x32_bf16 v[8:11], v[196:199], v[100:103], v[8:11]
	v_mfma_f32_16x16x32_bf16 v[4:7], v[200:203], v[100:103], v[4:7]
	v_mfma_f32_16x16x32_bf16 v[0:3], v[208:211], v[100:103], v[0:3]
	s_cbranch_scc0 .LBB0_105
	v_add_u32_e32 v74, v86, v87
	v_add_u32_e32 v75, v74, v85
	s_waitcnt vmcnt(0)
	s_waitcnt vmcnt(0)
	s_barrier
; DEVI uint32_t pack2(float lo, float hi) { f32x2_t v = {lo, hi}; bf16x2_t b = __builtin_convertvector(v, bf16x2_t); return __builtin_bit_cast(uint32_t, b); }
; DEVI f32x4 mfma16(bf16x8 a, bf16x8 b, f32x4 c) { return __builtin_amdgcn_mfma_f32_16x16x32_bf16(a, b, c, 0, 0, 0); }
; #define EPI_END } __builtin_amdgcn_sched_barrier(0); } }
; template <bool SWAP, class RP>
; DEVI void gemm_main(const int TIDX, const int BIDX, const int GDIM, f32x4 (&acc)[4][4], RP rowoff, const bf16_t* __restrict__ Bt, int ldb, int K, unsigned char* smem) {
;     ...
;         af[i] = *(const bf16x8*)(A + i * 2048 + po);
;         bfr[i] = *(const bf16x8*)(B + i * 2048 + po);
;       }
; #pragma unroll
;       for (int mi = 0; mi < 4; ++mi)
; #pragma unroll
;         for (int ni = 0; ni < 4; ++ni)
;           acc[mi][ni] = SWAP ? mfma16(bfr[ni], af[mi], acc[mi][ni]) : mfma16(af[mi], bfr[ni], acc[mi][ni]);
;     }
;   }
;   __syncthreads();
; DEVI void phase_p6(const int TIDX, const int BIDX, const int GDIM, KAP KA, unsigned char* WSB, float* OUTB, int l, unsigned char* smem) {
;     ...
;     gemm_main<true>(TIDX, BIDX, GDIM, acc, rp, W + (size_t)n0 * 1024, 1024, 1024, smem);
;     EPI_SWAP_BEGIN(m0, n0)
;       const f32x4 a = acc[mi][ni];
;       *(uint2*)((bf16_t*)PRE + (size_t)row * 1024 + col) = make_uint2(pack2(a[0], a[1]), pack2(a[2], a[3]));
;     EPI_END
	ds_read_b128 v[66:69], v75 offset:49152
	v_add_u32_e32 v100, v65, v85
	ds_read_b128 v[70:73], v75 offset:51200
	ds_read_b128 v[84:87], v100 offset:32768
	ds_read_b128 v[88:91], v100 offset:34816
	ds_read_b128 v[92:95], v75 offset:53248
	ds_read_b128 v[96:99], v75 offset:55296
	s_waitcnt lgkmcnt(3)
	v_mfma_f32_16x16x32_bf16 v[60:63], v[66:69], v[84:87], v[60:63]
	v_add_u32_e32 v74, v74, v83
	v_add_u32_e32 v65, v65, v83
	v_mfma_f32_16x16x32_bf16 v[56:59], v[70:73], v[84:87], v[56:59]
	s_waitcnt lgkmcnt(1)
	v_mfma_f32_16x16x32_bf16 v[52:55], v[92:95], v[84:87], v[52:55]
	s_waitcnt lgkmcnt(0)
	v_mfma_f32_16x16x32_bf16 v[48:51], v[96:99], v[84:87], v[48:51]
	v_mfma_f32_16x16x32_bf16 v[44:47], v[66:69], v[88:91], v[44:47]
	v_mfma_f32_16x16x32_bf16 v[40:43], v[70:73], v[88:91], v[40:43]
	v_mfma_f32_16x16x32_bf16 v[36:39], v[92:95], v[88:91], v[36:39]
	v_mfma_f32_16x16x32_bf16 v[32:35], v[96:99], v[88:91], v[32:35]
	ds_read_b128 v[84:87], v100 offset:36864
	ds_read_b128 v[88:91], v100 offset:38912
	s_waitcnt lgkmcnt(1)
	v_mfma_f32_16x16x32_bf16 v[28:31], v[66:69], v[84:87], v[28:31]
	s_waitcnt lgkmcnt(0)
	v_mfma_f32_16x16x32_bf16 v[12:15], v[66:69], v[88:91], v[12:15]
	ds_read_b128 v[66:69], v74 offset:49152
	v_mfma_f32_16x16x32_bf16 v[24:27], v[70:73], v[84:87], v[24:27]
	v_mfma_f32_16x16x32_bf16 v[20:23], v[92:95], v[84:87], v[20:23]
	v_mfma_f32_16x16x32_bf16 v[16:19], v[96:99], v[84:87], v[16:19]
	v_mfma_f32_16x16x32_bf16 v[8:11], v[70:73], v[88:91], v[8:11]
	v_mfma_f32_16x16x32_bf16 v[4:7], v[92:95], v[88:91], v[4:7]
	v_mfma_f32_16x16x32_bf16 v[0:3], v[96:99], v[88:91], v[0:3]
	ds_read_b128 v[70:73], v74 offset:51200
	ds_read_b128 v[84:87], v65 offset:32768
	ds_read_b128 v[88:91], v65 offset:34816
	ds_read_b128 v[92:95], v74 offset:53248
	ds_read_b128 v[96:99], v74 offset:55296
	s_waitcnt lgkmcnt(3)
	v_mfma_f32_16x16x32_bf16 v[60:63], v[66:69], v[84:87], v[60:63]
	v_add_u32_e32 v74, s4, v76
	v_ashrrev_i32_e32 v75, 31, v74
	v_lshlrev_b64 v[100:101], 11, v[74:75]
	v_mfma_f32_16x16x32_bf16 v[56:59], v[70:73], v[84:87], v[56:59]
	v_lshl_add_u64 v[100:101], s[0:1], 0, v[100:101]
	s_nop 2
	v_cvt_pk_bf16_f32 v60, v60, v61
	v_cvt_pk_bf16_f32 v61, v62, v63
	s_waitcnt lgkmcnt(1)
	v_mfma_f32_16x16x32_bf16 v[52:55], v[92:95], v[84:87], v[52:55]
	v_mov_b32_e32 v63, v129
	v_cvt_pk_bf16_f32 v56, v56, v57
	v_cvt_pk_bf16_f32 v57, v58, v59
	s_waitcnt lgkmcnt(0)
	v_mfma_f32_16x16x32_bf16 v[48:51], v[96:99], v[84:87], v[48:51]
	v_mfma_f32_16x16x32_bf16 v[44:47], v[66:69], v[88:91], v[44:47]
	s_nop 1
	v_cvt_pk_bf16_f32 v52, v52, v53
	v_cvt_pk_bf16_f32 v53, v54, v55
	s_nop 2
	v_cvt_pk_bf16_f32 v48, v48, v49
	v_mfma_f32_16x16x32_bf16 v[40:43], v[70:73], v[88:91], v[40:43]
	v_cvt_pk_bf16_f32 v49, v50, v51
	v_mfma_f32_16x16x32_bf16 v[36:39], v[92:95], v[88:91], v[36:39]
	v_mfma_f32_16x16x32_bf16 v[32:35], v[96:99], v[88:91], v[32:35]
	ds_read_b128 v[84:87], v65 offset:36864
	ds_read_b128 v[88:91], v65 offset:38912
	v_or_b32_e32 v65, s25, v77
	v_lshlrev_b32_e32 v62, 1, v65
	s_waitcnt lgkmcnt(1)
	v_mfma_f32_16x16x32_bf16 v[28:31], v[66:69], v[84:87], v[28:31]
	s_waitcnt lgkmcnt(0)
	s_barrier
	v_mfma_f32_16x16x32_bf16 v[24:27], v[70:73], v[84:87], v[24:27]
	v_mfma_f32_16x16x32_bf16 v[20:23], v[92:95], v[84:87], v[20:23]
	v_mfma_f32_16x16x32_bf16 v[16:19], v[96:99], v[84:87], v[16:19]
	v_lshl_add_u64 v[84:85], v[100:101], 0, v[62:63]
	global_store_dwordx2 v[84:85], v[60:61], off
	global_store_dwordx2 v[84:85], v[56:57], off offset:32
	v_mfma_f32_16x16x32_bf16 v[12:15], v[66:69], v[88:91], v[12:15]
	global_store_dwordx2 v[84:85], v[52:53], off offset:64
	global_store_dwordx2 v[84:85], v[48:49], off offset:96
	v_mfma_f32_16x16x32_bf16 v[8:11], v[70:73], v[88:91], v[8:11]
	v_mfma_f32_16x16x32_bf16 v[4:7], v[92:95], v[88:91], v[4:7]
	v_mfma_f32_16x16x32_bf16 v[0:3], v[96:99], v[88:91], v[0:3]
	v_or_b32_e32 v48, 16, v74
	v_ashrrev_i32_e32 v49, 31, v48
	v_lshlrev_b64 v[48:49], 11, v[48:49]
	v_lshl_add_u64 v[48:49], s[0:1], 0, v[48:49]
	v_cvt_pk_bf16_f32 v44, v44, v45
	v_cvt_pk_bf16_f32 v45, v46, v47
	v_lshl_add_u64 v[46:47], v[48:49], 0, v[62:63]
	v_cvt_pk_bf16_f32 v40, v40, v41
	v_cvt_pk_bf16_f32 v41, v42, v43
	v_cvt_pk_bf16_f32 v36, v36, v37
	v_cvt_pk_bf16_f32 v37, v38, v39
	v_cvt_pk_bf16_f32 v32, v32, v33
	v_cvt_pk_bf16_f32 v33, v34, v35
	global_store_dwordx2 v[46:47], v[44:45], off
	global_store_dwordx2 v[46:47], v[40:41], off offset:32
	global_store_dwordx2 v[46:47], v[36:37], off offset:64
	global_store_dwordx2 v[46:47], v[32:33], off offset:96
	v_or_b32_e32 v32, 32, v74
	v_ashrrev_i32_e32 v33, 31, v32
	v_lshlrev_b64 v[32:33], 11, v[32:33]
	v_lshl_add_u64 v[32:33], s[0:1], 0, v[32:33]
	v_cvt_pk_bf16_f32 v28, v28, v29
	v_cvt_pk_bf16_f32 v29, v30, v31
	v_lshl_add_u64 v[30:31], v[32:33], 0, v[62:63]
	v_cvt_pk_bf16_f32 v24, v24, v25
	v_cvt_pk_bf16_f32 v25, v26, v27
	v_cvt_pk_bf16_f32 v20, v20, v21
	v_cvt_pk_bf16_f32 v21, v22, v23
	v_cvt_pk_bf16_f32 v16, v16, v17
	v_cvt_pk_bf16_f32 v17, v18, v19
	global_store_dwordx2 v[30:31], v[28:29], off
	global_store_dwordx2 v[30:31], v[24:25], off offset:32
	global_store_dwordx2 v[30:31], v[20:21], off offset:64
	global_store_dwordx2 v[30:31], v[16:17], off offset:96
	v_or_b32_e32 v16, 48, v74
	v_ashrrev_i32_e32 v17, 31, v16
	v_lshlrev_b64 v[16:17], 11, v[16:17]
	v_lshl_add_u64 v[16:17], s[0:1], 0, v[16:17]
	v_cvt_pk_bf16_f32 v12, v12, v13
	v_cvt_pk_bf16_f32 v13, v14, v15
	v_lshl_add_u64 v[14:15], v[16:17], 0, v[62:63]
	v_cvt_pk_bf16_f32 v8, v8, v9
	v_cvt_pk_bf16_f32 v9, v10, v11
	v_cvt_pk_bf16_f32 v4, v4, v5
	v_cvt_pk_bf16_f32 v5, v6, v7
	v_cvt_pk_bf16_f32 v0, v0, v1
	v_cvt_pk_bf16_f32 v1, v2, v3
	global_store_dwordx2 v[14:15], v[12:13], off
	global_store_dwordx2 v[14:15], v[8:9], off offset:32
	global_store_dwordx2 v[14:15], v[4:5], off offset:64
	global_store_dwordx2 v[14:15], v[0:1], off offset:96
	s_cmpk_gt_i32 s8, 0x17ff
	s_cbranch_scc1 .LBB0_103
	s_lshl_b32 s6, s8, 1
	s_mov_b64 s[4:5], -1
	s_movk_i32 s43, 0xc8

; DEVI f32x4 mfma16(bf16x8 a, bf16x8 b, f32x4 c) { return __builtin_amdgcn_mfma_f32_16x16x32_bf16(a, b, c, 0, 0, 0); }
; template <bool SWAP, class RP>
; DEVI void gemm_main(const int TIDX, const int BIDX, const int GDIM, f32x4 (&acc)[4][4], RP rowoff, const bf16_t* __restrict__ Bt, int ldb, int K, unsigned char* smem) {
;     ...
;   for (int kt = 0; kt < nk; ++kt) {
;     const int buf = kt & 1;
;     asm volatile("s_waitcnt vmcnt(0)" ::: "memory");
;     __syncthreads();
;     if (kt + 1 < nk) GM_STAGE(kt + 1, buf ^ 1);
;     const unsigned char* A = smem + buf * 32768 + (wr * 64 + li) * 128;
;     const unsigned char* B = smem + buf * 32768 + 16384 + (wc * 64 + li) * 128;
; #pragma unroll
;     for (int ks = 0; ks < 2; ++ks) {
;       const int po = (px ^ (ks * 4)) * 16;
;       bf16x8 af[4], bfr[4];
; #pragma unroll
;       for (int i = 0; i < 4; ++i) {
;         af[i] = *(const bf16x8*)(A + i * 2048 + po);
;         bfr[i] = *(const bf16x8*)(B + i * 2048 + po);
;       }
; #pragma unroll
;       for (int mi = 0; mi < 4; ++mi)
; #pragma unroll
;         for (int ni = 0; ni < 4; ++ni)
;           acc[mi][ni] = SWAP ? mfma16(bfr[ni], af[mi], acc[mi][ni]) : mfma16(af[mi], bfr[ni], acc[mi][ni]);
.LBB0_117:
	s_and_b32 s7, s6, 0x8000
	s_xor_b32 s14, s7, 0x8000
	v_add_u32_e32 v194, s14, v76
	v_add_u32_e32 v204, s7, v75
	v_or_b32_e32 v205, s7, v78
	v_add_u32_e32 v205, v205, v79
	v_add_u32_e32 v231, v204, v77
	v_add_u32_e32 v232, v205, v77
	v_readfirstlane_b32 s101, v194
	v_add_u32_e32 v204, v204, v74
	v_add_u32_e32 v205, v205, v74
	s_waitcnt vmcnt(0)
	s_barrier
	ds_read_b128 v[84:87], v231
	ds_read_b128 v[100:103], v232 offset:16384
	ds_read_b128 v[104:107], v232 offset:18432
	ds_read_b128 v[108:111], v232 offset:20480
	ds_read_b128 v[112:115], v232 offset:22528
	ds_read_b128 v[88:91], v231 offset:2048
	ds_read_b128 v[92:95], v231 offset:4096
	ds_read_b128 v[96:99], v231 offset:6144
	ds_read_b128 v[190:193], v205 offset:16384
	ds_read_b128 v[196:199], v205 offset:18432
	ds_read_b128 v[200:203], v205 offset:20480
	ds_read_b128 v[208:211], v205 offset:22528
	s_mov_b32 m0, s101
	v_lshl_add_u64 v[80:81], v[64:65], 0, s[0:1]
	global_load_lds_dwordx4 v[80:81], off
	s_add_i32 m0, s101, 0x1000
	v_lshl_add_u64 v[80:81], v[66:67], 0, s[0:1]
	global_load_lds_dwordx4 v[80:81], off
	s_waitcnt lgkmcnt(7)
	v_mfma_f32_16x16x32_bf16 v[60:63], v[100:103], v[84:87], v[60:63]
	v_mfma_f32_16x16x32_bf16 v[56:59], v[104:107], v[84:87], v[56:59]
	s_add_i32 m0, s101, 0x2000
	v_lshl_add_u64 v[80:81], v[68:69], 0, s[0:1]
	global_load_lds_dwordx4 v[80:81], off
	v_mfma_f32_16x16x32_bf16 v[52:55], v[108:111], v[84:87], v[52:55]
	v_mfma_f32_16x16x32_bf16 v[48:51], v[112:115], v[84:87], v[48:51]
	ds_read_b128 v[84:87], v204
	s_add_i32 m0, s101, 0x3000
	v_lshl_add_u64 v[80:81], v[70:71], 0, s[0:1]
	global_load_lds_dwordx4 v[80:81], off
	s_waitcnt lgkmcnt(7)
	v_mfma_f32_16x16x32_bf16 v[44:47], v[100:103], v[88:91], v[44:47]
	v_mfma_f32_16x16x32_bf16 v[40:43], v[104:107], v[88:91], v[40:43]
	s_add_i32 m0, s101, 0x4000
	s_mov_b64 s[14:15], 0x580080
	v_lshl_add_u64 v[80:81], v[72:73], 0, s[0:1]
	v_lshl_add_u64 v[80:81], v[80:81], 0, s[14:15]
	global_load_lds_dwordx4 v[80:81], off
	v_mfma_f32_16x16x32_bf16 v[36:39], v[108:111], v[88:91], v[36:39]
	v_mfma_f32_16x16x32_bf16 v[32:35], v[112:115], v[88:91], v[32:35]
	ds_read_b128 v[88:91], v204 offset:2048
	s_add_i32 m0, s101, 0x5000
	s_mov_b64 s[14:15], 0x590080
	v_lshl_add_u64 v[80:81], v[72:73], 0, s[0:1]
	v_lshl_add_u64 v[80:81], v[80:81], 0, s[14:15]
	global_load_lds_dwordx4 v[80:81], off
	s_waitcnt lgkmcnt(7)
	v_mfma_f32_16x16x32_bf16 v[28:31], v[100:103], v[92:95], v[28:31]
	v_mfma_f32_16x16x32_bf16 v[24:27], v[104:107], v[92:95], v[24:27]
	s_add_i32 m0, s101, 0x6000
	s_mov_b64 s[14:15], 0x5a0080
	v_lshl_add_u64 v[80:81], v[72:73], 0, s[0:1]
	v_lshl_add_u64 v[80:81], v[80:81], 0, s[14:15]
	global_load_lds_dwordx4 v[80:81], off
	v_mfma_f32_16x16x32_bf16 v[20:23], v[108:111], v[92:95], v[20:23]
	v_mfma_f32_16x16x32_bf16 v[16:19], v[112:115], v[92:95], v[16:19]
	ds_read_b128 v[92:95], v204 offset:4096
	s_add_i32 m0, s101, 0x7000
	s_mov_b64 s[14:15], 0x5b0080
	v_lshl_add_u64 v[80:81], v[72:73], 0, s[0:1]
	v_lshl_add_u64 v[80:81], v[80:81], 0, s[14:15]
	global_load_lds_dwordx4 v[80:81], off
	s_waitcnt lgkmcnt(7)
	v_mfma_f32_16x16x32_bf16 v[12:15], v[100:103], v[96:99], v[12:15]
	v_mfma_f32_16x16x32_bf16 v[8:11], v[104:107], v[96:99], v[8:11]
	v_mfma_f32_16x16x32_bf16 v[4:7], v[108:111], v[96:99], v[4:7]
	v_mfma_f32_16x16x32_bf16 v[0:3], v[112:115], v[96:99], v[0:3]
	ds_read_b128 v[96:99], v204 offset:6144
	s_waitcnt lgkmcnt(3)
	v_mfma_f32_16x16x32_bf16 v[60:63], v[190:193], v[84:87], v[60:63]
	v_mfma_f32_16x16x32_bf16 v[56:59], v[196:199], v[84:87], v[56:59]
	v_mfma_f32_16x16x32_bf16 v[52:55], v[200:203], v[84:87], v[52:55]
	v_mfma_f32_16x16x32_bf16 v[48:51], v[208:211], v[84:87], v[48:51]
	s_waitcnt lgkmcnt(2)
	v_mfma_f32_16x16x32_bf16 v[44:47], v[190:193], v[88:91], v[44:47]
	v_mfma_f32_16x16x32_bf16 v[40:43], v[196:199], v[88:91], v[40:43]
	v_mfma_f32_16x16x32_bf16 v[36:39], v[200:203], v[88:91], v[36:39]
	v_mfma_f32_16x16x32_bf16 v[32:35], v[208:211], v[88:91], v[32:35]
	s_waitcnt lgkmcnt(1)
	v_mfma_f32_16x16x32_bf16 v[28:31], v[190:193], v[92:95], v[28:31]
	v_mfma_f32_16x16x32_bf16 v[24:27], v[196:199], v[92:95], v[24:27]
	v_mfma_f32_16x16x32_bf16 v[20:23], v[200:203], v[92:95], v[20:23]
	v_mfma_f32_16x16x32_bf16 v[16:19], v[208:211], v[92:95], v[16:19]
	s_waitcnt lgkmcnt(0)
	s_add_u32 s0, s0, 0x80
	s_addc_u32 s1, s1, 0
	s_add_i32 s6, s6, 0x8000
	s_cmpk_eq_i32 s0, 0x780
	v_mfma_f32_16x16x32_bf16 v[12:15], v[190:193], v[96:99], v[12:15]
	v_mfma_f32_16x16x32_bf16 v[8:11], v[196:199], v[96:99], v[8:11]
	v_mfma_f32_16x16x32_bf16 v[4:7], v[200:203], v[96:99], v[4:7]
	v_mfma_f32_16x16x32_bf16 v[0:3], v[208:211], v[96:99], v[0:3]
	s_cbranch_scc0 .LBB0_117
	v_add_u32_e32 v72, v78, v79
	v_add_u32_e32 v73, v75, v77
	s_waitcnt vmcnt(0)
	s_waitcnt vmcnt(0)
	s_barrier
; DEVI uint32_t pack2(float lo, float hi) { f32x2_t v = {lo, hi}; bf16x2_t b = __builtin_convertvector(v, bf16x2_t); return __builtin_bit_cast(uint32_t, b); }
; DEVI float sigmoidf_(float x) { return 1.f / (1.f + __expf(-x)); }
; DEVI f32x4 mfma16(bf16x8 a, bf16x8 b, f32x4 c) { return __builtin_amdgcn_mfma_f32_16x16x32_bf16(a, b, c, 0, 0, 0); }
; template <bool SWAP, class RP>
; DEVI void gemm_main(const int TIDX, const int BIDX, const int GDIM, f32x4 (&acc)[4][4], RP rowoff, const bf16_t* __restrict__ Bt, int ldb, int K, unsigned char* smem) {
;     ...
;         af[i] = *(const bf16x8*)(A + i * 2048 + po);
;         bfr[i] = *(const bf16x8*)(B + i * 2048 + po);
;       }
; #pragma unroll
;       for (int mi = 0; mi < 4; ++mi)
; #pragma unroll
;         for (int ni = 0; ni < 4; ++ni)
;           acc[mi][ni] = SWAP ? mfma16(bfr[ni], af[mi], acc[mi][ni]) : mfma16(af[mi], bfr[ni], acc[mi][ni]);
;     }
;   }
;   __syncthreads();
; DEVI void phase_p5(const int TIDX, const int BIDX, const int GDIM, KAP KA, unsigned char* WSB, float* OUTB, int l, unsigned char* smem) {
;     ...
;     gemm_main<true>(TIDX, BIDX, GDIM, acc, rx, W + WO_G + (size_t)n0 * 1024, 1024, 1024, smem);
; #pragma unroll
;     for (int i = 0; i < 4; ++i)
; #pragma unroll
;       for (int j = 0; j < 4; ++j) gp[i][j] = make_uint2(pack2(sigmoidf_(acc[i][j][0]), sigmoidf_(acc[i][j][1])), pack2(sigmoidf_(acc[i][j][2]), sigmoidf_(acc[i][j][3])));
	v_add_u32_e32 v80, v72, v77
	ds_read_b128 v[64:67], v73 offset:32768
	ds_read_b128 v[68:71], v80 offset:49152
	ds_read_b128 v[76:79], v73 offset:34816
	ds_read_b128 v[84:87], v80 offset:51200
	ds_read_b128 v[88:91], v73 offset:36864
	ds_read_b128 v[92:95], v80 offset:53248
	ds_read_b128 v[96:99], v73 offset:38912
	ds_read_b128 v[100:103], v80 offset:55296
	s_waitcnt lgkmcnt(6)
	v_mfma_f32_16x16x32_bf16 v[60:63], v[68:71], v[64:67], v[60:63]
	v_add_u32_e32 v80, v75, v74
	v_add_u32_e32 v81, v72, v74
	s_lshl_b64 s[6:7], s[12:13], 9
	s_waitcnt lgkmcnt(4)
	v_mfma_f32_16x16x32_bf16 v[56:59], v[84:87], v[64:67], v[56:59]
	s_lshl_b64 s[0:1], s[12:13], 10
	s_add_u32 s14, s17, s0
	s_addc_u32 s15, s18, s1
	s_waitcnt lgkmcnt(2)
	v_mfma_f32_16x16x32_bf16 v[52:55], v[92:95], v[64:67], v[52:55]
	s_movk_i32 s40, 0x1c00
	s_lshl_b32 s13, s38, 9
	s_mov_b64 s[42:43], 0x8080
	s_waitcnt lgkmcnt(0)
	v_mfma_f32_16x16x32_bf16 v[48:51], v[100:103], v[64:67], v[48:51]
	s_mov_b32 s39, 0
	v_mfma_f32_16x16x32_bf16 v[44:47], v[68:71], v[76:79], v[44:47]
	v_mfma_f32_16x16x32_bf16 v[40:43], v[84:87], v[76:79], v[40:43]
	v_mfma_f32_16x16x32_bf16 v[36:39], v[92:95], v[76:79], v[36:39]
	v_mfma_f32_16x16x32_bf16 v[32:35], v[100:103], v[76:79], v[32:35]
	v_mfma_f32_16x16x32_bf16 v[28:31], v[68:71], v[88:91], v[28:31]
	v_mfma_f32_16x16x32_bf16 v[24:27], v[84:87], v[88:91], v[24:27]
	v_mfma_f32_16x16x32_bf16 v[20:23], v[92:95], v[88:91], v[20:23]
	v_mfma_f32_16x16x32_bf16 v[16:19], v[100:103], v[88:91], v[16:19]
	v_mfma_f32_16x16x32_bf16 v[12:15], v[68:71], v[96:99], v[12:15]
	v_mfma_f32_16x16x32_bf16 v[8:11], v[84:87], v[96:99], v[8:11]
	v_mfma_f32_16x16x32_bf16 v[4:7], v[92:95], v[96:99], v[4:7]
	v_mfma_f32_16x16x32_bf16 v[0:3], v[100:103], v[96:99], v[0:3]
	ds_read_b128 v[64:67], v80 offset:32768
	ds_read_b128 v[68:71], v81 offset:49152
	ds_read_b128 v[72:75], v80 offset:34816
	ds_read_b128 v[76:79], v81 offset:51200
	ds_read_b128 v[84:87], v80 offset:36864
	ds_read_b128 v[88:91], v81 offset:53248
	ds_read_b128 v[92:95], v80 offset:38912
	ds_read_b128 v[96:99], v81 offset:55296
	s_waitcnt lgkmcnt(0)
	s_barrier
	v_mfma_f32_16x16x32_bf16 v[60:63], v[68:71], v[64:67], v[60:63]
	v_mfma_f32_16x16x32_bf16 v[56:59], v[76:79], v[64:67], v[56:59]
	v_mfma_f32_16x16x32_bf16 v[52:55], v[88:91], v[64:67], v[52:55]
	s_nop 5
	v_mul_f32_e32 v60, 0xbfb8aa3b, v60
	v_mul_f32_e32 v61, 0xbfb8aa3b, v61
	v_exp_f32_e32 v60, v60
	v_exp_f32_e32 v61, v61
	v_mfma_f32_16x16x32_bf16 v[48:51], v[96:99], v[64:67], v[48:51]
	v_mul_f32_e32 v56, 0xbfb8aa3b, v56
	v_mul_f32_e32 v57, 0xbfb8aa3b, v57
	v_pk_add_f32 v[60:61], v[60:61], 1.0 op_sel_hi:[1,0]
	v_mfma_f32_16x16x32_bf16 v[44:47], v[68:71], v[72:75], v[44:47]
	v_div_scale_f32 v64, s[0:1], v61, v61, 1.0
	v_rcp_f32_e32 v65, v64
	v_mfma_f32_16x16x32_bf16 v[28:31], v[68:71], v[84:87], v[28:31]
	v_exp_f32_e32 v56, v56
	v_exp_f32_e32 v57, v57
	v_fma_f32 v66, -v64, v65, 1.0
	v_fmac_f32_e32 v65, v66, v65
	v_div_scale_f32 v66, vcc, 1.0, v61, 1.0
	v_mul_f32_e32 v67, v66, v65
	v_mfma_f32_16x16x32_bf16 v[12:15], v[68:71], v[92:95], v[12:15]
	v_fma_f32 v68, -v64, v67, v66
	v_fmac_f32_e32 v67, v68, v65
	v_fma_f32 v64, -v64, v67, v66
	v_div_fmas_f32 v64, v64, v65, v67
	v_div_fixup_f32 v61, v64, v61, 1.0
	v_div_scale_f32 v64, s[0:1], v60, v60, 1.0
	v_rcp_f32_e32 v65, v64
	v_mfma_f32_16x16x32_bf16 v[40:43], v[76:79], v[72:75], v[40:43]
	v_add_f32_e64 v56, v56, 1.0
	v_add_f32_e64 v57, v57, 1.0
	v_mul_f32_e32 v52, 0xbfb8aa3b, v52
	v_fma_f32 v66, -v64, v65, 1.0
	v_fmac_f32_e32 v65, v66, v65
	v_div_scale_f32 v66, vcc, 1.0, v60, 1.0
	v_mul_f32_e32 v67, v66, v65
	v_fma_f32 v68, -v64, v67, v66
	v_fmac_f32_e32 v67, v68, v65
	v_fma_f32 v64, -v64, v67, v66
	v_div_fmas_f32 v64, v64, v65, v67
	v_div_fixup_f32 v60, v64, v60, 1.0
	v_mfma_f32_16x16x32_bf16 v[36:39], v[88:91], v[72:75], v[36:39]
	v_mul_f32_e32 v53, 0xbfb8aa3b, v53
	v_exp_f32_e32 v52, v52
	v_exp_f32_e32 v53, v53
	v_mfma_f32_16x16x32_bf16 v[32:35], v[96:99], v[72:75], v[32:35]
	v_cvt_pk_bf16_f32 v74, v60, v61
	v_mul_f32_e32 v60, 0xbfb8aa3b, v62
	v_mul_f32_e32 v61, 0xbfb8aa3b, v63
	v_exp_f32_e32 v60, v60
	v_exp_f32_e32 v61, v61
	v_mfma_f32_16x16x32_bf16 v[24:27], v[76:79], v[84:87], v[24:27]
	v_add_f32_e64 v52, v52, 1.0
	v_add_f32_e64 v53, v53, 1.0
	v_mul_f32_e32 v48, 0xbfb8aa3b, v48
	v_pk_add_f32 v[60:61], v[60:61], 1.0 op_sel_hi:[1,0]
	v_mfma_f32_16x16x32_bf16 v[8:11], v[76:79], v[92:95], v[8:11]
	v_div_scale_f32 v62, s[0:1], v61, v61, 1.0
	v_rcp_f32_e32 v63, v62
	v_mul_f32_e32 v49, 0xbfb8aa3b, v49
	v_exp_f32_e32 v48, v48
	v_exp_f32_e32 v49, v49
	v_fma_f32 v64, -v62, v63, 1.0
	v_fmac_f32_e32 v63, v64, v63
	v_div_scale_f32 v64, vcc, 1.0, v61, 1.0
	v_mul_f32_e32 v65, v64, v63
	v_fma_f32 v66, -v62, v65, v64
	v_fmac_f32_e32 v65, v66, v63
	v_fma_f32 v62, -v62, v65, v64
	v_div_fmas_f32 v62, v62, v63, v65
	v_div_fixup_f32 v61, v62, v61, 1.0
	v_div_scale_f32 v62, s[0:1], v60, v60, 1.0
	v_rcp_f32_e32 v63, v62
	v_pk_add_f32 v[48:49], v[48:49], 1.0 op_sel_hi:[1,0]
	v_mul_f32_e32 v44, 0xbfb8aa3b, v44
	v_mul_f32_e32 v45, 0xbfb8aa3b, v45
	v_fma_f32 v64, -v62, v63, 1.0
	v_fmac_f32_e32 v63, v64, v63
	v_div_scale_f32 v64, vcc, 1.0, v60, 1.0
	v_mul_f32_e32 v65, v64, v63
	v_fma_f32 v66, -v62, v65, v64
	v_fmac_f32_e32 v65, v66, v63
	v_fma_f32 v62, -v62, v65, v64
	v_div_fmas_f32 v62, v62, v63, v65
	v_div_fixup_f32 v60, v62, v60, 1.0
	v_cvt_pk_bf16_f32 v75, v60, v61
	v_div_scale_f32 v60, s[0:1], v57, v57, 1.0
	v_rcp_f32_e32 v61, v60
	v_exp_f32_e32 v44, v44
	v_exp_f32_e32 v45, v45
	v_mfma_f32_16x16x32_bf16 v[20:23], v[88:91], v[84:87], v[20:23]
	v_fma_f32 v62, -v60, v61, 1.0
	v_fmac_f32_e32 v61, v62, v61
	v_div_scale_f32 v62, vcc, 1.0, v57, 1.0
; DEVI uint32_t pack2(float lo, float hi) { f32x2_t v = {lo, hi}; bf16x2_t b = __builtin_convertvector(v, bf16x2_t); return __builtin_bit_cast(uint32_t, b); }
; DEVI float sigmoidf_(float x) { return 1.f / (1.f + __expf(-x)); }
; DEVI void phase_p5(const int TIDX, const int BIDX, const int GDIM, KAP KA, unsigned char* WSB, float* OUTB, int l, unsigned char* smem) {
;     ...
;     for (int i = 0; i < 4; ++i)
; #pragma unroll
;       for (int j = 0; j < 4; ++j) gp[i][j] = make_uint2(pack2(sigmoidf_(acc[i][j][0]), sigmoidf_(acc[i][j][1])), pack2(sigmoidf_(acc[i][j][2]), sigmoidf_(acc[i][j][3])));
	v_mul_f32_e32 v63, v62, v61
	v_fma_f32 v64, -v60, v63, v62
	v_fmac_f32_e32 v63, v64, v61
	v_fma_f32 v60, -v60, v63, v62
	v_div_fmas_f32 v60, v60, v61, v63
	v_div_fixup_f32 v57, v60, v57, 1.0
	v_div_scale_f32 v60, s[0:1], v56, v56, 1.0
	v_rcp_f32_e32 v61, v60
	v_pk_add_f32 v[44:45], v[44:45], 1.0 op_sel_hi:[1,0]
	v_mfma_f32_16x16x32_bf16 v[16:19], v[96:99], v[84:87], v[16:19]
	v_mul_f32_e32 v40, 0xbfb8aa3b, v40
	v_fma_f32 v62, -v60, v61, 1.0
	v_fmac_f32_e32 v61, v62, v61
	v_div_scale_f32 v62, vcc, 1.0, v56, 1.0
	v_mul_f32_e32 v63, v62, v61
	v_fma_f32 v64, -v60, v63, v62
	v_fmac_f32_e32 v63, v64, v61
	v_fma_f32 v60, -v60, v63, v62
	v_div_fmas_f32 v60, v60, v61, v63
	v_div_fixup_f32 v56, v60, v56, 1.0
	v_cvt_pk_bf16_f32 v76, v56, v57
	v_mul_f32_e32 v56, 0xbfb8aa3b, v58
	v_mul_f32_e32 v57, 0xbfb8aa3b, v59
	v_exp_f32_e32 v56, v56
	v_exp_f32_e32 v57, v57
	v_mul_f32_e32 v41, 0xbfb8aa3b, v41
	v_exp_f32_e32 v40, v40
	v_exp_f32_e32 v41, v41
	v_pk_add_f32 v[56:57], v[56:57], 1.0 op_sel_hi:[1,0]
	v_mul_f32_e32 v36, 0xbfb8aa3b, v36
	v_div_scale_f32 v58, s[0:1], v57, v57, 1.0
	v_rcp_f32_e32 v59, v58
	v_pk_add_f32 v[40:41], v[40:41], 1.0 op_sel_hi:[1,0]
	v_mul_f32_e32 v37, 0xbfb8aa3b, v37
	v_exp_f32_e32 v36, v36
	v_fma_f32 v60, -v58, v59, 1.0
	v_fmac_f32_e32 v59, v60, v59
	v_div_scale_f32 v60, vcc, 1.0, v57, 1.0
	v_mul_f32_e32 v61, v60, v59
	v_fma_f32 v62, -v58, v61, v60
	v_fmac_f32_e32 v61, v62, v59
	v_fma_f32 v58, -v58, v61, v60
	v_div_fmas_f32 v58, v58, v59, v61
	v_div_fixup_f32 v57, v58, v57, 1.0
	v_div_scale_f32 v58, s[0:1], v56, v56, 1.0
	v_rcp_f32_e32 v59, v58
	v_exp_f32_e32 v37, v37
	v_mfma_f32_16x16x32_bf16 v[4:7], v[88:91], v[92:95], v[4:7]
	v_mul_f32_e32 v32, 0xbfb8aa3b, v32
	v_fma_f32 v60, -v58, v59, 1.0
	v_fmac_f32_e32 v59, v60, v59
	v_div_scale_f32 v60, vcc, 1.0, v56, 1.0
	v_mul_f32_e32 v61, v60, v59
	v_fma_f32 v62, -v58, v61, v60
	v_fmac_f32_e32 v61, v62, v59
	v_fma_f32 v58, -v58, v61, v60
	v_div_fmas_f32 v58, v58, v59, v61
	v_div_fixup_f32 v56, v58, v56, 1.0
	v_cvt_pk_bf16_f32 v77, v56, v57
	v_div_scale_f32 v56, s[0:1], v53, v53, 1.0
	v_rcp_f32_e32 v57, v56
	v_pk_add_f32 v[36:37], v[36:37], 1.0 op_sel_hi:[1,0]
	v_mul_f32_e32 v33, 0xbfb8aa3b, v33
	v_exp_f32_e32 v32, v32
	v_fma_f32 v58, -v56, v57, 1.0
	v_fmac_f32_e32 v57, v58, v57
	v_div_scale_f32 v58, vcc, 1.0, v53, 1.0
	v_mul_f32_e32 v59, v58, v57
	v_fma_f32 v60, -v56, v59, v58
	v_fmac_f32_e32 v59, v60, v57
	v_fma_f32 v56, -v56, v59, v58
	v_div_fmas_f32 v56, v56, v57, v59
	v_div_fixup_f32 v53, v56, v53, 1.0
	v_div_scale_f32 v56, s[0:1], v52, v52, 1.0
	v_rcp_f32_e32 v57, v56
	v_exp_f32_e32 v33, v33
	v_mul_f32_e32 v28, 0xbfb8aa3b, v28
	v_mul_f32_e32 v29, 0xbfb8aa3b, v29
	v_fma_f32 v58, -v56, v57, 1.0
	v_fmac_f32_e32 v57, v58, v57
	v_div_scale_f32 v58, vcc, 1.0, v52, 1.0
	v_mul_f32_e32 v59, v58, v57
	v_fma_f32 v60, -v56, v59, v58
	v_fmac_f32_e32 v59, v60, v57
	v_fma_f32 v56, -v56, v59, v58
	v_div_fmas_f32 v56, v56, v57, v59
	v_div_fixup_f32 v52, v56, v52, 1.0
	v_cvt_pk_bf16_f32 v78, v52, v53
	v_mul_f32_e32 v52, 0xbfb8aa3b, v54
	v_mul_f32_e32 v53, 0xbfb8aa3b, v55
	v_exp_f32_e32 v52, v52
	v_exp_f32_e32 v53, v53
	v_pk_add_f32 v[32:33], v[32:33], 1.0 op_sel_hi:[1,0]
	v_exp_f32_e32 v28, v28
	v_exp_f32_e32 v29, v29
	v_pk_add_f32 v[52:53], v[52:53], 1.0 op_sel_hi:[1,0]
	v_mfma_f32_16x16x32_bf16 v[0:3], v[96:99], v[92:95], v[0:3]
	v_div_scale_f32 v54, s[0:1], v53, v53, 1.0
	v_rcp_f32_e32 v55, v54
	v_pk_add_f32 v[28:29], v[28:29], 1.0 op_sel_hi:[1,0]
	v_mul_f32_e32 v24, 0xbfb8aa3b, v24
	v_mul_f32_e32 v25, 0xbfb8aa3b, v25
	v_fma_f32 v56, -v54, v55, 1.0
	v_fmac_f32_e32 v55, v56, v55
	v_div_scale_f32 v56, vcc, 1.0, v53, 1.0
	v_mul_f32_e32 v57, v56, v55
	v_fma_f32 v58, -v54, v57, v56
	v_fmac_f32_e32 v57, v58, v55
	v_fma_f32 v54, -v54, v57, v56
	v_div_fmas_f32 v54, v54, v55, v57
	v_div_fixup_f32 v53, v54, v53, 1.0
	v_div_scale_f32 v54, s[0:1], v52, v52, 1.0
	v_rcp_f32_e32 v55, v54
	v_exp_f32_e32 v24, v24
	v_exp_f32_e32 v25, v25
	v_mul_f32_e32 v20, 0xbfb8aa3b, v20
	v_fma_f32 v56, -v54, v55, 1.0
	v_fmac_f32_e32 v55, v56, v55
	v_div_scale_f32 v56, vcc, 1.0, v52, 1.0
	v_mul_f32_e32 v57, v56, v55
	v_fma_f32 v58, -v54, v57, v56
	v_fmac_f32_e32 v57, v58, v55
	v_fma_f32 v54, -v54, v57, v56
	v_div_fmas_f32 v54, v54, v55, v57
	v_div_fixup_f32 v52, v54, v52, 1.0
	v_cvt_pk_bf16_f32 v79, v52, v53
	v_div_scale_f32 v52, s[0:1], v49, v49, 1.0
	v_rcp_f32_e32 v53, v52
	v_pk_add_f32 v[24:25], v[24:25], 1.0 op_sel_hi:[1,0]
	v_mul_f32_e32 v21, 0xbfb8aa3b, v21
	v_exp_f32_e32 v20, v20
	v_fma_f32 v54, -v52, v53, 1.0
	v_fmac_f32_e32 v53, v54, v53
	v_div_scale_f32 v54, vcc, 1.0, v49, 1.0
	v_mul_f32_e32 v55, v54, v53
	v_fma_f32 v56, -v52, v55, v54
	v_fmac_f32_e32 v55, v56, v53
	v_fma_f32 v52, -v52, v55, v54
	v_div_fmas_f32 v52, v52, v53, v55
	v_div_fixup_f32 v49, v52, v49, 1.0
	v_div_scale_f32 v52, s[0:1], v48, v48, 1.0
	v_rcp_f32_e32 v53, v52
	v_exp_f32_e32 v21, v21
	v_mul_f32_e32 v16, 0xbfb8aa3b, v16
	v_mul_f32_e32 v17, 0xbfb8aa3b, v17
	v_fma_f32 v54, -v52, v53, 1.0
	v_fmac_f32_e32 v53, v54, v53
	v_div_scale_f32 v54, vcc, 1.0, v48, 1.0
	v_mul_f32_e32 v55, v54, v53
	v_fma_f32 v56, -v52, v55, v54
	v_fmac_f32_e32 v55, v56, v53
	v_fma_f32 v52, -v52, v55, v54
	v_div_fmas_f32 v52, v52, v53, v55
	v_div_fixup_f32 v48, v52, v48, 1.0
	v_cvt_pk_bf16_f32 v80, v48, v49
	v_mul_f32_e32 v48, 0xbfb8aa3b, v50
	v_mul_f32_e32 v49, 0xbfb8aa3b, v51
	v_exp_f32_e32 v48, v48
	v_exp_f32_e32 v49, v49
	v_pk_add_f32 v[20:21], v[20:21], 1.0 op_sel_hi:[1,0]
	v_exp_f32_e32 v16, v16
	v_exp_f32_e32 v17, v17
	v_pk_add_f32 v[48:49], v[48:49], 1.0 op_sel_hi:[1,0]
	v_mul_f32_e32 v12, 0xbfb8aa3b, v12
	v_div_scale_f32 v50, s[0:1], v49, v49, 1.0
	v_rcp_f32_e32 v51, v50
; DEVI uint32_t pack2(float lo, float hi) { f32x2_t v = {lo, hi}; bf16x2_t b = __builtin_convertvector(v, bf16x2_t); return __builtin_bit_cast(uint32_t, b); }
; DEVI float sigmoidf_(float x) { return 1.f / (1.f + __expf(-x)); }
; DEVI void phase_p5(const int TIDX, const int BIDX, const int GDIM, KAP KA, unsigned char* WSB, float* OUTB, int l, unsigned char* smem) {
;     ...
;     for (int i = 0; i < 4; ++i)
; #pragma unroll
;       for (int j = 0; j < 4; ++j) gp[i][j] = make_uint2(pack2(sigmoidf_(acc[i][j][0]), sigmoidf_(acc[i][j][1])), pack2(sigmoidf_(acc[i][j][2]), sigmoidf_(acc[i][j][3])));
	v_pk_add_f32 v[16:17], v[16:17], 1.0 op_sel_hi:[1,0]
	v_mul_f32_e32 v13, 0xbfb8aa3b, v13
	v_exp_f32_e32 v12, v12
	v_fma_f32 v52, -v50, v51, 1.0
	v_fmac_f32_e32 v51, v52, v51
	v_div_scale_f32 v52, vcc, 1.0, v49, 1.0
	v_mul_f32_e32 v53, v52, v51
	v_fma_f32 v54, -v50, v53, v52
	v_fmac_f32_e32 v53, v54, v51
	v_fma_f32 v50, -v50, v53, v52
	v_div_fmas_f32 v50, v50, v51, v53
	v_div_fixup_f32 v49, v50, v49, 1.0
	v_div_scale_f32 v50, s[0:1], v48, v48, 1.0
	v_rcp_f32_e32 v51, v50
	v_exp_f32_e32 v13, v13
	v_mul_f32_e32 v8, 0xbfb8aa3b, v8
	v_mul_f32_e32 v9, 0xbfb8aa3b, v9
	v_fma_f32 v52, -v50, v51, 1.0
	v_fmac_f32_e32 v51, v52, v51
	v_div_scale_f32 v52, vcc, 1.0, v48, 1.0
	v_mul_f32_e32 v53, v52, v51
	v_fma_f32 v54, -v50, v53, v52
	v_fmac_f32_e32 v53, v54, v51
	v_fma_f32 v50, -v50, v53, v52
	v_div_fmas_f32 v50, v50, v51, v53
	v_div_fixup_f32 v48, v50, v48, 1.0
	v_cvt_pk_bf16_f32 v81, v48, v49
	v_div_scale_f32 v48, s[0:1], v45, v45, 1.0
	v_rcp_f32_e32 v49, v48
	v_pk_add_f32 v[12:13], v[12:13], 1.0 op_sel_hi:[1,0]
	v_exp_f32_e32 v8, v8
	v_exp_f32_e32 v9, v9
	v_fma_f32 v50, -v48, v49, 1.0
	v_fmac_f32_e32 v49, v50, v49
	v_div_scale_f32 v50, vcc, 1.0, v45, 1.0
	v_mul_f32_e32 v51, v50, v49
	v_fma_f32 v52, -v48, v51, v50
	v_fmac_f32_e32 v51, v52, v49
	v_fma_f32 v48, -v48, v51, v50
	v_div_fmas_f32 v48, v48, v49, v51
	v_div_fixup_f32 v45, v48, v45, 1.0
	v_div_scale_f32 v48, s[0:1], v44, v44, 1.0
	v_rcp_f32_e32 v49, v48
	v_pk_add_f32 v[8:9], v[8:9], 1.0 op_sel_hi:[1,0]
	v_mul_f32_e32 v4, 0xbfb8aa3b, v4
	v_mul_f32_e32 v5, 0xbfb8aa3b, v5
	v_fma_f32 v50, -v48, v49, 1.0
	v_fmac_f32_e32 v49, v50, v49
	v_div_scale_f32 v50, vcc, 1.0, v44, 1.0
	v_mul_f32_e32 v51, v50, v49
	v_fma_f32 v52, -v48, v51, v50
	v_fmac_f32_e32 v51, v52, v49
	v_fma_f32 v48, -v48, v51, v50
	v_div_fmas_f32 v48, v48, v49, v51
	v_div_fixup_f32 v44, v48, v44, 1.0
	v_cvt_pk_bf16_f32 v84, v44, v45
	v_mul_f32_e32 v44, 0xbfb8aa3b, v46
	v_mul_f32_e32 v45, 0xbfb8aa3b, v47
	v_exp_f32_e32 v44, v44
	v_exp_f32_e32 v45, v45
	v_exp_f32_e32 v4, v4
	v_exp_f32_e32 v5, v5
	v_mul_f32_e32 v0, 0xbfb8aa3b, v0
	v_pk_add_f32 v[44:45], v[44:45], 1.0 op_sel_hi:[1,0]
	v_mul_f32_e32 v1, 0xbfb8aa3b, v1
	v_div_scale_f32 v46, s[0:1], v45, v45, 1.0
	v_rcp_f32_e32 v47, v46
	v_pk_add_f32 v[4:5], v[4:5], 1.0 op_sel_hi:[1,0]
	v_exp_f32_e32 v0, v0
	v_exp_f32_e32 v1, v1
	v_fma_f32 v48, -v46, v47, 1.0
	v_fmac_f32_e32 v47, v48, v47
	v_div_scale_f32 v48, vcc, 1.0, v45, 1.0
	v_mul_f32_e32 v49, v48, v47
	v_fma_f32 v50, -v46, v49, v48
	v_fmac_f32_e32 v49, v50, v47
	v_fma_f32 v46, -v46, v49, v48
	v_div_fmas_f32 v46, v46, v47, v49
	v_div_fixup_f32 v45, v46, v45, 1.0
	v_div_scale_f32 v46, s[0:1], v44, v44, 1.0
	v_rcp_f32_e32 v47, v46
	v_pk_add_f32 v[0:1], v[0:1], 1.0 op_sel_hi:[1,0]
	v_fma_f32 v48, -v46, v47, 1.0
	v_fmac_f32_e32 v47, v48, v47
	v_div_scale_f32 v48, vcc, 1.0, v44, 1.0
	v_mul_f32_e32 v49, v48, v47
	v_fma_f32 v50, -v46, v49, v48
	v_fmac_f32_e32 v49, v50, v47
	v_fma_f32 v46, -v46, v49, v48
	v_div_fmas_f32 v46, v46, v47, v49
	v_div_fixup_f32 v44, v46, v44, 1.0
	v_cvt_pk_bf16_f32 v85, v44, v45
	v_div_scale_f32 v44, s[0:1], v41, v41, 1.0
	v_rcp_f32_e32 v45, v44
	s_nop 0
	v_fma_f32 v46, -v44, v45, 1.0
	v_fmac_f32_e32 v45, v46, v45
	v_div_scale_f32 v46, vcc, 1.0, v41, 1.0
	v_mul_f32_e32 v47, v46, v45
	v_fma_f32 v48, -v44, v47, v46
	v_fmac_f32_e32 v47, v48, v45
	v_fma_f32 v44, -v44, v47, v46
	v_div_fmas_f32 v44, v44, v45, v47
	v_div_fixup_f32 v41, v44, v41, 1.0
	v_div_scale_f32 v44, s[0:1], v40, v40, 1.0
	v_rcp_f32_e32 v45, v44
	s_nop 0
	v_fma_f32 v46, -v44, v45, 1.0
	v_fmac_f32_e32 v45, v46, v45
	v_div_scale_f32 v46, vcc, 1.0, v40, 1.0
	v_mul_f32_e32 v47, v46, v45
	v_fma_f32 v48, -v44, v47, v46
	v_fmac_f32_e32 v47, v48, v45
	v_fma_f32 v44, -v44, v47, v46
	v_div_fmas_f32 v44, v44, v45, v47
	v_div_fixup_f32 v40, v44, v40, 1.0
	v_cvt_pk_bf16_f32 v86, v40, v41
	v_mul_f32_e32 v40, 0xbfb8aa3b, v42
	v_mul_f32_e32 v41, 0xbfb8aa3b, v43
	v_exp_f32_e32 v40, v40
	v_exp_f32_e32 v41, v41
	s_nop 0
	v_pk_add_f32 v[40:41], v[40:41], 1.0 op_sel_hi:[1,0]
	s_nop 0
	v_div_scale_f32 v42, s[0:1], v41, v41, 1.0
	v_rcp_f32_e32 v43, v42
	s_nop 0
	v_fma_f32 v44, -v42, v43, 1.0
	v_fmac_f32_e32 v43, v44, v43
	v_div_scale_f32 v44, vcc, 1.0, v41, 1.0
	v_mul_f32_e32 v45, v44, v43
	v_fma_f32 v46, -v42, v45, v44
	v_fmac_f32_e32 v45, v46, v43
	v_fma_f32 v42, -v42, v45, v44
	v_div_fmas_f32 v42, v42, v43, v45
	v_div_fixup_f32 v41, v42, v41, 1.0
	v_div_scale_f32 v42, s[0:1], v40, v40, 1.0
	v_rcp_f32_e32 v43, v42
	s_nop 0
	v_fma_f32 v44, -v42, v43, 1.0
	v_fmac_f32_e32 v43, v44, v43
	v_div_scale_f32 v44, vcc, 1.0, v40, 1.0
	v_mul_f32_e32 v45, v44, v43
	v_fma_f32 v46, -v42, v45, v44
	v_fmac_f32_e32 v45, v46, v43
	v_fma_f32 v42, -v42, v45, v44
	v_div_fmas_f32 v42, v42, v43, v45
	v_div_fixup_f32 v40, v42, v40, 1.0
	v_cvt_pk_bf16_f32 v87, v40, v41
	v_div_scale_f32 v40, s[0:1], v37, v37, 1.0
	v_rcp_f32_e32 v41, v40
	s_nop 0
	v_fma_f32 v42, -v40, v41, 1.0
	v_fmac_f32_e32 v41, v42, v41
	v_div_scale_f32 v42, vcc, 1.0, v37, 1.0
	v_mul_f32_e32 v43, v42, v41
	v_fma_f32 v44, -v40, v43, v42
	v_fmac_f32_e32 v43, v44, v41
	v_fma_f32 v40, -v40, v43, v42
	v_div_fmas_f32 v40, v40, v41, v43
	v_div_fixup_f32 v37, v40, v37, 1.0
	v_div_scale_f32 v40, s[0:1], v36, v36, 1.0
	v_rcp_f32_e32 v41, v40
	s_nop 0
	v_fma_f32 v42, -v40, v41, 1.0
	v_fmac_f32_e32 v41, v42, v41
	v_div_scale_f32 v42, vcc, 1.0, v36, 1.0
	v_mul_f32_e32 v43, v42, v41
	v_fma_f32 v44, -v40, v43, v42
	v_fmac_f32_e32 v43, v44, v41
	v_fma_f32 v40, -v40, v43, v42
	v_div_fmas_f32 v40, v40, v41, v43
	v_div_fixup_f32 v36, v40, v36, 1.0
	v_cvt_pk_bf16_f32 v88, v36, v37
	v_mul_f32_e32 v36, 0xbfb8aa3b, v38
	v_mul_f32_e32 v37, 0xbfb8aa3b, v39
; DEVI uint32_t pack2(float lo, float hi) { f32x2_t v = {lo, hi}; bf16x2_t b = __builtin_convertvector(v, bf16x2_t); return __builtin_bit_cast(uint32_t, b); }
; DEVI float sigmoidf_(float x) { return 1.f / (1.f + __expf(-x)); }
; DEVI void phase_p5(const int TIDX, const int BIDX, const int GDIM, KAP KA, unsigned char* WSB, float* OUTB, int l, unsigned char* smem) {
;     ...
;     for (int i = 0; i < 4; ++i)
; #pragma unroll
;       for (int j = 0; j < 4; ++j) gp[i][j] = make_uint2(pack2(sigmoidf_(acc[i][j][0]), sigmoidf_(acc[i][j][1])), pack2(sigmoidf_(acc[i][j][2]), sigmoidf_(acc[i][j][3])));
	v_exp_f32_e32 v36, v36
	v_exp_f32_e32 v37, v37
	s_nop 0
	v_pk_add_f32 v[36:37], v[36:37], 1.0 op_sel_hi:[1,0]
	s_nop 0
	v_div_scale_f32 v38, s[0:1], v37, v37, 1.0
	v_rcp_f32_e32 v39, v38
	s_nop 0
	v_fma_f32 v40, -v38, v39, 1.0
	v_fmac_f32_e32 v39, v40, v39
	v_div_scale_f32 v40, vcc, 1.0, v37, 1.0
	v_mul_f32_e32 v41, v40, v39
	v_fma_f32 v42, -v38, v41, v40
	v_fmac_f32_e32 v41, v42, v39
	v_fma_f32 v38, -v38, v41, v40
	v_div_fmas_f32 v38, v38, v39, v41
	v_div_fixup_f32 v37, v38, v37, 1.0
	v_div_scale_f32 v38, s[0:1], v36, v36, 1.0
	v_rcp_f32_e32 v39, v38
	s_nop 0
	v_fma_f32 v40, -v38, v39, 1.0
	v_fmac_f32_e32 v39, v40, v39
	v_div_scale_f32 v40, vcc, 1.0, v36, 1.0
	v_mul_f32_e32 v41, v40, v39
	v_fma_f32 v42, -v38, v41, v40
	v_fmac_f32_e32 v41, v42, v39
	v_fma_f32 v38, -v38, v41, v40
	v_div_fmas_f32 v38, v38, v39, v41
	v_div_fixup_f32 v36, v38, v36, 1.0
	v_cvt_pk_bf16_f32 v89, v36, v37
	v_div_scale_f32 v36, s[0:1], v33, v33, 1.0
	v_rcp_f32_e32 v37, v36
	s_nop 0
	v_fma_f32 v38, -v36, v37, 1.0
	v_fmac_f32_e32 v37, v38, v37
	v_div_scale_f32 v38, vcc, 1.0, v33, 1.0
	v_mul_f32_e32 v39, v38, v37
	v_fma_f32 v40, -v36, v39, v38
	v_fmac_f32_e32 v39, v40, v37
	v_fma_f32 v36, -v36, v39, v38
	v_div_fmas_f32 v36, v36, v37, v39
	v_div_fixup_f32 v33, v36, v33, 1.0
	v_div_scale_f32 v36, s[0:1], v32, v32, 1.0
	v_rcp_f32_e32 v37, v36
	s_nop 0
	v_fma_f32 v38, -v36, v37, 1.0
	v_fmac_f32_e32 v37, v38, v37
	v_div_scale_f32 v38, vcc, 1.0, v32, 1.0
	v_mul_f32_e32 v39, v38, v37
	v_fma_f32 v40, -v36, v39, v38
	v_fmac_f32_e32 v39, v40, v37
	v_fma_f32 v36, -v36, v39, v38
	v_div_fmas_f32 v36, v36, v37, v39
	v_div_fixup_f32 v32, v36, v32, 1.0
	v_cvt_pk_bf16_f32 v90, v32, v33
	v_mul_f32_e32 v32, 0xbfb8aa3b, v34
	v_mul_f32_e32 v33, 0xbfb8aa3b, v35
	v_exp_f32_e32 v32, v32
	v_exp_f32_e32 v33, v33
	s_nop 0
	v_pk_add_f32 v[32:33], v[32:33], 1.0 op_sel_hi:[1,0]
	s_nop 0
	v_div_scale_f32 v34, s[0:1], v33, v33, 1.0
	v_rcp_f32_e32 v35, v34
	s_nop 0
	v_fma_f32 v36, -v34, v35, 1.0
	v_fmac_f32_e32 v35, v36, v35
	v_div_scale_f32 v36, vcc, 1.0, v33, 1.0
	v_mul_f32_e32 v37, v36, v35
	v_fma_f32 v38, -v34, v37, v36
	v_fmac_f32_e32 v37, v38, v35
	v_fma_f32 v34, -v34, v37, v36
	v_div_fmas_f32 v34, v34, v35, v37
	v_div_fixup_f32 v33, v34, v33, 1.0
	v_div_scale_f32 v34, s[0:1], v32, v32, 1.0
	v_rcp_f32_e32 v35, v34
	s_nop 0
	v_fma_f32 v36, -v34, v35, 1.0
	v_fmac_f32_e32 v35, v36, v35
	v_div_scale_f32 v36, vcc, 1.0, v32, 1.0
	v_mul_f32_e32 v37, v36, v35
	v_fma_f32 v38, -v34, v37, v36
	v_fmac_f32_e32 v37, v38, v35
	v_fma_f32 v34, -v34, v37, v36
	v_div_fmas_f32 v34, v34, v35, v37
	v_div_fixup_f32 v32, v34, v32, 1.0
	v_cvt_pk_bf16_f32 v91, v32, v33
	v_div_scale_f32 v32, s[0:1], v29, v29, 1.0
	v_rcp_f32_e32 v33, v32
	s_nop 0
	v_fma_f32 v34, -v32, v33, 1.0
	v_fmac_f32_e32 v33, v34, v33
	v_div_scale_f32 v34, vcc, 1.0, v29, 1.0
	v_mul_f32_e32 v35, v34, v33
	v_fma_f32 v36, -v32, v35, v34
	v_fmac_f32_e32 v35, v36, v33
	v_fma_f32 v32, -v32, v35, v34
	v_div_fmas_f32 v32, v32, v33, v35
	v_div_fixup_f32 v29, v32, v29, 1.0
	v_div_scale_f32 v32, s[0:1], v28, v28, 1.0
	v_rcp_f32_e32 v33, v32
	s_nop 0
	v_fma_f32 v34, -v32, v33, 1.0
	v_fmac_f32_e32 v33, v34, v33
	v_div_scale_f32 v34, vcc, 1.0, v28, 1.0
	v_mul_f32_e32 v35, v34, v33
	v_fma_f32 v36, -v32, v35, v34
	v_fmac_f32_e32 v35, v36, v33
	v_fma_f32 v32, -v32, v35, v34
	v_div_fmas_f32 v32, v32, v33, v35
	v_div_fixup_f32 v28, v32, v28, 1.0
	v_cvt_pk_bf16_f32 v92, v28, v29
	v_mul_f32_e32 v28, 0xbfb8aa3b, v30
	v_mul_f32_e32 v29, 0xbfb8aa3b, v31
	v_exp_f32_e32 v28, v28
	v_exp_f32_e32 v29, v29
	s_nop 0
	v_pk_add_f32 v[28:29], v[28:29], 1.0 op_sel_hi:[1,0]
	s_nop 0
	v_div_scale_f32 v30, s[0:1], v29, v29, 1.0
	v_rcp_f32_e32 v31, v30
	s_nop 0
	v_fma_f32 v32, -v30, v31, 1.0
	v_fmac_f32_e32 v31, v32, v31
	v_div_scale_f32 v32, vcc, 1.0, v29, 1.0
	v_mul_f32_e32 v33, v32, v31
	v_fma_f32 v34, -v30, v33, v32
	v_fmac_f32_e32 v33, v34, v31
	v_fma_f32 v30, -v30, v33, v32
	v_div_fmas_f32 v30, v30, v31, v33
	v_div_fixup_f32 v29, v30, v29, 1.0
	v_div_scale_f32 v30, s[0:1], v28, v28, 1.0
	v_rcp_f32_e32 v31, v30
	s_nop 0
	v_fma_f32 v32, -v30, v31, 1.0
	v_fmac_f32_e32 v31, v32, v31
	v_div_scale_f32 v32, vcc, 1.0, v28, 1.0
	v_mul_f32_e32 v33, v32, v31
	v_fma_f32 v34, -v30, v33, v32
	v_fmac_f32_e32 v33, v34, v31
	v_fma_f32 v30, -v30, v33, v32
	v_div_fmas_f32 v30, v30, v31, v33
	v_div_fixup_f32 v28, v30, v28, 1.0
	v_cvt_pk_bf16_f32 v93, v28, v29
	v_div_scale_f32 v28, s[0:1], v25, v25, 1.0
	v_rcp_f32_e32 v29, v28
	s_nop 0
	v_fma_f32 v30, -v28, v29, 1.0
	v_fmac_f32_e32 v29, v30, v29
	v_div_scale_f32 v30, vcc, 1.0, v25, 1.0
	v_mul_f32_e32 v31, v30, v29
	v_fma_f32 v32, -v28, v31, v30
	v_fmac_f32_e32 v31, v32, v29
	v_fma_f32 v28, -v28, v31, v30
	v_div_fmas_f32 v28, v28, v29, v31
	v_div_fixup_f32 v25, v28, v25, 1.0
	v_div_scale_f32 v28, s[0:1], v24, v24, 1.0
	v_rcp_f32_e32 v29, v28
	s_nop 0
	v_fma_f32 v30, -v28, v29, 1.0
	v_fmac_f32_e32 v29, v30, v29
	v_div_scale_f32 v30, vcc, 1.0, v24, 1.0
	v_mul_f32_e32 v31, v30, v29
	v_fma_f32 v32, -v28, v31, v30
	v_fmac_f32_e32 v31, v32, v29
	v_fma_f32 v28, -v28, v31, v30
	v_div_fmas_f32 v28, v28, v29, v31
	v_div_fixup_f32 v24, v28, v24, 1.0
	v_cvt_pk_bf16_f32 v94, v24, v25
	v_mul_f32_e32 v24, 0xbfb8aa3b, v26
	v_mul_f32_e32 v25, 0xbfb8aa3b, v27
	v_exp_f32_e32 v24, v24
	v_exp_f32_e32 v25, v25
	s_nop 0
	v_pk_add_f32 v[24:25], v[24:25], 1.0 op_sel_hi:[1,0]
	s_nop 0
	v_div_scale_f32 v26, s[0:1], v25, v25, 1.0
	v_rcp_f32_e32 v27, v26
	s_nop 0
	v_fma_f32 v28, -v26, v27, 1.0
	v_fmac_f32_e32 v27, v28, v27
	v_div_scale_f32 v28, vcc, 1.0, v25, 1.0
	v_mul_f32_e32 v29, v28, v27
	v_fma_f32 v30, -v26, v29, v28
	v_fmac_f32_e32 v29, v30, v27
	v_fma_f32 v26, -v26, v29, v28
; DEVI uint32_t pack2(float lo, float hi) { f32x2_t v = {lo, hi}; bf16x2_t b = __builtin_convertvector(v, bf16x2_t); return __builtin_bit_cast(uint32_t, b); }
; DEVI float sigmoidf_(float x) { return 1.f / (1.f + __expf(-x)); }
; DEVI void phase_p5(const int TIDX, const int BIDX, const int GDIM, KAP KA, unsigned char* WSB, float* OUTB, int l, unsigned char* smem) {
;     ...
;     for (int i = 0; i < 4; ++i)
; #pragma unroll
;       for (int j = 0; j < 4; ++j) gp[i][j] = make_uint2(pack2(sigmoidf_(acc[i][j][0]), sigmoidf_(acc[i][j][1])), pack2(sigmoidf_(acc[i][j][2]), sigmoidf_(acc[i][j][3])));
	v_div_fmas_f32 v26, v26, v27, v29
	v_div_fixup_f32 v25, v26, v25, 1.0
	v_div_scale_f32 v26, s[0:1], v24, v24, 1.0
	v_rcp_f32_e32 v27, v26
	s_nop 0
	v_fma_f32 v28, -v26, v27, 1.0
	v_fmac_f32_e32 v27, v28, v27
	v_div_scale_f32 v28, vcc, 1.0, v24, 1.0
	v_mul_f32_e32 v29, v28, v27
	v_fma_f32 v30, -v26, v29, v28
	v_fmac_f32_e32 v29, v30, v27
	v_fma_f32 v26, -v26, v29, v28
	v_div_fmas_f32 v26, v26, v27, v29
	v_div_fixup_f32 v24, v26, v24, 1.0
	v_cvt_pk_bf16_f32 v95, v24, v25
	v_div_scale_f32 v24, s[0:1], v21, v21, 1.0
	v_rcp_f32_e32 v25, v24
	s_nop 0
	v_fma_f32 v26, -v24, v25, 1.0
	v_fmac_f32_e32 v25, v26, v25
	v_div_scale_f32 v26, vcc, 1.0, v21, 1.0
	v_mul_f32_e32 v27, v26, v25
	v_fma_f32 v28, -v24, v27, v26
	v_fmac_f32_e32 v27, v28, v25
	v_fma_f32 v24, -v24, v27, v26
	v_div_fmas_f32 v24, v24, v25, v27
	v_div_fixup_f32 v21, v24, v21, 1.0
	v_div_scale_f32 v24, s[0:1], v20, v20, 1.0
	v_rcp_f32_e32 v25, v24
	s_nop 0
	v_fma_f32 v26, -v24, v25, 1.0
	v_fmac_f32_e32 v25, v26, v25
	v_div_scale_f32 v26, vcc, 1.0, v20, 1.0
	v_mul_f32_e32 v27, v26, v25
	v_fma_f32 v28, -v24, v27, v26
	v_fmac_f32_e32 v27, v28, v25
	v_fma_f32 v24, -v24, v27, v26
	v_div_fmas_f32 v24, v24, v25, v27
	v_div_fixup_f32 v20, v24, v20, 1.0
	v_cvt_pk_bf16_f32 v96, v20, v21
	v_mul_f32_e32 v20, 0xbfb8aa3b, v22
	v_mul_f32_e32 v21, 0xbfb8aa3b, v23
	v_exp_f32_e32 v20, v20
	v_exp_f32_e32 v21, v21
	s_nop 0
	v_pk_add_f32 v[20:21], v[20:21], 1.0 op_sel_hi:[1,0]
	s_nop 0
	v_div_scale_f32 v22, s[0:1], v21, v21, 1.0
	v_rcp_f32_e32 v23, v22
	s_nop 0
	v_fma_f32 v24, -v22, v23, 1.0
	v_fmac_f32_e32 v23, v24, v23
	v_div_scale_f32 v24, vcc, 1.0, v21, 1.0
	v_mul_f32_e32 v25, v24, v23
	v_fma_f32 v26, -v22, v25, v24
	v_fmac_f32_e32 v25, v26, v23
	v_fma_f32 v22, -v22, v25, v24
	v_div_fmas_f32 v22, v22, v23, v25
	v_div_fixup_f32 v21, v22, v21, 1.0
	v_div_scale_f32 v22, s[0:1], v20, v20, 1.0
	v_rcp_f32_e32 v23, v22
	s_nop 0
	v_fma_f32 v24, -v22, v23, 1.0
	v_fmac_f32_e32 v23, v24, v23
	v_div_scale_f32 v24, vcc, 1.0, v20, 1.0
	v_mul_f32_e32 v25, v24, v23
	v_fma_f32 v26, -v22, v25, v24
	v_fmac_f32_e32 v25, v26, v23
	v_fma_f32 v22, -v22, v25, v24
	v_div_fmas_f32 v22, v22, v23, v25
	v_div_fixup_f32 v20, v22, v20, 1.0
	v_cvt_pk_bf16_f32 v97, v20, v21
	v_div_scale_f32 v20, s[0:1], v17, v17, 1.0
	v_rcp_f32_e32 v21, v20
	s_nop 0
	v_fma_f32 v22, -v20, v21, 1.0
	v_fmac_f32_e32 v21, v22, v21
	v_div_scale_f32 v22, vcc, 1.0, v17, 1.0
	v_mul_f32_e32 v23, v22, v21
	v_fma_f32 v24, -v20, v23, v22
	v_fmac_f32_e32 v23, v24, v21
	v_fma_f32 v20, -v20, v23, v22
	v_div_fmas_f32 v20, v20, v21, v23
	v_div_fixup_f32 v17, v20, v17, 1.0
	v_div_scale_f32 v20, s[0:1], v16, v16, 1.0
	v_rcp_f32_e32 v21, v20
	s_nop 0
	v_fma_f32 v22, -v20, v21, 1.0
	v_fmac_f32_e32 v21, v22, v21
	v_div_scale_f32 v22, vcc, 1.0, v16, 1.0
	v_mul_f32_e32 v23, v22, v21
	v_fma_f32 v24, -v20, v23, v22
	v_fmac_f32_e32 v23, v24, v21
	v_fma_f32 v20, -v20, v23, v22
	v_div_fmas_f32 v20, v20, v21, v23
	v_div_fixup_f32 v16, v20, v16, 1.0
	v_cvt_pk_bf16_f32 v98, v16, v17
	v_mul_f32_e32 v16, 0xbfb8aa3b, v18
	v_mul_f32_e32 v17, 0xbfb8aa3b, v19
	v_exp_f32_e32 v16, v16
	v_exp_f32_e32 v17, v17
	s_nop 0
	v_pk_add_f32 v[16:17], v[16:17], 1.0 op_sel_hi:[1,0]
	s_nop 0
	v_div_scale_f32 v18, s[0:1], v17, v17, 1.0
	v_rcp_f32_e32 v19, v18
	s_nop 0
	v_fma_f32 v20, -v18, v19, 1.0
	v_fmac_f32_e32 v19, v20, v19
	v_div_scale_f32 v20, vcc, 1.0, v17, 1.0
	v_mul_f32_e32 v21, v20, v19
	v_fma_f32 v22, -v18, v21, v20
	v_fmac_f32_e32 v21, v22, v19
	v_fma_f32 v18, -v18, v21, v20
	v_div_fmas_f32 v18, v18, v19, v21
	v_div_fixup_f32 v17, v18, v17, 1.0
	v_div_scale_f32 v18, s[0:1], v16, v16, 1.0
	v_rcp_f32_e32 v19, v18
	s_nop 0
	v_fma_f32 v20, -v18, v19, 1.0
	v_fmac_f32_e32 v19, v20, v19
	v_div_scale_f32 v20, vcc, 1.0, v16, 1.0
	v_mul_f32_e32 v21, v20, v19
	v_fma_f32 v22, -v18, v21, v20
	v_fmac_f32_e32 v21, v22, v19
	v_fma_f32 v18, -v18, v21, v20
	v_div_fmas_f32 v18, v18, v19, v21
	v_div_fixup_f32 v16, v18, v16, 1.0
	v_cvt_pk_bf16_f32 v99, v16, v17
	v_div_scale_f32 v16, s[0:1], v13, v13, 1.0
	v_rcp_f32_e32 v17, v16
	s_nop 0
	v_fma_f32 v18, -v16, v17, 1.0
	v_fmac_f32_e32 v17, v18, v17
	v_div_scale_f32 v18, vcc, 1.0, v13, 1.0
	v_mul_f32_e32 v19, v18, v17
	v_fma_f32 v20, -v16, v19, v18
	v_fmac_f32_e32 v19, v20, v17
	v_fma_f32 v16, -v16, v19, v18
	v_div_fmas_f32 v16, v16, v17, v19
	v_div_fixup_f32 v13, v16, v13, 1.0
	v_div_scale_f32 v16, s[0:1], v12, v12, 1.0
	v_rcp_f32_e32 v17, v16
	s_nop 0
	v_fma_f32 v18, -v16, v17, 1.0
	v_fmac_f32_e32 v17, v18, v17
	v_div_scale_f32 v18, vcc, 1.0, v12, 1.0
	v_mul_f32_e32 v19, v18, v17
	v_fma_f32 v20, -v16, v19, v18
	v_fmac_f32_e32 v19, v20, v17
	v_fma_f32 v16, -v16, v19, v18
	v_div_fmas_f32 v16, v16, v17, v19
	v_div_fixup_f32 v12, v16, v12, 1.0
	v_cvt_pk_bf16_f32 v100, v12, v13
	v_mul_f32_e32 v12, 0xbfb8aa3b, v14
	v_mul_f32_e32 v13, 0xbfb8aa3b, v15
	v_exp_f32_e32 v12, v12
	v_exp_f32_e32 v13, v13
	s_nop 0
	v_pk_add_f32 v[12:13], v[12:13], 1.0 op_sel_hi:[1,0]
	s_nop 0
	v_div_scale_f32 v14, s[0:1], v13, v13, 1.0
	v_rcp_f32_e32 v15, v14
	s_nop 0
	v_fma_f32 v16, -v14, v15, 1.0
	v_fmac_f32_e32 v15, v16, v15
	v_div_scale_f32 v16, vcc, 1.0, v13, 1.0
	v_mul_f32_e32 v17, v16, v15
	v_fma_f32 v18, -v14, v17, v16
	v_fmac_f32_e32 v17, v18, v15
	v_fma_f32 v14, -v14, v17, v16
	v_div_fmas_f32 v14, v14, v15, v17
	v_div_fixup_f32 v13, v14, v13, 1.0
	v_div_scale_f32 v14, s[0:1], v12, v12, 1.0
	v_rcp_f32_e32 v15, v14
	s_nop 0
	v_fma_f32 v16, -v14, v15, 1.0
	v_fmac_f32_e32 v15, v16, v15
	v_div_scale_f32 v16, vcc, 1.0, v12, 1.0
	v_mul_f32_e32 v17, v16, v15
	v_fma_f32 v18, -v14, v17, v16
	v_fmac_f32_e32 v17, v18, v15
	v_fma_f32 v14, -v14, v17, v16
	v_div_fmas_f32 v14, v14, v15, v17
; DEVI uint32_t pack2(float lo, float hi) { f32x2_t v = {lo, hi}; bf16x2_t b = __builtin_convertvector(v, bf16x2_t); return __builtin_bit_cast(uint32_t, b); }
; DEVI float sigmoidf_(float x) { return 1.f / (1.f + __expf(-x)); }
; template <bool SWAP, class RP>
; DEVI void gemm_main(const int TIDX, const int BIDX, const int GDIM, f32x4 (&acc)[4][4], RP rowoff, const bf16_t* __restrict__ Bt, int ldb, int K, unsigned char* smem) {
;     ...
;   const int lane = tid & 63, w = tid >> 6, wr = w >> 1, wc = w & 1, li = lane & 15, lg = lane >> 4;
;   const unsigned char* abase = rowoff.base;
;   const unsigned char* bbase = (const unsigned char*)Bt;
;   const uint32_t schunk = (uint32_t)((lane & 7) ^ (((lane >> 4) + 4 * (w & 1)) & 7)) * 16u;
;   uint32_t ao0, ao1, ao2, ao3;
;   const int rsub = w * 8 + (lane >> 3);
;   ao0 = rowoff(rsub) + schunk; ao1 = rowoff(rsub + 32) + schunk; ao2 = rowoff(rsub + 64) + schunk; ao3 = rowoff(rsub + 96) + schunk;
;   const uint32_t bo = (uint32_t)(rsub * ldb) * 2u + schunk, bstep = (uint32_t)(32 * ldb) * 2u;
;   unsigned char* sbase = smem + w * 1024;
; DEVI void phase_p5(const int TIDX, const int BIDX, const int GDIM, KAP KA, unsigned char* WSB, float* OUTB, int l, unsigned char* smem) {
;     ...
;     for (int i = 0; i < 4; ++i)
; #pragma unroll
;       for (int j = 0; j < 4; ++j) gp[i][j] = make_uint2(pack2(sigmoidf_(acc[i][j][0]), sigmoidf_(acc[i][j][1])), pack2(sigmoidf_(acc[i][j][2]), sigmoidf_(acc[i][j][3])));
;     zero_acc(acc);
;     gemm_main<true>(TIDX, BIDX, GDIM, acc, ra, W + WO_BRA + (size_t)n0 * 512, 512, 512, smem);
	v_div_fixup_f32 v12, v14, v12, 1.0
	v_cvt_pk_bf16_f32 v101, v12, v13
	v_div_scale_f32 v12, s[0:1], v9, v9, 1.0
	v_rcp_f32_e32 v13, v12
	s_nop 0
	v_fma_f32 v14, -v12, v13, 1.0
	v_fmac_f32_e32 v13, v14, v13
	v_div_scale_f32 v14, vcc, 1.0, v9, 1.0
	v_mul_f32_e32 v15, v14, v13
	v_fma_f32 v16, -v12, v15, v14
	v_fmac_f32_e32 v15, v16, v13
	v_fma_f32 v12, -v12, v15, v14
	v_div_fmas_f32 v12, v12, v13, v15
	v_div_fixup_f32 v9, v12, v9, 1.0
	v_div_scale_f32 v12, s[0:1], v8, v8, 1.0
	v_rcp_f32_e32 v13, v12
	s_nop 0
	v_fma_f32 v14, -v12, v13, 1.0
	v_fmac_f32_e32 v13, v14, v13
	v_div_scale_f32 v14, vcc, 1.0, v8, 1.0
	v_mul_f32_e32 v15, v14, v13
	v_fma_f32 v16, -v12, v15, v14
	v_fmac_f32_e32 v15, v16, v13
	v_fma_f32 v12, -v12, v15, v14
	v_div_fmas_f32 v12, v12, v13, v15
	v_div_fixup_f32 v8, v12, v8, 1.0
	v_cvt_pk_bf16_f32 v102, v8, v9
	v_mul_f32_e32 v8, 0xbfb8aa3b, v10
	v_mul_f32_e32 v9, 0xbfb8aa3b, v11
	v_exp_f32_e32 v8, v8
	v_exp_f32_e32 v9, v9
	s_nop 0
	v_pk_add_f32 v[8:9], v[8:9], 1.0 op_sel_hi:[1,0]
	s_nop 0
	v_div_scale_f32 v10, s[0:1], v9, v9, 1.0
	v_rcp_f32_e32 v11, v10
	s_nop 0
	v_fma_f32 v12, -v10, v11, 1.0
	v_fmac_f32_e32 v11, v12, v11
	v_div_scale_f32 v12, vcc, 1.0, v9, 1.0
	v_mul_f32_e32 v13, v12, v11
	v_fma_f32 v14, -v10, v13, v12
	v_fmac_f32_e32 v13, v14, v11
	v_fma_f32 v10, -v10, v13, v12
	v_div_fmas_f32 v10, v10, v11, v13
	v_div_fixup_f32 v9, v10, v9, 1.0
	v_div_scale_f32 v10, s[0:1], v8, v8, 1.0
	v_rcp_f32_e32 v11, v10
	s_nop 0
	v_fma_f32 v12, -v10, v11, 1.0
	v_fmac_f32_e32 v11, v12, v11
	v_div_scale_f32 v12, vcc, 1.0, v8, 1.0
	v_mul_f32_e32 v13, v12, v11
	v_fma_f32 v14, -v10, v13, v12
	v_fmac_f32_e32 v13, v14, v11
	v_fma_f32 v10, -v10, v13, v12
	v_div_fmas_f32 v10, v10, v11, v13
	v_div_fixup_f32 v8, v10, v8, 1.0
	v_cvt_pk_bf16_f32 v103, v8, v9
	v_div_scale_f32 v8, s[0:1], v5, v5, 1.0
	v_rcp_f32_e32 v9, v8
	s_nop 0
	v_fma_f32 v10, -v8, v9, 1.0
	v_fmac_f32_e32 v9, v10, v9
	v_div_scale_f32 v10, vcc, 1.0, v5, 1.0
	v_mul_f32_e32 v11, v10, v9
	v_fma_f32 v12, -v8, v11, v10
	v_fmac_f32_e32 v11, v12, v9
	v_fma_f32 v8, -v8, v11, v10
	v_div_fmas_f32 v8, v8, v9, v11
	v_div_fixup_f32 v5, v8, v5, 1.0
	v_div_scale_f32 v8, s[0:1], v4, v4, 1.0
	v_rcp_f32_e32 v9, v8
	s_nop 0
	v_fma_f32 v10, -v8, v9, 1.0
	v_fmac_f32_e32 v9, v10, v9
	v_div_scale_f32 v10, vcc, 1.0, v4, 1.0
	v_mul_f32_e32 v11, v10, v9
	v_fma_f32 v12, -v8, v11, v10
	v_fmac_f32_e32 v11, v12, v9
	v_fma_f32 v8, -v8, v11, v10
	v_div_fmas_f32 v8, v8, v9, v11
	v_div_fixup_f32 v4, v8, v4, 1.0
	v_cvt_pk_bf16_f32 v104, v4, v5
	v_mul_f32_e32 v4, 0xbfb8aa3b, v6
	v_mul_f32_e32 v5, 0xbfb8aa3b, v7
	v_exp_f32_e32 v4, v4
	v_exp_f32_e32 v5, v5
	s_nop 0
	v_pk_add_f32 v[4:5], v[4:5], 1.0 op_sel_hi:[1,0]
	s_nop 0
	v_div_scale_f32 v6, s[0:1], v5, v5, 1.0
	v_rcp_f32_e32 v7, v6
	s_nop 0
	v_fma_f32 v8, -v6, v7, 1.0
	v_fmac_f32_e32 v7, v8, v7
	v_div_scale_f32 v8, vcc, 1.0, v5, 1.0
	v_mul_f32_e32 v9, v8, v7
	v_fma_f32 v10, -v6, v9, v8
	v_fmac_f32_e32 v9, v10, v7
	v_fma_f32 v6, -v6, v9, v8
	v_div_fmas_f32 v6, v6, v7, v9
	v_div_fixup_f32 v5, v6, v5, 1.0
	v_div_scale_f32 v6, s[0:1], v4, v4, 1.0
	v_rcp_f32_e32 v7, v6
	s_nop 0
	v_fma_f32 v8, -v6, v7, 1.0
	v_fmac_f32_e32 v7, v8, v7
	v_div_scale_f32 v8, vcc, 1.0, v4, 1.0
	v_mul_f32_e32 v9, v8, v7
	v_fma_f32 v10, -v6, v9, v8
	v_fmac_f32_e32 v9, v10, v7
	v_fma_f32 v6, -v6, v9, v8
	v_div_fmas_f32 v6, v6, v7, v9
	v_div_fixup_f32 v4, v6, v4, 1.0
	v_cvt_pk_bf16_f32 v105, v4, v5
	v_div_scale_f32 v4, s[0:1], v1, v1, 1.0
	v_rcp_f32_e32 v5, v4
	v_mov_b32_e32 v10, v130
	v_mov_b32_e32 v9, v129
	v_fma_f32 v6, -v4, v5, 1.0
	v_fmac_f32_e32 v5, v6, v5
	v_div_scale_f32 v6, vcc, 1.0, v1, 1.0
	v_mul_f32_e32 v7, v6, v5
	v_fma_f32 v8, -v4, v7, v6
	v_fmac_f32_e32 v7, v8, v5
	v_fma_f32 v4, -v4, v7, v6
	v_div_fmas_f32 v4, v4, v5, v7
	v_div_fixup_f32 v1, v4, v1, 1.0
	v_div_scale_f32 v4, s[0:1], v0, v0, 1.0
	v_rcp_f32_e32 v5, v4
	s_nop 0
	v_fma_f32 v6, -v4, v5, 1.0
	v_fmac_f32_e32 v5, v6, v5
	v_div_scale_f32 v6, vcc, 1.0, v0, 1.0
	v_mul_f32_e32 v7, v6, v5
	v_fma_f32 v8, -v4, v7, v6
	v_fmac_f32_e32 v7, v8, v5
	v_fma_f32 v4, -v4, v7, v6
	v_div_fmas_f32 v4, v4, v5, v7
	v_div_fixup_f32 v0, v4, v0, 1.0
	v_cvt_pk_bf16_f32 v106, v0, v1
	v_mul_f32_e32 v0, 0xbfb8aa3b, v2
	v_mul_f32_e32 v1, 0xbfb8aa3b, v3
	v_exp_f32_e32 v0, v0
	v_exp_f32_e32 v1, v1
	s_nop 0
	v_pk_add_f32 v[0:1], v[0:1], 1.0 op_sel_hi:[1,0]
	s_nop 0
	v_div_scale_f32 v2, s[0:1], v1, v1, 1.0
	v_rcp_f32_e32 v3, v2
	s_nop 0
	v_fma_f32 v4, -v2, v3, 1.0
	v_fmac_f32_e32 v3, v4, v3
	v_div_scale_f32 v4, vcc, 1.0, v1, 1.0
	v_mul_f32_e32 v5, v4, v3
	v_fma_f32 v6, -v2, v5, v4
	v_fmac_f32_e32 v5, v6, v3
	v_fma_f32 v2, -v2, v5, v4
	v_div_fmas_f32 v2, v2, v3, v5
	v_div_fixup_f32 v1, v2, v1, 1.0
	v_div_scale_f32 v2, s[0:1], v0, v0, 1.0
	v_rcp_f32_e32 v3, v2
	s_lshl_b32 s0, s38, 10
	s_add_u32 s0, s25, s0
	s_addc_u32 s1, s26, 0
	v_fma_f32 v4, -v2, v3, 1.0
	v_fmac_f32_e32 v3, v4, v3
	v_div_scale_f32 v4, vcc, 1.0, v0, 1.0
	v_mul_f32_e32 v5, v4, v3
	v_fma_f32 v6, -v2, v5, v4
	v_fmac_f32_e32 v5, v6, v3
	v_fma_f32 v2, -v2, v5, v4
	v_div_fmas_f32 v2, v2, v3, v5
	v_div_fixup_f32 v0, v2, v0, 1.0
	v_cvt_pk_bf16_f32 v107, v0, v1
	v_mov_b32_e32 v0, v129
	s_mov_b64 vcc, 0x18080
	v_ashrrev_i32_e32 v5, 6, v10
	v_and_b32_e32 v11, 1, v5
	v_bfe_u32 v4, v10, 4, 2
	v_and_b32_e32 v6, 7, v10
	v_lshlrev_b32_e32 v7, 2, v11
	v_bitop3_b32 v4, v7, v6, v4 bitop3:0x36
	v_lshlrev_b32_e32 v6, 13, v5
	v_lshlrev_b32_e32 v7, 7, v10
	v_and_or_b32 v6, v7, s40, v6
	v_lshl_or_b32 v128, v4, 4, v6
	v_add_u32_e32 v4, 0x8000, v128
	v_lshlrev_b32_e32 v13, 10, v5
	v_mov_b32_e32 v5, v129
	v_readfirstlane_b32 s44, v13
	v_lshl_add_u64 v[68:69], s[14:15], 0, v[4:5]
	v_add_u32_e32 v5, 0x1000, v13
; DEVI f32x4 mfma16(bf16x8 a, bf16x8 b, f32x4 c) { return __builtin_amdgcn_mfma_f32_16x16x32_bf16(a, b, c, 0, 0, 0); }
; template <bool SWAP, class RP>
; DEVI void gemm_main(const int TIDX, const int BIDX, const int GDIM, f32x4 (&acc)[4][4], RP rowoff, const bf16_t* __restrict__ Bt, int ldb, int K, unsigned char* smem) {
;     ...
;   const int nk = K >> 6;
;   const int px = lg ^ (li >> 1);
;   GM_STAGE(0, 0);
;   for (int kt = 0; kt < nk; ++kt) {
;     const int buf = kt & 1;
;     asm volatile("s_waitcnt vmcnt(0)" ::: "memory");
;     __syncthreads();
;     if (kt + 1 < nk) GM_STAGE(kt + 1, buf ^ 1);
;     const unsigned char* A = smem + buf * 32768 + (wr * 64 + li) * 128;
;     const unsigned char* B = smem + buf * 32768 + 16384 + (wc * 64 + li) * 128;
; #pragma unroll
;     for (int ks = 0; ks < 2; ++ks) {
;       const int po = (px ^ (ks * 4)) * 16;
;       bf16x8 af[4], bfr[4];
; #pragma unroll
;       for (int i = 0; i < 4; ++i) {
;         af[i] = *(const bf16x8*)(A + i * 2048 + po);
;         bfr[i] = *(const bf16x8*)(B + i * 2048 + po);
;       }
; #pragma unroll
;       for (int mi = 0; mi < 4; ++mi)
; #pragma unroll
;         for (int ni = 0; ni < 4; ++ni)
;           acc[mi][ni] = SWAP ? mfma16(bfr[ni], af[mi], acc[mi][ni]) : mfma16(af[mi], bfr[ni], acc[mi][ni]);
	s_mov_b32 m0, s44
	v_readfirstlane_b32 s45, v5
	global_load_lds_dwordx4 v128, s[14:15]
	s_mov_b32 m0, s45
	v_add_u32_e32 v6, 0x10000, v128
	global_load_lds_dwordx4 v4, s[14:15]
	v_add_u32_e32 v4, 0x2000, v13
	v_add_u32_e32 v14, 0x4000, v13
	v_readfirstlane_b32 s46, v4
	v_add_u32_e32 v4, 0x3000, v13
	v_mov_b32_e32 v7, v129
	s_mov_b32 m0, s46
	v_readfirstlane_b32 s47, v4
	v_add_u32_e32 v8, 0x18000, v128
	v_lshl_add_u64 v[70:71], s[14:15], 0, v[6:7]
	global_load_lds_dwordx4 v6, s[14:15]
	s_mov_b32 m0, s47
	v_readfirstlane_b32 s54, v14
	v_add_u32_e32 v6, 0x5000, v13
	global_load_lds_dwordx4 v8, s[14:15]
	v_lshl_add_u64 v[66:67], s[0:1], 0, v[128:129]
	s_mov_b32 m0, s54
	v_readfirstlane_b32 s62, v6
	v_add_u32_e32 v6, 0x6000, v13
	global_load_lds_dwordx4 v128, s[0:1]
	v_lshl_add_u64 v[4:5], v[66:67], 0, s[58:59]
	s_mov_b32 m0, s62
	v_readfirstlane_b32 s63, v6
	v_add_u32_e32 v6, 0x7000, v13
	global_load_lds_dwordx4 v[4:5], off
	v_lshl_add_u64 v[4:5], v[66:67], 0, s[74:75]
	s_mov_b32 m0, s63
	s_mov_b64 s[0:1], 0x18000
	v_readfirstlane_b32 s76, v6
	global_load_lds_dwordx4 v[4:5], off
	v_lshl_add_u64 v[4:5], v[66:67], 0, s[0:1]
	s_mov_b32 m0, s76
	v_lshrrev_b32_e32 v6, 1, v10
	global_load_lds_dwordx4 v[4:5], off
	v_and_b32_e32 v4, 15, v10
	s_mov_b32 s74, 0x1ffffc0
	v_lshrrev_b32_e32 v12, 4, v10
	v_bfe_u32 v5, v10, 1, 3
	v_and_or_b32 v6, v6, s74, v4
	v_add_u32_e32 v7, 0x8000, v13
	v_lshl_add_u64 v[64:65], s[14:15], 0, v[128:129]
	v_lshlrev_b32_e32 v108, 7, v6
	v_lshlrev_b32_e32 v6, 7, v4
	v_bitop3_b32 v4, v5, v12, 3 bitop3:0x78
	v_readfirstlane_b32 s0, v7
	v_add_u32_e32 v7, 0x9000, v13
	v_lshlrev_b32_e32 v110, 4, v4
	v_lshl_add_u64 v[4:5], v[64:65], 0, s[66:67]
	s_mov_b32 m0, s0
	v_readfirstlane_b32 s1, v7
	v_add_u32_e32 v7, 0xa000, v13
	v_lshl_add_u64 v[72:73], s[14:15], 0, v[8:9]
	s_waitcnt vmcnt(0)
	s_waitcnt vmcnt(0) lgkmcnt(0)
	s_barrier
	global_load_lds_dwordx4 v[4:5], off
	v_lshl_add_u64 v[4:5], v[68:69], 0, s[66:67]
	s_mov_b32 m0, s1
	v_readfirstlane_b32 s14, v7
	v_add_u32_e32 v7, 0xb000, v13
	v_add_u32_e32 v8, 0xc000, v13
	global_load_lds_dwordx4 v[4:5], off
	v_lshl_add_u64 v[4:5], v[70:71], 0, s[66:67]
	s_mov_b32 m0, s14
	v_readfirstlane_b32 s15, v7
	global_load_lds_dwordx4 v[4:5], off
	v_lshl_add_u64 v[4:5], v[72:73], 0, s[66:67]
	s_mov_b32 m0, s15
	v_readfirstlane_b32 s40, v8
	v_add_u32_e32 v7, 0xd000, v13
	global_load_lds_dwordx4 v[4:5], off
	v_lshl_add_u64 v[4:5], v[66:67], 0, s[66:67]
	s_mov_b32 m0, s40
	v_readfirstlane_b32 s41, v7
	v_add_u32_e32 v7, 0xe000, v13
	global_load_lds_dwordx4 v[4:5], off
	v_lshl_add_u64 v[4:5], v[66:67], 0, s[42:43]
	s_mov_b32 m0, s41
	v_readfirstlane_b32 s42, v7
	v_add_u32_e32 v7, 0xf000, v13
	global_load_lds_dwordx4 v[4:5], off
	v_lshl_add_u64 v[4:5], v[66:67], 0, s[70:71]
	s_mov_b32 m0, s42
	v_readfirstlane_b32 s43, v7
	global_load_lds_dwordx4 v[4:5], off
	v_lshl_add_u64 v[4:5], v[66:67], 0, vcc
	s_mov_b32 m0, s43
	v_lshl_or_b32 v121, v11, 13, v6
	global_load_lds_dwordx4 v[4:5], off
	v_or_b32_e32 v109, v108, v110
	v_or_b32_e32 v111, v121, v110
	ds_read_b128 v[4:7], v109
	ds_read_b128 v[8:11], v111 offset:16384
	ds_read_b128 v[12:15], v109 offset:2048
	ds_read_b128 v[16:19], v111 offset:18432
	ds_read_b128 v[20:23], v109 offset:4096
	ds_read_b128 v[24:27], v111 offset:20480
	ds_read_b128 v[28:31], v109 offset:6144
	ds_read_b128 v[32:35], v111 offset:22528
	v_mov_b32_e32 v1, v0
	v_mov_b32_e32 v2, v0
	v_mov_b32_e32 v3, v0
	v_xor_b32_e32 v120, 64, v110
	v_bitop3_b32 v108, v108, v110, 64 bitop3:0xf6
	s_waitcnt lgkmcnt(0)
	v_mfma_f32_16x16x32_bf16 v[36:39], v[8:11], v[4:7], v[0:3]
	v_or_b32_e32 v110, v121, v120
	s_mov_b64 vcc, 0x100
	s_mov_b32 m0, s44
	v_mfma_f32_16x16x32_bf16 v[40:43], v[16:19], v[4:7], v[0:3]
	v_mfma_f32_16x16x32_bf16 v[44:47], v[24:27], v[4:7], v[0:3]
	v_mfma_f32_16x16x32_bf16 v[4:7], v[32:35], v[4:7], v[0:3]
	v_mfma_f32_16x16x32_bf16 v[48:51], v[8:11], v[12:15], v[0:3]
	v_mfma_f32_16x16x32_bf16 v[52:55], v[16:19], v[12:15], v[0:3]
	v_mfma_f32_16x16x32_bf16 v[56:59], v[24:27], v[12:15], v[0:3]
	v_mfma_f32_16x16x32_bf16 v[12:15], v[32:35], v[12:15], v[0:3]
	v_mfma_f32_16x16x32_bf16 v[60:63], v[8:11], v[20:23], v[0:3]
	v_mfma_f32_16x16x32_bf16 v[112:115], v[16:19], v[20:23], v[0:3]
	v_mfma_f32_16x16x32_bf16 v[116:119], v[24:27], v[20:23], v[0:3]
	v_mfma_f32_16x16x32_bf16 v[20:23], v[32:35], v[20:23], v[0:3]
	v_mfma_f32_16x16x32_bf16 v[8:11], v[8:11], v[28:31], v[0:3]
	v_mfma_f32_16x16x32_bf16 v[16:19], v[16:19], v[28:31], v[0:3]
	v_mfma_f32_16x16x32_bf16 v[24:27], v[24:27], v[28:31], v[0:3]
	v_mfma_f32_16x16x32_bf16 v[28:31], v[32:35], v[28:31], v[0:3]
	s_nop 2
	ds_read_b128 v[0:3], v108
	ds_read_b128 v[32:35], v110 offset:16384
	ds_read_b128 v[120:123], v108 offset:2048
	ds_read_b128 v[124:127], v110 offset:18432
	ds_read_b128 v[132:135], v108 offset:4096
	ds_read_b128 v[136:139], v110 offset:20480
	ds_read_b128 v[140:143], v108 offset:6144
	ds_read_b128 v[144:147], v110 offset:22528
	s_waitcnt vmcnt(0)
	s_waitcnt vmcnt(0) lgkmcnt(0)
	v_mfma_f32_16x16x32_bf16 v[36:39], v[32:35], v[0:3], v[36:39]
	s_barrier
; DEVI f32x4 mfma16(bf16x8 a, bf16x8 b, f32x4 c) { return __builtin_amdgcn_mfma_f32_16x16x32_bf16(a, b, c, 0, 0, 0); }
; template <bool SWAP, class RP>
; DEVI void gemm_main(const int TIDX, const int BIDX, const int GDIM, f32x4 (&acc)[4][4], RP rowoff, const bf16_t* __restrict__ Bt, int ldb, int K, unsigned char* smem) {
;     ...
;   for (int kt = 0; kt < nk; ++kt) {
;     const int buf = kt & 1;
;     asm volatile("s_waitcnt vmcnt(0)" ::: "memory");
;     __syncthreads();
;     if (kt + 1 < nk) GM_STAGE(kt + 1, buf ^ 1);
;     const unsigned char* A = smem + buf * 32768 + (wr * 64 + li) * 128;
;     const unsigned char* B = smem + buf * 32768 + 16384 + (wc * 64 + li) * 128;
; #pragma unroll
;     for (int ks = 0; ks < 2; ++ks) {
;       const int po = (px ^ (ks * 4)) * 16;
;       bf16x8 af[4], bfr[4];
; #pragma unroll
;       for (int i = 0; i < 4; ++i) {
;         af[i] = *(const bf16x8*)(A + i * 2048 + po);
;         bfr[i] = *(const bf16x8*)(B + i * 2048 + po);
;       }
; #pragma unroll
;       for (int mi = 0; mi < 4; ++mi)
; #pragma unroll
;         for (int ni = 0; ni < 4; ++ni)
;           acc[mi][ni] = SWAP ? mfma16(bfr[ni], af[mi], acc[mi][ni]) : mfma16(af[mi], bfr[ni], acc[mi][ni]);
	v_mfma_f32_16x16x32_bf16 v[40:43], v[124:127], v[0:3], v[40:43]
	v_mfma_f32_16x16x32_bf16 v[44:47], v[136:139], v[0:3], v[44:47]
	v_mfma_f32_16x16x32_bf16 v[148:151], v[144:147], v[0:3], v[4:7]
	v_mfma_f32_16x16x32_bf16 v[0:3], v[136:139], v[140:143], v[24:27]
	s_nop 2
	v_lshl_add_u64 v[24:25], v[64:65], 0, vcc
	global_load_lds_dwordx4 v[24:25], off
	v_lshl_add_u64 v[24:25], v[68:69], 0, vcc
	s_mov_b32 m0, s45
	v_mfma_f32_16x16x32_bf16 v[112:115], v[124:127], v[132:135], v[112:115]
	global_load_lds_dwordx4 v[24:25], off
	v_lshl_add_u64 v[24:25], v[70:71], 0, vcc
	s_mov_b32 m0, s46
	v_mfma_f32_16x16x32_bf16 v[48:51], v[32:35], v[120:123], v[48:51]
	global_load_lds_dwordx4 v[24:25], off
	v_lshl_add_u64 v[24:25], v[72:73], 0, vcc
	s_mov_b32 m0, s47
	v_mfma_f32_16x16x32_bf16 v[52:55], v[124:127], v[120:123], v[52:55]
	global_load_lds_dwordx4 v[24:25], off
	v_lshl_add_u64 v[24:25], v[66:67], 0, vcc
	s_mov_b32 m0, s54
	s_mov_b64 vcc, 0x8100
	global_load_lds_dwordx4 v[24:25], off
	v_lshl_add_u64 v[24:25], v[66:67], 0, vcc
	s_mov_b32 m0, s62
	s_mov_b64 vcc, 0x10100
	global_load_lds_dwordx4 v[24:25], off
	v_lshl_add_u64 v[24:25], v[66:67], 0, vcc
	s_mov_b32 m0, s63
	s_mov_b64 vcc, 0x18100
	global_load_lds_dwordx4 v[24:25], off
	v_lshl_add_u64 v[24:25], v[66:67], 0, vcc
	s_mov_b32 m0, s76
	v_mfma_f32_16x16x32_bf16 v[56:59], v[136:139], v[120:123], v[56:59]
	global_load_lds_dwordx4 v[24:25], off
	s_mov_b64 vcc, 0x180
	v_mfma_f32_16x16x32_bf16 v[12:15], v[144:147], v[120:123], v[12:15]
	s_mov_b32 m0, s0
	v_mfma_f32_16x16x32_bf16 v[60:63], v[32:35], v[132:135], v[60:63]
	v_mfma_f32_16x16x32_bf16 v[116:119], v[136:139], v[132:135], v[116:119]
	v_mfma_f32_16x16x32_bf16 v[20:23], v[144:147], v[132:135], v[20:23]
	v_mfma_f32_16x16x32_bf16 v[8:11], v[32:35], v[140:143], v[8:11]
	v_mfma_f32_16x16x32_bf16 v[16:19], v[124:127], v[140:143], v[16:19]
	v_mfma_f32_16x16x32_bf16 v[4:7], v[144:147], v[140:143], v[28:31]
	ds_read_b128 v[24:27], v109 offset:32768
	s_nop 1
	ds_read_b128 v[28:31], v111 offset:49152
	ds_read_b128 v[32:35], v109 offset:34816
	ds_read_b128 v[120:123], v111 offset:51200
	ds_read_b128 v[124:127], v109 offset:36864
	ds_read_b128 v[132:135], v111 offset:53248
	ds_read_b128 v[136:139], v109 offset:38912
	ds_read_b128 v[140:143], v111 offset:55296
	s_waitcnt lgkmcnt(0)
	v_mfma_f32_16x16x32_bf16 v[112:115], v[120:123], v[124:127], v[112:115]
	v_mfma_f32_16x16x32_bf16 v[40:43], v[120:123], v[24:27], v[40:43]
	v_mfma_f32_16x16x32_bf16 v[44:47], v[132:135], v[24:27], v[44:47]
	v_mfma_f32_16x16x32_bf16 v[144:147], v[140:143], v[24:27], v[148:151]
	v_mfma_f32_16x16x32_bf16 v[152:155], v[120:123], v[32:35], v[52:55]
	v_mfma_f32_16x16x32_bf16 v[56:59], v[132:135], v[32:35], v[56:59]
	v_mfma_f32_16x16x32_bf16 v[12:15], v[140:143], v[32:35], v[12:15]
	v_mfma_f32_16x16x32_bf16 v[60:63], v[28:31], v[124:127], v[60:63]
	v_mfma_f32_16x16x32_bf16 v[116:119], v[132:135], v[124:127], v[116:119]
	v_mfma_f32_16x16x32_bf16 v[20:23], v[140:143], v[124:127], v[20:23]
	v_mfma_f32_16x16x32_bf16 v[8:11], v[28:31], v[136:139], v[8:11]
	v_mfma_f32_16x16x32_bf16 v[120:123], v[120:123], v[136:139], v[16:19]
	v_mfma_f32_16x16x32_bf16 v[124:127], v[132:135], v[136:139], v[0:3]
	v_mfma_f32_16x16x32_bf16 v[132:135], v[140:143], v[136:139], v[4:7]
	s_nop 1
	ds_read_b128 v[0:3], v108 offset:32768
	ds_read_b128 v[136:139], v110 offset:49152
	ds_read_b128 v[4:7], v108 offset:34816
	ds_read_b128 v[140:143], v110 offset:51200
	ds_read_b128 v[156:159], v108 offset:36864
	ds_read_b128 v[162:165], v110 offset:53248
	ds_read_b128 v[166:169], v108 offset:38912
	ds_read_b128 v[170:173], v110 offset:55296
	s_waitcnt vmcnt(0)
	s_waitcnt vmcnt(0) lgkmcnt(0)
	v_mfma_f32_16x16x32_bf16 v[16:19], v[140:143], v[156:159], v[112:115]
	s_barrier
	s_nop 1
	v_lshl_add_u64 v[112:113], v[64:65], 0, vcc
	global_load_lds_dwordx4 v[112:113], off
	v_lshl_add_u64 v[112:113], v[68:69], 0, vcc
	s_mov_b32 m0, s1
	v_mfma_f32_16x16x32_bf16 v[36:39], v[28:31], v[24:27], v[36:39]
	global_load_lds_dwordx4 v[112:113], off
	v_lshl_add_u64 v[112:113], v[70:71], 0, vcc
	s_mov_b32 m0, s14
	v_mfma_f32_16x16x32_bf16 v[148:151], v[28:31], v[32:35], v[48:51]
	global_load_lds_dwordx4 v[112:113], off
	v_lshl_add_u64 v[112:113], v[72:73], 0, vcc
	s_mov_b32 m0, s15
	v_mfma_f32_16x16x32_bf16 v[48:51], v[136:139], v[0:3], v[36:39]
	global_load_lds_dwordx4 v[112:113], off
	v_lshl_add_u64 v[112:113], v[66:67], 0, vcc
	s_mov_b32 m0, s40
	s_mov_b64 vcc, 0x8180
	global_load_lds_dwordx4 v[112:113], off
	v_lshl_add_u64 v[112:113], v[66:67], 0, vcc
	s_mov_b32 m0, s41
	s_mov_b64 vcc, 0x10180
	global_load_lds_dwordx4 v[112:113], off
	v_lshl_add_u64 v[112:113], v[66:67], 0, vcc
	s_mov_b32 m0, s42
	s_mov_b64 vcc, 0x18180
	global_load_lds_dwordx4 v[112:113], off
	v_lshl_add_u64 v[112:113], v[66:67], 0, vcc
	s_mov_b32 m0, s43
	v_mfma_f32_16x16x32_bf16 v[24:27], v[140:143], v[0:3], v[40:43]
	global_load_lds_dwordx4 v[112:113], off
	s_mov_b64 vcc, 0x200
	v_mfma_f32_16x16x32_bf16 v[28:31], v[162:165], v[0:3], v[44:47]
	s_mov_b32 m0, s44
	v_mfma_f32_16x16x32_bf16 v[32:35], v[170:173], v[0:3], v[144:147]
	v_mfma_f32_16x16x32_bf16 v[52:55], v[136:139], v[4:7], v[148:151]
	v_mfma_f32_16x16x32_bf16 v[36:39], v[140:143], v[4:7], v[152:155]
	v_mfma_f32_16x16x32_bf16 v[40:43], v[162:165], v[4:7], v[56:59]
	v_mfma_f32_16x16x32_bf16 v[44:47], v[170:173], v[4:7], v[12:15]
	v_mfma_f32_16x16x32_bf16 v[12:15], v[136:139], v[156:159], v[60:63]
	v_mfma_f32_16x16x32_bf16 v[0:3], v[162:165], v[156:159], v[116:119]
	v_mfma_f32_16x16x32_bf16 v[4:7], v[170:173], v[156:159], v[20:23]
	v_mfma_f32_16x16x32_bf16 v[8:11], v[136:139], v[166:169], v[8:11]
	v_mfma_f32_16x16x32_bf16 v[20:23], v[140:143], v[166:169], v[120:123]
	v_mfma_f32_16x16x32_bf16 v[56:59], v[162:165], v[166:169], v[124:127]
	v_mfma_f32_16x16x32_bf16 v[60:63], v[170:173], v[166:169], v[132:135]
	ds_read_b128 v[112:115], v109
	ds_read_b128 v[116:119], v111 offset:16384
	ds_read_b128 v[120:123], v109 offset:2048
	ds_read_b128 v[124:127], v111 offset:18432
	ds_read_b128 v[132:135], v109 offset:4096
	ds_read_b128 v[136:139], v111 offset:20480
	ds_read_b128 v[140:143], v109 offset:6144
	ds_read_b128 v[144:147], v111 offset:22528
	s_waitcnt lgkmcnt(0)
; DEVI f32x4 mfma16(bf16x8 a, bf16x8 b, f32x4 c) { return __builtin_amdgcn_mfma_f32_16x16x32_bf16(a, b, c, 0, 0, 0); }
; template <bool SWAP, class RP>
; DEVI void gemm_main(const int TIDX, const int BIDX, const int GDIM, f32x4 (&acc)[4][4], RP rowoff, const bf16_t* __restrict__ Bt, int ldb, int K, unsigned char* smem) {
;     ...
;   for (int kt = 0; kt < nk; ++kt) {
;     const int buf = kt & 1;
;     asm volatile("s_waitcnt vmcnt(0)" ::: "memory");
;     __syncthreads();
;     if (kt + 1 < nk) GM_STAGE(kt + 1, buf ^ 1);
;     const unsigned char* A = smem + buf * 32768 + (wr * 64 + li) * 128;
;     const unsigned char* B = smem + buf * 32768 + 16384 + (wc * 64 + li) * 128;
; #pragma unroll
;     for (int ks = 0; ks < 2; ++ks) {
;       const int po = (px ^ (ks * 4)) * 16;
;       bf16x8 af[4], bfr[4];
; #pragma unroll
;       for (int i = 0; i < 4; ++i) {
;         af[i] = *(const bf16x8*)(A + i * 2048 + po);
;         bfr[i] = *(const bf16x8*)(B + i * 2048 + po);
;       }
; #pragma unroll
;       for (int mi = 0; mi < 4; ++mi)
; #pragma unroll
;         for (int ni = 0; ni < 4; ++ni)
;           acc[mi][ni] = SWAP ? mfma16(bfr[ni], af[mi], acc[mi][ni]) : mfma16(af[mi], bfr[ni], acc[mi][ni]);
	v_mfma_f32_16x16x32_bf16 v[48:51], v[116:119], v[112:115], v[48:51]
	v_mfma_f32_16x16x32_bf16 v[24:27], v[124:127], v[112:115], v[24:27]
	v_mfma_f32_16x16x32_bf16 v[28:31], v[136:139], v[112:115], v[28:31]
	v_mfma_f32_16x16x32_bf16 v[32:35], v[144:147], v[112:115], v[32:35]
	v_mfma_f32_16x16x32_bf16 v[52:55], v[116:119], v[120:123], v[52:55]
	v_mfma_f32_16x16x32_bf16 v[36:39], v[124:127], v[120:123], v[36:39]
	v_mfma_f32_16x16x32_bf16 v[40:43], v[136:139], v[120:123], v[40:43]
	v_mfma_f32_16x16x32_bf16 v[44:47], v[144:147], v[120:123], v[44:47]
	v_mfma_f32_16x16x32_bf16 v[12:15], v[116:119], v[132:135], v[12:15]
	v_mfma_f32_16x16x32_bf16 v[16:19], v[124:127], v[132:135], v[16:19]
	v_mfma_f32_16x16x32_bf16 v[0:3], v[136:139], v[132:135], v[0:3]
	v_mfma_f32_16x16x32_bf16 v[4:7], v[144:147], v[132:135], v[4:7]
	v_mfma_f32_16x16x32_bf16 v[8:11], v[116:119], v[140:143], v[8:11]
	v_mfma_f32_16x16x32_bf16 v[20:23], v[124:127], v[140:143], v[20:23]
	v_mfma_f32_16x16x32_bf16 v[56:59], v[136:139], v[140:143], v[56:59]
	v_mfma_f32_16x16x32_bf16 v[60:63], v[144:147], v[140:143], v[60:63]
	ds_read_b128 v[112:115], v108
	ds_read_b128 v[116:119], v110 offset:16384
	ds_read_b128 v[120:123], v108 offset:2048
	ds_read_b128 v[124:127], v110 offset:18432
	ds_read_b128 v[132:135], v108 offset:4096
	ds_read_b128 v[136:139], v110 offset:20480
	ds_read_b128 v[140:143], v108 offset:6144
	ds_read_b128 v[144:147], v110 offset:22528
	s_waitcnt vmcnt(0)
	s_waitcnt vmcnt(0) lgkmcnt(0)
	v_mfma_f32_16x16x32_bf16 v[48:51], v[116:119], v[112:115], v[48:51]
	s_barrier
	v_mfma_f32_16x16x32_bf16 v[24:27], v[124:127], v[112:115], v[24:27]
	v_mfma_f32_16x16x32_bf16 v[28:31], v[136:139], v[112:115], v[28:31]
	v_mfma_f32_16x16x32_bf16 v[32:35], v[144:147], v[112:115], v[32:35]
	v_mfma_f32_16x16x32_bf16 v[112:115], v[136:139], v[132:135], v[0:3]
	v_mfma_f32_16x16x32_bf16 v[0:3], v[136:139], v[140:143], v[56:59]
	s_nop 2
	v_lshl_add_u64 v[56:57], v[64:65], 0, vcc
	global_load_lds_dwordx4 v[56:57], off
	v_lshl_add_u64 v[56:57], v[68:69], 0, vcc
	s_mov_b32 m0, s45
	v_mfma_f32_16x16x32_bf16 v[52:55], v[116:119], v[120:123], v[52:55]
	global_load_lds_dwordx4 v[56:57], off
	v_lshl_add_u64 v[56:57], v[70:71], 0, vcc
	s_mov_b32 m0, s46
	v_mfma_f32_16x16x32_bf16 v[36:39], v[124:127], v[120:123], v[36:39]
	global_load_lds_dwordx4 v[56:57], off
	v_lshl_add_u64 v[56:57], v[72:73], 0, vcc
	s_mov_b32 m0, s47
	v_mfma_f32_16x16x32_bf16 v[40:43], v[136:139], v[120:123], v[40:43]
	global_load_lds_dwordx4 v[56:57], off
	v_lshl_add_u64 v[56:57], v[66:67], 0, vcc
	s_mov_b32 m0, s54
	s_mov_b64 vcc, 0x8200
	global_load_lds_dwordx4 v[56:57], off
	v_lshl_add_u64 v[56:57], v[66:67], 0, vcc
	s_mov_b32 m0, s62
	s_mov_b64 vcc, 0x10200
	global_load_lds_dwordx4 v[56:57], off
	v_lshl_add_u64 v[56:57], v[66:67], 0, vcc
	s_mov_b32 m0, s63
	s_mov_b64 vcc, 0x18200
	global_load_lds_dwordx4 v[56:57], off
	v_lshl_add_u64 v[56:57], v[66:67], 0, vcc
	s_mov_b32 m0, s76
	v_mfma_f32_16x16x32_bf16 v[44:47], v[144:147], v[120:123], v[44:47]
	global_load_lds_dwordx4 v[56:57], off
	s_mov_b64 vcc, 0x280
	v_mfma_f32_16x16x32_bf16 v[12:15], v[116:119], v[132:135], v[12:15]
	s_mov_b32 m0, s0
	v_mfma_f32_16x16x32_bf16 v[16:19], v[124:127], v[132:135], v[16:19]
	v_mfma_f32_16x16x32_bf16 v[120:123], v[144:147], v[132:135], v[4:7]
	v_mfma_f32_16x16x32_bf16 v[8:11], v[116:119], v[140:143], v[8:11]
	v_mfma_f32_16x16x32_bf16 v[20:23], v[124:127], v[140:143], v[20:23]
	v_mfma_f32_16x16x32_bf16 v[4:7], v[144:147], v[140:143], v[60:63]
	ds_read_b128 v[56:59], v109 offset:32768
	s_nop 1
	ds_read_b128 v[60:63], v111 offset:49152
	ds_read_b128 v[116:119], v109 offset:34816
	ds_read_b128 v[124:127], v111 offset:51200
	ds_read_b128 v[132:135], v109 offset:36864
	ds_read_b128 v[136:139], v111 offset:53248
	ds_read_b128 v[140:143], v109 offset:38912
	ds_read_b128 v[144:147], v111 offset:55296
	s_waitcnt lgkmcnt(0)
	v_mfma_f32_16x16x32_bf16 v[48:51], v[60:63], v[56:59], v[48:51]
	v_mfma_f32_16x16x32_bf16 v[24:27], v[124:127], v[56:59], v[24:27]
	v_mfma_f32_16x16x32_bf16 v[28:31], v[136:139], v[56:59], v[28:31]
	v_mfma_f32_16x16x32_bf16 v[32:35], v[144:147], v[56:59], v[32:35]
	v_mfma_f32_16x16x32_bf16 v[52:55], v[60:63], v[116:119], v[52:55]
	v_mfma_f32_16x16x32_bf16 v[56:59], v[124:127], v[116:119], v[36:39]
	v_mfma_f32_16x16x32_bf16 v[148:151], v[136:139], v[116:119], v[40:43]
	v_mfma_f32_16x16x32_bf16 v[116:119], v[144:147], v[116:119], v[44:47]
	v_mfma_f32_16x16x32_bf16 v[12:15], v[60:63], v[132:135], v[12:15]
	v_mfma_f32_16x16x32_bf16 v[16:19], v[124:127], v[132:135], v[16:19]
	v_mfma_f32_16x16x32_bf16 v[112:115], v[136:139], v[132:135], v[112:115]
	v_mfma_f32_16x16x32_bf16 v[120:123], v[144:147], v[132:135], v[120:123]
	v_mfma_f32_16x16x32_bf16 v[60:63], v[60:63], v[140:143], v[8:11]
	v_mfma_f32_16x16x32_bf16 v[20:23], v[124:127], v[140:143], v[20:23]
	v_mfma_f32_16x16x32_bf16 v[124:127], v[136:139], v[140:143], v[0:3]
	v_mfma_f32_16x16x32_bf16 v[132:135], v[144:147], v[140:143], v[4:7]
	s_nop 1
	ds_read_b128 v[0:3], v108 offset:32768
	ds_read_b128 v[4:7], v110 offset:49152
	ds_read_b128 v[8:11], v108 offset:34816
	ds_read_b128 v[136:139], v110 offset:51200
	ds_read_b128 v[140:143], v108 offset:36864
	ds_read_b128 v[144:147], v110 offset:53248
	ds_read_b128 v[152:155], v108 offset:38912
	ds_read_b128 v[156:159], v110 offset:55296
	s_waitcnt vmcnt(0)
	s_waitcnt vmcnt(0) lgkmcnt(0)
	v_mfma_f32_16x16x32_bf16 v[162:165], v[4:7], v[0:3], v[48:51]
	s_barrier
; DEVI f32x4 mfma16(bf16x8 a, bf16x8 b, f32x4 c) { return __builtin_amdgcn_mfma_f32_16x16x32_bf16(a, b, c, 0, 0, 0); }
; template <bool SWAP, class RP>
; DEVI void gemm_main(const int TIDX, const int BIDX, const int GDIM, f32x4 (&acc)[4][4], RP rowoff, const bf16_t* __restrict__ Bt, int ldb, int K, unsigned char* smem) {
;     ...
;   for (int kt = 0; kt < nk; ++kt) {
;     const int buf = kt & 1;
;     asm volatile("s_waitcnt vmcnt(0)" ::: "memory");
;     __syncthreads();
;     if (kt + 1 < nk) GM_STAGE(kt + 1, buf ^ 1);
;     const unsigned char* A = smem + buf * 32768 + (wr * 64 + li) * 128;
;     const unsigned char* B = smem + buf * 32768 + 16384 + (wc * 64 + li) * 128;
; #pragma unroll
;     for (int ks = 0; ks < 2; ++ks) {
;       const int po = (px ^ (ks * 4)) * 16;
;       bf16x8 af[4], bfr[4];
; #pragma unroll
;       for (int i = 0; i < 4; ++i) {
;         af[i] = *(const bf16x8*)(A + i * 2048 + po);
;         bfr[i] = *(const bf16x8*)(B + i * 2048 + po);
;       }
; #pragma unroll
;       for (int mi = 0; mi < 4; ++mi)
; #pragma unroll
;         for (int ni = 0; ni < 4; ++ni)
;           acc[mi][ni] = SWAP ? mfma16(bfr[ni], af[mi], acc[mi][ni]) : mfma16(af[mi], bfr[ni], acc[mi][ni]);
	v_mfma_f32_16x16x32_bf16 v[40:43], v[4:7], v[8:11], v[52:55]
	v_mfma_f32_16x16x32_bf16 v[12:15], v[4:7], v[140:143], v[12:15]
	v_mfma_f32_16x16x32_bf16 v[4:7], v[4:7], v[152:155], v[60:63]
	s_nop 2
	v_lshl_add_u64 v[60:61], v[64:65], 0, vcc
	global_load_lds_dwordx4 v[60:61], off
	v_lshl_add_u64 v[60:61], v[68:69], 0, vcc
	s_mov_b32 m0, s1
	v_mfma_f32_16x16x32_bf16 v[48:51], v[136:139], v[0:3], v[24:27]
	global_load_lds_dwordx4 v[60:61], off
	v_lshl_add_u64 v[60:61], v[70:71], 0, vcc
	s_mov_b32 m0, s14
	v_mfma_f32_16x16x32_bf16 v[44:47], v[144:147], v[0:3], v[28:31]
	global_load_lds_dwordx4 v[60:61], off
	v_lshl_add_u64 v[60:61], v[72:73], 0, vcc
	s_mov_b32 m0, s15
	v_mfma_f32_16x16x32_bf16 v[36:39], v[156:159], v[0:3], v[32:35]
	global_load_lds_dwordx4 v[60:61], off
	v_lshl_add_u64 v[60:61], v[66:67], 0, vcc
	s_mov_b32 m0, s40
	s_mov_b64 vcc, 0x8280
	global_load_lds_dwordx4 v[60:61], off
	v_lshl_add_u64 v[60:61], v[66:67], 0, vcc
	s_mov_b32 m0, s41
	s_mov_b64 vcc, 0x10280
	global_load_lds_dwordx4 v[60:61], off
	v_lshl_add_u64 v[60:61], v[66:67], 0, vcc
	s_mov_b32 m0, s42
	s_mov_b64 vcc, 0x18280
	global_load_lds_dwordx4 v[60:61], off
	v_lshl_add_u64 v[60:61], v[66:67], 0, vcc
	s_mov_b32 m0, s43
	v_mfma_f32_16x16x32_bf16 v[32:35], v[136:139], v[8:11], v[56:59]
	global_load_lds_dwordx4 v[60:61], off
	s_mov_b64 vcc, 0x300
	v_mfma_f32_16x16x32_bf16 v[28:31], v[144:147], v[8:11], v[148:151]
	s_mov_b32 m0, s44
	v_mfma_f32_16x16x32_bf16 v[24:27], v[156:159], v[8:11], v[116:119]
	v_mfma_f32_16x16x32_bf16 v[16:19], v[136:139], v[140:143], v[16:19]
	v_mfma_f32_16x16x32_bf16 v[8:11], v[144:147], v[140:143], v[112:115]
	v_mfma_f32_16x16x32_bf16 v[0:3], v[156:159], v[140:143], v[120:123]
	v_mfma_f32_16x16x32_bf16 v[20:23], v[136:139], v[152:155], v[20:23]
	v_mfma_f32_16x16x32_bf16 v[52:55], v[144:147], v[152:155], v[124:127]
	v_mfma_f32_16x16x32_bf16 v[56:59], v[156:159], v[152:155], v[132:135]
	ds_read_b128 v[60:63], v109
	ds_read_b128 v[112:115], v111 offset:16384
	ds_read_b128 v[116:119], v109 offset:2048
	ds_read_b128 v[120:123], v111 offset:18432
	ds_read_b128 v[124:127], v109 offset:4096
	ds_read_b128 v[132:135], v111 offset:20480
	ds_read_b128 v[136:139], v109 offset:6144
	ds_read_b128 v[140:143], v111 offset:22528
	s_waitcnt lgkmcnt(0)
	v_mfma_f32_16x16x32_bf16 v[144:147], v[112:115], v[60:63], v[162:165]
	v_mfma_f32_16x16x32_bf16 v[48:51], v[120:123], v[60:63], v[48:51]
	v_mfma_f32_16x16x32_bf16 v[148:151], v[132:135], v[60:63], v[44:47]
	v_mfma_f32_16x16x32_bf16 v[36:39], v[140:143], v[60:63], v[36:39]
	v_mfma_f32_16x16x32_bf16 v[40:43], v[112:115], v[116:119], v[40:43]
	v_mfma_f32_16x16x32_bf16 v[32:35], v[120:123], v[116:119], v[32:35]
	v_mfma_f32_16x16x32_bf16 v[28:31], v[132:135], v[116:119], v[28:31]
	v_mfma_f32_16x16x32_bf16 v[24:27], v[140:143], v[116:119], v[24:27]
	v_mfma_f32_16x16x32_bf16 v[12:15], v[112:115], v[124:127], v[12:15]
	v_mfma_f32_16x16x32_bf16 v[60:63], v[120:123], v[124:127], v[16:19]
	v_mfma_f32_16x16x32_bf16 v[116:119], v[132:135], v[124:127], v[8:11]
	v_mfma_f32_16x16x32_bf16 v[0:3], v[140:143], v[124:127], v[0:3]
	v_mfma_f32_16x16x32_bf16 v[4:7], v[112:115], v[136:139], v[4:7]
	v_mfma_f32_16x16x32_bf16 v[112:115], v[120:123], v[136:139], v[20:23]
	v_mfma_f32_16x16x32_bf16 v[120:123], v[132:135], v[136:139], v[52:55]
	v_mfma_f32_16x16x32_bf16 v[56:59], v[140:143], v[136:139], v[56:59]
	ds_read_b128 v[8:11], v108
	ds_read_b128 v[124:127], v110 offset:16384
	ds_read_b128 v[20:23], v108 offset:2048
	ds_read_b128 v[132:135], v110 offset:18432
	ds_read_b128 v[136:139], v108 offset:4096
	ds_read_b128 v[140:143], v110 offset:20480
	ds_read_b128 v[152:155], v108 offset:6144
	ds_read_b128 v[156:159], v110 offset:22528
	s_waitcnt vmcnt(0)
	s_waitcnt vmcnt(0) lgkmcnt(0)
	v_mfma_f32_16x16x32_bf16 v[44:47], v[132:135], v[8:11], v[48:51]
	s_barrier
	v_mfma_f32_16x16x32_bf16 v[48:51], v[132:135], v[20:23], v[32:35]
	v_mfma_f32_16x16x32_bf16 v[32:35], v[140:143], v[20:23], v[28:31]
	v_mfma_f32_16x16x32_bf16 v[28:31], v[124:127], v[152:155], v[4:7]
	v_mfma_f32_16x16x32_bf16 v[4:7], v[156:159], v[152:155], v[56:59]
	s_nop 2
	v_lshl_add_u64 v[56:57], v[64:65], 0, vcc
	global_load_lds_dwordx4 v[56:57], off
	v_lshl_add_u64 v[56:57], v[68:69], 0, vcc
	s_mov_b32 m0, s45
	s_mov_b64 s[44:45], 0x8300
	global_load_lds_dwordx4 v[56:57], off
	v_lshl_add_u64 v[56:57], v[70:71], 0, vcc
	s_mov_b32 m0, s46
	v_mfma_f32_16x16x32_bf16 v[144:147], v[124:127], v[8:11], v[144:147]
	global_load_lds_dwordx4 v[56:57], off
	v_lshl_add_u64 v[56:57], v[72:73], 0, vcc
	s_mov_b32 m0, s47
	v_mfma_f32_16x16x32_bf16 v[148:151], v[140:143], v[8:11], v[148:151]
	global_load_lds_dwordx4 v[56:57], off
	v_lshl_add_u64 v[56:57], v[66:67], 0, vcc
	s_mov_b32 m0, s54
	v_mfma_f32_16x16x32_bf16 v[16:19], v[156:159], v[8:11], v[36:39]
	global_load_lds_dwordx4 v[56:57], off
	v_lshl_add_u64 v[56:57], v[66:67], 0, s[44:45]
	s_mov_b32 m0, s62
	s_mov_b64 s[44:45], 0x10300
	global_load_lds_dwordx4 v[56:57], off
	v_lshl_add_u64 v[56:57], v[66:67], 0, s[44:45]
	s_mov_b32 m0, s63
	s_mov_b64 s[44:45], 0x18300
	global_load_lds_dwordx4 v[56:57], off
	v_lshl_add_u64 v[56:57], v[66:67], 0, s[44:45]
	s_mov_b32 m0, s76
	v_mfma_f32_16x16x32_bf16 v[52:55], v[124:127], v[20:23], v[40:43]
	global_load_lds_dwordx4 v[56:57], off
	s_mov_b64 s[44:45], 0x380
	v_mfma_f32_16x16x32_bf16 v[36:39], v[156:159], v[20:23], v[24:27]
	v_lshl_add_u64 v[64:65], v[64:65], 0, s[44:45]
	s_mov_b32 m0, s0
	v_mfma_f32_16x16x32_bf16 v[8:11], v[124:127], v[136:139], v[12:15]
	v_mfma_f32_16x16x32_bf16 v[40:43], v[132:135], v[136:139], v[60:63]
	v_mfma_f32_16x16x32_bf16 v[20:23], v[140:143], v[136:139], v[116:119]
	v_mfma_f32_16x16x32_bf16 v[24:27], v[156:159], v[136:139], v[0:3]
	v_mfma_f32_16x16x32_bf16 v[12:15], v[132:135], v[152:155], v[112:115]
	v_mfma_f32_16x16x32_bf16 v[0:3], v[140:143], v[152:155], v[120:123]
	ds_read_b128 v[56:59], v109 offset:32768
	ds_read_b128 v[60:63], v111 offset:49152
	ds_read_b128 v[112:115], v109 offset:34816
	ds_read_b128 v[116:119], v111 offset:51200
	ds_read_b128 v[120:123], v109 offset:36864
	ds_read_b128 v[124:127], v111 offset:53248
	ds_read_b128 v[132:135], v109 offset:38912
	ds_read_b128 v[136:139], v111 offset:55296
	s_waitcnt lgkmcnt(0)
; DEVI f32x4 mfma16(bf16x8 a, bf16x8 b, f32x4 c) { return __builtin_amdgcn_mfma_f32_16x16x32_bf16(a, b, c, 0, 0, 0); }
; template <bool SWAP, class RP>
; DEVI void gemm_main(const int TIDX, const int BIDX, const int GDIM, f32x4 (&acc)[4][4], RP rowoff, const bf16_t* __restrict__ Bt, int ldb, int K, unsigned char* smem) {
;     ...
;   for (int kt = 0; kt < nk; ++kt) {
;     const int buf = kt & 1;
;     asm volatile("s_waitcnt vmcnt(0)" ::: "memory");
;     __syncthreads();
;     if (kt + 1 < nk) GM_STAGE(kt + 1, buf ^ 1);
;     const unsigned char* A = smem + buf * 32768 + (wr * 64 + li) * 128;
;     const unsigned char* B = smem + buf * 32768 + 16384 + (wc * 64 + li) * 128;
; #pragma unroll
;     for (int ks = 0; ks < 2; ++ks) {
;       const int po = (px ^ (ks * 4)) * 16;
;       bf16x8 af[4], bfr[4];
; #pragma unroll
;       for (int i = 0; i < 4; ++i) {
;         af[i] = *(const bf16x8*)(A + i * 2048 + po);
;         bfr[i] = *(const bf16x8*)(B + i * 2048 + po);
;       }
; #pragma unroll
;       for (int mi = 0; mi < 4; ++mi)
; #pragma unroll
;         for (int ni = 0; ni < 4; ++ni)
;           acc[mi][ni] = SWAP ? mfma16(bfr[ni], af[mi], acc[mi][ni]) : mfma16(af[mi], bfr[ni], acc[mi][ni]);
	v_mfma_f32_16x16x32_bf16 v[140:143], v[60:63], v[56:59], v[144:147]
	v_mfma_f32_16x16x32_bf16 v[44:47], v[116:119], v[56:59], v[44:47]
	v_mfma_f32_16x16x32_bf16 v[144:147], v[124:127], v[56:59], v[148:151]
	v_mfma_f32_16x16x32_bf16 v[16:19], v[136:139], v[56:59], v[16:19]
	v_mfma_f32_16x16x32_bf16 v[52:55], v[60:63], v[112:115], v[52:55]
	v_mfma_f32_16x16x32_bf16 v[56:59], v[116:119], v[112:115], v[48:51]
	v_mfma_f32_16x16x32_bf16 v[148:151], v[124:127], v[112:115], v[32:35]
	v_mfma_f32_16x16x32_bf16 v[112:115], v[136:139], v[112:115], v[36:39]
	v_mfma_f32_16x16x32_bf16 v[8:11], v[60:63], v[120:123], v[8:11]
	v_mfma_f32_16x16x32_bf16 v[152:155], v[116:119], v[120:123], v[40:43]
	v_mfma_f32_16x16x32_bf16 v[156:159], v[124:127], v[120:123], v[20:23]
	v_mfma_f32_16x16x32_bf16 v[120:123], v[136:139], v[120:123], v[24:27]
	v_mfma_f32_16x16x32_bf16 v[162:165], v[60:63], v[132:135], v[28:31]
	v_mfma_f32_16x16x32_bf16 v[116:119], v[116:119], v[132:135], v[12:15]
	v_mfma_f32_16x16x32_bf16 v[124:127], v[124:127], v[132:135], v[0:3]
	v_mfma_f32_16x16x32_bf16 v[132:135], v[136:139], v[132:135], v[4:7]
	s_nop 1
	ds_read_b128 v[0:3], v108 offset:32768
	ds_read_b128 v[136:139], v110 offset:49152
	ds_read_b128 v[4:7], v108 offset:34816
	ds_read_b128 v[166:169], v110 offset:51200
	ds_read_b128 v[170:173], v108 offset:36864
	ds_read_b128 v[174:177], v110 offset:53248
	ds_read_b128 v[178:181], v108 offset:38912
	ds_read_b128 v[182:185], v110 offset:55296
	s_waitcnt vmcnt(0)
	s_waitcnt vmcnt(0) lgkmcnt(0)
	s_barrier
	global_load_lds_dwordx4 v[64:65], off
	v_lshl_add_u64 v[64:65], v[68:69], 0, s[44:45]
	s_mov_b32 m0, s1
	s_mov_b64 s[0:1], 0x8380
	global_load_lds_dwordx4 v[64:65], off
	v_lshl_add_u64 v[64:65], v[70:71], 0, s[44:45]
	s_mov_b32 m0, s14
	v_mfma_f32_16x16x32_bf16 v[60:63], v[136:139], v[0:3], v[140:143]
	global_load_lds_dwordx4 v[64:65], off
	v_lshl_add_u64 v[64:65], v[72:73], 0, s[44:45]
	s_mov_b32 m0, s15
	v_mfma_f32_16x16x32_bf16 v[24:27], v[182:185], v[0:3], v[16:19]
	global_load_lds_dwordx4 v[64:65], off
	v_lshl_add_u64 v[64:65], v[66:67], 0, s[44:45]
	s_mov_b32 m0, s40
	v_mfma_f32_16x16x32_bf16 v[48:51], v[136:139], v[4:7], v[52:55]
	global_load_lds_dwordx4 v[64:65], off
	v_lshl_add_u64 v[64:65], v[66:67], 0, s[0:1]
	s_mov_b32 m0, s41
	s_mov_b64 s[0:1], 0x10380
	global_load_lds_dwordx4 v[64:65], off
	v_lshl_add_u64 v[64:65], v[66:67], 0, s[0:1]
	s_mov_b32 m0, s42
	s_mov_b64 s[0:1], 0x18380
	global_load_lds_dwordx4 v[64:65], off
	v_lshl_add_u64 v[64:65], v[66:67], 0, s[0:1]
	s_mov_b32 m0, s43
	v_mfma_f32_16x16x32_bf16 v[28:31], v[166:169], v[4:7], v[56:59]
	global_load_lds_dwordx4 v[64:65], off
	v_mfma_f32_16x16x32_bf16 v[36:39], v[174:177], v[4:7], v[148:151]
	v_mfma_f32_16x16x32_bf16 v[40:43], v[182:185], v[4:7], v[112:115]
	v_mfma_f32_16x16x32_bf16 v[20:23], v[136:139], v[170:173], v[8:11]
	v_mfma_f32_16x16x32_bf16 v[4:7], v[182:185], v[170:173], v[120:123]
	v_mfma_f32_16x16x32_bf16 v[8:11], v[136:139], v[178:181], v[162:165]
	v_mfma_f32_16x16x32_bf16 v[16:19], v[166:169], v[178:181], v[116:119]
	v_mfma_f32_16x16x32_bf16 v[52:55], v[174:177], v[178:181], v[124:127]
	v_mfma_f32_16x16x32_bf16 v[56:59], v[182:185], v[178:181], v[132:135]
	ds_read_b128 v[64:67], v109
	ds_read_b128 v[68:71], v111 offset:16384
	ds_read_b128 v[112:115], v109 offset:2048
	ds_read_b128 v[116:119], v111 offset:18432
	ds_read_b128 v[120:123], v109 offset:4096
	ds_read_b128 v[124:127], v111 offset:20480
	ds_read_b128 v[132:135], v109 offset:6144
	ds_read_b128 v[136:139], v111 offset:22528
	v_mfma_f32_16x16x32_bf16 v[44:47], v[166:169], v[0:3], v[44:47]
	v_mfma_f32_16x16x32_bf16 v[32:35], v[174:177], v[0:3], v[144:147]
	v_mfma_f32_16x16x32_bf16 v[12:15], v[166:169], v[170:173], v[152:155]
	v_mfma_f32_16x16x32_bf16 v[0:3], v[174:177], v[170:173], v[156:159]
	s_waitcnt lgkmcnt(0)
	v_mfma_f32_16x16x32_bf16 v[60:63], v[68:71], v[64:67], v[60:63]
	v_mfma_f32_16x16x32_bf16 v[44:47], v[116:119], v[64:67], v[44:47]
	v_mfma_f32_16x16x32_bf16 v[32:35], v[124:127], v[64:67], v[32:35]
	v_mfma_f32_16x16x32_bf16 v[24:27], v[136:139], v[64:67], v[24:27]
	v_mfma_f32_16x16x32_bf16 v[48:51], v[68:71], v[112:115], v[48:51]
	v_mfma_f32_16x16x32_bf16 v[28:31], v[116:119], v[112:115], v[28:31]
	v_mfma_f32_16x16x32_bf16 v[36:39], v[124:127], v[112:115], v[36:39]
	v_mfma_f32_16x16x32_bf16 v[40:43], v[136:139], v[112:115], v[40:43]
	v_mfma_f32_16x16x32_bf16 v[20:23], v[68:71], v[120:123], v[20:23]
	v_mfma_f32_16x16x32_bf16 v[12:15], v[116:119], v[120:123], v[12:15]
	v_mfma_f32_16x16x32_bf16 v[0:3], v[124:127], v[120:123], v[0:3]
	v_mfma_f32_16x16x32_bf16 v[4:7], v[136:139], v[120:123], v[4:7]
	v_mfma_f32_16x16x32_bf16 v[8:11], v[68:71], v[132:135], v[8:11]
	v_mfma_f32_16x16x32_bf16 v[16:19], v[116:119], v[132:135], v[16:19]
	v_mfma_f32_16x16x32_bf16 v[52:55], v[124:127], v[132:135], v[52:55]
	v_mfma_f32_16x16x32_bf16 v[56:59], v[136:139], v[132:135], v[56:59]
	ds_read_b128 v[64:67], v108
	ds_read_b128 v[68:71], v110 offset:16384
	ds_read_b128 v[112:115], v108 offset:2048
	ds_read_b128 v[116:119], v110 offset:18432
	ds_read_b128 v[120:123], v108 offset:4096
	ds_read_b128 v[124:127], v110 offset:20480
	ds_read_b128 v[132:135], v108 offset:6144
	ds_read_b128 v[136:139], v110 offset:22528
	s_waitcnt vmcnt(0)
	s_waitcnt vmcnt(0) lgkmcnt(0)
	v_mfma_f32_16x16x32_bf16 v[60:63], v[68:71], v[64:67], v[60:63]
	s_barrier
; DEVI uint32_t pack2(float lo, float hi) { f32x2_t v = {lo, hi}; bf16x2_t b = __builtin_convertvector(v, bf16x2_t); return __builtin_bit_cast(uint32_t, b); }
; DEVI float lo2f(uint32_t u) { return __uint_as_float(u << 16); }
; DEVI float hi2f(uint32_t u) { return __uint_as_float(u & 0xffff0000u); }
; DEVI f32x4 mfma16(bf16x8 a, bf16x8 b, f32x4 c) { return __builtin_amdgcn_mfma_f32_16x16x32_bf16(a, b, c, 0, 0, 0); }
; #define EPI_END } __builtin_amdgcn_sched_barrier(0); } }
; template <bool SWAP, class RP>
; DEVI void gemm_main(const int TIDX, const int BIDX, const int GDIM, f32x4 (&acc)[4][4], RP rowoff, const bf16_t* __restrict__ Bt, int ldb, int K, unsigned char* smem) {
;     ...
;   for (int kt = 0; kt < nk; ++kt) {
;     const int buf = kt & 1;
;     asm volatile("s_waitcnt vmcnt(0)" ::: "memory");
;     __syncthreads();
;     if (kt + 1 < nk) GM_STAGE(kt + 1, buf ^ 1);
;     const unsigned char* A = smem + buf * 32768 + (wr * 64 + li) * 128;
;     const unsigned char* B = smem + buf * 32768 + 16384 + (wc * 64 + li) * 128;
; #pragma unroll
;     for (int ks = 0; ks < 2; ++ks) {
;       const int po = (px ^ (ks * 4)) * 16;
;       bf16x8 af[4], bfr[4];
; #pragma unroll
;       for (int i = 0; i < 4; ++i) {
;         af[i] = *(const bf16x8*)(A + i * 2048 + po);
;         bfr[i] = *(const bf16x8*)(B + i * 2048 + po);
;       }
; #pragma unroll
;       for (int mi = 0; mi < 4; ++mi)
; #pragma unroll
;         for (int ni = 0; ni < 4; ++ni)
;           acc[mi][ni] = SWAP ? mfma16(bfr[ni], af[mi], acc[mi][ni]) : mfma16(af[mi], bfr[ni], acc[mi][ni]);
;     }
;   }
;   __syncthreads();
; DEVI void phase_p5(const int TIDX, const int BIDX, const int GDIM, KAP KA, unsigned char* WSB, float* OUTB, int l, unsigned char* smem) {
;     ...
;     EPI_SWAP_BEGIN(m0, n0)
;       const f32x4 a = acc[mi][ni];
;       const uint2 g = gp[mi][ni];
;       *(uint2*)(MG + (size_t)row * 1024 + col) = make_uint2(pack2(a[0] * lo2f(g.x), a[1] * hi2f(g.x)), pack2(a[2] * lo2f(g.y), a[3] * hi2f(g.y)));
;     EPI_END
	v_mfma_f32_16x16x32_bf16 v[44:47], v[116:119], v[64:67], v[44:47]
	v_mfma_f32_16x16x32_bf16 v[32:35], v[124:127], v[64:67], v[32:35]
	v_mfma_f32_16x16x32_bf16 v[24:27], v[136:139], v[64:67], v[24:27]
	v_mfma_f32_16x16x32_bf16 v[48:51], v[68:71], v[112:115], v[48:51]
	v_mfma_f32_16x16x32_bf16 v[28:31], v[116:119], v[112:115], v[28:31]
	v_mfma_f32_16x16x32_bf16 v[36:39], v[124:127], v[112:115], v[36:39]
	v_mfma_f32_16x16x32_bf16 v[40:43], v[136:139], v[112:115], v[40:43]
	v_mfma_f32_16x16x32_bf16 v[20:23], v[68:71], v[120:123], v[20:23]
	v_mfma_f32_16x16x32_bf16 v[12:15], v[116:119], v[120:123], v[12:15]
	v_mfma_f32_16x16x32_bf16 v[0:3], v[124:127], v[120:123], v[0:3]
	v_mfma_f32_16x16x32_bf16 v[4:7], v[136:139], v[120:123], v[4:7]
	v_mfma_f32_16x16x32_bf16 v[8:11], v[68:71], v[132:135], v[8:11]
	v_mfma_f32_16x16x32_bf16 v[16:19], v[116:119], v[132:135], v[16:19]
	v_mfma_f32_16x16x32_bf16 v[52:55], v[124:127], v[132:135], v[52:55]
	v_mfma_f32_16x16x32_bf16 v[56:59], v[136:139], v[132:135], v[56:59]
	ds_read_b128 v[64:67], v109 offset:32768
	ds_read_b128 v[68:71], v111 offset:49152
	ds_read_b128 v[112:115], v109 offset:34816
	ds_read_b128 v[116:119], v111 offset:51200
	ds_read_b128 v[120:123], v109 offset:36864
	ds_read_b128 v[124:127], v111 offset:53248
	ds_read_b128 v[132:135], v109 offset:38912
	ds_read_b128 v[136:139], v111 offset:55296
	s_waitcnt lgkmcnt(6)
	v_mfma_f32_16x16x32_bf16 v[60:63], v[68:71], v[64:67], v[60:63]
	s_waitcnt lgkmcnt(4)
	v_mfma_f32_16x16x32_bf16 v[44:47], v[116:119], v[64:67], v[44:47]
	s_waitcnt lgkmcnt(2)
	v_mfma_f32_16x16x32_bf16 v[32:35], v[124:127], v[64:67], v[32:35]
	s_waitcnt lgkmcnt(0)
	v_mfma_f32_16x16x32_bf16 v[24:27], v[136:139], v[64:67], v[24:27]
	v_mfma_f32_16x16x32_bf16 v[48:51], v[68:71], v[112:115], v[48:51]
	v_mfma_f32_16x16x32_bf16 v[28:31], v[116:119], v[112:115], v[28:31]
	v_mfma_f32_16x16x32_bf16 v[36:39], v[124:127], v[112:115], v[36:39]
	v_mfma_f32_16x16x32_bf16 v[40:43], v[136:139], v[112:115], v[40:43]
	v_mfma_f32_16x16x32_bf16 v[20:23], v[68:71], v[120:123], v[20:23]
	v_mfma_f32_16x16x32_bf16 v[12:15], v[116:119], v[120:123], v[12:15]
	v_mfma_f32_16x16x32_bf16 v[0:3], v[124:127], v[120:123], v[0:3]
	v_mfma_f32_16x16x32_bf16 v[4:7], v[136:139], v[120:123], v[4:7]
	v_mfma_f32_16x16x32_bf16 v[8:11], v[68:71], v[132:135], v[8:11]
	v_mfma_f32_16x16x32_bf16 v[64:67], v[116:119], v[132:135], v[16:19]
	v_mfma_f32_16x16x32_bf16 v[52:55], v[124:127], v[132:135], v[52:55]
	v_mfma_f32_16x16x32_bf16 v[56:59], v[136:139], v[132:135], v[56:59]
	s_nop 0
	ds_read_b128 v[16:19], v108 offset:32768
	ds_read_b128 v[68:71], v110 offset:49152
	ds_read_b128 v[112:115], v108 offset:34816
	ds_read_b128 v[116:119], v110 offset:51200
	ds_read_b128 v[120:123], v108 offset:36864
	ds_read_b128 v[124:127], v110 offset:53248
	ds_read_b128 v[132:135], v108 offset:38912
	ds_read_b128 v[108:111], v110 offset:55296
	s_waitcnt lgkmcnt(0)
	s_barrier
	v_mfma_f32_16x16x32_bf16 v[136:139], v[124:127], v[16:19], v[32:35]
	v_mfma_f32_16x16x32_bf16 v[32:35], v[108:111], v[112:115], v[40:43]
	s_nop 2
	v_add_u32_e32 v40, s12, v82
	v_mfma_f32_16x16x32_bf16 v[44:47], v[116:119], v[16:19], v[44:47]
	v_ashrrev_i32_e32 v41, 31, v40
	v_lshlrev_b64 v[42:43], 11, v[40:41]
	v_lshl_add_u64 v[42:43], s[4:5], 0, v[42:43]
	v_mfma_f32_16x16x32_bf16 v[144:147], v[116:119], v[112:115], v[28:31]
	v_mfma_f32_16x16x32_bf16 v[28:31], v[68:71], v[120:123], v[20:23]
	v_mfma_f32_16x16x32_bf16 v[20:23], v[124:127], v[120:123], v[0:3]
	v_mfma_f32_16x16x32_bf16 v[0:3], v[108:111], v[132:135], v[56:59]
	s_nop 2
	v_or_b32_e32 v56, s38, v83
	v_lshlrev_b32_e32 v128, 1, v56
	v_mfma_f32_16x16x32_bf16 v[60:63], v[68:71], v[16:19], v[60:63]
	v_mfma_f32_16x16x32_bf16 v[140:143], v[108:111], v[16:19], v[24:27]
	v_mfma_f32_16x16x32_bf16 v[48:51], v[68:71], v[112:115], v[48:51]
	v_mfma_f32_16x16x32_bf16 v[24:27], v[116:119], v[120:123], v[12:15]
	v_mfma_f32_16x16x32_bf16 v[12:15], v[68:71], v[132:135], v[8:11]
	v_lshl_add_u64 v[70:71], v[42:43], 0, v[128:129]
	v_lshlrev_b32_e32 v42, 16, v76
	v_and_b32_e32 v43, 0xffff0000, v76
	v_pk_mul_f32 v[42:43], v[44:45], v[42:43]
	v_lshlrev_b32_e32 v44, 16, v77
	v_and_b32_e32 v45, 0xffff0000, v77
	v_pk_mul_f32 v[44:45], v[46:47], v[44:45]
	v_cvt_pk_bf16_f32 v42, v42, v43
	v_cvt_pk_bf16_f32 v43, v44, v45
	global_store_dwordx2 v[70:71], v[42:43], off offset:32
	v_lshlrev_b32_e32 v42, 16, v78
	v_and_b32_e32 v43, 0xffff0000, v78
	v_lshlrev_b32_e32 v44, 16, v79
	v_and_b32_e32 v45, 0xffff0000, v79
	v_pk_mul_f32 v[42:43], v[136:137], v[42:43]
	v_pk_mul_f32 v[44:45], v[138:139], v[44:45]
	v_mfma_f32_16x16x32_bf16 v[36:39], v[124:127], v[112:115], v[36:39]
	v_cvt_pk_bf16_f32 v42, v42, v43
	v_cvt_pk_bf16_f32 v43, v44, v45
	global_store_dwordx2 v[70:71], v[42:43], off offset:64
	v_mfma_f32_16x16x32_bf16 v[16:19], v[108:111], v[120:123], v[4:7]
	v_lshlrev_b32_e32 v42, 16, v80
	v_and_b32_e32 v43, 0xffff0000, v80
	v_lshlrev_b32_e32 v44, 16, v81
	v_mfma_f32_16x16x32_bf16 v[8:11], v[116:119], v[132:135], v[64:67]
	v_and_b32_e32 v45, 0xffff0000, v81
	v_pk_mul_f32 v[42:43], v[140:141], v[42:43]
	v_pk_mul_f32 v[44:45], v[142:143], v[44:45]
	v_mfma_f32_16x16x32_bf16 v[4:7], v[124:127], v[132:135], v[52:55]
	v_cvt_pk_bf16_f32 v42, v42, v43
	v_cvt_pk_bf16_f32 v43, v44, v45
	global_store_dwordx2 v[70:71], v[42:43], off offset:96
	v_lshlrev_b32_e32 v52, 16, v74
	v_and_b32_e32 v53, 0xffff0000, v74
	v_lshlrev_b32_e32 v54, 16, v75
	v_and_b32_e32 v55, 0xffff0000, v75
	v_pk_mul_f32 v[52:53], v[60:61], v[52:53]
	v_pk_mul_f32 v[54:55], v[62:63], v[54:55]
	v_cvt_pk_bf16_f32 v52, v52, v53
	v_cvt_pk_bf16_f32 v53, v54, v55
	global_store_dwordx2 v[70:71], v[52:53], off
; DEVI uint32_t pack2(float lo, float hi) { f32x2_t v = {lo, hi}; bf16x2_t b = __builtin_convertvector(v, bf16x2_t); return __builtin_bit_cast(uint32_t, b); }
; DEVI float lo2f(uint32_t u) { return __uint_as_float(u << 16); }
; DEVI float hi2f(uint32_t u) { return __uint_as_float(u & 0xffff0000u); }
; #define EPI_END } __builtin_amdgcn_sched_barrier(0); } }
; template <bool SWAP, class RP>
; DEVI void gemm_main(const int TIDX, const int BIDX, const int GDIM, f32x4 (&acc)[4][4], RP rowoff, const bf16_t* __restrict__ Bt, int ldb, int K, unsigned char* smem) {
;     ...
;   const int lane = tid & 63, w = tid >> 6, wr = w >> 1, wc = w & 1, li = lane & 15, lg = lane >> 4;
;   const unsigned char* abase = rowoff.base;
;   const unsigned char* bbase = (const unsigned char*)Bt;
;   const uint32_t schunk = (uint32_t)((lane & 7) ^ (((lane >> 4) + 4 * (w & 1)) & 7)) * 16u;
;   uint32_t ao0, ao1, ao2, ao3;
;   const int rsub = w * 8 + (lane >> 3);
;   ao0 = rowoff(rsub) + schunk; ao1 = rowoff(rsub + 32) + schunk; ao2 = rowoff(rsub + 64) + schunk; ao3 = rowoff(rsub + 96) + schunk;
;   const uint32_t bo = (uint32_t)(rsub * ldb) * 2u + schunk, bstep = (uint32_t)(32 * ldb) * 2u;
;   unsigned char* sbase = smem + w * 1024;
; DEVI void phase_p5(const int TIDX, const int BIDX, const int GDIM, KAP KA, unsigned char* WSB, float* OUTB, int l, unsigned char* smem) {
;     ...
;     EPI_SWAP_BEGIN(m0, n0)
;       const f32x4 a = acc[mi][ni];
;       const uint2 g = gp[mi][ni];
;       *(uint2*)(MG + (size_t)row * 1024 + col) = make_uint2(pack2(a[0] * lo2f(g.x), a[1] * hi2f(g.x)), pack2(a[2] * lo2f(g.y), a[3] * hi2f(g.y)));
;     EPI_END
;     zero_acc(acc);
;     gemm_main<true>(TIDX, BIDX, GDIM, acc, rx, W + WO_G + (size_t)(1024 + n0) * 1024, 1024, 1024, smem);
	v_or_b32_e32 v42, 16, v40
	v_ashrrev_i32_e32 v43, 31, v42
	v_lshlrev_b64 v[42:43], 11, v[42:43]
	v_lshlrev_b32_e32 v44, 16, v84
	v_and_b32_e32 v45, 0xffff0000, v84
	v_lshlrev_b32_e32 v46, 16, v85
	v_and_b32_e32 v47, 0xffff0000, v85
	v_lshl_add_u64 v[42:43], s[4:5], 0, v[42:43]
	v_pk_mul_f32 v[44:45], v[48:49], v[44:45]
	v_pk_mul_f32 v[46:47], v[50:51], v[46:47]
	v_cvt_pk_bf16_f32 v44, v44, v45
	v_cvt_pk_bf16_f32 v45, v46, v47
	v_lshl_add_u64 v[68:69], v[42:43], 0, v[128:129]
	global_store_dwordx2 v[68:69], v[44:45], off
	v_lshlrev_b32_e32 v42, 16, v86
	v_and_b32_e32 v43, 0xffff0000, v86
	v_lshlrev_b32_e32 v44, 16, v87
	v_and_b32_e32 v45, 0xffff0000, v87
	v_pk_mul_f32 v[42:43], v[144:145], v[42:43]
	v_pk_mul_f32 v[44:45], v[146:147], v[44:45]
	v_cvt_pk_bf16_f32 v42, v42, v43
	v_cvt_pk_bf16_f32 v43, v44, v45
	global_store_dwordx2 v[68:69], v[42:43], off offset:32
	v_lshlrev_b32_e32 v42, 16, v88
	v_and_b32_e32 v43, 0xffff0000, v88
	v_pk_mul_f32 v[36:37], v[36:37], v[42:43]
	v_lshlrev_b32_e32 v42, 16, v89
	v_and_b32_e32 v43, 0xffff0000, v89
	v_pk_mul_f32 v[38:39], v[38:39], v[42:43]
	v_cvt_pk_bf16_f32 v36, v36, v37
	v_cvt_pk_bf16_f32 v37, v38, v39
	global_store_dwordx2 v[68:69], v[36:37], off offset:64
	v_lshlrev_b32_e32 v36, 16, v90
	v_and_b32_e32 v37, 0xffff0000, v90
	v_pk_mul_f32 v[32:33], v[32:33], v[36:37]
	v_lshlrev_b32_e32 v36, 16, v91
	v_and_b32_e32 v37, 0xffff0000, v91
	v_pk_mul_f32 v[34:35], v[34:35], v[36:37]
	v_cvt_pk_bf16_f32 v32, v32, v33
	v_cvt_pk_bf16_f32 v33, v34, v35
	global_store_dwordx2 v[68:69], v[32:33], off offset:96
	v_or_b32_e32 v32, 32, v40
	v_ashrrev_i32_e32 v33, 31, v32
	v_lshlrev_b32_e32 v34, 16, v92
	v_and_b32_e32 v35, 0xffff0000, v92
	v_lshlrev_b64 v[32:33], 11, v[32:33]
	v_pk_mul_f32 v[28:29], v[28:29], v[34:35]
	v_lshlrev_b32_e32 v34, 16, v93
	v_and_b32_e32 v35, 0xffff0000, v93
	v_lshl_add_u64 v[32:33], s[4:5], 0, v[32:33]
	v_pk_mul_f32 v[30:31], v[30:31], v[34:35]
	v_cvt_pk_bf16_f32 v28, v28, v29
	v_cvt_pk_bf16_f32 v29, v30, v31
	v_lshl_add_u64 v[66:67], v[32:33], 0, v[128:129]
	global_store_dwordx2 v[66:67], v[28:29], off
	v_lshlrev_b32_e32 v28, 16, v94
	v_and_b32_e32 v29, 0xffff0000, v94
	v_pk_mul_f32 v[24:25], v[24:25], v[28:29]
	v_lshlrev_b32_e32 v28, 16, v95
	v_and_b32_e32 v29, 0xffff0000, v95
	v_pk_mul_f32 v[26:27], v[26:27], v[28:29]
	v_cvt_pk_bf16_f32 v24, v24, v25
	v_cvt_pk_bf16_f32 v25, v26, v27
	global_store_dwordx2 v[66:67], v[24:25], off offset:32
	v_lshlrev_b32_e32 v24, 16, v96
	v_and_b32_e32 v25, 0xffff0000, v96
	v_pk_mul_f32 v[20:21], v[20:21], v[24:25]
	v_lshlrev_b32_e32 v24, 16, v97
	v_and_b32_e32 v25, 0xffff0000, v97
	v_pk_mul_f32 v[22:23], v[22:23], v[24:25]
	v_cvt_pk_bf16_f32 v20, v20, v21
	v_cvt_pk_bf16_f32 v21, v22, v23
	global_store_dwordx2 v[66:67], v[20:21], off offset:64
	v_lshlrev_b32_e32 v20, 16, v98
	v_and_b32_e32 v21, 0xffff0000, v98
	v_pk_mul_f32 v[16:17], v[16:17], v[20:21]
	v_lshlrev_b32_e32 v20, 16, v99
	v_and_b32_e32 v21, 0xffff0000, v99
	v_pk_mul_f32 v[18:19], v[18:19], v[20:21]
	v_cvt_pk_bf16_f32 v16, v16, v17
	v_cvt_pk_bf16_f32 v17, v18, v19
	global_store_dwordx2 v[66:67], v[16:17], off offset:96
	v_or_b32_e32 v16, 48, v40
	v_ashrrev_i32_e32 v17, 31, v16
	v_lshlrev_b32_e32 v18, 16, v100
	v_and_b32_e32 v19, 0xffff0000, v100
	v_lshlrev_b64 v[16:17], 11, v[16:17]
	v_pk_mul_f32 v[12:13], v[12:13], v[18:19]
	v_lshlrev_b32_e32 v18, 16, v101
	v_and_b32_e32 v19, 0xffff0000, v101
	v_lshl_add_u64 v[16:17], s[4:5], 0, v[16:17]
	v_pk_mul_f32 v[14:15], v[14:15], v[18:19]
	v_cvt_pk_bf16_f32 v12, v12, v13
	v_cvt_pk_bf16_f32 v13, v14, v15
	v_lshl_add_u64 v[64:65], v[16:17], 0, v[128:129]
	global_store_dwordx2 v[64:65], v[12:13], off
	v_lshlrev_b32_e32 v12, 16, v102
	v_and_b32_e32 v13, 0xffff0000, v102
	v_pk_mul_f32 v[8:9], v[8:9], v[12:13]
	v_lshlrev_b32_e32 v12, 16, v103
	v_and_b32_e32 v13, 0xffff0000, v103
	v_pk_mul_f32 v[10:11], v[10:11], v[12:13]
	v_cvt_pk_bf16_f32 v8, v8, v9
	v_cvt_pk_bf16_f32 v9, v10, v11
	global_store_dwordx2 v[64:65], v[8:9], off offset:32
	v_lshlrev_b32_e32 v8, 16, v104
	v_and_b32_e32 v9, 0xffff0000, v104
	v_pk_mul_f32 v[4:5], v[4:5], v[8:9]
	v_lshlrev_b32_e32 v8, 16, v105
	v_and_b32_e32 v9, 0xffff0000, v105
	v_pk_mul_f32 v[6:7], v[6:7], v[8:9]
	v_cvt_pk_bf16_f32 v4, v4, v5
	v_cvt_pk_bf16_f32 v5, v6, v7
	global_store_dwordx2 v[64:65], v[4:5], off offset:64
	v_lshlrev_b32_e32 v4, 16, v106
	v_and_b32_e32 v5, 0xffff0000, v106
	v_pk_mul_f32 v[0:1], v[0:1], v[4:5]
	v_lshlrev_b32_e32 v4, 16, v107
	v_and_b32_e32 v5, 0xffff0000, v107
	v_pk_mul_f32 v[2:3], v[2:3], v[4:5]
	v_cvt_pk_bf16_f32 v0, v0, v1
	v_cvt_pk_bf16_f32 v1, v2, v3
	global_store_dwordx2 v[64:65], v[0:1], off offset:96
	v_mov_b32_e32 v0, v129
	v_mov_b32_e32 v1, v130
	s_movk_i32 s12, 0x3800
	v_ashrrev_i32_e32 v2, 6, v1
	v_and_b32_e32 v3, 1, v2
	v_bfe_u32 v4, v1, 4, 2
	v_and_b32_e32 v6, 7, v1
	v_lshlrev_b32_e32 v7, 2, v3
	v_bitop3_b32 v4, v7, v6, v4 bitop3:0x36
	v_lshlrev_b32_e32 v6, 14, v2
	v_lshlrev_b32_e32 v7, 8, v1
	v_and_or_b32 v6, v7, s12, v6
	v_lshlrev_b32_e32 v86, 10, v2
	s_lshl_b32 s0, s38, 11
	v_lshl_or_b32 v128, v4, 4, v6
	v_readfirstlane_b32 s12, v86
	v_add_u32_e32 v4, 0x1000, v86
	s_add_u32 s0, s23, s0
	s_mov_b32 m0, s12
	v_readfirstlane_b32 s12, v4
	v_add_u32_e32 v6, 0x2000, v86
	s_addc_u32 s1, s24, 0
	global_load_lds_dwordx4 v128, s[10:11]
	v_add_u32_e32 v2, 0x10000, v128
	s_mov_b32 m0, s12
	v_readfirstlane_b32 s12, v6
	v_add_u32_e32 v8, 0x3000, v86
	v_add_u32_e32 v7, 0x4000, v86
	global_load_lds_dwordx4 v2, s[10:11]
	v_add_u32_e32 v4, 0x20000, v128
	s_mov_b32 m0, s12
	v_readfirstlane_b32 s12, v8
	v_lshl_add_u64 v[8:9], s[0:1], 0, v[128:129]
	s_mov_b64 s[0:1], 0x200000
; DEVI float zero_f() { float z = 0.f; asm volatile("" : "+v"(z)); return z; }
; template <bool SWAP, class RP>
; DEVI void gemm_main(const int TIDX, const int BIDX, const int GDIM, f32x4 (&acc)[4][4], RP rowoff, const bf16_t* __restrict__ Bt, int ldb, int K, unsigned char* smem) {
;     ...
;   const uint32_t schunk = (uint32_t)((lane & 7) ^ (((lane >> 4) + 4 * (w & 1)) & 7)) * 16u;
;   uint32_t ao0, ao1, ao2, ao3;
;   const int rsub = w * 8 + (lane >> 3);
;   ao0 = rowoff(rsub) + schunk; ao1 = rowoff(rsub + 32) + schunk; ao2 = rowoff(rsub + 64) + schunk; ao3 = rowoff(rsub + 96) + schunk;
;   const uint32_t bo = (uint32_t)(rsub * ldb) * 2u + schunk, bstep = (uint32_t)(32 * ldb) * 2u;
;   unsigned char* sbase = smem + w * 1024;
;     ...
;   const int nk = K >> 6;
;   const int px = lg ^ (li >> 1);
;   GM_STAGE(0, 0);
;   for (int kt = 0; kt < nk; ++kt) {
;     const int buf = kt & 1;
;     asm volatile("s_waitcnt vmcnt(0)" ::: "memory");
;     __syncthreads();
;     if (kt + 1 < nk) GM_STAGE(kt + 1, buf ^ 1);
;     const unsigned char* A = smem + buf * 32768 + (wr * 64 + li) * 128;
;     const unsigned char* B = smem + buf * 32768 + 16384 + (wc * 64 + li) * 128;
; DEVI void zero_acc(f32x4 (&acc)[4][4]) {
;   const float z = zero_f();
; #pragma unroll
;   for (int i = 0; i < 4; ++i)
; #pragma unroll
;     for (int j = 0; j < 4; ++j) acc[i][j] = (f32x4){z, z, z, z};
; }
	global_load_lds_dwordx4 v4, s[10:11]
	v_add_u32_e32 v6, 0x30000, v128
	s_mov_b32 m0, s12
	v_lshl_add_u64 v[10:11], v[8:9], 0, s[0:1]
	v_readfirstlane_b32 s0, v7
	global_load_lds_dwordx4 v6, s[10:11]
	s_mov_b32 m0, s0
	s_mov_b64 s[0:1], 0x210000
	v_add_u32_e32 v7, 0x5000, v86
	global_load_lds_dwordx4 v[10:11], off
	v_lshl_add_u64 v[10:11], v[8:9], 0, s[0:1]
	v_readfirstlane_b32 s0, v7
	s_mov_b32 m0, s0
	s_mov_b64 s[0:1], 0x220000
	v_add_u32_e32 v7, 0x6000, v86
	global_load_lds_dwordx4 v[10:11], off
	v_lshl_add_u64 v[10:11], v[8:9], 0, s[0:1]
	v_readfirstlane_b32 s0, v7
	s_mov_b32 m0, s0
	s_mov_b64 s[0:1], 0x230000
	v_add_u32_e32 v7, 0x7000, v86
	v_lshl_add_u64 v[8:9], v[8:9], 0, s[0:1]
	v_readfirstlane_b32 s0, v7
	global_load_lds_dwordx4 v[10:11], off
	s_mov_b32 m0, s0
	v_lshrrev_b32_e32 v5, 4, v1
	global_load_lds_dwordx4 v[8:9], off
	v_and_b32_e32 v7, 15, v1
	v_bfe_u32 v8, v1, 1, 3
	v_lshrrev_b32_e32 v1, 1, v1
	v_and_or_b32 v1, v1, s74, v7
	s_add_u32 s0, s29, s8
	v_lshlrev_b32_e32 v85, 7, v1
	v_lshlrev_b32_e32 v88, 13, v3
	v_lshlrev_b32_e32 v89, 7, v7
	v_bitop3_b32 v1, v8, v5, 3 bitop3:0x78
	s_addc_u32 s1, s30, s9
	v_mov_b32_e32 v3, v129
	v_mov_b32_e32 v5, v129
	v_mov_b32_e32 v7, v129
	v_lshl_add_u64 v[72:73], s[0:1], 0, v[128:129]
	v_lshl_add_u64 v[74:75], s[0:1], 0, v[2:3]
	v_lshl_add_u64 v[76:77], s[0:1], 0, v[4:5]
	v_lshl_add_u64 v[78:79], s[0:1], 0, v[6:7]
	s_add_u32 s0, s21, s37
	v_lshlrev_b32_e32 v87, 4, v1
	s_addc_u32 s1, s22, 0
	v_xor_b32_e32 v84, 64, v87
	v_lshl_add_u64 v[80:81], s[0:1], 0, v[128:129]
	s_mov_b64 s[0:1], 0
	v_mov_b32_e32 v1, v0
	v_mov_b32_e32 v2, v0
	v_mov_b32_e32 v3, v0
	v_mov_b32_e32 v4, v0
	v_mov_b32_e32 v5, v0
	v_mov_b32_e32 v6, v0
	v_mov_b32_e32 v7, v0
	v_mov_b32_e32 v8, v0
	v_mov_b32_e32 v9, v0
	v_mov_b32_e32 v10, v0
	v_mov_b32_e32 v11, v0
	v_mov_b32_e32 v12, v0
	v_mov_b32_e32 v13, v0
	v_mov_b32_e32 v14, v0
	v_mov_b32_e32 v15, v0
	v_mov_b32_e32 v16, v0
	v_mov_b32_e32 v17, v0
	v_mov_b32_e32 v18, v0
	v_mov_b32_e32 v19, v0
	v_mov_b32_e32 v20, v0
	v_mov_b32_e32 v21, v0
	v_mov_b32_e32 v22, v0
	v_mov_b32_e32 v23, v0
	v_mov_b32_e32 v24, v0
	v_mov_b32_e32 v25, v0
	v_mov_b32_e32 v26, v0
	v_mov_b32_e32 v27, v0
	v_mov_b32_e32 v28, v0
	v_mov_b32_e32 v29, v0
	v_mov_b32_e32 v30, v0
	v_mov_b32_e32 v31, v0
	v_mov_b32_e32 v32, v0
	v_mov_b32_e32 v33, v0
	v_mov_b32_e32 v34, v0
	v_mov_b32_e32 v35, v0
	v_mov_b32_e32 v36, v0
	v_mov_b32_e32 v37, v0
	v_mov_b32_e32 v38, v0
	v_mov_b32_e32 v39, v0
	v_mov_b32_e32 v40, v0
	v_mov_b32_e32 v41, v0
	v_mov_b32_e32 v42, v0
	v_mov_b32_e32 v43, v0
	v_mov_b32_e32 v44, v0
	v_mov_b32_e32 v45, v0
	v_mov_b32_e32 v46, v0
	v_mov_b32_e32 v47, v0
	v_mov_b32_e32 v48, v0
	v_mov_b32_e32 v49, v0
	v_mov_b32_e32 v50, v0
	v_mov_b32_e32 v51, v0
	v_mov_b32_e32 v52, v0
	v_mov_b32_e32 v53, v0
	v_mov_b32_e32 v54, v0
	v_mov_b32_e32 v55, v0
	v_mov_b32_e32 v56, v0
	v_mov_b32_e32 v57, v0
	v_mov_b32_e32 v58, v0
	v_mov_b32_e32 v59, v0
	v_mov_b32_e32 v60, v0
	v_mov_b32_e32 v61, v0
	v_mov_b32_e32 v62, v0
	v_mov_b32_e32 v63, v0
.LBB0_119:
	s_and_b32 s10, s39, 0x8000
	s_xor_b32 s11, s10, 0x8000
	v_add_u32_e32 v116, s11, v86
	v_add_u32_e32 v194, s10, v85
	v_or_b32_e32 v204, s10, v88
	v_add_u32_e32 v204, v204, v89
	v_add_u32_e32 v205, v194, v87
	v_add_u32_e32 v231, v204, v87
	v_readfirstlane_b32 s101, v116
	v_add_u32_e32 v194, v194, v84
	v_add_u32_e32 v204, v204, v84
	s_waitcnt vmcnt(0)
	s_barrier
	ds_read_b128 v[90:93], v205
	ds_read_b128 v[106:109], v231 offset:16384
	ds_read_b128 v[110:113], v231 offset:18432
	ds_read_b128 v[190:193], v231 offset:20480
	ds_read_b128 v[196:199], v231 offset:22528
	ds_read_b128 v[94:97], v205 offset:2048
	ds_read_b128 v[98:101], v205 offset:4096
	ds_read_b128 v[102:105], v205 offset:6144
	ds_read_b128 v[200:203], v204 offset:16384
	ds_read_b128 v[208:211], v204 offset:18432
	ds_read_b128 v[236:239], v204 offset:20480
	ds_read_b128 v[240:243], v204 offset:22528
	s_mov_b32 m0, s101
	v_lshl_add_u64 v[114:115], v[72:73], 0, s[0:1]
	global_load_lds_dwordx4 v[114:115], off
	s_add_i32 m0, s101, 0x1000
	v_lshl_add_u64 v[114:115], v[74:75], 0, s[0:1]
	global_load_lds_dwordx4 v[114:115], off
	s_waitcnt lgkmcnt(7)
	v_mfma_f32_16x16x32_bf16 v[60:63], v[106:109], v[90:93], v[60:63]
	v_mfma_f32_16x16x32_bf16 v[56:59], v[110:113], v[90:93], v[56:59]
	s_add_i32 m0, s101, 0x2000
	v_lshl_add_u64 v[114:115], v[76:77], 0, s[0:1]
	global_load_lds_dwordx4 v[114:115], off
	v_mfma_f32_16x16x32_bf16 v[52:55], v[190:193], v[90:93], v[52:55]
	v_mfma_f32_16x16x32_bf16 v[48:51], v[196:199], v[90:93], v[48:51]
	ds_read_b128 v[90:93], v194
	s_add_i32 m0, s101, 0x3000
	v_lshl_add_u64 v[114:115], v[78:79], 0, s[0:1]
	global_load_lds_dwordx4 v[114:115], off
	s_waitcnt lgkmcnt(7)
	v_mfma_f32_16x16x32_bf16 v[44:47], v[106:109], v[94:97], v[44:47]
	v_mfma_f32_16x16x32_bf16 v[40:43], v[110:113], v[94:97], v[40:43]
	s_add_i32 m0, s101, 0x4000
	s_mov_b64 s[8:9], 0x780080
	v_lshl_add_u64 v[114:115], v[80:81], 0, s[0:1]
	v_lshl_add_u64 v[114:115], v[114:115], 0, s[8:9]
	global_load_lds_dwordx4 v[114:115], off
	v_mfma_f32_16x16x32_bf16 v[36:39], v[190:193], v[94:97], v[36:39]
	v_mfma_f32_16x16x32_bf16 v[32:35], v[196:199], v[94:97], v[32:35]
	ds_read_b128 v[94:97], v194 offset:2048
	s_add_i32 m0, s101, 0x5000
	s_mov_b64 s[8:9], 0x790080
	v_lshl_add_u64 v[114:115], v[80:81], 0, s[0:1]
	v_lshl_add_u64 v[114:115], v[114:115], 0, s[8:9]
	global_load_lds_dwordx4 v[114:115], off
	s_waitcnt lgkmcnt(7)
; DEVI f32x4 mfma16(bf16x8 a, bf16x8 b, f32x4 c) { return __builtin_amdgcn_mfma_f32_16x16x32_bf16(a, b, c, 0, 0, 0); }
; template <bool SWAP, class RP>
; DEVI void gemm_main(const int TIDX, const int BIDX, const int GDIM, f32x4 (&acc)[4][4], RP rowoff, const bf16_t* __restrict__ Bt, int ldb, int K, unsigned char* smem) {
;     ...
;   for (int kt = 0; kt < nk; ++kt) {
;     const int buf = kt & 1;
;     asm volatile("s_waitcnt vmcnt(0)" ::: "memory");
;     __syncthreads();
;     if (kt + 1 < nk) GM_STAGE(kt + 1, buf ^ 1);
;     const unsigned char* A = smem + buf * 32768 + (wr * 64 + li) * 128;
;     const unsigned char* B = smem + buf * 32768 + 16384 + (wc * 64 + li) * 128;
; #pragma unroll
;     for (int ks = 0; ks < 2; ++ks) {
;       const int po = (px ^ (ks * 4)) * 16;
;       bf16x8 af[4], bfr[4];
; #pragma unroll
;       for (int i = 0; i < 4; ++i) {
;         af[i] = *(const bf16x8*)(A + i * 2048 + po);
;         bfr[i] = *(const bf16x8*)(B + i * 2048 + po);
;       }
; #pragma unroll
;       for (int mi = 0; mi < 4; ++mi)
; #pragma unroll
;         for (int ni = 0; ni < 4; ++ni)
;           acc[mi][ni] = SWAP ? mfma16(bfr[ni], af[mi], acc[mi][ni]) : mfma16(af[mi], bfr[ni], acc[mi][ni]);
;     }
;   }
;   __syncthreads();
	v_mfma_f32_16x16x32_bf16 v[28:31], v[106:109], v[98:101], v[28:31]
	v_mfma_f32_16x16x32_bf16 v[24:27], v[110:113], v[98:101], v[24:27]
	s_add_i32 m0, s101, 0x6000
	s_mov_b64 s[8:9], 0x7a0080
	v_lshl_add_u64 v[114:115], v[80:81], 0, s[0:1]
	v_lshl_add_u64 v[114:115], v[114:115], 0, s[8:9]
	global_load_lds_dwordx4 v[114:115], off
	v_mfma_f32_16x16x32_bf16 v[20:23], v[190:193], v[98:101], v[20:23]
	v_mfma_f32_16x16x32_bf16 v[16:19], v[196:199], v[98:101], v[16:19]
	ds_read_b128 v[98:101], v194 offset:4096
	s_add_i32 m0, s101, 0x7000
	s_mov_b64 s[8:9], 0x7b0080
	v_lshl_add_u64 v[114:115], v[80:81], 0, s[0:1]
	v_lshl_add_u64 v[114:115], v[114:115], 0, s[8:9]
	global_load_lds_dwordx4 v[114:115], off
	s_waitcnt lgkmcnt(7)
	v_mfma_f32_16x16x32_bf16 v[12:15], v[106:109], v[102:105], v[12:15]
	v_mfma_f32_16x16x32_bf16 v[8:11], v[110:113], v[102:105], v[8:11]
	v_mfma_f32_16x16x32_bf16 v[4:7], v[190:193], v[102:105], v[4:7]
	v_mfma_f32_16x16x32_bf16 v[0:3], v[196:199], v[102:105], v[0:3]
	ds_read_b128 v[102:105], v194 offset:6144
	s_waitcnt lgkmcnt(3)
	v_mfma_f32_16x16x32_bf16 v[60:63], v[200:203], v[90:93], v[60:63]
	v_mfma_f32_16x16x32_bf16 v[56:59], v[208:211], v[90:93], v[56:59]
	v_mfma_f32_16x16x32_bf16 v[52:55], v[236:239], v[90:93], v[52:55]
	v_mfma_f32_16x16x32_bf16 v[48:51], v[240:243], v[90:93], v[48:51]
	s_waitcnt lgkmcnt(2)
	v_mfma_f32_16x16x32_bf16 v[44:47], v[200:203], v[94:97], v[44:47]
	v_mfma_f32_16x16x32_bf16 v[40:43], v[208:211], v[94:97], v[40:43]
	v_mfma_f32_16x16x32_bf16 v[36:39], v[236:239], v[94:97], v[36:39]
	v_mfma_f32_16x16x32_bf16 v[32:35], v[240:243], v[94:97], v[32:35]
	s_waitcnt lgkmcnt(1)
	v_mfma_f32_16x16x32_bf16 v[28:31], v[200:203], v[98:101], v[28:31]
	v_mfma_f32_16x16x32_bf16 v[24:27], v[208:211], v[98:101], v[24:27]
	v_mfma_f32_16x16x32_bf16 v[20:23], v[236:239], v[98:101], v[20:23]
	v_mfma_f32_16x16x32_bf16 v[16:19], v[240:243], v[98:101], v[16:19]
	s_waitcnt lgkmcnt(0)
	s_add_u32 s0, s0, 0x80
	s_addc_u32 s1, s1, 0
	s_add_i32 s39, s39, 0x8000
	s_cmpk_eq_i32 s0, 0x780
	v_mfma_f32_16x16x32_bf16 v[12:15], v[200:203], v[102:105], v[12:15]
	v_mfma_f32_16x16x32_bf16 v[8:11], v[208:211], v[102:105], v[8:11]
	v_mfma_f32_16x16x32_bf16 v[4:7], v[236:239], v[102:105], v[4:7]
	v_mfma_f32_16x16x32_bf16 v[0:3], v[240:243], v[102:105], v[0:3]
	s_cbranch_scc0 .LBB0_119
	v_add_u32_e32 v80, v88, v89
	v_add_u32_e32 v81, v85, v87
	v_add_u32_e32 v106, v80, v87
	s_waitcnt vmcnt(0)
	s_waitcnt vmcnt(0)
	s_barrier
	ds_read_b128 v[72:75], v81 offset:32768
	ds_read_b128 v[76:79], v106 offset:49152
	ds_read_b128 v[86:89], v81 offset:34816
	ds_read_b128 v[90:93], v106 offset:51200
	ds_read_b128 v[94:97], v81 offset:36864
	ds_read_b128 v[98:101], v106 offset:53248
	ds_read_b128 v[102:105], v81 offset:38912
	ds_read_b128 v[106:109], v106 offset:55296
	s_waitcnt lgkmcnt(6)
	v_mfma_f32_16x16x32_bf16 v[60:63], v[76:79], v[72:75], v[60:63]
	v_add_u32_e32 v81, v85, v84
	v_add_u32_e32 v80, v80, v84
	s_movk_i32 s8, 0x1c00
	s_waitcnt lgkmcnt(4)
	v_mfma_f32_16x16x32_bf16 v[56:59], v[90:93], v[72:75], v[56:59]
	s_mov_b64 s[42:43], 0x10000
	s_mov_b32 s41, 0x1ffffc0
	s_mov_b64 s[10:11], 0x8080
	s_waitcnt lgkmcnt(2)
	v_mfma_f32_16x16x32_bf16 v[52:55], v[98:101], v[72:75], v[52:55]
	s_mov_b64 s[44:45], 0x18080
	s_waitcnt lgkmcnt(0)
	v_mfma_f32_16x16x32_bf16 v[48:51], v[106:109], v[72:75], v[48:51]
	v_mfma_f32_16x16x32_bf16 v[44:47], v[76:79], v[86:89], v[44:47]
	v_mfma_f32_16x16x32_bf16 v[40:43], v[90:93], v[86:89], v[40:43]
	v_mfma_f32_16x16x32_bf16 v[36:39], v[98:101], v[86:89], v[36:39]
	v_mfma_f32_16x16x32_bf16 v[32:35], v[106:109], v[86:89], v[32:35]
	v_mfma_f32_16x16x32_bf16 v[28:31], v[76:79], v[94:97], v[28:31]
	v_mfma_f32_16x16x32_bf16 v[24:27], v[90:93], v[94:97], v[24:27]
	v_mfma_f32_16x16x32_bf16 v[20:23], v[98:101], v[94:97], v[20:23]
	v_mfma_f32_16x16x32_bf16 v[16:19], v[106:109], v[94:97], v[16:19]
	v_mfma_f32_16x16x32_bf16 v[12:15], v[76:79], v[102:105], v[12:15]
	v_mfma_f32_16x16x32_bf16 v[8:11], v[90:93], v[102:105], v[8:11]
	v_mfma_f32_16x16x32_bf16 v[4:7], v[98:101], v[102:105], v[4:7]
	v_mfma_f32_16x16x32_bf16 v[0:3], v[106:109], v[102:105], v[0:3]
	ds_read_b128 v[72:75], v81 offset:32768
	ds_read_b128 v[76:79], v80 offset:49152
	ds_read_b128 v[84:87], v81 offset:34816
	ds_read_b128 v[88:91], v80 offset:51200
	ds_read_b128 v[92:95], v81 offset:36864
	ds_read_b128 v[96:99], v80 offset:53248
	ds_read_b128 v[100:103], v81 offset:38912
	ds_read_b128 v[104:107], v80 offset:55296
	s_waitcnt lgkmcnt(0)
	s_barrier
; DEVI uint32_t pack2(float lo, float hi) { f32x2_t v = {lo, hi}; bf16x2_t b = __builtin_convertvector(v, bf16x2_t); return __builtin_bit_cast(uint32_t, b); }
; DEVI float sigmoidf_(float x) { return 1.f / (1.f + __expf(-x)); }
; DEVI void phase_p5(const int TIDX, const int BIDX, const int GDIM, KAP KA, unsigned char* WSB, float* OUTB, int l, unsigned char* smem) {
;     ...
; #pragma unroll
;     for (int i = 0; i < 4; ++i)
; #pragma unroll
;       for (int j = 0; j < 4; ++j) gp[i][j] = make_uint2(pack2(sigmoidf_(acc[i][j][0]), sigmoidf_(acc[i][j][1])), pack2(sigmoidf_(acc[i][j][2]), sigmoidf_(acc[i][j][3])));
	v_mfma_f32_16x16x32_bf16 v[60:63], v[76:79], v[72:75], v[60:63]
	v_mfma_f32_16x16x32_bf16 v[56:59], v[88:91], v[72:75], v[56:59]
	v_mfma_f32_16x16x32_bf16 v[52:55], v[96:99], v[72:75], v[52:55]
	s_nop 5
	v_mul_f32_e32 v60, 0xbfb8aa3b, v60
	v_mul_f32_e32 v61, 0xbfb8aa3b, v61
	v_exp_f32_e32 v60, v60
	v_exp_f32_e32 v61, v61
	v_mfma_f32_16x16x32_bf16 v[48:51], v[104:107], v[72:75], v[48:51]
	v_mul_f32_e32 v56, 0xbfb8aa3b, v56
	v_mul_f32_e32 v57, 0xbfb8aa3b, v57
	v_pk_add_f32 v[60:61], v[60:61], 1.0 op_sel_hi:[1,0]
	v_mfma_f32_16x16x32_bf16 v[44:47], v[76:79], v[84:87], v[44:47]
	v_div_scale_f32 v72, s[0:1], v61, v61, 1.0
	v_rcp_f32_e32 v73, v72
	v_mfma_f32_16x16x32_bf16 v[28:31], v[76:79], v[92:95], v[28:31]
	v_exp_f32_e32 v56, v56
	v_exp_f32_e32 v57, v57
	v_fma_f32 v74, -v72, v73, 1.0
	v_fmac_f32_e32 v73, v74, v73
	v_div_scale_f32 v74, vcc, 1.0, v61, 1.0
	v_mul_f32_e32 v75, v74, v73
	v_mfma_f32_16x16x32_bf16 v[12:15], v[76:79], v[100:103], v[12:15]
	v_fma_f32 v76, -v72, v75, v74
	v_fmac_f32_e32 v75, v76, v73
	v_fma_f32 v72, -v72, v75, v74
	v_div_fmas_f32 v72, v72, v73, v75
	v_div_fixup_f32 v61, v72, v61, 1.0
	v_div_scale_f32 v72, s[0:1], v60, v60, 1.0
	v_rcp_f32_e32 v73, v72
	v_mfma_f32_16x16x32_bf16 v[40:43], v[88:91], v[84:87], v[40:43]
	v_add_f32_e64 v56, v56, 1.0
	v_add_f32_e64 v57, v57, 1.0
	v_mul_f32_e32 v52, 0xbfb8aa3b, v52
	v_fma_f32 v74, -v72, v73, 1.0
	v_fmac_f32_e32 v73, v74, v73
	v_div_scale_f32 v74, vcc, 1.0, v60, 1.0
	v_mul_f32_e32 v75, v74, v73
	v_fma_f32 v76, -v72, v75, v74
	v_fmac_f32_e32 v75, v76, v73
	v_fma_f32 v72, -v72, v75, v74
	v_div_fmas_f32 v72, v72, v73, v75
	v_div_fixup_f32 v60, v72, v60, 1.0
	v_mfma_f32_16x16x32_bf16 v[36:39], v[96:99], v[84:87], v[36:39]
	v_mul_f32_e32 v53, 0xbfb8aa3b, v53
	v_exp_f32_e32 v52, v52
	v_exp_f32_e32 v53, v53
	v_mfma_f32_16x16x32_bf16 v[32:35], v[104:107], v[84:87], v[32:35]
	v_cvt_pk_bf16_f32 v86, v60, v61
	v_mul_f32_e32 v60, 0xbfb8aa3b, v62
	v_mul_f32_e32 v61, 0xbfb8aa3b, v63
	v_exp_f32_e32 v60, v60
	v_exp_f32_e32 v61, v61
	v_mfma_f32_16x16x32_bf16 v[24:27], v[88:91], v[92:95], v[24:27]
	v_add_f32_e64 v52, v52, 1.0
	v_add_f32_e64 v53, v53, 1.0
	v_mul_f32_e32 v48, 0xbfb8aa3b, v48
	v_pk_add_f32 v[60:61], v[60:61], 1.0 op_sel_hi:[1,0]
	v_mfma_f32_16x16x32_bf16 v[20:23], v[96:99], v[92:95], v[20:23]
	v_div_scale_f32 v62, s[0:1], v61, v61, 1.0
	v_rcp_f32_e32 v63, v62
	v_mfma_f32_16x16x32_bf16 v[16:19], v[104:107], v[92:95], v[16:19]
	v_mul_f32_e32 v49, 0xbfb8aa3b, v49
	v_exp_f32_e32 v48, v48
	v_fma_f32 v72, -v62, v63, 1.0
	v_fmac_f32_e32 v63, v72, v63
	v_div_scale_f32 v72, vcc, 1.0, v61, 1.0
	v_mul_f32_e32 v73, v72, v63
	v_fma_f32 v74, -v62, v73, v72
	v_fmac_f32_e32 v73, v74, v63
	v_fma_f32 v62, -v62, v73, v72
	v_div_fmas_f32 v62, v62, v63, v73
	v_div_fixup_f32 v61, v62, v61, 1.0
	v_div_scale_f32 v62, s[0:1], v60, v60, 1.0
	v_rcp_f32_e32 v63, v62
	v_mfma_f32_16x16x32_bf16 v[8:11], v[88:91], v[100:103], v[8:11]
	v_exp_f32_e32 v49, v49
	v_mul_f32_e32 v44, 0xbfb8aa3b, v44
	v_fma_f32 v72, -v62, v63, 1.0
	v_fmac_f32_e32 v63, v72, v63
	v_div_scale_f32 v72, vcc, 1.0, v60, 1.0
	v_mul_f32_e32 v73, v72, v63
	v_fma_f32 v74, -v62, v73, v72
	v_fmac_f32_e32 v73, v74, v63
	v_fma_f32 v62, -v62, v73, v72
	v_div_fmas_f32 v62, v62, v63, v73
	v_div_fixup_f32 v60, v62, v60, 1.0
	v_cvt_pk_bf16_f32 v94, v60, v61
	v_div_scale_f32 v60, s[0:1], v57, v57, 1.0
	v_rcp_f32_e32 v61, v60
	v_mfma_f32_16x16x32_bf16 v[4:7], v[96:99], v[100:103], v[4:7]
	v_add_f32_e64 v48, v48, 1.0
	v_add_f32_e64 v49, v49, 1.0
	v_mul_f32_e32 v45, 0xbfb8aa3b, v45
	v_fma_f32 v62, -v60, v61, 1.0
	v_fmac_f32_e32 v61, v62, v61
	v_div_scale_f32 v62, vcc, 1.0, v57, 1.0
	v_mul_f32_e32 v63, v62, v61
	v_fma_f32 v72, -v60, v63, v62
	v_fmac_f32_e32 v63, v72, v61
	v_fma_f32 v60, -v60, v63, v62
	v_div_fmas_f32 v60, v60, v61, v63
	v_div_fixup_f32 v57, v60, v57, 1.0
	v_div_scale_f32 v60, s[0:1], v56, v56, 1.0
	v_rcp_f32_e32 v61, v60
	v_mfma_f32_16x16x32_bf16 v[0:3], v[104:107], v[100:103], v[0:3]
	v_exp_f32_e32 v44, v44
	v_exp_f32_e32 v45, v45
	v_fma_f32 v62, -v60, v61, 1.0
	v_fmac_f32_e32 v61, v62, v61
	v_div_scale_f32 v62, vcc, 1.0, v56, 1.0
	v_mul_f32_e32 v63, v62, v61
	v_fma_f32 v72, -v60, v63, v62
	v_fmac_f32_e32 v63, v72, v61
	v_fma_f32 v60, -v60, v63, v62
	v_div_fmas_f32 v60, v60, v61, v63
	v_div_fixup_f32 v56, v60, v56, 1.0
	v_cvt_pk_bf16_f32 v95, v56, v57
	v_mul_f32_e32 v56, 0xbfb8aa3b, v58
	v_mul_f32_e32 v57, 0xbfb8aa3b, v59
	v_exp_f32_e32 v56, v56
	v_exp_f32_e32 v57, v57
	v_pk_add_f32 v[44:45], v[44:45], 1.0 op_sel_hi:[1,0]
	v_mul_f32_e32 v40, 0xbfb8aa3b, v40
	v_mul_f32_e32 v41, 0xbfb8aa3b, v41
	v_pk_add_f32 v[56:57], v[56:57], 1.0 op_sel_hi:[1,0]
	v_exp_f32_e32 v40, v40
	v_div_scale_f32 v58, s[0:1], v57, v57, 1.0
	v_rcp_f32_e32 v59, v58
	v_exp_f32_e32 v41, v41
	v_mul_f32_e32 v36, 0xbfb8aa3b, v36
	v_mul_f32_e32 v37, 0xbfb8aa3b, v37
	v_fma_f32 v60, -v58, v59, 1.0
	v_fmac_f32_e32 v59, v60, v59
	v_div_scale_f32 v60, vcc, 1.0, v57, 1.0
	v_mul_f32_e32 v61, v60, v59
	v_fma_f32 v62, -v58, v61, v60
	v_fmac_f32_e32 v61, v62, v59
	v_fma_f32 v58, -v58, v61, v60
	v_div_fmas_f32 v58, v58, v59, v61
	v_div_fixup_f32 v57, v58, v57, 1.0
	v_div_scale_f32 v58, s[0:1], v56, v56, 1.0
	v_rcp_f32_e32 v59, v58
	v_pk_add_f32 v[40:41], v[40:41], 1.0 op_sel_hi:[1,0]
	v_exp_f32_e32 v36, v36
	v_exp_f32_e32 v37, v37
	v_fma_f32 v60, -v58, v59, 1.0
	v_fmac_f32_e32 v59, v60, v59
	v_div_scale_f32 v60, vcc, 1.0, v56, 1.0
	v_mul_f32_e32 v61, v60, v59
	v_fma_f32 v62, -v58, v61, v60
	v_fmac_f32_e32 v61, v62, v59
	v_fma_f32 v58, -v58, v61, v60
	v_div_fmas_f32 v58, v58, v59, v61
	v_div_fixup_f32 v56, v58, v56, 1.0
	v_cvt_pk_bf16_f32 v102, v56, v57
	v_div_scale_f32 v56, s[0:1], v53, v53, 1.0
; DEVI uint32_t pack2(float lo, float hi) { f32x2_t v = {lo, hi}; bf16x2_t b = __builtin_convertvector(v, bf16x2_t); return __builtin_bit_cast(uint32_t, b); }
; DEVI float sigmoidf_(float x) { return 1.f / (1.f + __expf(-x)); }
; DEVI void phase_p5(const int TIDX, const int BIDX, const int GDIM, KAP KA, unsigned char* WSB, float* OUTB, int l, unsigned char* smem) {
;     ...
; #pragma unroll
;     for (int i = 0; i < 4; ++i)
; #pragma unroll
;       for (int j = 0; j < 4; ++j) gp[i][j] = make_uint2(pack2(sigmoidf_(acc[i][j][0]), sigmoidf_(acc[i][j][1])), pack2(sigmoidf_(acc[i][j][2]), sigmoidf_(acc[i][j][3])));
	v_rcp_f32_e32 v57, v56
	v_pk_add_f32 v[36:37], v[36:37], 1.0 op_sel_hi:[1,0]
	v_mul_f32_e32 v32, 0xbfb8aa3b, v32
	v_mul_f32_e32 v33, 0xbfb8aa3b, v33
	v_fma_f32 v58, -v56, v57, 1.0
	v_fmac_f32_e32 v57, v58, v57
	v_div_scale_f32 v58, vcc, 1.0, v53, 1.0
	v_mul_f32_e32 v59, v58, v57
	v_fma_f32 v60, -v56, v59, v58
	v_fmac_f32_e32 v59, v60, v57
	v_fma_f32 v56, -v56, v59, v58
	v_div_fmas_f32 v56, v56, v57, v59
	v_div_fixup_f32 v53, v56, v53, 1.0
	v_div_scale_f32 v56, s[0:1], v52, v52, 1.0
	v_rcp_f32_e32 v57, v56
	v_exp_f32_e32 v32, v32
	v_exp_f32_e32 v33, v33
	v_mul_f32_e32 v28, 0xbfb8aa3b, v28
	v_fma_f32 v58, -v56, v57, 1.0
	v_fmac_f32_e32 v57, v58, v57
	v_div_scale_f32 v58, vcc, 1.0, v52, 1.0
	v_mul_f32_e32 v59, v58, v57
	v_fma_f32 v60, -v56, v59, v58
	v_fmac_f32_e32 v59, v60, v57
	v_fma_f32 v56, -v56, v59, v58
	v_div_fmas_f32 v56, v56, v57, v59
	v_div_fixup_f32 v52, v56, v52, 1.0
	v_cvt_pk_bf16_f32 v100, v52, v53
	v_mul_f32_e32 v52, 0xbfb8aa3b, v54
	v_mul_f32_e32 v53, 0xbfb8aa3b, v55
	v_exp_f32_e32 v52, v52
	v_exp_f32_e32 v53, v53
	v_pk_add_f32 v[32:33], v[32:33], 1.0 op_sel_hi:[1,0]
	v_mul_f32_e32 v29, 0xbfb8aa3b, v29
	v_exp_f32_e32 v28, v28
	v_pk_add_f32 v[52:53], v[52:53], 1.0 op_sel_hi:[1,0]
	v_exp_f32_e32 v29, v29
	v_div_scale_f32 v54, s[0:1], v53, v53, 1.0
	v_rcp_f32_e32 v55, v54
	v_pk_add_f32 v[28:29], v[28:29], 1.0 op_sel_hi:[1,0]
	v_mul_f32_e32 v24, 0xbfb8aa3b, v24
	v_mul_f32_e32 v25, 0xbfb8aa3b, v25
	v_fma_f32 v56, -v54, v55, 1.0
	v_fmac_f32_e32 v55, v56, v55
	v_div_scale_f32 v56, vcc, 1.0, v53, 1.0
	v_mul_f32_e32 v57, v56, v55
	v_fma_f32 v58, -v54, v57, v56
	v_fmac_f32_e32 v57, v58, v55
	v_fma_f32 v54, -v54, v57, v56
	v_div_fmas_f32 v54, v54, v55, v57
	v_div_fixup_f32 v53, v54, v53, 1.0
	v_div_scale_f32 v54, s[0:1], v52, v52, 1.0
	v_rcp_f32_e32 v55, v54
	v_exp_f32_e32 v24, v24
	v_exp_f32_e32 v25, v25
	v_mul_f32_e32 v20, 0xbfb8aa3b, v20
	v_fma_f32 v56, -v54, v55, 1.0
	v_fmac_f32_e32 v55, v56, v55
	v_div_scale_f32 v56, vcc, 1.0, v52, 1.0
	v_mul_f32_e32 v57, v56, v55
	v_fma_f32 v58, -v54, v57, v56
	v_fmac_f32_e32 v57, v58, v55
	v_fma_f32 v54, -v54, v57, v56
	v_div_fmas_f32 v54, v54, v55, v57
	v_div_fixup_f32 v52, v54, v52, 1.0
	v_cvt_pk_bf16_f32 v108, v52, v53
	v_div_scale_f32 v52, s[0:1], v49, v49, 1.0
	v_rcp_f32_e32 v53, v52
	v_pk_add_f32 v[24:25], v[24:25], 1.0 op_sel_hi:[1,0]
	v_mul_f32_e32 v21, 0xbfb8aa3b, v21
	v_exp_f32_e32 v20, v20
	v_fma_f32 v54, -v52, v53, 1.0
	v_fmac_f32_e32 v53, v54, v53
	v_div_scale_f32 v54, vcc, 1.0, v49, 1.0
	v_mul_f32_e32 v55, v54, v53
	v_fma_f32 v56, -v52, v55, v54
	v_fmac_f32_e32 v55, v56, v53
	v_fma_f32 v52, -v52, v55, v54
	v_div_fmas_f32 v52, v52, v53, v55
	v_div_fixup_f32 v49, v52, v49, 1.0
	v_div_scale_f32 v52, s[0:1], v48, v48, 1.0
	v_rcp_f32_e32 v53, v52
	v_exp_f32_e32 v21, v21
	v_mul_f32_e32 v16, 0xbfb8aa3b, v16
	v_mul_f32_e32 v17, 0xbfb8aa3b, v17
	v_fma_f32 v54, -v52, v53, 1.0
	v_fmac_f32_e32 v53, v54, v53
	v_div_scale_f32 v54, vcc, 1.0, v48, 1.0
	v_mul_f32_e32 v55, v54, v53
	v_fma_f32 v56, -v52, v55, v54
	v_fmac_f32_e32 v55, v56, v53
	v_fma_f32 v52, -v52, v55, v54
	v_div_fmas_f32 v52, v52, v53, v55
	v_div_fixup_f32 v48, v52, v48, 1.0
	v_cvt_pk_bf16_f32 v91, v48, v49
	v_mul_f32_e32 v48, 0xbfb8aa3b, v50
	v_mul_f32_e32 v49, 0xbfb8aa3b, v51
	v_exp_f32_e32 v48, v48
	v_exp_f32_e32 v49, v49
	v_pk_add_f32 v[20:21], v[20:21], 1.0 op_sel_hi:[1,0]
	v_exp_f32_e32 v16, v16
	v_exp_f32_e32 v17, v17
	v_pk_add_f32 v[48:49], v[48:49], 1.0 op_sel_hi:[1,0]
	v_mul_f32_e32 v12, 0xbfb8aa3b, v12
	v_div_scale_f32 v50, s[0:1], v49, v49, 1.0
	v_rcp_f32_e32 v51, v50
	v_pk_add_f32 v[16:17], v[16:17], 1.0 op_sel_hi:[1,0]
	v_mul_f32_e32 v13, 0xbfb8aa3b, v13
	v_exp_f32_e32 v12, v12
	v_fma_f32 v52, -v50, v51, 1.0
	v_fmac_f32_e32 v51, v52, v51
	v_div_scale_f32 v52, vcc, 1.0, v49, 1.0
	v_mul_f32_e32 v53, v52, v51
	v_fma_f32 v54, -v50, v53, v52
	v_fmac_f32_e32 v53, v54, v51
	v_fma_f32 v50, -v50, v53, v52
	v_div_fmas_f32 v50, v50, v51, v53
	v_div_fixup_f32 v49, v50, v49, 1.0
	v_div_scale_f32 v50, s[0:1], v48, v48, 1.0
	v_rcp_f32_e32 v51, v50
	v_exp_f32_e32 v13, v13
	v_mul_f32_e32 v8, 0xbfb8aa3b, v8
	v_mul_f32_e32 v9, 0xbfb8aa3b, v9
	v_fma_f32 v52, -v50, v51, 1.0
	v_fmac_f32_e32 v51, v52, v51
	v_div_scale_f32 v52, vcc, 1.0, v48, 1.0
	v_mul_f32_e32 v53, v52, v51
	v_fma_f32 v54, -v50, v53, v52
	v_fmac_f32_e32 v53, v54, v51
	v_fma_f32 v50, -v50, v53, v52
	v_div_fmas_f32 v50, v50, v51, v53
	v_div_fixup_f32 v48, v50, v48, 1.0
	v_cvt_pk_bf16_f32 v97, v48, v49
	v_div_scale_f32 v48, s[0:1], v45, v45, 1.0
	v_rcp_f32_e32 v49, v48
	v_pk_add_f32 v[12:13], v[12:13], 1.0 op_sel_hi:[1,0]
	v_exp_f32_e32 v8, v8
	v_exp_f32_e32 v9, v9
	v_fma_f32 v50, -v48, v49, 1.0
	v_fmac_f32_e32 v49, v50, v49
	v_div_scale_f32 v50, vcc, 1.0, v45, 1.0
	v_mul_f32_e32 v51, v50, v49
	v_fma_f32 v52, -v48, v51, v50
	v_fmac_f32_e32 v51, v52, v49
	v_fma_f32 v48, -v48, v51, v50
	v_div_fmas_f32 v48, v48, v49, v51
	v_div_fixup_f32 v45, v48, v45, 1.0
	v_div_scale_f32 v48, s[0:1], v44, v44, 1.0
	v_rcp_f32_e32 v49, v48
	v_pk_add_f32 v[8:9], v[8:9], 1.0 op_sel_hi:[1,0]
	v_mul_f32_e32 v4, 0xbfb8aa3b, v4
	v_mul_f32_e32 v5, 0xbfb8aa3b, v5
	v_fma_f32 v50, -v48, v49, 1.0
	v_fmac_f32_e32 v49, v50, v49
	v_div_scale_f32 v50, vcc, 1.0, v44, 1.0
	v_mul_f32_e32 v51, v50, v49
	v_fma_f32 v52, -v48, v51, v50
	v_fmac_f32_e32 v51, v52, v49
	v_fma_f32 v48, -v48, v51, v50
	v_div_fmas_f32 v48, v48, v49, v51
	v_div_fixup_f32 v44, v48, v44, 1.0
	v_cvt_pk_bf16_f32 v104, v44, v45
	v_mul_f32_e32 v44, 0xbfb8aa3b, v46
	v_mul_f32_e32 v45, 0xbfb8aa3b, v47
	v_exp_f32_e32 v44, v44
	v_exp_f32_e32 v45, v45
	v_exp_f32_e32 v4, v4
	v_exp_f32_e32 v5, v5
	v_mul_f32_e32 v0, 0xbfb8aa3b, v0
; DEVI uint32_t pack2(float lo, float hi) { f32x2_t v = {lo, hi}; bf16x2_t b = __builtin_convertvector(v, bf16x2_t); return __builtin_bit_cast(uint32_t, b); }
; DEVI float sigmoidf_(float x) { return 1.f / (1.f + __expf(-x)); }
; DEVI void phase_p5(const int TIDX, const int BIDX, const int GDIM, KAP KA, unsigned char* WSB, float* OUTB, int l, unsigned char* smem) {
;     ...
; #pragma unroll
;     for (int i = 0; i < 4; ++i)
; #pragma unroll
;       for (int j = 0; j < 4; ++j) gp[i][j] = make_uint2(pack2(sigmoidf_(acc[i][j][0]), sigmoidf_(acc[i][j][1])), pack2(sigmoidf_(acc[i][j][2]), sigmoidf_(acc[i][j][3])));
	v_pk_add_f32 v[44:45], v[44:45], 1.0 op_sel_hi:[1,0]
	v_mul_f32_e32 v1, 0xbfb8aa3b, v1
	v_div_scale_f32 v46, s[0:1], v45, v45, 1.0
	v_rcp_f32_e32 v47, v46
	v_pk_add_f32 v[4:5], v[4:5], 1.0 op_sel_hi:[1,0]
	v_exp_f32_e32 v0, v0
	v_exp_f32_e32 v1, v1
	v_fma_f32 v48, -v46, v47, 1.0
	v_fmac_f32_e32 v47, v48, v47
	v_div_scale_f32 v48, vcc, 1.0, v45, 1.0
	v_mul_f32_e32 v49, v48, v47
	v_fma_f32 v50, -v46, v49, v48
	v_fmac_f32_e32 v49, v50, v47
	v_fma_f32 v46, -v46, v49, v48
	v_div_fmas_f32 v46, v46, v47, v49
	v_div_fixup_f32 v45, v46, v45, 1.0
	v_div_scale_f32 v46, s[0:1], v44, v44, 1.0
	v_rcp_f32_e32 v47, v46
	v_pk_add_f32 v[0:1], v[0:1], 1.0 op_sel_hi:[1,0]
	v_fma_f32 v48, -v46, v47, 1.0
	v_fmac_f32_e32 v47, v48, v47
	v_div_scale_f32 v48, vcc, 1.0, v44, 1.0
	v_mul_f32_e32 v49, v48, v47
	v_fma_f32 v50, -v46, v49, v48
	v_fmac_f32_e32 v49, v50, v47
	v_fma_f32 v46, -v46, v49, v48
	v_div_fmas_f32 v46, v46, v47, v49
	v_div_fixup_f32 v44, v46, v44, 1.0
	v_cvt_pk_bf16_f32 v109, v44, v45
	v_div_scale_f32 v44, s[0:1], v41, v41, 1.0
	v_rcp_f32_e32 v45, v44
	s_nop 0
	v_fma_f32 v46, -v44, v45, 1.0
	v_fmac_f32_e32 v45, v46, v45
	v_div_scale_f32 v46, vcc, 1.0, v41, 1.0
	v_mul_f32_e32 v47, v46, v45
	v_fma_f32 v48, -v44, v47, v46
	v_fmac_f32_e32 v47, v48, v45
	v_fma_f32 v44, -v44, v47, v46
	v_div_fmas_f32 v44, v44, v45, v47
	v_div_fixup_f32 v41, v44, v41, 1.0
	v_div_scale_f32 v44, s[0:1], v40, v40, 1.0
	v_rcp_f32_e32 v45, v44
	s_nop 0
	v_fma_f32 v46, -v44, v45, 1.0
	v_fmac_f32_e32 v45, v46, v45
	v_div_scale_f32 v46, vcc, 1.0, v40, 1.0
	v_mul_f32_e32 v47, v46, v45
	v_fma_f32 v48, -v44, v47, v46
	v_fmac_f32_e32 v47, v48, v45
	v_fma_f32 v44, -v44, v47, v46
	v_div_fmas_f32 v44, v44, v45, v47
	v_div_fixup_f32 v40, v44, v40, 1.0
	v_cvt_pk_bf16_f32 v112, v40, v41
	v_mul_f32_e32 v40, 0xbfb8aa3b, v42
	v_mul_f32_e32 v41, 0xbfb8aa3b, v43
	v_exp_f32_e32 v40, v40
	v_exp_f32_e32 v41, v41
	s_nop 0
	v_pk_add_f32 v[40:41], v[40:41], 1.0 op_sel_hi:[1,0]
	s_nop 0
	v_div_scale_f32 v42, s[0:1], v41, v41, 1.0
	v_rcp_f32_e32 v43, v42
	s_nop 0
	v_fma_f32 v44, -v42, v43, 1.0
	v_fmac_f32_e32 v43, v44, v43
	v_div_scale_f32 v44, vcc, 1.0, v41, 1.0
	v_mul_f32_e32 v45, v44, v43
	v_fma_f32 v46, -v42, v45, v44
	v_fmac_f32_e32 v45, v46, v43
	v_fma_f32 v42, -v42, v45, v44
	v_div_fmas_f32 v42, v42, v43, v45
	v_div_fixup_f32 v41, v42, v41, 1.0
	v_div_scale_f32 v42, s[0:1], v40, v40, 1.0
	v_rcp_f32_e32 v43, v42
	s_nop 0
	v_fma_f32 v44, -v42, v43, 1.0
	v_fmac_f32_e32 v43, v44, v43
	v_div_scale_f32 v44, vcc, 1.0, v40, 1.0
	v_mul_f32_e32 v45, v44, v43
	v_fma_f32 v46, -v42, v45, v44
	v_fmac_f32_e32 v45, v46, v43
	v_fma_f32 v42, -v42, v45, v44
	v_div_fmas_f32 v42, v42, v43, v45
	v_div_fixup_f32 v40, v42, v40, 1.0
	v_cvt_pk_bf16_f32 v115, v40, v41
	v_div_scale_f32 v40, s[0:1], v37, v37, 1.0
	v_rcp_f32_e32 v41, v40
	s_nop 0
	v_fma_f32 v42, -v40, v41, 1.0
	v_fmac_f32_e32 v41, v42, v41
	v_div_scale_f32 v42, vcc, 1.0, v37, 1.0
	v_mul_f32_e32 v43, v42, v41
	v_fma_f32 v44, -v40, v43, v42
	v_fmac_f32_e32 v43, v44, v41
	v_fma_f32 v40, -v40, v43, v42
	v_div_fmas_f32 v40, v40, v41, v43
	v_div_fixup_f32 v37, v40, v37, 1.0
	v_div_scale_f32 v40, s[0:1], v36, v36, 1.0
	v_rcp_f32_e32 v41, v40
	s_nop 0
	v_fma_f32 v42, -v40, v41, 1.0
	v_fmac_f32_e32 v41, v42, v41
	v_div_scale_f32 v42, vcc, 1.0, v36, 1.0
	v_mul_f32_e32 v43, v42, v41
	v_fma_f32 v44, -v40, v43, v42
	v_fmac_f32_e32 v43, v44, v41
	v_fma_f32 v40, -v40, v43, v42
	v_div_fmas_f32 v40, v40, v41, v43
	v_div_fixup_f32 v36, v40, v36, 1.0
	v_cvt_pk_bf16_f32 v113, v36, v37
	v_mul_f32_e32 v36, 0xbfb8aa3b, v38
	v_mul_f32_e32 v37, 0xbfb8aa3b, v39
	v_exp_f32_e32 v36, v36
	v_exp_f32_e32 v37, v37
	s_nop 0
	v_pk_add_f32 v[36:37], v[36:37], 1.0 op_sel_hi:[1,0]
	s_nop 0
	v_div_scale_f32 v38, s[0:1], v37, v37, 1.0
	v_rcp_f32_e32 v39, v38
	s_nop 0
	v_fma_f32 v40, -v38, v39, 1.0
	v_fmac_f32_e32 v39, v40, v39
	v_div_scale_f32 v40, vcc, 1.0, v37, 1.0
	v_mul_f32_e32 v41, v40, v39
	v_fma_f32 v42, -v38, v41, v40
	v_fmac_f32_e32 v41, v42, v39
	v_fma_f32 v38, -v38, v41, v40
	v_div_fmas_f32 v38, v38, v39, v41
	v_div_fixup_f32 v37, v38, v37, 1.0
	v_div_scale_f32 v38, s[0:1], v36, v36, 1.0
	v_rcp_f32_e32 v39, v38
	s_nop 0
	v_fma_f32 v40, -v38, v39, 1.0
	v_fmac_f32_e32 v39, v40, v39
	v_div_scale_f32 v40, vcc, 1.0, v36, 1.0
	v_mul_f32_e32 v41, v40, v39
	v_fma_f32 v42, -v38, v41, v40
	v_fmac_f32_e32 v41, v42, v39
	v_fma_f32 v38, -v38, v41, v40
	v_div_fmas_f32 v38, v38, v39, v41
	v_div_fixup_f32 v36, v38, v36, 1.0
	v_cvt_pk_bf16_f32 v114, v36, v37
	v_div_scale_f32 v36, s[0:1], v33, v33, 1.0
	v_rcp_f32_e32 v37, v36
	s_nop 0
	v_fma_f32 v38, -v36, v37, 1.0
	v_fmac_f32_e32 v37, v38, v37
	v_div_scale_f32 v38, vcc, 1.0, v33, 1.0
	v_mul_f32_e32 v39, v38, v37
	v_fma_f32 v40, -v36, v39, v38
	v_fmac_f32_e32 v39, v40, v37
	v_fma_f32 v36, -v36, v39, v38
	v_div_fmas_f32 v36, v36, v37, v39
	v_div_fixup_f32 v33, v36, v33, 1.0
	v_div_scale_f32 v36, s[0:1], v32, v32, 1.0
	v_rcp_f32_e32 v37, v36
	s_nop 0
	v_fma_f32 v38, -v36, v37, 1.0
	v_fmac_f32_e32 v37, v38, v37
	v_div_scale_f32 v38, vcc, 1.0, v32, 1.0
	v_mul_f32_e32 v39, v38, v37
	v_fma_f32 v40, -v36, v39, v38
	v_fmac_f32_e32 v39, v40, v37
	v_fma_f32 v36, -v36, v39, v38
	v_div_fmas_f32 v36, v36, v37, v39
	v_div_fixup_f32 v32, v36, v32, 1.0
	v_cvt_pk_bf16_f32 v110, v32, v33
	v_mul_f32_e32 v32, 0xbfb8aa3b, v34
	v_mul_f32_e32 v33, 0xbfb8aa3b, v35
	v_exp_f32_e32 v32, v32
	v_exp_f32_e32 v33, v33
	s_nop 0
	v_pk_add_f32 v[32:33], v[32:33], 1.0 op_sel_hi:[1,0]
	s_nop 0
	v_div_scale_f32 v34, s[0:1], v33, v33, 1.0
	v_rcp_f32_e32 v35, v34
	s_nop 0
	v_fma_f32 v36, -v34, v35, 1.0
	v_fmac_f32_e32 v35, v36, v35
	v_div_scale_f32 v36, vcc, 1.0, v33, 1.0
	v_mul_f32_e32 v37, v36, v35
; DEVI uint32_t pack2(float lo, float hi) { f32x2_t v = {lo, hi}; bf16x2_t b = __builtin_convertvector(v, bf16x2_t); return __builtin_bit_cast(uint32_t, b); }
; DEVI float sigmoidf_(float x) { return 1.f / (1.f + __expf(-x)); }
; DEVI void phase_p5(const int TIDX, const int BIDX, const int GDIM, KAP KA, unsigned char* WSB, float* OUTB, int l, unsigned char* smem) {
;     ...
; #pragma unroll
;     for (int i = 0; i < 4; ++i)
; #pragma unroll
;       for (int j = 0; j < 4; ++j) gp[i][j] = make_uint2(pack2(sigmoidf_(acc[i][j][0]), sigmoidf_(acc[i][j][1])), pack2(sigmoidf_(acc[i][j][2]), sigmoidf_(acc[i][j][3])));
	v_fma_f32 v38, -v34, v37, v36
	v_fmac_f32_e32 v37, v38, v35
	v_fma_f32 v34, -v34, v37, v36
	v_div_fmas_f32 v34, v34, v35, v37
	v_div_fixup_f32 v33, v34, v33, 1.0
	v_div_scale_f32 v34, s[0:1], v32, v32, 1.0
	v_rcp_f32_e32 v35, v34
	s_nop 0
	v_fma_f32 v36, -v34, v35, 1.0
	v_fmac_f32_e32 v35, v36, v35
	v_div_scale_f32 v36, vcc, 1.0, v32, 1.0
	v_mul_f32_e32 v37, v36, v35
	v_fma_f32 v38, -v34, v37, v36
	v_fmac_f32_e32 v37, v38, v35
	v_fma_f32 v34, -v34, v37, v36
	v_div_fmas_f32 v34, v34, v35, v37
	v_div_fixup_f32 v32, v34, v32, 1.0
	v_cvt_pk_bf16_f32 v111, v32, v33
	v_div_scale_f32 v32, s[0:1], v29, v29, 1.0
	v_rcp_f32_e32 v33, v32
	s_nop 0
	v_fma_f32 v34, -v32, v33, 1.0
	v_fmac_f32_e32 v33, v34, v33
	v_div_scale_f32 v34, vcc, 1.0, v29, 1.0
	v_mul_f32_e32 v35, v34, v33
	v_fma_f32 v36, -v32, v35, v34
	v_fmac_f32_e32 v35, v36, v33
	v_fma_f32 v32, -v32, v35, v34
	v_div_fmas_f32 v32, v32, v33, v35
	v_div_fixup_f32 v29, v32, v29, 1.0
	v_div_scale_f32 v32, s[0:1], v28, v28, 1.0
	v_rcp_f32_e32 v33, v32
	s_nop 0
	v_fma_f32 v34, -v32, v33, 1.0
	v_fmac_f32_e32 v33, v34, v33
	v_div_scale_f32 v34, vcc, 1.0, v28, 1.0
	v_mul_f32_e32 v35, v34, v33
	v_fma_f32 v36, -v32, v35, v34
	v_fmac_f32_e32 v35, v36, v33
	v_fma_f32 v32, -v32, v35, v34
	v_div_fmas_f32 v32, v32, v33, v35
	v_div_fixup_f32 v28, v32, v28, 1.0
	v_cvt_pk_bf16_f32 v105, v28, v29
	v_mul_f32_e32 v28, 0xbfb8aa3b, v30
	v_mul_f32_e32 v29, 0xbfb8aa3b, v31
	v_exp_f32_e32 v28, v28
	v_exp_f32_e32 v29, v29
	s_nop 0
	v_pk_add_f32 v[28:29], v[28:29], 1.0 op_sel_hi:[1,0]
	s_nop 0
	v_div_scale_f32 v30, s[0:1], v29, v29, 1.0
	v_rcp_f32_e32 v31, v30
	s_nop 0
	v_fma_f32 v32, -v30, v31, 1.0
	v_fmac_f32_e32 v31, v32, v31
	v_div_scale_f32 v32, vcc, 1.0, v29, 1.0
	v_mul_f32_e32 v33, v32, v31
	v_fma_f32 v34, -v30, v33, v32
	v_fmac_f32_e32 v33, v34, v31
	v_fma_f32 v30, -v30, v33, v32
	v_div_fmas_f32 v30, v30, v31, v33
	v_div_fixup_f32 v29, v30, v29, 1.0
	v_div_scale_f32 v30, s[0:1], v28, v28, 1.0
	v_rcp_f32_e32 v31, v30
	s_nop 0
	v_fma_f32 v32, -v30, v31, 1.0
	v_fmac_f32_e32 v31, v32, v31
	v_div_scale_f32 v32, vcc, 1.0, v28, 1.0
	v_mul_f32_e32 v33, v32, v31
	v_fma_f32 v34, -v30, v33, v32
	v_fmac_f32_e32 v33, v34, v31
	v_fma_f32 v30, -v30, v33, v32
	v_div_fmas_f32 v30, v30, v31, v33
	v_div_fixup_f32 v28, v30, v28, 1.0
	v_cvt_pk_bf16_f32 v107, v28, v29
	v_div_scale_f32 v28, s[0:1], v25, v25, 1.0
	v_rcp_f32_e32 v29, v28
	s_nop 0
	v_fma_f32 v30, -v28, v29, 1.0
	v_fmac_f32_e32 v29, v30, v29
	v_div_scale_f32 v30, vcc, 1.0, v25, 1.0
	v_mul_f32_e32 v31, v30, v29
	v_fma_f32 v32, -v28, v31, v30
	v_fmac_f32_e32 v31, v32, v29
	v_fma_f32 v28, -v28, v31, v30
	v_div_fmas_f32 v28, v28, v29, v31
	v_div_fixup_f32 v25, v28, v25, 1.0
	v_div_scale_f32 v28, s[0:1], v24, v24, 1.0
	v_rcp_f32_e32 v29, v28
	s_nop 0
	v_fma_f32 v30, -v28, v29, 1.0
	v_fmac_f32_e32 v29, v30, v29
	v_div_scale_f32 v30, vcc, 1.0, v24, 1.0
	v_mul_f32_e32 v31, v30, v29
	v_fma_f32 v32, -v28, v31, v30
	v_fmac_f32_e32 v31, v32, v29
	v_fma_f32 v28, -v28, v31, v30
	v_div_fmas_f32 v28, v28, v29, v31
	v_div_fixup_f32 v24, v28, v24, 1.0
	v_cvt_pk_bf16_f32 v101, v24, v25
	v_mul_f32_e32 v24, 0xbfb8aa3b, v26
	v_mul_f32_e32 v25, 0xbfb8aa3b, v27
	v_exp_f32_e32 v24, v24
	v_exp_f32_e32 v25, v25
	s_nop 0
	v_pk_add_f32 v[24:25], v[24:25], 1.0 op_sel_hi:[1,0]
	s_nop 0
	v_div_scale_f32 v26, s[0:1], v25, v25, 1.0
	v_rcp_f32_e32 v27, v26
	s_nop 0
	v_fma_f32 v28, -v26, v27, 1.0
	v_fmac_f32_e32 v27, v28, v27
	v_div_scale_f32 v28, vcc, 1.0, v25, 1.0
	v_mul_f32_e32 v29, v28, v27
	v_fma_f32 v30, -v26, v29, v28
	v_fmac_f32_e32 v29, v30, v27
	v_fma_f32 v26, -v26, v29, v28
	v_div_fmas_f32 v26, v26, v27, v29
	v_div_fixup_f32 v25, v26, v25, 1.0
	v_div_scale_f32 v26, s[0:1], v24, v24, 1.0
	v_rcp_f32_e32 v27, v26
	s_nop 0
	v_fma_f32 v28, -v26, v27, 1.0
	v_fmac_f32_e32 v27, v28, v27
	v_div_scale_f32 v28, vcc, 1.0, v24, 1.0
	v_mul_f32_e32 v29, v28, v27
	v_fma_f32 v30, -v26, v29, v28
	v_fmac_f32_e32 v29, v30, v27
	v_fma_f32 v26, -v26, v29, v28
	v_div_fmas_f32 v26, v26, v27, v29
	v_div_fixup_f32 v24, v26, v24, 1.0
	v_cvt_pk_bf16_f32 v106, v24, v25
	v_div_scale_f32 v24, s[0:1], v21, v21, 1.0
	v_rcp_f32_e32 v25, v24
	s_nop 0
	v_fma_f32 v26, -v24, v25, 1.0
	v_fmac_f32_e32 v25, v26, v25
	v_div_scale_f32 v26, vcc, 1.0, v21, 1.0
	v_mul_f32_e32 v27, v26, v25
	v_fma_f32 v28, -v24, v27, v26
	v_fmac_f32_e32 v27, v28, v25
	v_fma_f32 v24, -v24, v27, v26
	v_div_fmas_f32 v24, v24, v25, v27
	v_div_fixup_f32 v21, v24, v21, 1.0
	v_div_scale_f32 v24, s[0:1], v20, v20, 1.0
	v_rcp_f32_e32 v25, v24
	s_nop 0
	v_fma_f32 v26, -v24, v25, 1.0
	v_fmac_f32_e32 v25, v26, v25
	v_div_scale_f32 v26, vcc, 1.0, v20, 1.0
	v_mul_f32_e32 v27, v26, v25
	v_fma_f32 v28, -v24, v27, v26
	v_fmac_f32_e32 v27, v28, v25
	v_fma_f32 v24, -v24, v27, v26
	v_div_fmas_f32 v24, v24, v25, v27
	v_div_fixup_f32 v20, v24, v20, 1.0
	v_cvt_pk_bf16_f32 v99, v20, v21
	v_mul_f32_e32 v20, 0xbfb8aa3b, v22
	v_mul_f32_e32 v21, 0xbfb8aa3b, v23
	v_exp_f32_e32 v20, v20
	v_exp_f32_e32 v21, v21
	s_nop 0
	v_pk_add_f32 v[20:21], v[20:21], 1.0 op_sel_hi:[1,0]
	s_nop 0
	v_div_scale_f32 v22, s[0:1], v21, v21, 1.0
	v_rcp_f32_e32 v23, v22
	s_nop 0
	v_fma_f32 v24, -v22, v23, 1.0
	v_fmac_f32_e32 v23, v24, v23
	v_div_scale_f32 v24, vcc, 1.0, v21, 1.0
	v_mul_f32_e32 v25, v24, v23
	v_fma_f32 v26, -v22, v25, v24
	v_fmac_f32_e32 v25, v26, v23
	v_fma_f32 v22, -v22, v25, v24
	v_div_fmas_f32 v22, v22, v23, v25
	v_div_fixup_f32 v21, v22, v21, 1.0
	v_div_scale_f32 v22, s[0:1], v20, v20, 1.0
	v_rcp_f32_e32 v23, v22
	s_nop 0
	v_fma_f32 v24, -v22, v23, 1.0
	v_fmac_f32_e32 v23, v24, v23
	v_div_scale_f32 v24, vcc, 1.0, v20, 1.0
	v_mul_f32_e32 v25, v24, v23
	v_fma_f32 v26, -v22, v25, v24
; DEVI uint32_t pack2(float lo, float hi) { f32x2_t v = {lo, hi}; bf16x2_t b = __builtin_convertvector(v, bf16x2_t); return __builtin_bit_cast(uint32_t, b); }
; DEVI float sigmoidf_(float x) { return 1.f / (1.f + __expf(-x)); }
; DEVI void phase_p5(const int TIDX, const int BIDX, const int GDIM, KAP KA, unsigned char* WSB, float* OUTB, int l, unsigned char* smem) {
;     ...
; #pragma unroll
;     for (int i = 0; i < 4; ++i)
; #pragma unroll
;       for (int j = 0; j < 4; ++j) gp[i][j] = make_uint2(pack2(sigmoidf_(acc[i][j][0]), sigmoidf_(acc[i][j][1])), pack2(sigmoidf_(acc[i][j][2]), sigmoidf_(acc[i][j][3])));
	v_fmac_f32_e32 v25, v26, v23
	v_fma_f32 v22, -v22, v25, v24
	v_div_fmas_f32 v22, v22, v23, v25
	v_div_fixup_f32 v20, v22, v20, 1.0
	v_cvt_pk_bf16_f32 v103, v20, v21
	v_div_scale_f32 v20, s[0:1], v17, v17, 1.0
	v_rcp_f32_e32 v21, v20
	s_nop 0
	v_fma_f32 v22, -v20, v21, 1.0
	v_fmac_f32_e32 v21, v22, v21
	v_div_scale_f32 v22, vcc, 1.0, v17, 1.0
	v_mul_f32_e32 v23, v22, v21
	v_fma_f32 v24, -v20, v23, v22
	v_fmac_f32_e32 v23, v24, v21
	v_fma_f32 v20, -v20, v23, v22
	v_div_fmas_f32 v20, v20, v21, v23
	v_div_fixup_f32 v17, v20, v17, 1.0
	v_div_scale_f32 v20, s[0:1], v16, v16, 1.0
	v_rcp_f32_e32 v21, v20
	s_nop 0
	v_fma_f32 v22, -v20, v21, 1.0
	v_fmac_f32_e32 v21, v22, v21
	v_div_scale_f32 v22, vcc, 1.0, v16, 1.0
	v_mul_f32_e32 v23, v22, v21
	v_fma_f32 v24, -v20, v23, v22
	v_fmac_f32_e32 v23, v24, v21
	v_fma_f32 v20, -v20, v23, v22
	v_div_fmas_f32 v20, v20, v21, v23
	v_div_fixup_f32 v16, v20, v16, 1.0
	v_cvt_pk_bf16_f32 v96, v16, v17
	v_mul_f32_e32 v16, 0xbfb8aa3b, v18
	v_mul_f32_e32 v17, 0xbfb8aa3b, v19
	v_exp_f32_e32 v16, v16
	v_exp_f32_e32 v17, v17
	s_nop 0
	v_pk_add_f32 v[16:17], v[16:17], 1.0 op_sel_hi:[1,0]
	s_nop 0
	v_div_scale_f32 v18, s[0:1], v17, v17, 1.0
	v_rcp_f32_e32 v19, v18
	s_nop 0
	v_fma_f32 v20, -v18, v19, 1.0
	v_fmac_f32_e32 v19, v20, v19
	v_div_scale_f32 v20, vcc, 1.0, v17, 1.0
	v_mul_f32_e32 v21, v20, v19
	v_fma_f32 v22, -v18, v21, v20
	v_fmac_f32_e32 v21, v22, v19
	v_fma_f32 v18, -v18, v21, v20
	v_div_fmas_f32 v18, v18, v19, v21
	v_div_fixup_f32 v17, v18, v17, 1.0
	v_div_scale_f32 v18, s[0:1], v16, v16, 1.0
	v_rcp_f32_e32 v19, v18
	s_nop 0
	v_fma_f32 v20, -v18, v19, 1.0
	v_fmac_f32_e32 v19, v20, v19
	v_div_scale_f32 v20, vcc, 1.0, v16, 1.0
	v_mul_f32_e32 v21, v20, v19
	v_fma_f32 v22, -v18, v21, v20
	v_fmac_f32_e32 v21, v22, v19
	v_fma_f32 v18, -v18, v21, v20
	v_div_fmas_f32 v18, v18, v19, v21
	v_div_fixup_f32 v16, v18, v16, 1.0
	v_cvt_pk_bf16_f32 v98, v16, v17
	v_div_scale_f32 v16, s[0:1], v13, v13, 1.0
	v_rcp_f32_e32 v17, v16
	s_nop 0
	v_fma_f32 v18, -v16, v17, 1.0
	v_fmac_f32_e32 v17, v18, v17
	v_div_scale_f32 v18, vcc, 1.0, v13, 1.0
	v_mul_f32_e32 v19, v18, v17
	v_fma_f32 v20, -v16, v19, v18
	v_fmac_f32_e32 v19, v20, v17
	v_fma_f32 v16, -v16, v19, v18
	v_div_fmas_f32 v16, v16, v17, v19
	v_div_fixup_f32 v13, v16, v13, 1.0
	v_div_scale_f32 v16, s[0:1], v12, v12, 1.0
	v_rcp_f32_e32 v17, v16
	s_nop 0
	v_fma_f32 v18, -v16, v17, 1.0
	v_fmac_f32_e32 v17, v18, v17
	v_div_scale_f32 v18, vcc, 1.0, v12, 1.0
	v_mul_f32_e32 v19, v18, v17
	v_fma_f32 v20, -v16, v19, v18
	v_fmac_f32_e32 v19, v20, v17
	v_fma_f32 v16, -v16, v19, v18
	v_div_fmas_f32 v16, v16, v17, v19
	v_div_fixup_f32 v12, v16, v12, 1.0
	v_cvt_pk_bf16_f32 v90, v12, v13
	v_mul_f32_e32 v12, 0xbfb8aa3b, v14
	v_mul_f32_e32 v13, 0xbfb8aa3b, v15
	v_exp_f32_e32 v12, v12
	v_exp_f32_e32 v13, v13
	s_nop 0
	v_pk_add_f32 v[12:13], v[12:13], 1.0 op_sel_hi:[1,0]
	s_nop 0
	v_div_scale_f32 v14, s[0:1], v13, v13, 1.0
	v_rcp_f32_e32 v15, v14
	s_nop 0
	v_fma_f32 v16, -v14, v15, 1.0
	v_fmac_f32_e32 v15, v16, v15
	v_div_scale_f32 v16, vcc, 1.0, v13, 1.0
	v_mul_f32_e32 v17, v16, v15
	v_fma_f32 v18, -v14, v17, v16
	v_fmac_f32_e32 v17, v18, v15
	v_fma_f32 v14, -v14, v17, v16
	v_div_fmas_f32 v14, v14, v15, v17
	v_div_fixup_f32 v13, v14, v13, 1.0
	v_div_scale_f32 v14, s[0:1], v12, v12, 1.0
	v_rcp_f32_e32 v15, v14
	s_nop 0
	v_fma_f32 v16, -v14, v15, 1.0
	v_fmac_f32_e32 v15, v16, v15
	v_div_scale_f32 v16, vcc, 1.0, v12, 1.0
	v_mul_f32_e32 v17, v16, v15
	v_fma_f32 v18, -v14, v17, v16
	v_fmac_f32_e32 v17, v18, v15
	v_fma_f32 v14, -v14, v17, v16
	v_div_fmas_f32 v14, v14, v15, v17
	v_div_fixup_f32 v12, v14, v12, 1.0
	v_cvt_pk_bf16_f32 v93, v12, v13
	v_div_scale_f32 v12, s[0:1], v9, v9, 1.0
	v_rcp_f32_e32 v13, v12
	s_nop 0
	v_fma_f32 v14, -v12, v13, 1.0
	v_fmac_f32_e32 v13, v14, v13
	v_div_scale_f32 v14, vcc, 1.0, v9, 1.0
	v_mul_f32_e32 v15, v14, v13
	v_fma_f32 v16, -v12, v15, v14
	v_fmac_f32_e32 v15, v16, v13
	v_fma_f32 v12, -v12, v15, v14
	v_div_fmas_f32 v12, v12, v13, v15
	v_div_fixup_f32 v9, v12, v9, 1.0
	v_div_scale_f32 v12, s[0:1], v8, v8, 1.0
	v_rcp_f32_e32 v13, v12
	s_nop 0
	v_fma_f32 v14, -v12, v13, 1.0
	v_fmac_f32_e32 v13, v14, v13
	v_div_scale_f32 v14, vcc, 1.0, v8, 1.0
	v_mul_f32_e32 v15, v14, v13
	v_fma_f32 v16, -v12, v15, v14
	v_fmac_f32_e32 v15, v16, v13
	v_fma_f32 v12, -v12, v15, v14
	v_div_fmas_f32 v12, v12, v13, v15
	v_div_fixup_f32 v8, v12, v8, 1.0
	v_cvt_pk_bf16_f32 v88, v8, v9
	v_mul_f32_e32 v8, 0xbfb8aa3b, v10
	v_mul_f32_e32 v9, 0xbfb8aa3b, v11
	v_exp_f32_e32 v8, v8
	v_exp_f32_e32 v9, v9
	s_nop 0
	v_pk_add_f32 v[8:9], v[8:9], 1.0 op_sel_hi:[1,0]
	s_nop 0
	v_div_scale_f32 v10, s[0:1], v9, v9, 1.0
	v_rcp_f32_e32 v11, v10
	s_nop 0
	v_fma_f32 v12, -v10, v11, 1.0
	v_fmac_f32_e32 v11, v12, v11
	v_div_scale_f32 v12, vcc, 1.0, v9, 1.0
	v_mul_f32_e32 v13, v12, v11
	v_fma_f32 v14, -v10, v13, v12
	v_fmac_f32_e32 v13, v14, v11
	v_fma_f32 v10, -v10, v13, v12
	v_div_fmas_f32 v10, v10, v11, v13
	v_div_fixup_f32 v9, v10, v9, 1.0
	v_div_scale_f32 v10, s[0:1], v8, v8, 1.0
	v_rcp_f32_e32 v11, v10
	s_nop 0
	v_fma_f32 v12, -v10, v11, 1.0
	v_fmac_f32_e32 v11, v12, v11
	v_div_scale_f32 v12, vcc, 1.0, v8, 1.0
	v_mul_f32_e32 v13, v12, v11
	v_fma_f32 v14, -v10, v13, v12
	v_fmac_f32_e32 v13, v14, v11
	v_fma_f32 v10, -v10, v13, v12
	v_div_fmas_f32 v10, v10, v11, v13
	v_div_fixup_f32 v8, v10, v8, 1.0
	v_cvt_pk_bf16_f32 v92, v8, v9
	v_div_scale_f32 v8, s[0:1], v5, v5, 1.0
	v_rcp_f32_e32 v9, v8
	s_nop 0
	v_fma_f32 v10, -v8, v9, 1.0
	v_fmac_f32_e32 v9, v10, v9
	v_div_scale_f32 v10, vcc, 1.0, v5, 1.0
	v_mul_f32_e32 v11, v10, v9
	v_fma_f32 v12, -v8, v11, v10
	v_fmac_f32_e32 v11, v12, v9
	v_fma_f32 v8, -v8, v11, v10
; DEVI uint32_t pack2(float lo, float hi) { f32x2_t v = {lo, hi}; bf16x2_t b = __builtin_convertvector(v, bf16x2_t); return __builtin_bit_cast(uint32_t, b); }
; DEVI float sigmoidf_(float x) { return 1.f / (1.f + __expf(-x)); }
; template <bool SWAP, class RP>
; DEVI void gemm_main(const int TIDX, const int BIDX, const int GDIM, f32x4 (&acc)[4][4], RP rowoff, const bf16_t* __restrict__ Bt, int ldb, int K, unsigned char* smem) {
;     ...
;   const uint32_t schunk = (uint32_t)((lane & 7) ^ (((lane >> 4) + 4 * (w & 1)) & 7)) * 16u;
;   uint32_t ao0, ao1, ao2, ao3;
;   const int rsub = w * 8 + (lane >> 3);
;   ao0 = rowoff(rsub) + schunk; ao1 = rowoff(rsub + 32) + schunk; ao2 = rowoff(rsub + 64) + schunk; ao3 = rowoff(rsub + 96) + schunk;
;   const uint32_t bo = (uint32_t)(rsub * ldb) * 2u + schunk, bstep = (uint32_t)(32 * ldb) * 2u;
;   unsigned char* sbase = smem + w * 1024;
;     ...
;   const int nk = K >> 6;
;   const int px = lg ^ (li >> 1);
;   GM_STAGE(0, 0);
; DEVI void phase_p5(const int TIDX, const int BIDX, const int GDIM, KAP KA, unsigned char* WSB, float* OUTB, int l, unsigned char* smem) {
;     ...
; #pragma unroll
;     for (int i = 0; i < 4; ++i)
; #pragma unroll
;       for (int j = 0; j < 4; ++j) gp[i][j] = make_uint2(pack2(sigmoidf_(acc[i][j][0]), sigmoidf_(acc[i][j][1])), pack2(sigmoidf_(acc[i][j][2]), sigmoidf_(acc[i][j][3])));
;     zero_acc(acc);
;     gemm_main<true>(TIDX, BIDX, GDIM, acc, ro, W + WO_BRB + (size_t)n0 * 512, 512, 512, smem);
	v_div_fmas_f32 v8, v8, v9, v11
	v_div_fixup_f32 v5, v8, v5, 1.0
	v_div_scale_f32 v8, s[0:1], v4, v4, 1.0
	v_rcp_f32_e32 v9, v8
	s_nop 0
	v_fma_f32 v10, -v8, v9, 1.0
	v_fmac_f32_e32 v9, v10, v9
	v_div_scale_f32 v10, vcc, 1.0, v4, 1.0
	v_mul_f32_e32 v11, v10, v9
	v_fma_f32 v12, -v8, v11, v10
	v_fmac_f32_e32 v11, v12, v9
	v_fma_f32 v8, -v8, v11, v10
	v_div_fmas_f32 v8, v8, v9, v11
	v_div_fixup_f32 v4, v8, v4, 1.0
	v_cvt_pk_bf16_f32 v87, v4, v5
	v_mul_f32_e32 v4, 0xbfb8aa3b, v6
	v_mul_f32_e32 v5, 0xbfb8aa3b, v7
	v_exp_f32_e32 v4, v4
	v_exp_f32_e32 v5, v5
	s_nop 0
	v_pk_add_f32 v[4:5], v[4:5], 1.0 op_sel_hi:[1,0]
	s_nop 0
	v_div_scale_f32 v6, s[0:1], v5, v5, 1.0
	v_rcp_f32_e32 v7, v6
	s_nop 0
	v_fma_f32 v8, -v6, v7, 1.0
	v_fmac_f32_e32 v7, v8, v7
	v_div_scale_f32 v8, vcc, 1.0, v5, 1.0
	v_mul_f32_e32 v9, v8, v7
	v_fma_f32 v10, -v6, v9, v8
	v_fmac_f32_e32 v9, v10, v7
	v_fma_f32 v6, -v6, v9, v8
	v_div_fmas_f32 v6, v6, v7, v9
	v_div_fixup_f32 v5, v6, v5, 1.0
	v_div_scale_f32 v6, s[0:1], v4, v4, 1.0
	v_rcp_f32_e32 v7, v6
	s_nop 0
	v_fma_f32 v8, -v6, v7, 1.0
	v_fmac_f32_e32 v7, v8, v7
	v_div_scale_f32 v8, vcc, 1.0, v4, 1.0
	v_mul_f32_e32 v9, v8, v7
	v_fma_f32 v10, -v6, v9, v8
	v_fmac_f32_e32 v9, v10, v7
	v_fma_f32 v6, -v6, v9, v8
	v_div_fmas_f32 v6, v6, v7, v9
	v_div_fixup_f32 v4, v6, v4, 1.0
	v_cvt_pk_bf16_f32 v89, v4, v5
	v_div_scale_f32 v4, s[0:1], v1, v1, 1.0
	v_rcp_f32_e32 v5, v4
	v_mov_b32_e32 v10, v130
	v_mov_b32_e32 v9, v129
	v_fma_f32 v6, -v4, v5, 1.0
	v_fmac_f32_e32 v5, v6, v5
	v_div_scale_f32 v6, vcc, 1.0, v1, 1.0
	v_mul_f32_e32 v7, v6, v5
	v_fma_f32 v8, -v4, v7, v6
	v_fmac_f32_e32 v7, v8, v5
	v_fma_f32 v4, -v4, v7, v6
	v_div_fmas_f32 v4, v4, v5, v7
	v_div_fixup_f32 v1, v4, v1, 1.0
	v_div_scale_f32 v4, s[0:1], v0, v0, 1.0
	v_rcp_f32_e32 v5, v4
	s_nop 0
	v_fma_f32 v6, -v4, v5, 1.0
	v_fmac_f32_e32 v5, v6, v5
	v_div_scale_f32 v6, vcc, 1.0, v0, 1.0
	v_mul_f32_e32 v7, v6, v5
	v_fma_f32 v8, -v4, v7, v6
	v_fmac_f32_e32 v7, v8, v5
	v_fma_f32 v4, -v4, v7, v6
	v_div_fmas_f32 v4, v4, v5, v7
	v_div_fixup_f32 v0, v4, v0, 1.0
	v_cvt_pk_bf16_f32 v84, v0, v1
	v_mul_f32_e32 v0, 0xbfb8aa3b, v2
	v_mul_f32_e32 v1, 0xbfb8aa3b, v3
	v_exp_f32_e32 v0, v0
	v_exp_f32_e32 v1, v1
	s_nop 0
	v_pk_add_f32 v[0:1], v[0:1], 1.0 op_sel_hi:[1,0]
	s_nop 0
	v_div_scale_f32 v2, s[0:1], v1, v1, 1.0
	v_rcp_f32_e32 v3, v2
	s_nop 0
	v_fma_f32 v4, -v2, v3, 1.0
	v_fmac_f32_e32 v3, v4, v3
	v_div_scale_f32 v4, vcc, 1.0, v1, 1.0
	v_mul_f32_e32 v5, v4, v3
	v_fma_f32 v6, -v2, v5, v4
	v_fmac_f32_e32 v5, v6, v3
	v_fma_f32 v2, -v2, v5, v4
	v_div_fmas_f32 v2, v2, v3, v5
	v_div_fixup_f32 v1, v2, v1, 1.0
	v_div_scale_f32 v2, s[0:1], v0, v0, 1.0
	v_rcp_f32_e32 v3, v2
	s_lshl_b64 s[0:1], s[6:7], 1
	s_add_u32 s0, s19, s0
	s_addc_u32 s1, s20, s1
	v_fma_f32 v4, -v2, v3, 1.0
	v_fmac_f32_e32 v3, v4, v3
	v_div_scale_f32 v4, vcc, 1.0, v0, 1.0
	v_mul_f32_e32 v5, v4, v3
	v_fma_f32 v6, -v2, v5, v4
	v_fmac_f32_e32 v5, v6, v3
	v_fma_f32 v2, -v2, v5, v4
	v_div_fmas_f32 v2, v2, v3, v5
	v_div_fixup_f32 v0, v2, v0, 1.0
	v_cvt_pk_bf16_f32 v85, v0, v1
	v_mov_b32_e32 v0, v129
	s_lshl_b32 s6, s13, 1
	v_ashrrev_i32_e32 v5, 6, v10
	v_and_b32_e32 v11, 1, v5
	v_bfe_u32 v4, v10, 4, 2
	v_and_b32_e32 v6, 7, v10
	v_lshlrev_b32_e32 v7, 2, v11
	v_bitop3_b32 v4, v7, v6, v4 bitop3:0x36
	v_lshlrev_b32_e32 v6, 13, v5
	v_lshlrev_b32_e32 v7, 7, v10
	v_and_or_b32 v6, v7, s8, v6
	v_lshl_or_b32 v128, v4, 4, v6
	v_add_u32_e32 v4, 0x8000, v128
	v_lshlrev_b32_e32 v13, 10, v5
	v_mov_b32_e32 v5, v129
	v_readfirstlane_b32 s12, v13
	v_lshl_add_u64 v[76:77], s[0:1], 0, v[4:5]
	v_add_u32_e32 v5, 0x1000, v13
	s_mov_b32 m0, s12
	v_readfirstlane_b32 s13, v5
	global_load_lds_dwordx4 v128, s[0:1]
	s_mov_b32 m0, s13
	s_add_u32 s6, s27, s6
	global_load_lds_dwordx4 v4, s[0:1]
	v_add_u32_e32 v4, 0x2000, v13
	v_add_u32_e32 v6, 0x10000, v128
	v_readfirstlane_b32 s14, v4
	v_add_u32_e32 v4, 0x3000, v13
	v_add_u32_e32 v14, 0x4000, v13
	v_mov_b32_e32 v7, v129
	s_mov_b32 m0, s14
	v_readfirstlane_b32 s15, v4
	s_addc_u32 s7, s28, 0
	v_add_u32_e32 v8, 0x18000, v128
	v_lshl_add_u64 v[78:79], s[0:1], 0, v[6:7]
	global_load_lds_dwordx4 v6, s[0:1]
	s_mov_b32 m0, s15
	v_readfirstlane_b32 s37, v14
	v_add_u32_e32 v6, 0x5000, v13
	global_load_lds_dwordx4 v8, s[0:1]
	v_lshl_add_u64 v[74:75], s[6:7], 0, v[128:129]
	s_mov_b32 m0, s37
	v_readfirstlane_b32 s38, v6
	v_add_u32_e32 v6, 0x6000, v13
	global_load_lds_dwordx4 v128, s[6:7]
	v_lshl_add_u64 v[4:5], v[74:75], 0, s[58:59]
	s_mov_b32 m0, s38
	v_readfirstlane_b32 s39, v6
	v_add_u32_e32 v6, 0x7000, v13
	v_lshl_add_u64 v[72:73], s[0:1], 0, v[128:129]
	v_lshl_add_u64 v[80:81], s[0:1], 0, v[8:9]
	global_load_lds_dwordx4 v[4:5], off
	v_lshl_add_u64 v[4:5], v[74:75], 0, s[42:43]
	s_mov_b32 m0, s39
	s_mov_b64 s[0:1], 0x18000
	v_readfirstlane_b32 s40, v6
	global_load_lds_dwordx4 v[4:5], off
	v_lshl_add_u64 v[4:5], v[74:75], 0, s[0:1]
	s_mov_b32 m0, s40
	v_lshrrev_b32_e32 v6, 1, v10
	global_load_lds_dwordx4 v[4:5], off
	v_and_b32_e32 v4, 15, v10
	v_lshrrev_b32_e32 v12, 4, v10
	v_bfe_u32 v5, v10, 1, 3
	v_and_or_b32 v6, v6, s41, v4
	v_add_u32_e32 v7, 0x8000, v13
	v_lshlrev_b32_e32 v44, 7, v6
	v_lshlrev_b32_e32 v6, 7, v4
	v_bitop3_b32 v4, v5, v12, 3 bitop3:0x78
	v_readfirstlane_b32 s0, v7
	v_add_u32_e32 v7, 0x9000, v13
	v_lshlrev_b32_e32 v45, 4, v4
	v_lshl_add_u64 v[4:5], v[72:73], 0, s[66:67]
	s_mov_b32 m0, s0
	v_readfirstlane_b32 s1, v7
	v_add_u32_e32 v7, 0xa000, v13
	s_waitcnt vmcnt(0)
	s_waitcnt vmcnt(0) lgkmcnt(0)
	s_barrier
; DEVI f32x4 mfma16(bf16x8 a, bf16x8 b, f32x4 c) { return __builtin_amdgcn_mfma_f32_16x16x32_bf16(a, b, c, 0, 0, 0); }
; template <bool SWAP, class RP>
; DEVI void gemm_main(const int TIDX, const int BIDX, const int GDIM, f32x4 (&acc)[4][4], RP rowoff, const bf16_t* __restrict__ Bt, int ldb, int K, unsigned char* smem) {
;     ...
;   GM_STAGE(0, 0);
;   for (int kt = 0; kt < nk; ++kt) {
;     const int buf = kt & 1;
;     asm volatile("s_waitcnt vmcnt(0)" ::: "memory");
;     __syncthreads();
;     if (kt + 1 < nk) GM_STAGE(kt + 1, buf ^ 1);
;     const unsigned char* A = smem + buf * 32768 + (wr * 64 + li) * 128;
;     const unsigned char* B = smem + buf * 32768 + 16384 + (wc * 64 + li) * 128;
; #pragma unroll
;     for (int ks = 0; ks < 2; ++ks) {
;       const int po = (px ^ (ks * 4)) * 16;
;       bf16x8 af[4], bfr[4];
; #pragma unroll
;       for (int i = 0; i < 4; ++i) {
;         af[i] = *(const bf16x8*)(A + i * 2048 + po);
;         bfr[i] = *(const bf16x8*)(B + i * 2048 + po);
;       }
; #pragma unroll
;       for (int mi = 0; mi < 4; ++mi)
; #pragma unroll
;         for (int ni = 0; ni < 4; ++ni)
;           acc[mi][ni] = SWAP ? mfma16(bfr[ni], af[mi], acc[mi][ni]) : mfma16(af[mi], bfr[ni], acc[mi][ni]);
;     }
;   }
	global_load_lds_dwordx4 v[4:5], off
	v_lshl_add_u64 v[4:5], v[76:77], 0, s[66:67]
	s_mov_b32 m0, s1
	v_readfirstlane_b32 s6, v7
	v_add_u32_e32 v7, 0xb000, v13
	v_add_u32_e32 v8, 0xc000, v13
	global_load_lds_dwordx4 v[4:5], off
	v_lshl_add_u64 v[4:5], v[78:79], 0, s[66:67]
	s_mov_b32 m0, s6
	v_readfirstlane_b32 s7, v7
	global_load_lds_dwordx4 v[4:5], off
	v_lshl_add_u64 v[4:5], v[80:81], 0, s[66:67]
	s_mov_b32 m0, s7
	v_readfirstlane_b32 s8, v8
	v_add_u32_e32 v7, 0xd000, v13
	global_load_lds_dwordx4 v[4:5], off
	v_lshl_add_u64 v[4:5], v[74:75], 0, s[66:67]
	s_mov_b32 m0, s8
	v_readfirstlane_b32 s9, v7
	v_add_u32_e32 v7, 0xe000, v13
	global_load_lds_dwordx4 v[4:5], off
	v_lshl_add_u64 v[4:5], v[74:75], 0, s[10:11]
	s_mov_b32 m0, s9
	v_readfirstlane_b32 s10, v7
	v_add_u32_e32 v7, 0xf000, v13
	global_load_lds_dwordx4 v[4:5], off
	v_lshl_add_u64 v[4:5], v[74:75], 0, s[70:71]
	s_mov_b32 m0, s10
	v_readfirstlane_b32 s11, v7
	global_load_lds_dwordx4 v[4:5], off
	v_lshl_add_u64 v[4:5], v[74:75], 0, s[44:45]
	s_mov_b32 m0, s11
	v_lshl_or_b32 v47, v11, 13, v6
	global_load_lds_dwordx4 v[4:5], off
	v_or_b32_e32 v116, v44, v45
	v_or_b32_e32 v117, v47, v45
	ds_read_b128 v[4:7], v116
	ds_read_b128 v[8:11], v117 offset:16384
	ds_read_b128 v[12:15], v116 offset:2048
	ds_read_b128 v[16:19], v117 offset:18432
	ds_read_b128 v[20:23], v116 offset:4096
	ds_read_b128 v[24:27], v117 offset:20480
	ds_read_b128 v[28:31], v116 offset:6144
	ds_read_b128 v[32:35], v117 offset:22528
	v_mov_b32_e32 v1, v0
	v_mov_b32_e32 v2, v0
	v_mov_b32_e32 v3, v0
	v_xor_b32_e32 v46, 64, v45
	v_bitop3_b32 v118, v44, v45, 64 bitop3:0xf6
	s_waitcnt lgkmcnt(0)
	v_mfma_f32_16x16x32_bf16 v[48:51], v[24:27], v[4:7], v[0:3]
	v_or_b32_e32 v119, v47, v46
	s_mov_b64 s[44:45], 0x100
	s_mov_b32 m0, s12
	v_mfma_f32_16x16x32_bf16 v[56:59], v[16:19], v[12:15], v[0:3]
	v_mfma_f32_16x16x32_bf16 v[36:39], v[8:11], v[4:7], v[0:3]
	v_mfma_f32_16x16x32_bf16 v[40:43], v[16:19], v[4:7], v[0:3]
	v_mfma_f32_16x16x32_bf16 v[4:7], v[32:35], v[4:7], v[0:3]
	v_mfma_f32_16x16x32_bf16 v[52:55], v[8:11], v[12:15], v[0:3]
	v_mfma_f32_16x16x32_bf16 v[60:63], v[24:27], v[12:15], v[0:3]
	v_mfma_f32_16x16x32_bf16 v[12:15], v[32:35], v[12:15], v[0:3]
	v_mfma_f32_16x16x32_bf16 v[120:123], v[8:11], v[20:23], v[0:3]
	v_mfma_f32_16x16x32_bf16 v[124:127], v[16:19], v[20:23], v[0:3]
	v_mfma_f32_16x16x32_bf16 v[132:135], v[24:27], v[20:23], v[0:3]
	v_mfma_f32_16x16x32_bf16 v[20:23], v[32:35], v[20:23], v[0:3]
	v_mfma_f32_16x16x32_bf16 v[136:139], v[8:11], v[28:31], v[0:3]
	v_mfma_f32_16x16x32_bf16 v[140:143], v[16:19], v[28:31], v[0:3]
	v_mfma_f32_16x16x32_bf16 v[144:147], v[24:27], v[28:31], v[0:3]
	v_mfma_f32_16x16x32_bf16 v[148:151], v[32:35], v[28:31], v[0:3]
	s_nop 2
	ds_read_b128 v[0:3], v118
	ds_read_b128 v[24:27], v119 offset:16384
	ds_read_b128 v[8:11], v118 offset:2048
	ds_read_b128 v[152:155], v119 offset:18432
	ds_read_b128 v[156:159], v118 offset:4096
	ds_read_b128 v[162:165], v119 offset:20480
	ds_read_b128 v[166:169], v118 offset:6144
	ds_read_b128 v[170:173], v119 offset:22528
	s_waitcnt vmcnt(0)
	s_waitcnt vmcnt(0) lgkmcnt(0)
	v_mfma_f32_16x16x32_bf16 v[178:181], v[162:165], v[0:3], v[48:51]
	s_barrier
	v_mfma_f32_16x16x32_bf16 v[48:51], v[152:155], v[8:11], v[56:59]
	s_nop 2
	v_lshl_add_u64 v[56:57], v[72:73], 0, s[44:45]
	global_load_lds_dwordx4 v[56:57], off
	v_lshl_add_u64 v[56:57], v[76:77], 0, s[44:45]
	s_mov_b32 m0, s13
	v_mfma_f32_16x16x32_bf16 v[174:177], v[24:27], v[0:3], v[36:39]
	global_load_lds_dwordx4 v[56:57], off
	v_lshl_add_u64 v[56:57], v[78:79], 0, s[44:45]
	s_mov_b32 m0, s14
	v_mfma_f32_16x16x32_bf16 v[44:47], v[152:155], v[0:3], v[40:43]
	global_load_lds_dwordx4 v[56:57], off
	v_lshl_add_u64 v[56:57], v[80:81], 0, s[44:45]
	s_mov_b32 m0, s15
	v_mfma_f32_16x16x32_bf16 v[28:31], v[170:173], v[0:3], v[4:7]
	global_load_lds_dwordx4 v[56:57], off
	v_lshl_add_u64 v[56:57], v[74:75], 0, s[44:45]
	s_mov_b32 m0, s37
	s_mov_b64 s[44:45], 0x8100
	global_load_lds_dwordx4 v[56:57], off
	v_lshl_add_u64 v[56:57], v[74:75], 0, s[44:45]
	s_mov_b32 m0, s38
	s_mov_b64 s[44:45], 0x10100
	global_load_lds_dwordx4 v[56:57], off
	v_lshl_add_u64 v[56:57], v[74:75], 0, s[44:45]
	s_mov_b32 m0, s39
	s_mov_b64 s[44:45], 0x18100
	global_load_lds_dwordx4 v[56:57], off
	v_lshl_add_u64 v[56:57], v[74:75], 0, s[44:45]
	s_mov_b32 m0, s40
	v_mfma_f32_16x16x32_bf16 v[52:55], v[24:27], v[8:11], v[52:55]
	global_load_lds_dwordx4 v[56:57], off
	s_mov_b64 s[44:45], 0x180
	v_mfma_f32_16x16x32_bf16 v[32:35], v[162:165], v[8:11], v[60:63]
	s_mov_b32 m0, s0
	v_mfma_f32_16x16x32_bf16 v[36:39], v[170:173], v[8:11], v[12:15]
	v_mfma_f32_16x16x32_bf16 v[8:11], v[24:27], v[156:159], v[120:123]
	v_mfma_f32_16x16x32_bf16 v[40:43], v[152:155], v[156:159], v[124:127]
	v_mfma_f32_16x16x32_bf16 v[16:19], v[162:165], v[156:159], v[132:135]
	v_mfma_f32_16x16x32_bf16 v[24:27], v[24:27], v[166:169], v[136:139]
	v_mfma_f32_16x16x32_bf16 v[12:15], v[152:155], v[166:169], v[140:143]
	v_mfma_f32_16x16x32_bf16 v[0:3], v[162:165], v[166:169], v[144:147]
	ds_read_b128 v[56:59], v116 offset:32768
	ds_read_b128 v[60:63], v117 offset:49152
	ds_read_b128 v[120:123], v116 offset:34816
	ds_read_b128 v[124:127], v117 offset:51200
	ds_read_b128 v[132:135], v116 offset:36864
	ds_read_b128 v[136:139], v117 offset:53248
	ds_read_b128 v[140:143], v116 offset:38912
	ds_read_b128 v[144:147], v117 offset:55296
	v_mfma_f32_16x16x32_bf16 v[20:23], v[170:173], v[156:159], v[20:23]
	v_mfma_f32_16x16x32_bf16 v[4:7], v[170:173], v[166:169], v[148:151]
	s_waitcnt lgkmcnt(0)
; DEVI f32x4 mfma16(bf16x8 a, bf16x8 b, f32x4 c) { return __builtin_amdgcn_mfma_f32_16x16x32_bf16(a, b, c, 0, 0, 0); }
; template <bool SWAP, class RP>
; DEVI void gemm_main(const int TIDX, const int BIDX, const int GDIM, f32x4 (&acc)[4][4], RP rowoff, const bf16_t* __restrict__ Bt, int ldb, int K, unsigned char* smem) {
;     ...
;   GM_STAGE(0, 0);
;   for (int kt = 0; kt < nk; ++kt) {
;     const int buf = kt & 1;
;     asm volatile("s_waitcnt vmcnt(0)" ::: "memory");
;     __syncthreads();
;     if (kt + 1 < nk) GM_STAGE(kt + 1, buf ^ 1);
;     const unsigned char* A = smem + buf * 32768 + (wr * 64 + li) * 128;
;     const unsigned char* B = smem + buf * 32768 + 16384 + (wc * 64 + li) * 128;
; #pragma unroll
;     for (int ks = 0; ks < 2; ++ks) {
;       const int po = (px ^ (ks * 4)) * 16;
;       bf16x8 af[4], bfr[4];
; #pragma unroll
;       for (int i = 0; i < 4; ++i) {
;         af[i] = *(const bf16x8*)(A + i * 2048 + po);
;         bfr[i] = *(const bf16x8*)(B + i * 2048 + po);
;       }
; #pragma unroll
;       for (int mi = 0; mi < 4; ++mi)
; #pragma unroll
;         for (int ni = 0; ni < 4; ++ni)
;           acc[mi][ni] = SWAP ? mfma16(bfr[ni], af[mi], acc[mi][ni]) : mfma16(af[mi], bfr[ni], acc[mi][ni]);
;     }
;   }
	v_mfma_f32_16x16x32_bf16 v[148:151], v[60:63], v[56:59], v[174:177]
	v_mfma_f32_16x16x32_bf16 v[44:47], v[124:127], v[56:59], v[44:47]
	v_mfma_f32_16x16x32_bf16 v[152:155], v[136:139], v[56:59], v[178:181]
	v_mfma_f32_16x16x32_bf16 v[28:31], v[144:147], v[56:59], v[28:31]
	v_mfma_f32_16x16x32_bf16 v[52:55], v[60:63], v[120:123], v[52:55]
	v_mfma_f32_16x16x32_bf16 v[56:59], v[124:127], v[120:123], v[48:51]
	v_mfma_f32_16x16x32_bf16 v[156:159], v[136:139], v[120:123], v[32:35]
	v_mfma_f32_16x16x32_bf16 v[120:123], v[144:147], v[120:123], v[36:39]
	v_mfma_f32_16x16x32_bf16 v[8:11], v[60:63], v[132:135], v[8:11]
	v_mfma_f32_16x16x32_bf16 v[162:165], v[124:127], v[132:135], v[40:43]
	v_mfma_f32_16x16x32_bf16 v[16:19], v[136:139], v[132:135], v[16:19]
	v_mfma_f32_16x16x32_bf16 v[132:135], v[144:147], v[132:135], v[20:23]
	v_mfma_f32_16x16x32_bf16 v[166:169], v[60:63], v[140:143], v[24:27]
	v_mfma_f32_16x16x32_bf16 v[124:127], v[124:127], v[140:143], v[12:15]
	v_mfma_f32_16x16x32_bf16 v[136:139], v[136:139], v[140:143], v[0:3]
	v_mfma_f32_16x16x32_bf16 v[140:143], v[144:147], v[140:143], v[4:7]
	s_nop 1
	ds_read_b128 v[0:3], v118 offset:32768
	ds_read_b128 v[144:147], v119 offset:49152
	ds_read_b128 v[4:7], v118 offset:34816
	ds_read_b128 v[170:173], v119 offset:51200
	ds_read_b128 v[174:177], v118 offset:36864
	ds_read_b128 v[178:181], v119 offset:53248
	ds_read_b128 v[182:185], v118 offset:38912
	ds_read_b128 v[186:189], v119 offset:55296
	s_waitcnt vmcnt(0)
	s_waitcnt vmcnt(0) lgkmcnt(0)
	v_mfma_f32_16x16x32_bf16 v[40:43], v[186:189], v[4:7], v[120:123]
	s_barrier
	s_nop 1
	v_lshl_add_u64 v[120:121], v[72:73], 0, s[44:45]
	global_load_lds_dwordx4 v[120:121], off
	v_lshl_add_u64 v[120:121], v[76:77], 0, s[44:45]
	s_mov_b32 m0, s1
	v_mfma_f32_16x16x32_bf16 v[60:63], v[144:147], v[0:3], v[148:151]
	global_load_lds_dwordx4 v[120:121], off
	v_lshl_add_u64 v[120:121], v[78:79], 0, s[44:45]
	s_mov_b32 m0, s6
	v_mfma_f32_16x16x32_bf16 v[44:47], v[170:173], v[0:3], v[44:47]
	global_load_lds_dwordx4 v[120:121], off
	v_lshl_add_u64 v[120:121], v[80:81], 0, s[44:45]
	s_mov_b32 m0, s7
	v_mfma_f32_16x16x32_bf16 v[32:35], v[178:181], v[0:3], v[152:155]
	global_load_lds_dwordx4 v[120:121], off
	v_lshl_add_u64 v[120:121], v[74:75], 0, s[44:45]
	s_mov_b32 m0, s8
	s_mov_b64 s[44:45], 0x8180
	global_load_lds_dwordx4 v[120:121], off
	v_lshl_add_u64 v[120:121], v[74:75], 0, s[44:45]
	s_mov_b32 m0, s9
	s_mov_b64 s[44:45], 0x10180
	global_load_lds_dwordx4 v[120:121], off
	v_lshl_add_u64 v[120:121], v[74:75], 0, s[44:45]
	s_mov_b32 m0, s10
	s_mov_b64 s[44:45], 0x18180
	global_load_lds_dwordx4 v[120:121], off
	v_lshl_add_u64 v[120:121], v[74:75], 0, s[44:45]
	s_mov_b32 m0, s11
	v_mfma_f32_16x16x32_bf16 v[24:27], v[186:189], v[0:3], v[28:31]
	global_load_lds_dwordx4 v[120:121], off
	s_mov_b64 s[44:45], 0x200
	v_mfma_f32_16x16x32_bf16 v[48:51], v[144:147], v[4:7], v[52:55]
	s_mov_b32 m0, s12
	v_mfma_f32_16x16x32_bf16 v[28:31], v[170:173], v[4:7], v[56:59]
	v_mfma_f32_16x16x32_bf16 v[36:39], v[178:181], v[4:7], v[156:159]
	v_mfma_f32_16x16x32_bf16 v[20:23], v[144:147], v[174:177], v[8:11]
	v_mfma_f32_16x16x32_bf16 v[0:3], v[178:181], v[174:177], v[16:19]
	v_mfma_f32_16x16x32_bf16 v[4:7], v[186:189], v[174:177], v[132:135]
	v_mfma_f32_16x16x32_bf16 v[8:11], v[144:147], v[182:185], v[166:169]
	v_mfma_f32_16x16x32_bf16 v[16:19], v[170:173], v[182:185], v[124:127]
	v_mfma_f32_16x16x32_bf16 v[52:55], v[178:181], v[182:185], v[136:139]
	v_mfma_f32_16x16x32_bf16 v[56:59], v[186:189], v[182:185], v[140:143]
	ds_read_b128 v[120:123], v116
	ds_read_b128 v[124:127], v117 offset:16384
	ds_read_b128 v[132:135], v116 offset:2048
	ds_read_b128 v[136:139], v117 offset:18432
	ds_read_b128 v[140:143], v116 offset:4096
	ds_read_b128 v[144:147], v117 offset:20480
	ds_read_b128 v[148:151], v116 offset:6144
	ds_read_b128 v[152:155], v117 offset:22528
	v_mfma_f32_16x16x32_bf16 v[12:15], v[170:173], v[174:177], v[162:165]
	s_waitcnt lgkmcnt(0)
	v_mfma_f32_16x16x32_bf16 v[60:63], v[124:127], v[120:123], v[60:63]
	v_mfma_f32_16x16x32_bf16 v[44:47], v[136:139], v[120:123], v[44:47]
	v_mfma_f32_16x16x32_bf16 v[32:35], v[144:147], v[120:123], v[32:35]
	v_mfma_f32_16x16x32_bf16 v[24:27], v[152:155], v[120:123], v[24:27]
	v_mfma_f32_16x16x32_bf16 v[48:51], v[124:127], v[132:135], v[48:51]
	v_mfma_f32_16x16x32_bf16 v[120:123], v[136:139], v[132:135], v[28:31]
	v_mfma_f32_16x16x32_bf16 v[36:39], v[144:147], v[132:135], v[36:39]
	v_mfma_f32_16x16x32_bf16 v[40:43], v[152:155], v[132:135], v[40:43]
	v_mfma_f32_16x16x32_bf16 v[132:135], v[124:127], v[140:143], v[20:23]
	v_mfma_f32_16x16x32_bf16 v[12:15], v[136:139], v[140:143], v[12:15]
	v_mfma_f32_16x16x32_bf16 v[0:3], v[144:147], v[140:143], v[0:3]
	v_mfma_f32_16x16x32_bf16 v[4:7], v[152:155], v[140:143], v[4:7]
	v_mfma_f32_16x16x32_bf16 v[124:127], v[124:127], v[148:151], v[8:11]
	v_mfma_f32_16x16x32_bf16 v[136:139], v[136:139], v[148:151], v[16:19]
	v_mfma_f32_16x16x32_bf16 v[140:143], v[144:147], v[148:151], v[52:55]
	v_mfma_f32_16x16x32_bf16 v[56:59], v[152:155], v[148:151], v[56:59]
	ds_read_b128 v[8:11], v118
	ds_read_b128 v[144:147], v119 offset:16384
	ds_read_b128 v[20:23], v118 offset:2048
	ds_read_b128 v[148:151], v119 offset:18432
	ds_read_b128 v[152:155], v118 offset:4096
	ds_read_b128 v[156:159], v119 offset:20480
	ds_read_b128 v[162:165], v118 offset:6144
	ds_read_b128 v[166:169], v119 offset:22528
	s_waitcnt vmcnt(0)
	s_waitcnt vmcnt(0) lgkmcnt(0)
	v_mfma_f32_16x16x32_bf16 v[16:19], v[156:159], v[20:23], v[36:39]
	s_barrier
; DEVI f32x4 mfma16(bf16x8 a, bf16x8 b, f32x4 c) { return __builtin_amdgcn_mfma_f32_16x16x32_bf16(a, b, c, 0, 0, 0); }
; template <bool SWAP, class RP>
; DEVI void gemm_main(const int TIDX, const int BIDX, const int GDIM, f32x4 (&acc)[4][4], RP rowoff, const bf16_t* __restrict__ Bt, int ldb, int K, unsigned char* smem) {
;     ...
;   GM_STAGE(0, 0);
;   for (int kt = 0; kt < nk; ++kt) {
;     const int buf = kt & 1;
;     asm volatile("s_waitcnt vmcnt(0)" ::: "memory");
;     __syncthreads();
;     if (kt + 1 < nk) GM_STAGE(kt + 1, buf ^ 1);
;     const unsigned char* A = smem + buf * 32768 + (wr * 64 + li) * 128;
;     const unsigned char* B = smem + buf * 32768 + 16384 + (wc * 64 + li) * 128;
; #pragma unroll
;     for (int ks = 0; ks < 2; ++ks) {
;       const int po = (px ^ (ks * 4)) * 16;
;       bf16x8 af[4], bfr[4];
; #pragma unroll
;       for (int i = 0; i < 4; ++i) {
;         af[i] = *(const bf16x8*)(A + i * 2048 + po);
;         bfr[i] = *(const bf16x8*)(B + i * 2048 + po);
;       }
; #pragma unroll
;       for (int mi = 0; mi < 4; ++mi)
; #pragma unroll
;         for (int ni = 0; ni < 4; ++ni)
;           acc[mi][ni] = SWAP ? mfma16(bfr[ni], af[mi], acc[mi][ni]) : mfma16(af[mi], bfr[ni], acc[mi][ni]);
;     }
;   }
	v_mfma_f32_16x16x32_bf16 v[36:39], v[166:169], v[152:155], v[4:7]
	v_mfma_f32_16x16x32_bf16 v[4:7], v[166:169], v[162:165], v[56:59]
	s_nop 2
	v_lshl_add_u64 v[56:57], v[72:73], 0, s[44:45]
	global_load_lds_dwordx4 v[56:57], off
	v_lshl_add_u64 v[56:57], v[76:77], 0, s[44:45]
	s_mov_b32 m0, s13
	v_mfma_f32_16x16x32_bf16 v[60:63], v[144:147], v[8:11], v[60:63]
	global_load_lds_dwordx4 v[56:57], off
	v_lshl_add_u64 v[56:57], v[78:79], 0, s[44:45]
	s_mov_b32 m0, s14
	v_mfma_f32_16x16x32_bf16 v[44:47], v[148:151], v[8:11], v[44:47]
	global_load_lds_dwordx4 v[56:57], off
	v_lshl_add_u64 v[56:57], v[80:81], 0, s[44:45]
	s_mov_b32 m0, s15
	v_mfma_f32_16x16x32_bf16 v[170:173], v[156:159], v[8:11], v[32:35]
	global_load_lds_dwordx4 v[56:57], off
	v_lshl_add_u64 v[56:57], v[74:75], 0, s[44:45]
	s_mov_b32 m0, s37
	s_mov_b64 s[44:45], 0x8200
	global_load_lds_dwordx4 v[56:57], off
	v_lshl_add_u64 v[56:57], v[74:75], 0, s[44:45]
	s_mov_b32 m0, s38
	s_mov_b64 s[44:45], 0x10200
	global_load_lds_dwordx4 v[56:57], off
	v_lshl_add_u64 v[56:57], v[74:75], 0, s[44:45]
	s_mov_b32 m0, s39
	s_mov_b64 s[44:45], 0x18200
	global_load_lds_dwordx4 v[56:57], off
	v_lshl_add_u64 v[56:57], v[74:75], 0, s[44:45]
	s_mov_b32 m0, s40
	v_mfma_f32_16x16x32_bf16 v[28:31], v[166:169], v[8:11], v[24:27]
	global_load_lds_dwordx4 v[56:57], off
	s_mov_b64 s[44:45], 0x280
	v_mfma_f32_16x16x32_bf16 v[48:51], v[144:147], v[20:23], v[48:51]
	s_mov_b32 m0, s0
	v_mfma_f32_16x16x32_bf16 v[52:55], v[148:151], v[20:23], v[120:123]
	v_mfma_f32_16x16x32_bf16 v[20:23], v[166:169], v[20:23], v[40:43]
	v_mfma_f32_16x16x32_bf16 v[8:11], v[144:147], v[152:155], v[132:135]
	v_mfma_f32_16x16x32_bf16 v[24:27], v[148:151], v[152:155], v[12:15]
	v_mfma_f32_16x16x32_bf16 v[32:35], v[156:159], v[152:155], v[0:3]
	v_mfma_f32_16x16x32_bf16 v[40:43], v[144:147], v[162:165], v[124:127]
	v_mfma_f32_16x16x32_bf16 v[12:15], v[148:151], v[162:165], v[136:139]
	v_mfma_f32_16x16x32_bf16 v[0:3], v[156:159], v[162:165], v[140:143]
	ds_read_b128 v[56:59], v116 offset:32768
	ds_read_b128 v[120:123], v117 offset:49152
	ds_read_b128 v[124:127], v116 offset:34816
	ds_read_b128 v[132:135], v117 offset:51200
	ds_read_b128 v[136:139], v116 offset:36864
	ds_read_b128 v[140:143], v117 offset:53248
	ds_read_b128 v[144:147], v116 offset:38912
	ds_read_b128 v[148:151], v117 offset:55296
	s_waitcnt lgkmcnt(0)
	v_mfma_f32_16x16x32_bf16 v[60:63], v[120:123], v[56:59], v[60:63]
	v_mfma_f32_16x16x32_bf16 v[44:47], v[132:135], v[56:59], v[44:47]
	v_mfma_f32_16x16x32_bf16 v[152:155], v[140:143], v[56:59], v[170:173]
	v_mfma_f32_16x16x32_bf16 v[56:59], v[148:151], v[56:59], v[28:31]
	v_mfma_f32_16x16x32_bf16 v[156:159], v[120:123], v[124:127], v[48:51]
	v_mfma_f32_16x16x32_bf16 v[162:165], v[132:135], v[124:127], v[52:55]
	v_mfma_f32_16x16x32_bf16 v[16:19], v[140:143], v[124:127], v[16:19]
	v_mfma_f32_16x16x32_bf16 v[20:23], v[148:151], v[124:127], v[20:23]
	v_mfma_f32_16x16x32_bf16 v[8:11], v[120:123], v[136:139], v[8:11]
	v_mfma_f32_16x16x32_bf16 v[124:127], v[132:135], v[136:139], v[24:27]
	v_mfma_f32_16x16x32_bf16 v[166:169], v[140:143], v[136:139], v[32:35]
	v_mfma_f32_16x16x32_bf16 v[136:139], v[148:151], v[136:139], v[36:39]
	v_mfma_f32_16x16x32_bf16 v[120:123], v[120:123], v[144:147], v[40:43]
	v_mfma_f32_16x16x32_bf16 v[132:135], v[132:135], v[144:147], v[12:15]
	v_mfma_f32_16x16x32_bf16 v[140:143], v[140:143], v[144:147], v[0:3]
	v_mfma_f32_16x16x32_bf16 v[144:147], v[148:151], v[144:147], v[4:7]
	s_nop 1
	ds_read_b128 v[0:3], v118 offset:32768
	ds_read_b128 v[148:151], v119 offset:49152
	ds_read_b128 v[4:7], v118 offset:34816
	ds_read_b128 v[170:173], v119 offset:51200
	ds_read_b128 v[174:177], v118 offset:36864
	ds_read_b128 v[178:181], v119 offset:53248
	ds_read_b128 v[182:185], v118 offset:38912
	ds_read_b128 v[186:189], v119 offset:55296
	s_waitcnt vmcnt(0)
	s_waitcnt vmcnt(0) lgkmcnt(0)
	v_mfma_f32_16x16x32_bf16 v[12:15], v[148:151], v[174:177], v[8:11]
	s_barrier
	v_mfma_f32_16x16x32_bf16 v[8:11], v[148:151], v[182:185], v[120:123]
	s_nop 2
	v_lshl_add_u64 v[120:121], v[72:73], 0, s[44:45]
	global_load_lds_dwordx4 v[120:121], off
	v_lshl_add_u64 v[120:121], v[76:77], 0, s[44:45]
	s_mov_b32 m0, s1
	v_mfma_f32_16x16x32_bf16 v[52:55], v[148:151], v[4:7], v[156:159]
	global_load_lds_dwordx4 v[120:121], off
	v_lshl_add_u64 v[120:121], v[78:79], 0, s[44:45]
	s_mov_b32 m0, s6
	v_mfma_f32_16x16x32_bf16 v[48:51], v[148:151], v[0:3], v[60:63]
	global_load_lds_dwordx4 v[120:121], off
	v_lshl_add_u64 v[120:121], v[80:81], 0, s[44:45]
	s_mov_b32 m0, s7
	v_mfma_f32_16x16x32_bf16 v[24:27], v[170:173], v[0:3], v[44:47]
	global_load_lds_dwordx4 v[120:121], off
	v_lshl_add_u64 v[120:121], v[74:75], 0, s[44:45]
	s_mov_b32 m0, s8
	s_mov_b64 s[44:45], 0x8280
	global_load_lds_dwordx4 v[120:121], off
	v_lshl_add_u64 v[120:121], v[74:75], 0, s[44:45]
	s_mov_b32 m0, s9
	s_mov_b64 s[44:45], 0x10280
	global_load_lds_dwordx4 v[120:121], off
	v_lshl_add_u64 v[120:121], v[74:75], 0, s[44:45]
	s_mov_b32 m0, s10
	s_mov_b64 s[44:45], 0x18280
	global_load_lds_dwordx4 v[120:121], off
	v_lshl_add_u64 v[120:121], v[74:75], 0, s[44:45]
	s_mov_b32 m0, s11
	v_mfma_f32_16x16x32_bf16 v[28:31], v[178:181], v[0:3], v[152:155]
	global_load_lds_dwordx4 v[120:121], off
	s_mov_b64 s[44:45], 0x300
	v_mfma_f32_16x16x32_bf16 v[32:35], v[186:189], v[0:3], v[56:59]
	s_mov_b32 m0, s12
	v_mfma_f32_16x16x32_bf16 v[36:39], v[170:173], v[4:7], v[162:165]
	v_mfma_f32_16x16x32_bf16 v[40:43], v[178:181], v[4:7], v[16:19]
	v_mfma_f32_16x16x32_bf16 v[44:47], v[186:189], v[4:7], v[20:23]
	v_mfma_f32_16x16x32_bf16 v[20:23], v[170:173], v[174:177], v[124:127]
	v_mfma_f32_16x16x32_bf16 v[4:7], v[186:189], v[174:177], v[136:139]
	v_mfma_f32_16x16x32_bf16 v[16:19], v[170:173], v[182:185], v[132:135]
	v_mfma_f32_16x16x32_bf16 v[56:59], v[178:181], v[182:185], v[140:143]
	v_mfma_f32_16x16x32_bf16 v[60:63], v[186:189], v[182:185], v[144:147]
	ds_read_b128 v[120:123], v116
	ds_read_b128 v[124:127], v117 offset:16384
	ds_read_b128 v[132:135], v116 offset:2048
	ds_read_b128 v[136:139], v117 offset:18432
	ds_read_b128 v[140:143], v116 offset:4096
	ds_read_b128 v[144:147], v117 offset:20480
	ds_read_b128 v[148:151], v116 offset:6144
	ds_read_b128 v[152:155], v117 offset:22528
	v_mfma_f32_16x16x32_bf16 v[0:3], v[178:181], v[174:177], v[166:169]
	s_waitcnt lgkmcnt(0)
; DEVI f32x4 mfma16(bf16x8 a, bf16x8 b, f32x4 c) { return __builtin_amdgcn_mfma_f32_16x16x32_bf16(a, b, c, 0, 0, 0); }
; template <bool SWAP, class RP>
; DEVI void gemm_main(const int TIDX, const int BIDX, const int GDIM, f32x4 (&acc)[4][4], RP rowoff, const bf16_t* __restrict__ Bt, int ldb, int K, unsigned char* smem) {
;     ...
;   GM_STAGE(0, 0);
;   for (int kt = 0; kt < nk; ++kt) {
;     const int buf = kt & 1;
;     asm volatile("s_waitcnt vmcnt(0)" ::: "memory");
;     __syncthreads();
;     if (kt + 1 < nk) GM_STAGE(kt + 1, buf ^ 1);
;     const unsigned char* A = smem + buf * 32768 + (wr * 64 + li) * 128;
;     const unsigned char* B = smem + buf * 32768 + 16384 + (wc * 64 + li) * 128;
; #pragma unroll
;     for (int ks = 0; ks < 2; ++ks) {
;       const int po = (px ^ (ks * 4)) * 16;
;       bf16x8 af[4], bfr[4];
; #pragma unroll
;       for (int i = 0; i < 4; ++i) {
;         af[i] = *(const bf16x8*)(A + i * 2048 + po);
;         bfr[i] = *(const bf16x8*)(B + i * 2048 + po);
;       }
; #pragma unroll
;       for (int mi = 0; mi < 4; ++mi)
; #pragma unroll
;         for (int ni = 0; ni < 4; ++ni)
;           acc[mi][ni] = SWAP ? mfma16(bfr[ni], af[mi], acc[mi][ni]) : mfma16(af[mi], bfr[ni], acc[mi][ni]);
;     }
;   }
	v_mfma_f32_16x16x32_bf16 v[52:55], v[124:127], v[132:135], v[52:55]
	v_mfma_f32_16x16x32_bf16 v[48:51], v[124:127], v[120:123], v[48:51]
	v_mfma_f32_16x16x32_bf16 v[24:27], v[136:139], v[120:123], v[24:27]
	v_mfma_f32_16x16x32_bf16 v[28:31], v[144:147], v[120:123], v[28:31]
	v_mfma_f32_16x16x32_bf16 v[32:35], v[152:155], v[120:123], v[32:35]
	v_mfma_f32_16x16x32_bf16 v[36:39], v[136:139], v[132:135], v[36:39]
	v_mfma_f32_16x16x32_bf16 v[40:43], v[144:147], v[132:135], v[40:43]
	v_mfma_f32_16x16x32_bf16 v[120:123], v[152:155], v[132:135], v[44:47]
	v_mfma_f32_16x16x32_bf16 v[12:15], v[124:127], v[140:143], v[12:15]
	v_mfma_f32_16x16x32_bf16 v[20:23], v[136:139], v[140:143], v[20:23]
	v_mfma_f32_16x16x32_bf16 v[0:3], v[144:147], v[140:143], v[0:3]
	v_mfma_f32_16x16x32_bf16 v[4:7], v[152:155], v[140:143], v[4:7]
	v_mfma_f32_16x16x32_bf16 v[8:11], v[124:127], v[148:151], v[8:11]
	v_mfma_f32_16x16x32_bf16 v[124:127], v[136:139], v[148:151], v[16:19]
	v_mfma_f32_16x16x32_bf16 v[56:59], v[144:147], v[148:151], v[56:59]
	v_mfma_f32_16x16x32_bf16 v[60:63], v[152:155], v[148:151], v[60:63]
	s_nop 0
	ds_read_b128 v[16:19], v118
	ds_read_b128 v[132:135], v119 offset:16384
	ds_read_b128 v[136:139], v118 offset:2048
	ds_read_b128 v[140:143], v119 offset:18432
	ds_read_b128 v[144:147], v118 offset:4096
	ds_read_b128 v[148:151], v119 offset:20480
	ds_read_b128 v[152:155], v118 offset:6144
	ds_read_b128 v[156:159], v119 offset:22528
	s_waitcnt vmcnt(0)
	s_waitcnt vmcnt(0) lgkmcnt(0)
	v_mfma_f32_16x16x32_bf16 v[44:47], v[132:135], v[136:139], v[52:55]
	s_barrier
	s_nop 1
	v_lshl_add_u64 v[52:53], v[72:73], 0, s[44:45]
	global_load_lds_dwordx4 v[52:53], off
	v_lshl_add_u64 v[52:53], v[76:77], 0, s[44:45]
	s_mov_b32 m0, s13
	s_mov_b64 s[12:13], 0x8300
	global_load_lds_dwordx4 v[52:53], off
	v_lshl_add_u64 v[52:53], v[78:79], 0, s[44:45]
	s_mov_b32 m0, s14
	v_mfma_f32_16x16x32_bf16 v[162:165], v[132:135], v[16:19], v[48:51]
	global_load_lds_dwordx4 v[52:53], off
	v_lshl_add_u64 v[52:53], v[80:81], 0, s[44:45]
	s_mov_b32 m0, s15
	v_mfma_f32_16x16x32_bf16 v[166:169], v[140:143], v[16:19], v[24:27]
	global_load_lds_dwordx4 v[52:53], off
	v_lshl_add_u64 v[52:53], v[74:75], 0, s[44:45]
	s_mov_b32 m0, s37
	v_mfma_f32_16x16x32_bf16 v[170:173], v[148:151], v[16:19], v[28:31]
	global_load_lds_dwordx4 v[52:53], off
	v_lshl_add_u64 v[52:53], v[74:75], 0, s[12:13]
	s_mov_b32 m0, s38
	s_mov_b64 s[12:13], 0x10300
	global_load_lds_dwordx4 v[52:53], off
	v_lshl_add_u64 v[52:53], v[74:75], 0, s[12:13]
	s_mov_b32 m0, s39
	s_mov_b64 s[12:13], 0x18300
	global_load_lds_dwordx4 v[52:53], off
	v_lshl_add_u64 v[52:53], v[74:75], 0, s[12:13]
	s_mov_b32 m0, s40
	v_mfma_f32_16x16x32_bf16 v[16:19], v[156:159], v[16:19], v[32:35]
	global_load_lds_dwordx4 v[52:53], off
	s_mov_b64 s[12:13], 0x380
	v_mfma_f32_16x16x32_bf16 v[48:51], v[140:143], v[136:139], v[36:39]
	s_mov_b32 m0, s0
	v_mfma_f32_16x16x32_bf16 v[24:27], v[148:151], v[136:139], v[40:43]
	v_mfma_f32_16x16x32_bf16 v[28:31], v[156:159], v[136:139], v[120:123]
	v_mfma_f32_16x16x32_bf16 v[12:15], v[132:135], v[144:147], v[12:15]
	v_mfma_f32_16x16x32_bf16 v[20:23], v[140:143], v[144:147], v[20:23]
	v_mfma_f32_16x16x32_bf16 v[32:35], v[148:151], v[144:147], v[0:3]
	v_mfma_f32_16x16x32_bf16 v[36:39], v[156:159], v[144:147], v[4:7]
	v_mfma_f32_16x16x32_bf16 v[40:43], v[132:135], v[152:155], v[8:11]
	v_mfma_f32_16x16x32_bf16 v[8:11], v[140:143], v[152:155], v[124:127]
	v_mfma_f32_16x16x32_bf16 v[0:3], v[148:151], v[152:155], v[56:59]
	v_mfma_f32_16x16x32_bf16 v[4:7], v[156:159], v[152:155], v[60:63]
	ds_read_b128 v[52:55], v116 offset:32768
	s_nop 0
	ds_read_b128 v[56:59], v117 offset:49152
	ds_read_b128 v[60:63], v116 offset:34816
	ds_read_b128 v[120:123], v117 offset:51200
	ds_read_b128 v[124:127], v116 offset:36864
	ds_read_b128 v[132:135], v117 offset:53248
	ds_read_b128 v[136:139], v116 offset:38912
	ds_read_b128 v[140:143], v117 offset:55296
	s_waitcnt lgkmcnt(0)
	v_mfma_f32_16x16x32_bf16 v[144:147], v[56:59], v[52:55], v[162:165]
	v_mfma_f32_16x16x32_bf16 v[148:151], v[120:123], v[52:55], v[166:169]
	v_mfma_f32_16x16x32_bf16 v[152:155], v[132:135], v[52:55], v[170:173]
	v_mfma_f32_16x16x32_bf16 v[16:19], v[140:143], v[52:55], v[16:19]
	v_mfma_f32_16x16x32_bf16 v[44:47], v[56:59], v[60:63], v[44:47]
	v_mfma_f32_16x16x32_bf16 v[48:51], v[120:123], v[60:63], v[48:51]
	v_mfma_f32_16x16x32_bf16 v[52:55], v[132:135], v[60:63], v[24:27]
	v_mfma_f32_16x16x32_bf16 v[60:63], v[140:143], v[60:63], v[28:31]
	v_mfma_f32_16x16x32_bf16 v[12:15], v[56:59], v[124:127], v[12:15]
	v_mfma_f32_16x16x32_bf16 v[156:159], v[120:123], v[124:127], v[20:23]
	v_mfma_f32_16x16x32_bf16 v[162:165], v[132:135], v[124:127], v[32:35]
	v_mfma_f32_16x16x32_bf16 v[124:127], v[140:143], v[124:127], v[36:39]
	v_mfma_f32_16x16x32_bf16 v[40:43], v[56:59], v[136:139], v[40:43]
	v_mfma_f32_16x16x32_bf16 v[56:59], v[120:123], v[136:139], v[8:11]
	v_mfma_f32_16x16x32_bf16 v[0:3], v[132:135], v[136:139], v[0:3]
	v_mfma_f32_16x16x32_bf16 v[4:7], v[140:143], v[136:139], v[4:7]
	s_nop 0
	ds_read_b128 v[8:11], v118 offset:32768
	ds_read_b128 v[120:123], v119 offset:49152
	ds_read_b128 v[132:135], v118 offset:34816
	ds_read_b128 v[136:139], v119 offset:51200
	ds_read_b128 v[140:143], v118 offset:36864
	ds_read_b128 v[166:169], v119 offset:53248
	ds_read_b128 v[170:173], v118 offset:38912
	ds_read_b128 v[174:177], v119 offset:55296
	s_waitcnt vmcnt(0)
	s_waitcnt vmcnt(0) lgkmcnt(0)
	v_mfma_f32_16x16x32_bf16 v[32:35], v[174:177], v[8:11], v[16:19]
	s_barrier
; DEVI f32x4 mfma16(bf16x8 a, bf16x8 b, f32x4 c) { return __builtin_amdgcn_mfma_f32_16x16x32_bf16(a, b, c, 0, 0, 0); }
; template <bool SWAP, class RP>
; DEVI void gemm_main(const int TIDX, const int BIDX, const int GDIM, f32x4 (&acc)[4][4], RP rowoff, const bf16_t* __restrict__ Bt, int ldb, int K, unsigned char* smem) {
;     ...
;   GM_STAGE(0, 0);
;   for (int kt = 0; kt < nk; ++kt) {
;     const int buf = kt & 1;
;     asm volatile("s_waitcnt vmcnt(0)" ::: "memory");
;     __syncthreads();
;     if (kt + 1 < nk) GM_STAGE(kt + 1, buf ^ 1);
;     const unsigned char* A = smem + buf * 32768 + (wr * 64 + li) * 128;
;     const unsigned char* B = smem + buf * 32768 + 16384 + (wc * 64 + li) * 128;
; #pragma unroll
;     for (int ks = 0; ks < 2; ++ks) {
;       const int po = (px ^ (ks * 4)) * 16;
;       bf16x8 af[4], bfr[4];
; #pragma unroll
;       for (int i = 0; i < 4; ++i) {
;         af[i] = *(const bf16x8*)(A + i * 2048 + po);
;         bfr[i] = *(const bf16x8*)(B + i * 2048 + po);
;       }
; #pragma unroll
;       for (int mi = 0; mi < 4; ++mi)
; #pragma unroll
;         for (int ni = 0; ni < 4; ++ni)
;           acc[mi][ni] = SWAP ? mfma16(bfr[ni], af[mi], acc[mi][ni]) : mfma16(af[mi], bfr[ni], acc[mi][ni]);
;     }
;   }
;   __syncthreads();
	v_mfma_f32_16x16x32_bf16 v[16:19], v[120:123], v[140:143], v[12:15]
	v_mfma_f32_16x16x32_bf16 v[12:15], v[136:139], v[170:173], v[56:59]
	s_nop 2
	v_lshl_add_u64 v[56:57], v[72:73], 0, s[12:13]
	global_load_lds_dwordx4 v[56:57], off
	v_lshl_add_u64 v[56:57], v[76:77], 0, s[12:13]
	s_mov_b32 m0, s1
	s_mov_b64 s[0:1], 0x8380
	global_load_lds_dwordx4 v[56:57], off
	v_lshl_add_u64 v[56:57], v[78:79], 0, s[12:13]
	s_mov_b32 m0, s6
	v_mfma_f32_16x16x32_bf16 v[20:23], v[120:123], v[8:11], v[144:147]
	global_load_lds_dwordx4 v[56:57], off
	v_lshl_add_u64 v[56:57], v[80:81], 0, s[12:13]
	s_mov_b32 m0, s7
	v_mfma_f32_16x16x32_bf16 v[24:27], v[136:139], v[8:11], v[148:151]
	global_load_lds_dwordx4 v[56:57], off
	v_lshl_add_u64 v[56:57], v[74:75], 0, s[12:13]
	s_mov_b32 m0, s8
	v_mfma_f32_16x16x32_bf16 v[28:31], v[166:169], v[8:11], v[152:155]
	global_load_lds_dwordx4 v[56:57], off
	v_lshl_add_u64 v[56:57], v[74:75], 0, s[0:1]
	s_mov_b32 m0, s9
	s_mov_b64 s[0:1], 0x10380
	global_load_lds_dwordx4 v[56:57], off
	v_lshl_add_u64 v[56:57], v[74:75], 0, s[0:1]
	s_mov_b32 m0, s10
	s_mov_b64 s[0:1], 0x18380
	global_load_lds_dwordx4 v[56:57], off
	v_lshl_add_u64 v[56:57], v[74:75], 0, s[0:1]
	s_mov_b32 m0, s11
	v_mfma_f32_16x16x32_bf16 v[44:47], v[120:123], v[132:135], v[44:47]
	global_load_lds_dwordx4 v[56:57], off
	v_mfma_f32_16x16x32_bf16 v[36:39], v[136:139], v[132:135], v[48:51]
	v_mfma_f32_16x16x32_bf16 v[48:51], v[166:169], v[132:135], v[52:55]
	v_mfma_f32_16x16x32_bf16 v[52:55], v[174:177], v[132:135], v[60:63]
	v_mfma_f32_16x16x32_bf16 v[60:63], v[136:139], v[140:143], v[156:159]
	v_mfma_f32_16x16x32_bf16 v[8:11], v[166:169], v[140:143], v[162:165]
	v_mfma_f32_16x16x32_bf16 v[124:127], v[174:177], v[140:143], v[124:127]
	v_mfma_f32_16x16x32_bf16 v[40:43], v[120:123], v[170:173], v[40:43]
	ds_read_b128 v[56:59], v116
	ds_read_b128 v[72:75], v117 offset:16384
	ds_read_b128 v[76:79], v116 offset:2048
	ds_read_b128 v[120:123], v117 offset:18432
	ds_read_b128 v[132:135], v116 offset:4096
	ds_read_b128 v[136:139], v117 offset:20480
	ds_read_b128 v[140:143], v116 offset:6144
	ds_read_b128 v[144:147], v117 offset:22528
	v_mfma_f32_16x16x32_bf16 v[0:3], v[166:169], v[170:173], v[0:3]
	v_mfma_f32_16x16x32_bf16 v[4:7], v[174:177], v[170:173], v[4:7]
	s_waitcnt lgkmcnt(0)
	v_mfma_f32_16x16x32_bf16 v[20:23], v[72:75], v[56:59], v[20:23]
	v_mfma_f32_16x16x32_bf16 v[24:27], v[120:123], v[56:59], v[24:27]
	v_mfma_f32_16x16x32_bf16 v[28:31], v[136:139], v[56:59], v[28:31]
	v_mfma_f32_16x16x32_bf16 v[32:35], v[144:147], v[56:59], v[32:35]
	v_mfma_f32_16x16x32_bf16 v[44:47], v[72:75], v[76:79], v[44:47]
	v_mfma_f32_16x16x32_bf16 v[36:39], v[120:123], v[76:79], v[36:39]
	v_mfma_f32_16x16x32_bf16 v[48:51], v[136:139], v[76:79], v[48:51]
	v_mfma_f32_16x16x32_bf16 v[52:55], v[144:147], v[76:79], v[52:55]
	v_mfma_f32_16x16x32_bf16 v[16:19], v[72:75], v[132:135], v[16:19]
	v_mfma_f32_16x16x32_bf16 v[56:59], v[120:123], v[132:135], v[60:63]
	v_mfma_f32_16x16x32_bf16 v[8:11], v[136:139], v[132:135], v[8:11]
	v_mfma_f32_16x16x32_bf16 v[60:63], v[144:147], v[132:135], v[124:127]
	v_mfma_f32_16x16x32_bf16 v[40:43], v[72:75], v[140:143], v[40:43]
	v_mfma_f32_16x16x32_bf16 v[12:15], v[120:123], v[140:143], v[12:15]
	v_mfma_f32_16x16x32_bf16 v[0:3], v[136:139], v[140:143], v[0:3]
	v_mfma_f32_16x16x32_bf16 v[4:7], v[144:147], v[140:143], v[4:7]
	ds_read_b128 v[72:75], v118
	ds_read_b128 v[76:79], v119 offset:16384
	ds_read_b128 v[120:123], v118 offset:2048
	ds_read_b128 v[124:127], v119 offset:18432
	ds_read_b128 v[132:135], v118 offset:4096
	ds_read_b128 v[136:139], v119 offset:20480
	ds_read_b128 v[140:143], v118 offset:6144
	ds_read_b128 v[144:147], v119 offset:22528
	s_waitcnt vmcnt(0)
	s_waitcnt vmcnt(0) lgkmcnt(0)
	v_mfma_f32_16x16x32_bf16 v[24:27], v[124:127], v[72:75], v[24:27]
	s_barrier
	v_mfma_f32_16x16x32_bf16 v[56:59], v[124:127], v[132:135], v[56:59]
	v_mfma_f32_16x16x32_bf16 v[20:23], v[76:79], v[72:75], v[20:23]
	v_mfma_f32_16x16x32_bf16 v[28:31], v[136:139], v[72:75], v[28:31]
	v_mfma_f32_16x16x32_bf16 v[32:35], v[144:147], v[72:75], v[32:35]
	v_mfma_f32_16x16x32_bf16 v[44:47], v[76:79], v[120:123], v[44:47]
	v_mfma_f32_16x16x32_bf16 v[36:39], v[124:127], v[120:123], v[36:39]
	v_mfma_f32_16x16x32_bf16 v[48:51], v[136:139], v[120:123], v[48:51]
	v_mfma_f32_16x16x32_bf16 v[52:55], v[144:147], v[120:123], v[52:55]
	v_mfma_f32_16x16x32_bf16 v[16:19], v[76:79], v[132:135], v[16:19]
	v_mfma_f32_16x16x32_bf16 v[8:11], v[136:139], v[132:135], v[8:11]
	v_mfma_f32_16x16x32_bf16 v[60:63], v[144:147], v[132:135], v[60:63]
	v_mfma_f32_16x16x32_bf16 v[40:43], v[76:79], v[140:143], v[40:43]
	v_mfma_f32_16x16x32_bf16 v[12:15], v[124:127], v[140:143], v[12:15]
	v_mfma_f32_16x16x32_bf16 v[0:3], v[136:139], v[140:143], v[0:3]
	v_mfma_f32_16x16x32_bf16 v[4:7], v[144:147], v[140:143], v[4:7]
	ds_read_b128 v[72:75], v116 offset:32768
	ds_read_b128 v[76:79], v117 offset:49152
	ds_read_b128 v[120:123], v116 offset:34816
	ds_read_b128 v[124:127], v117 offset:51200
	ds_read_b128 v[132:135], v116 offset:36864
	ds_read_b128 v[136:139], v117 offset:53248
	ds_read_b128 v[140:143], v116 offset:38912
	ds_read_b128 v[144:147], v117 offset:55296
	s_waitcnt lgkmcnt(4)
	v_mfma_f32_16x16x32_bf16 v[24:27], v[124:127], v[72:75], v[24:27]
	s_waitcnt lgkmcnt(3)
	v_mfma_f32_16x16x32_bf16 v[56:59], v[124:127], v[132:135], v[56:59]
	v_mfma_f32_16x16x32_bf16 v[20:23], v[76:79], v[72:75], v[20:23]
	s_waitcnt lgkmcnt(2)
	v_mfma_f32_16x16x32_bf16 v[28:31], v[136:139], v[72:75], v[28:31]
	s_waitcnt lgkmcnt(0)
	v_mfma_f32_16x16x32_bf16 v[32:35], v[144:147], v[72:75], v[32:35]
	v_mfma_f32_16x16x32_bf16 v[44:47], v[76:79], v[120:123], v[44:47]
	v_mfma_f32_16x16x32_bf16 v[36:39], v[124:127], v[120:123], v[36:39]
	v_mfma_f32_16x16x32_bf16 v[72:75], v[136:139], v[120:123], v[48:51]
	v_mfma_f32_16x16x32_bf16 v[120:123], v[144:147], v[120:123], v[52:55]
	v_mfma_f32_16x16x32_bf16 v[16:19], v[76:79], v[132:135], v[16:19]
	v_mfma_f32_16x16x32_bf16 v[8:11], v[136:139], v[132:135], v[8:11]
	v_mfma_f32_16x16x32_bf16 v[60:63], v[144:147], v[132:135], v[60:63]
	v_mfma_f32_16x16x32_bf16 v[76:79], v[76:79], v[140:143], v[40:43]
	v_mfma_f32_16x16x32_bf16 v[124:127], v[124:127], v[140:143], v[12:15]
	v_mfma_f32_16x16x32_bf16 v[0:3], v[136:139], v[140:143], v[0:3]
	v_mfma_f32_16x16x32_bf16 v[132:135], v[144:147], v[140:143], v[4:7]
	s_nop 2
	ds_read_b128 v[4:7], v118 offset:32768
	ds_read_b128 v[12:15], v119 offset:49152
	ds_read_b128 v[136:139], v118 offset:34816
	ds_read_b128 v[140:143], v119 offset:51200
	ds_read_b128 v[144:147], v118 offset:36864
	ds_read_b128 v[148:151], v119 offset:53248
	ds_read_b128 v[152:155], v118 offset:38912
	ds_read_b128 v[116:119], v119 offset:55296
	s_waitcnt lgkmcnt(0)
	s_barrier
; DEVI uint32_t pack2(float lo, float hi) { f32x2_t v = {lo, hi}; bf16x2_t b = __builtin_convertvector(v, bf16x2_t); return __builtin_bit_cast(uint32_t, b); }
; DEVI float lo2f(uint32_t u) { return __uint_as_float(u << 16); }
; DEVI float hi2f(uint32_t u) { return __uint_as_float(u & 0xffff0000u); }
; #define EPI_END } __builtin_amdgcn_sched_barrier(0); } }
; DEVI void phase_p5(const int TIDX, const int BIDX, const int GDIM, KAP KA, unsigned char* WSB, float* OUTB, int l, unsigned char* smem) {
;     ...
;     EPI_SWAP_BEGIN(m0, n0)
;       const f32x4 a = acc[mi][ni];
;       const uint2 g = gp[mi][ni], m = *(const uint2*)(MG + (size_t)row * 1024 + col);
;       const float o0 = lo2f(m.x) + a[0] * lo2f(g.x), o1 = hi2f(m.x) + a[1] * hi2f(g.x), o2 = lo2f(m.y) + a[2] * lo2f(g.y), o3 = hi2f(m.y) + a[3] * hi2f(g.y);
;       *(uint2*)(MG + (size_t)row * 1024 + col) = make_uint2(pack2(o0, o1), pack2(o2, o3));
;     EPI_END
	v_mfma_f32_16x16x32_bf16 v[162:165], v[140:143], v[4:7], v[24:27]
	v_mfma_f32_16x16x32_bf16 v[24:27], v[140:143], v[144:147], v[56:59]
	s_nop 2
	global_load_dwordx2 v[56:57], v[70:71], off
	v_mfma_f32_16x16x32_bf16 v[156:159], v[12:15], v[4:7], v[20:23]
	s_waitcnt vmcnt(0)
	v_lshlrev_b32_e32 v58, 16, v56
	v_mfma_f32_16x16x32_bf16 v[52:55], v[148:151], v[4:7], v[28:31]
	v_and_b32_e32 v59, 0xffff0000, v56
	v_lshlrev_b32_e32 v56, 16, v57
	v_and_b32_e32 v57, 0xffff0000, v57
	v_mfma_f32_16x16x32_bf16 v[28:31], v[12:15], v[144:147], v[16:19]
	v_mfma_f32_16x16x32_bf16 v[16:19], v[116:119], v[144:147], v[60:63]
	s_nop 2
	v_lshlrev_b32_e32 v60, 16, v86
	v_and_b32_e32 v61, 0xffff0000, v86
	v_pk_fma_f32 v[58:59], v[156:157], v[60:61], v[58:59]
	v_lshlrev_b32_e32 v60, 16, v94
	v_and_b32_e32 v61, 0xffff0000, v94
	v_pk_fma_f32 v[56:57], v[158:159], v[60:61], v[56:57]
	v_cvt_pk_bf16_f32 v58, v58, v59
	v_cvt_pk_bf16_f32 v59, v56, v57
	global_load_dwordx2 v[56:57], v[70:71], off offset:32
	v_lshlrev_b32_e32 v60, 16, v95
	global_store_dwordx2 v[70:71], v[58:59], off
	v_and_b32_e32 v61, 0xffff0000, v95
	v_mfma_f32_16x16x32_bf16 v[48:51], v[116:119], v[4:7], v[32:35]
	s_waitcnt vmcnt(1)
	v_lshlrev_b32_e32 v58, 16, v56
	v_and_b32_e32 v59, 0xffff0000, v56
	v_pk_fma_f32 v[58:59], v[162:163], v[60:61], v[58:59]
	v_lshlrev_b32_e32 v56, 16, v57
	v_lshlrev_b32_e32 v60, 16, v102
	v_and_b32_e32 v57, 0xffff0000, v57
	v_and_b32_e32 v61, 0xffff0000, v102
	v_pk_fma_f32 v[56:57], v[164:165], v[60:61], v[56:57]
	v_cvt_pk_bf16_f32 v58, v58, v59
	v_cvt_pk_bf16_f32 v59, v56, v57
	global_load_dwordx2 v[56:57], v[70:71], off offset:64
	v_lshlrev_b32_e32 v60, 16, v100
	global_store_dwordx2 v[70:71], v[58:59], off offset:32
	v_and_b32_e32 v61, 0xffff0000, v100
	v_mfma_f32_16x16x32_bf16 v[44:47], v[12:15], v[136:139], v[44:47]
	s_waitcnt vmcnt(1)
	v_lshlrev_b32_e32 v58, 16, v56
	v_and_b32_e32 v59, 0xffff0000, v56
	v_pk_fma_f32 v[52:53], v[52:53], v[60:61], v[58:59]
	v_lshlrev_b32_e32 v56, 16, v57
	v_lshlrev_b32_e32 v58, 16, v108
	v_and_b32_e32 v57, 0xffff0000, v57
	v_and_b32_e32 v59, 0xffff0000, v108
	v_pk_fma_f32 v[54:55], v[54:55], v[58:59], v[56:57]
	v_cvt_pk_bf16_f32 v52, v52, v53
	v_cvt_pk_bf16_f32 v53, v54, v55
	global_store_dwordx2 v[70:71], v[52:53], off offset:64
	global_load_dwordx2 v[52:53], v[70:71], off offset:96
	v_lshlrev_b32_e32 v56, 16, v91
	v_and_b32_e32 v57, 0xffff0000, v91
	v_mfma_f32_16x16x32_bf16 v[40:43], v[140:143], v[136:139], v[36:39]
	s_waitcnt vmcnt(0)
	v_lshlrev_b32_e32 v54, 16, v52
	v_and_b32_e32 v55, 0xffff0000, v52
	v_pk_fma_f32 v[48:49], v[48:49], v[56:57], v[54:55]
	v_lshlrev_b32_e32 v52, 16, v53
	v_lshlrev_b32_e32 v54, 16, v97
	v_and_b32_e32 v53, 0xffff0000, v53
	v_and_b32_e32 v55, 0xffff0000, v97
	v_pk_fma_f32 v[50:51], v[50:51], v[54:55], v[52:53]
	v_cvt_pk_bf16_f32 v48, v48, v49
	v_cvt_pk_bf16_f32 v49, v50, v51
	v_mfma_f32_16x16x32_bf16 v[36:39], v[148:151], v[136:139], v[72:75]
	global_store_dwordx2 v[70:71], v[48:49], off offset:96
	v_mfma_f32_16x16x32_bf16 v[32:35], v[116:119], v[136:139], v[120:123]
	v_mfma_f32_16x16x32_bf16 v[20:23], v[148:151], v[144:147], v[8:11]
	v_mfma_f32_16x16x32_bf16 v[12:15], v[12:15], v[152:155], v[76:79]
	v_mfma_f32_16x16x32_bf16 v[8:11], v[140:143], v[152:155], v[124:127]
	v_mfma_f32_16x16x32_bf16 v[4:7], v[148:151], v[152:155], v[0:3]
	v_mfma_f32_16x16x32_bf16 v[0:3], v[116:119], v[152:155], v[132:135]
	global_load_dwordx2 v[48:49], v[68:69], off
	v_lshlrev_b32_e32 v52, 16, v104
	v_and_b32_e32 v53, 0xffff0000, v104
	s_waitcnt vmcnt(0)
	v_lshlrev_b32_e32 v50, 16, v48
	v_and_b32_e32 v51, 0xffff0000, v48
	v_pk_fma_f32 v[44:45], v[44:45], v[52:53], v[50:51]
	v_lshlrev_b32_e32 v48, 16, v49
	v_lshlrev_b32_e32 v50, 16, v109
	v_and_b32_e32 v49, 0xffff0000, v49
	v_and_b32_e32 v51, 0xffff0000, v109
	v_pk_fma_f32 v[46:47], v[46:47], v[50:51], v[48:49]
	v_cvt_pk_bf16_f32 v44, v44, v45
	v_cvt_pk_bf16_f32 v45, v46, v47
	global_store_dwordx2 v[68:69], v[44:45], off
	global_load_dwordx2 v[44:45], v[68:69], off offset:32
	v_lshlrev_b32_e32 v48, 16, v112
	v_and_b32_e32 v49, 0xffff0000, v112
	s_waitcnt vmcnt(0)
	v_lshlrev_b32_e32 v46, 16, v44
	v_and_b32_e32 v47, 0xffff0000, v44
	v_pk_fma_f32 v[40:41], v[40:41], v[48:49], v[46:47]
	v_lshlrev_b32_e32 v44, 16, v45
	v_lshlrev_b32_e32 v46, 16, v115
	v_and_b32_e32 v45, 0xffff0000, v45
	v_and_b32_e32 v47, 0xffff0000, v115
	v_pk_fma_f32 v[42:43], v[42:43], v[46:47], v[44:45]
	v_cvt_pk_bf16_f32 v40, v40, v41
	v_cvt_pk_bf16_f32 v41, v42, v43
	global_store_dwordx2 v[68:69], v[40:41], off offset:32
	global_load_dwordx2 v[40:41], v[68:69], off offset:64
	v_lshlrev_b32_e32 v44, 16, v113
	v_and_b32_e32 v45, 0xffff0000, v113
	s_waitcnt vmcnt(0)
	v_lshlrev_b32_e32 v42, 16, v40
	v_and_b32_e32 v43, 0xffff0000, v40
	v_pk_fma_f32 v[36:37], v[36:37], v[44:45], v[42:43]
	v_lshlrev_b32_e32 v40, 16, v41
	v_lshlrev_b32_e32 v42, 16, v114
	v_and_b32_e32 v41, 0xffff0000, v41
	v_and_b32_e32 v43, 0xffff0000, v114
	v_pk_fma_f32 v[38:39], v[38:39], v[42:43], v[40:41]
	v_cvt_pk_bf16_f32 v36, v36, v37
	v_cvt_pk_bf16_f32 v37, v38, v39
	global_store_dwordx2 v[68:69], v[36:37], off offset:64
	global_load_dwordx2 v[36:37], v[68:69], off offset:96
	v_lshlrev_b32_e32 v40, 16, v110
	v_and_b32_e32 v41, 0xffff0000, v110
	s_waitcnt vmcnt(0)
; DEVI uint32_t pack2(float lo, float hi) { f32x2_t v = {lo, hi}; bf16x2_t b = __builtin_convertvector(v, bf16x2_t); return __builtin_bit_cast(uint32_t, b); }
; DEVI float lo2f(uint32_t u) { return __uint_as_float(u << 16); }
; DEVI float hi2f(uint32_t u) { return __uint_as_float(u & 0xffff0000u); }
; #define EPI_END } __builtin_amdgcn_sched_barrier(0); } }
; DEVI void phase_p5(const int TIDX, const int BIDX, const int GDIM, KAP KA, unsigned char* WSB, float* OUTB, int l, unsigned char* smem) {
;     ...
;   for (int item = (BIDX & 7) * (GDIM >> 3) + (BIDX >> 3); item < 516 * 8; item += GDIM) {
;     ...
;     EPI_SWAP_BEGIN(m0, n0)
;       const f32x4 a = acc[mi][ni];
;       const uint2 g = gp[mi][ni], m = *(const uint2*)(MG + (size_t)row * 1024 + col);
;       const float o0 = lo2f(m.x) + a[0] * lo2f(g.x), o1 = hi2f(m.x) + a[1] * hi2f(g.x), o2 = lo2f(m.y) + a[2] * lo2f(g.y), o3 = hi2f(m.y) + a[3] * hi2f(g.y);
;       *(uint2*)(MG + (size_t)row * 1024 + col) = make_uint2(pack2(o0, o1), pack2(o2, o3));
;     EPI_END
	v_lshlrev_b32_e32 v38, 16, v36
	v_and_b32_e32 v39, 0xffff0000, v36
	v_pk_fma_f32 v[32:33], v[32:33], v[40:41], v[38:39]
	v_lshlrev_b32_e32 v36, 16, v37
	v_lshlrev_b32_e32 v38, 16, v111
	v_and_b32_e32 v37, 0xffff0000, v37
	v_and_b32_e32 v39, 0xffff0000, v111
	v_pk_fma_f32 v[34:35], v[34:35], v[38:39], v[36:37]
	v_cvt_pk_bf16_f32 v32, v32, v33
	v_cvt_pk_bf16_f32 v33, v34, v35
	global_store_dwordx2 v[68:69], v[32:33], off offset:96
	global_load_dwordx2 v[32:33], v[66:67], off
	v_lshlrev_b32_e32 v36, 16, v105
	v_and_b32_e32 v37, 0xffff0000, v105
	s_waitcnt vmcnt(0)
	v_lshlrev_b32_e32 v34, 16, v32
	v_and_b32_e32 v35, 0xffff0000, v32
	v_pk_fma_f32 v[28:29], v[28:29], v[36:37], v[34:35]
	v_lshlrev_b32_e32 v32, 16, v33
	v_lshlrev_b32_e32 v34, 16, v107
	v_and_b32_e32 v33, 0xffff0000, v33
	v_and_b32_e32 v35, 0xffff0000, v107
	v_pk_fma_f32 v[30:31], v[30:31], v[34:35], v[32:33]
	v_cvt_pk_bf16_f32 v28, v28, v29
	v_cvt_pk_bf16_f32 v29, v30, v31
	global_store_dwordx2 v[66:67], v[28:29], off
	global_load_dwordx2 v[28:29], v[66:67], off offset:32
	v_lshlrev_b32_e32 v32, 16, v101
	v_and_b32_e32 v33, 0xffff0000, v101
	s_waitcnt vmcnt(0)
	v_lshlrev_b32_e32 v30, 16, v28
	v_and_b32_e32 v31, 0xffff0000, v28
	v_pk_fma_f32 v[24:25], v[24:25], v[32:33], v[30:31]
	v_lshlrev_b32_e32 v28, 16, v29
	v_lshlrev_b32_e32 v30, 16, v106
	v_and_b32_e32 v29, 0xffff0000, v29
	v_and_b32_e32 v31, 0xffff0000, v106
	v_pk_fma_f32 v[26:27], v[26:27], v[30:31], v[28:29]
	v_cvt_pk_bf16_f32 v24, v24, v25
	v_cvt_pk_bf16_f32 v25, v26, v27
	global_store_dwordx2 v[66:67], v[24:25], off offset:32
	global_load_dwordx2 v[24:25], v[66:67], off offset:64
	v_lshlrev_b32_e32 v28, 16, v99
	v_and_b32_e32 v29, 0xffff0000, v99
	s_waitcnt vmcnt(0)
	v_lshlrev_b32_e32 v26, 16, v24
	v_and_b32_e32 v27, 0xffff0000, v24
	v_pk_fma_f32 v[20:21], v[20:21], v[28:29], v[26:27]
	v_lshlrev_b32_e32 v24, 16, v25
	v_lshlrev_b32_e32 v26, 16, v103
	v_and_b32_e32 v25, 0xffff0000, v25
	v_and_b32_e32 v27, 0xffff0000, v103
	v_pk_fma_f32 v[22:23], v[22:23], v[26:27], v[24:25]
	v_cvt_pk_bf16_f32 v20, v20, v21
	v_cvt_pk_bf16_f32 v21, v22, v23
	global_store_dwordx2 v[66:67], v[20:21], off offset:64
	global_load_dwordx2 v[20:21], v[66:67], off offset:96
	v_lshlrev_b32_e32 v24, 16, v96
	v_and_b32_e32 v25, 0xffff0000, v96
	s_waitcnt vmcnt(0)
	v_lshlrev_b32_e32 v22, 16, v20
	v_and_b32_e32 v23, 0xffff0000, v20
	v_pk_fma_f32 v[16:17], v[16:17], v[24:25], v[22:23]
	v_lshlrev_b32_e32 v20, 16, v21
	v_lshlrev_b32_e32 v22, 16, v98
	v_and_b32_e32 v21, 0xffff0000, v21
	v_and_b32_e32 v23, 0xffff0000, v98
	v_pk_fma_f32 v[18:19], v[18:19], v[22:23], v[20:21]
	v_cvt_pk_bf16_f32 v16, v16, v17
	v_cvt_pk_bf16_f32 v17, v18, v19
	global_store_dwordx2 v[66:67], v[16:17], off offset:96
	global_load_dwordx2 v[16:17], v[64:65], off
	v_lshlrev_b32_e32 v20, 16, v90
	v_and_b32_e32 v21, 0xffff0000, v90
	s_waitcnt vmcnt(0)
	v_lshlrev_b32_e32 v18, 16, v16
	v_and_b32_e32 v19, 0xffff0000, v16
	v_pk_fma_f32 v[12:13], v[12:13], v[20:21], v[18:19]
	v_lshlrev_b32_e32 v16, 16, v17
	v_lshlrev_b32_e32 v18, 16, v93
	v_and_b32_e32 v17, 0xffff0000, v17
	v_and_b32_e32 v19, 0xffff0000, v93
	v_pk_fma_f32 v[14:15], v[14:15], v[18:19], v[16:17]
	v_cvt_pk_bf16_f32 v12, v12, v13
	v_cvt_pk_bf16_f32 v13, v14, v15
	global_store_dwordx2 v[64:65], v[12:13], off
	global_load_dwordx2 v[12:13], v[64:65], off offset:32
	v_lshlrev_b32_e32 v16, 16, v88
	v_and_b32_e32 v17, 0xffff0000, v88
	s_waitcnt vmcnt(0)
	v_lshlrev_b32_e32 v14, 16, v12
	v_and_b32_e32 v15, 0xffff0000, v12
	v_pk_fma_f32 v[8:9], v[8:9], v[16:17], v[14:15]
	v_lshlrev_b32_e32 v12, 16, v13
	v_lshlrev_b32_e32 v14, 16, v92
	v_and_b32_e32 v13, 0xffff0000, v13
	v_and_b32_e32 v15, 0xffff0000, v92
	v_pk_fma_f32 v[10:11], v[10:11], v[14:15], v[12:13]
	v_cvt_pk_bf16_f32 v8, v8, v9
	v_cvt_pk_bf16_f32 v9, v10, v11
	global_store_dwordx2 v[64:65], v[8:9], off offset:32
	global_load_dwordx2 v[8:9], v[64:65], off offset:64
	v_lshlrev_b32_e32 v12, 16, v87
	v_and_b32_e32 v13, 0xffff0000, v87
	s_waitcnt vmcnt(0)
	v_lshlrev_b32_e32 v10, 16, v8
	v_and_b32_e32 v11, 0xffff0000, v8
	v_pk_fma_f32 v[4:5], v[4:5], v[12:13], v[10:11]
	v_lshlrev_b32_e32 v8, 16, v9
	v_lshlrev_b32_e32 v10, 16, v89
	v_and_b32_e32 v9, 0xffff0000, v9
	v_and_b32_e32 v11, 0xffff0000, v89
	v_pk_fma_f32 v[6:7], v[6:7], v[10:11], v[8:9]
	v_cvt_pk_bf16_f32 v4, v4, v5
	v_cvt_pk_bf16_f32 v5, v6, v7
	global_store_dwordx2 v[64:65], v[4:5], off offset:64
	global_load_dwordx2 v[4:5], v[64:65], off offset:96
	v_lshlrev_b32_e32 v8, 16, v84
	v_and_b32_e32 v9, 0xffff0000, v84
	s_waitcnt vmcnt(0)
	v_lshlrev_b32_e32 v6, 16, v4
	v_and_b32_e32 v7, 0xffff0000, v4
	v_pk_fma_f32 v[0:1], v[0:1], v[8:9], v[6:7]
	v_lshlrev_b32_e32 v4, 16, v5
	v_lshlrev_b32_e32 v6, 16, v85
	v_and_b32_e32 v5, 0xffff0000, v5
	v_and_b32_e32 v7, 0xffff0000, v85
	v_pk_fma_f32 v[2:3], v[2:3], v[6:7], v[4:5]
	v_cvt_pk_bf16_f32 v0, v0, v1
	v_cvt_pk_bf16_f32 v1, v2, v3
	global_store_dwordx2 v[64:65], v[0:1], off offset:96
	s_add_i32 s2, s2, s84
	s_add_i32 s31, s31, s34
	s_add_i32 s35, s35, s36
	s_cmpk_gt_i32 s2, 0x101f
	s_cbranch_scc0 .LBB0_116

; DEVI f32x4 mfma16(bf16x8 a, bf16x8 b, f32x4 c) { return __builtin_amdgcn_mfma_f32_16x16x32_bf16(a, b, c, 0, 0, 0); }
; template <bool SWAP, class RP>
; DEVI void gemm_main(const int TIDX, const int BIDX, const int GDIM, f32x4 (&acc)[4][4], RP rowoff, const bf16_t* __restrict__ Bt, int ldb, int K, unsigned char* smem) {
;     ...
;   for (int kt = 0; kt < nk; ++kt) {
;     const int buf = kt & 1;
;     asm volatile("s_waitcnt vmcnt(0)" ::: "memory");
;     __syncthreads();
;     if (kt + 1 < nk) GM_STAGE(kt + 1, buf ^ 1);
;     const unsigned char* A = smem + buf * 32768 + (wr * 64 + li) * 128;
;     const unsigned char* B = smem + buf * 32768 + 16384 + (wc * 64 + li) * 128;
; #pragma unroll
;     for (int ks = 0; ks < 2; ++ks) {
;       const int po = (px ^ (ks * 4)) * 16;
;       bf16x8 af[4], bfr[4];
; #pragma unroll
;       for (int i = 0; i < 4; ++i) {
;         af[i] = *(const bf16x8*)(A + i * 2048 + po);
;         bfr[i] = *(const bf16x8*)(B + i * 2048 + po);
;       }
; #pragma unroll
;       for (int mi = 0; mi < 4; ++mi)
; #pragma unroll
;         for (int ni = 0; ni < 4; ++ni)
;           acc[mi][ni] = SWAP ? mfma16(bfr[ni], af[mi], acc[mi][ni]) : mfma16(af[mi], bfr[ni], acc[mi][ni]);
;     }
.LBB0_440:
	s_and_b32 s9, s8, 0x8000
	s_xor_b32 s17, s9, 0x8000
	v_add_u32_e32 v116, s17, v73
	v_add_u32_e32 v194, s9, v1
	v_or_b32_e32 v204, s9, v88
	v_add_u32_e32 v204, v204, v89
	v_add_u32_e32 v205, v194, v77
	v_add_u32_e32 v231, v204, v77
	v_readfirstlane_b32 s101, v116
	v_add_u32_e32 v194, v194, v71
	v_add_u32_e32 v204, v204, v71
	s_waitcnt vmcnt(0)
	s_barrier
	ds_read_b128 v[90:93], v205
	ds_read_b128 v[106:109], v231 offset:16384
	ds_read_b128 v[110:113], v231 offset:18432
	ds_read_b128 v[190:193], v231 offset:20480
	ds_read_b128 v[196:199], v231 offset:22528
	ds_read_b128 v[94:97], v205 offset:2048
	ds_read_b128 v[98:101], v205 offset:4096
	ds_read_b128 v[102:105], v205 offset:6144
	ds_read_b128 v[200:203], v204 offset:16384
	ds_read_b128 v[208:211], v204 offset:18432
	ds_read_b128 v[236:239], v204 offset:20480
	ds_read_b128 v[240:243], v204 offset:22528
	s_mov_b32 m0, s101
	v_lshl_add_u64 v[114:115], v[80:81], 0, s[6:7]
	global_load_lds_dwordx4 v[114:115], off
	s_add_i32 m0, s101, 0x1000
	v_lshl_add_u64 v[114:115], v[82:83], 0, s[6:7]
	global_load_lds_dwordx4 v[114:115], off
	s_waitcnt lgkmcnt(7)
	v_mfma_f32_16x16x32_bf16 v[62:65], v[106:109], v[90:93], v[62:65]
	v_mfma_f32_16x16x32_bf16 v[58:61], v[110:113], v[90:93], v[58:61]
	s_add_i32 m0, s101, 0x2000
	v_lshl_add_u64 v[114:115], v[84:85], 0, s[6:7]
	global_load_lds_dwordx4 v[114:115], off
	v_mfma_f32_16x16x32_bf16 v[54:57], v[190:193], v[90:93], v[54:57]
	v_mfma_f32_16x16x32_bf16 v[50:53], v[196:199], v[90:93], v[50:53]
	ds_read_b128 v[90:93], v194
	s_add_i32 m0, s101, 0x3000
	v_lshl_add_u64 v[114:115], v[86:87], 0, s[6:7]
	global_load_lds_dwordx4 v[114:115], off
	s_waitcnt lgkmcnt(7)
	v_mfma_f32_16x16x32_bf16 v[46:49], v[106:109], v[94:97], v[46:49]
	v_mfma_f32_16x16x32_bf16 v[38:41], v[110:113], v[94:97], v[38:41]
	s_add_i32 m0, s101, 0x4000
	v_lshl_add_u64 v[114:115], v[78:79], 0, s[6:7]
	v_lshl_add_u64 v[114:115], v[114:115], 0, s[66:67]
	global_load_lds_dwordx4 v[114:115], off
	v_mfma_f32_16x16x32_bf16 v[34:37], v[190:193], v[94:97], v[34:37]
	v_mfma_f32_16x16x32_bf16 v[30:33], v[196:199], v[94:97], v[30:33]
	ds_read_b128 v[94:97], v194 offset:2048
	s_add_i32 m0, s101, 0x5000
	v_lshl_add_u64 v[114:115], v[78:79], 0, s[6:7]
	v_lshl_add_u64 v[114:115], v[114:115], 0, s[70:71]
	global_load_lds_dwordx4 v[114:115], off
	s_waitcnt lgkmcnt(7)
	v_mfma_f32_16x16x32_bf16 v[26:29], v[106:109], v[98:101], v[26:29]
	v_mfma_f32_16x16x32_bf16 v[22:25], v[110:113], v[98:101], v[22:25]
	s_add_i32 m0, s101, 0x6000
	v_lshl_add_u64 v[114:115], v[78:79], 0, s[6:7]
	v_lshl_add_u64 v[114:115], v[114:115], 0, s[94:95]
	global_load_lds_dwordx4 v[114:115], off
	v_mfma_f32_16x16x32_bf16 v[18:21], v[190:193], v[98:101], v[18:21]
	v_mfma_f32_16x16x32_bf16 v[14:17], v[196:199], v[98:101], v[14:17]
	ds_read_b128 v[98:101], v194 offset:4096
	s_add_i32 m0, s101, 0x7000
	v_lshl_add_u64 v[114:115], v[78:79], 0, s[6:7]
	v_lshl_add_u64 v[114:115], v[114:115], 0, s[68:69]
	global_load_lds_dwordx4 v[114:115], off
	s_waitcnt lgkmcnt(7)
	v_mfma_f32_16x16x32_bf16 v[10:13], v[106:109], v[102:105], v[10:13]
	v_mfma_f32_16x16x32_bf16 v[6:9], v[110:113], v[102:105], v[6:9]
	v_mfma_f32_16x16x32_bf16 v[2:5], v[190:193], v[102:105], v[2:5]
	v_mfma_f32_16x16x32_bf16 v[42:45], v[196:199], v[102:105], v[42:45]
	ds_read_b128 v[102:105], v194 offset:6144
	s_waitcnt lgkmcnt(3)
	v_mfma_f32_16x16x32_bf16 v[62:65], v[200:203], v[90:93], v[62:65]
	v_mfma_f32_16x16x32_bf16 v[58:61], v[208:211], v[90:93], v[58:61]
	v_mfma_f32_16x16x32_bf16 v[54:57], v[236:239], v[90:93], v[54:57]
	v_mfma_f32_16x16x32_bf16 v[50:53], v[240:243], v[90:93], v[50:53]
	s_waitcnt lgkmcnt(2)
	v_mfma_f32_16x16x32_bf16 v[46:49], v[200:203], v[94:97], v[46:49]
	v_mfma_f32_16x16x32_bf16 v[38:41], v[208:211], v[94:97], v[38:41]
	v_mfma_f32_16x16x32_bf16 v[34:37], v[236:239], v[94:97], v[34:37]
	v_mfma_f32_16x16x32_bf16 v[30:33], v[240:243], v[94:97], v[30:33]
	s_waitcnt lgkmcnt(1)
	v_mfma_f32_16x16x32_bf16 v[26:29], v[200:203], v[98:101], v[26:29]
	v_mfma_f32_16x16x32_bf16 v[22:25], v[208:211], v[98:101], v[22:25]
	v_mfma_f32_16x16x32_bf16 v[18:21], v[236:239], v[98:101], v[18:21]
	v_mfma_f32_16x16x32_bf16 v[14:17], v[240:243], v[98:101], v[14:17]
	s_waitcnt lgkmcnt(0)
	s_add_u32 s6, s6, 0x80
	s_addc_u32 s7, s7, 0
	s_add_i32 s8, s8, 0x8000
	s_cmpk_eq_i32 s6, 0x780
	v_mfma_f32_16x16x32_bf16 v[10:13], v[200:203], v[102:105], v[10:13]
	v_mfma_f32_16x16x32_bf16 v[6:9], v[208:211], v[102:105], v[6:9]
	v_mfma_f32_16x16x32_bf16 v[2:5], v[236:239], v[102:105], v[2:5]
	v_mfma_f32_16x16x32_bf16 v[42:45], v[240:243], v[102:105], v[42:45]
	s_cbranch_scc0 .LBB0_440
; DEVI uint32_t pack2(float lo, float hi) { f32x2_t v = {lo, hi}; bf16x2_t b = __builtin_convertvector(v, bf16x2_t); return __builtin_bit_cast(uint32_t, b); }
; DEVI f32x4 mfma16(bf16x8 a, bf16x8 b, f32x4 c) { return __builtin_amdgcn_mfma_f32_16x16x32_bf16(a, b, c, 0, 0, 0); }
; template <bool SWAP, class RP>
; DEVI void gemm_main(const int TIDX, const int BIDX, const int GDIM, f32x4 (&acc)[4][4], RP rowoff, const bf16_t* __restrict__ Bt, int ldb, int K, unsigned char* smem) {
;     ...
;     for (int ks = 0; ks < 2; ++ks) {
;       const int po = (px ^ (ks * 4)) * 16;
;       bf16x8 af[4], bfr[4];
; #pragma unroll
;       for (int i = 0; i < 4; ++i) {
;         af[i] = *(const bf16x8*)(A + i * 2048 + po);
;         bfr[i] = *(const bf16x8*)(B + i * 2048 + po);
;       }
; #pragma unroll
;       for (int mi = 0; mi < 4; ++mi)
; #pragma unroll
;         for (int ni = 0; ni < 4; ++ni)
;           acc[mi][ni] = SWAP ? mfma16(bfr[ni], af[mi], acc[mi][ni]) : mfma16(af[mi], bfr[ni], acc[mi][ni]);
;     }
;   }
;   __syncthreads();
; DEVI void phase_p1(const int TIDX, const int BIDX, const int GDIM, KAP KA, unsigned char* WSB, float* OUTB, int l, unsigned char* smem) {
;     ...
;       EPI_SWAP_BEGIN(m0, 0)
;         const f32x4 a = acc[mi][ni];
;         if (nt < 3) {
;           *(uint2*)(CQ + (size_t)row * 384 + nt * 128 + col) = make_uint2(pack2(a[0], a[1]), pack2(a[2], a[3]));
;         } else if (nt < 5) {
;           *(f32x4*)(CKR + (size_t)row * 288 + (nt - 3) * 128 + col) = a;
;         } else if (nt == 5) {
;           if (col < 32) *(f32x4*)(CKR + (size_t)row * 288 + 256 + col) = a;
;         } else if (nt < 14) {
;           *(uint2*)(FQ + (size_t)row * 1024 + (nt - 6) * 128 + col) = make_uint2(pack2(a[0], a[1]), pack2(a[2], a[3]));
;         } else {
;           *(uint2*)(G + (size_t)row * 512 + (nt - 18) * 128 + col) = make_uint2(pack2(a[0], a[1]), pack2(a[2], a[3]));
;         }
	v_add_u32_e32 v73, v88, v89
	v_add_u32_e32 v98, v73, v77
	s_waitcnt vmcnt(0)
	s_waitcnt vmcnt(0)
	s_barrier
	ds_read_b128 v[78:81], v98 offset:49152
	v_add_u32_e32 v77, v1, v77
	ds_read_b128 v[82:85], v98 offset:51200
	ds_read_b128 v[86:89], v77 offset:32768
	ds_read_b128 v[90:93], v77 offset:34816
	ds_read_b128 v[94:97], v98 offset:53248
	ds_read_b128 v[98:101], v98 offset:55296
	s_waitcnt lgkmcnt(3)
	v_mfma_f32_16x16x32_bf16 v[62:65], v[78:81], v[86:89], v[62:65]
	s_cmp_gt_i32 s16, 2
	v_add_u32_e32 v73, v73, v71
	s_cselect_b64 s[6:7], -1, 0
	v_mfma_f32_16x16x32_bf16 v[58:61], v[82:85], v[86:89], v[58:61]
	s_cmp_gt_u32 s16, 4
	v_add_u32_e32 v1, v1, v71
	s_cselect_b64 s[28:29], -1, 0
	s_waitcnt lgkmcnt(1)
	v_mfma_f32_16x16x32_bf16 v[54:57], v[94:97], v[86:89], v[54:57]
	s_cmp_lg_u32 s16, 5
	s_cselect_b64 s[20:21], -1, 0
	s_cmp_gt_u32 s16, 13
	s_waitcnt lgkmcnt(0)
	v_mfma_f32_16x16x32_bf16 v[50:53], v[98:101], v[86:89], v[50:53]
	s_cselect_b64 s[18:19], -1, 0
	s_lshl_b32 s54, s16, 7
	s_lshl_b64 s[8:9], s[54:55], 1
	v_mfma_f32_16x16x32_bf16 v[46:49], v[78:81], v[90:93], v[46:49]
	s_add_u32 s24, s50, s8
	s_addc_u32 s25, s51, s9
	s_lshl_b64 s[8:9], s[54:55], 2
	v_mfma_f32_16x16x32_bf16 v[38:41], v[82:85], v[90:93], v[38:41]
	s_add_u32 s26, s0, s8
	s_addc_u32 s27, s1, s9
	s_ashr_i32 s9, s54, 31
	v_mfma_f32_16x16x32_bf16 v[34:37], v[94:97], v[90:93], v[34:37]
	s_mov_b32 s8, s54
	s_lshl_b64 s[8:9], s[8:9], 1
	s_add_u32 s22, s39, s8
	v_mfma_f32_16x16x32_bf16 v[30:33], v[98:101], v[90:93], v[30:33]
	ds_read_b128 v[86:89], v77 offset:36864
	ds_read_b128 v[90:93], v77 offset:38912
	s_addc_u32 s23, s40, s9
	s_mov_b64 s[8:9], 0xbbec600
	s_waitcnt lgkmcnt(1)
	v_mfma_f32_16x16x32_bf16 v[26:29], v[78:81], v[86:89], v[26:29]
	s_and_b64 vcc, exec, s[6:7]
	v_mfma_f32_16x16x32_bf16 v[22:25], v[82:85], v[86:89], v[22:25]
	v_mfma_f32_16x16x32_bf16 v[18:21], v[94:97], v[86:89], v[18:21]
	v_mfma_f32_16x16x32_bf16 v[14:17], v[98:101], v[86:89], v[14:17]
	s_waitcnt lgkmcnt(0)
	v_mfma_f32_16x16x32_bf16 v[10:13], v[78:81], v[90:93], v[10:13]
	v_add_u32_e32 v78, s10, v67
	v_ashrrev_i32_e32 v79, 31, v78
	v_mfma_f32_16x16x32_bf16 v[6:9], v[82:85], v[90:93], v[6:9]
	ds_read_b128 v[80:83], v73 offset:49152
	v_mfma_f32_16x16x32_bf16 v[2:5], v[94:97], v[90:93], v[2:5]
	v_mfma_f32_16x16x32_bf16 v[90:93], v[98:101], v[90:93], v[42:45]
	ds_read_b128 v[86:89], v73 offset:51200
	s_nop 1
	ds_read_b128 v[42:45], v1 offset:32768
	ds_read_b128 v[94:97], v1 offset:34816
	ds_read_b128 v[98:101], v73 offset:53248
	ds_read_b128 v[102:105], v73 offset:55296
	ds_read_b128 v[106:109], v1 offset:36864
	ds_read_b128 v[110:113], v1 offset:38912
	s_waitcnt lgkmcnt(5)
	v_mfma_f32_16x16x32_bf16 v[62:65], v[80:83], v[42:45], v[62:65]
	s_waitcnt lgkmcnt(0)
	s_barrier
	v_mfma_f32_16x16x32_bf16 v[58:61], v[86:89], v[42:45], v[58:61]
	v_mfma_f32_16x16x32_bf16 v[54:57], v[98:101], v[42:45], v[54:57]
	v_mfma_f32_16x16x32_bf16 v[50:53], v[102:105], v[42:45], v[50:53]
	v_mfma_f32_16x16x32_bf16 v[46:49], v[80:83], v[94:97], v[46:49]
	v_mfma_f32_16x16x32_bf16 v[42:45], v[86:89], v[94:97], v[38:41]
	v_mfma_f32_16x16x32_bf16 v[38:41], v[98:101], v[94:97], v[34:37]
	v_mfma_f32_16x16x32_bf16 v[34:37], v[102:105], v[94:97], v[30:33]
	v_lshlrev_b64 v[94:95], 10, v[78:79]
	v_lshl_add_u64 v[96:97], s[24:25], 0, v[94:95]
	v_lshl_add_u64 v[84:85], v[96:97], 0, s[8:9]
	v_mfma_f32_16x16x32_bf16 v[30:33], v[80:83], v[106:109], v[26:29]
	s_mov_b64 s[8:9], 0x1b5dd200
	v_mfma_f32_16x16x32_bf16 v[26:29], v[86:89], v[106:109], v[22:25]
	v_mfma_f32_16x16x32_bf16 v[22:25], v[98:101], v[106:109], v[18:21]
	v_mfma_f32_16x16x32_bf16 v[18:21], v[102:105], v[106:109], v[14:17]
	v_mfma_f32_16x16x32_bf16 v[14:17], v[80:83], v[110:113], v[10:13]
	v_mov_b64_e32 v[80:81], s[0:1]
	s_nop 1
	v_lshl_add_u64 v[10:11], v[96:97], 0, v[94:95]
	v_lshl_add_u64 v[82:83], v[10:11], 0, s[8:9]
	v_mfma_f32_16x16x32_bf16 v[10:13], v[86:89], v[110:113], v[6:9]
	v_mad_i64_i32 v[88:89], s[8:9], v78, s93, v[80:81]
	v_mov_b64_e32 v[80:81], s[26:27]
	v_mfma_f32_16x16x32_bf16 v[6:9], v[98:101], v[110:113], v[2:5]
	v_mad_i64_i32 v[80:81], s[8:9], v78, s93, v[80:81]
	s_mov_b64 s[8:9], -1
	v_mfma_f32_16x16x32_bf16 v[2:5], v[102:105], v[110:113], v[90:93]
	s_cbranch_vccz .LBB0_457
	s_and_b64 vcc, exec, s[28:29]
	s_cbranch_vccz .LBB0_454
	s_and_b64 vcc, exec, s[20:21]
	s_cbranch_vccz .LBB0_449
	v_cvt_pk_bf16_f32 v86, v62, v63
	v_cvt_pk_bf16_f32 v87, v64, v65
	s_and_b64 vcc, exec, s[18:19]
	s_cbranch_vccz .LBB0_446
	v_lshlrev_b32_e32 v128, 1, v66
	v_lshl_add_u64 v[90:91], v[84:85], 0, v[128:129]
	global_store_dwordx2 v[90:91], v[86:87], off
	s_mov_b64 s[8:9], 0

; DEVI f32x4 mfma16(bf16x8 a, bf16x8 b, f32x4 c) { return __builtin_amdgcn_mfma_f32_16x16x32_bf16(a, b, c, 0, 0, 0); }
; template <bool SWAP, class RP>
; DEVI void gemm_main(const int TIDX, const int BIDX, const int GDIM, f32x4 (&acc)[4][4], RP rowoff, const bf16_t* __restrict__ Bt, int ldb, int K, unsigned char* smem) {
;     ...
;   for (int kt = 0; kt < nk; ++kt) {
;     const int buf = kt & 1;
;     asm volatile("s_waitcnt vmcnt(0)" ::: "memory");
;     __syncthreads();
;     if (kt + 1 < nk) GM_STAGE(kt + 1, buf ^ 1);
;     const unsigned char* A = smem + buf * 32768 + (wr * 64 + li) * 128;
;     const unsigned char* B = smem + buf * 32768 + 16384 + (wc * 64 + li) * 128;
; #pragma unroll
;     for (int ks = 0; ks < 2; ++ks) {
;       const int po = (px ^ (ks * 4)) * 16;
;       bf16x8 af[4], bfr[4];
; #pragma unroll
;       for (int i = 0; i < 4; ++i) {
;         af[i] = *(const bf16x8*)(A + i * 2048 + po);
;         bfr[i] = *(const bf16x8*)(B + i * 2048 + po);
;       }
; #pragma unroll
;       for (int mi = 0; mi < 4; ++mi)
; #pragma unroll
;         for (int ni = 0; ni < 4; ++ni)
;           acc[mi][ni] = SWAP ? mfma16(bfr[ni], af[mi], acc[mi][ni]) : mfma16(af[mi], bfr[ni], acc[mi][ni]);
;     }
.LBB0_495:
	s_and_b32 s9, s8, 0x8000
	s_xor_b32 s12, s9, 0x8000
	v_add_u32_e32 v89, s12, v77
	v_add_u32_e32 v122, s9, v71
	v_or_b32_e32 v194, s9, v87
	v_add_u32_e32 v194, v194, v88
	v_add_u32_e32 v231, v122, v86
	v_add_u32_e32 v232, v194, v86
	v_readfirstlane_b32 s101, v89
	v_add_u32_e32 v122, v122, v73
	v_add_u32_e32 v194, v194, v73
	s_waitcnt vmcnt(0)
	s_barrier
	ds_read_b128 v[90:93], v231
	ds_read_b128 v[106:109], v232 offset:16384
	ds_read_b128 v[110:113], v232 offset:18432
	ds_read_b128 v[114:117], v232 offset:20480
	ds_read_b128 v[118:121], v232 offset:22528
	ds_read_b128 v[94:97], v231 offset:2048
	ds_read_b128 v[98:101], v231 offset:4096
	ds_read_b128 v[102:105], v231 offset:6144
	ds_read_b128 v[190:193], v194 offset:16384
	ds_read_b128 v[196:199], v194 offset:18432
	ds_read_b128 v[200:203], v194 offset:20480
	ds_read_b128 v[208:211], v194 offset:22528
	s_mov_b32 m0, s101
	v_lshl_add_u64 v[204:205], v[78:79], 0, s[6:7]
	global_load_lds_dwordx4 v[204:205], off
	s_add_i32 m0, s101, 0x1000
	v_lshl_add_u64 v[204:205], v[80:81], 0, s[6:7]
	global_load_lds_dwordx4 v[204:205], off
	s_waitcnt lgkmcnt(7)
	v_mfma_f32_16x16x32_bf16 v[60:63], v[90:93], v[106:109], v[60:63]
	v_mfma_f32_16x16x32_bf16 v[56:59], v[90:93], v[110:113], v[56:59]
	s_add_i32 m0, s101, 0x2000
	v_lshl_add_u64 v[204:205], v[82:83], 0, s[6:7]
	global_load_lds_dwordx4 v[204:205], off
	v_mfma_f32_16x16x32_bf16 v[52:55], v[90:93], v[114:117], v[52:55]
	v_mfma_f32_16x16x32_bf16 v[48:51], v[90:93], v[118:121], v[48:51]
	ds_read_b128 v[90:93], v122
	s_add_i32 m0, s101, 0x3000
	v_lshl_add_u64 v[204:205], v[84:85], 0, s[6:7]
	global_load_lds_dwordx4 v[204:205], off
	s_waitcnt lgkmcnt(7)
	v_mfma_f32_16x16x32_bf16 v[44:47], v[94:97], v[106:109], v[44:47]
	v_mfma_f32_16x16x32_bf16 v[40:43], v[94:97], v[110:113], v[40:43]
	s_add_i32 m0, s101, 0x4000
	v_lshl_add_u64 v[204:205], v[64:65], 0, s[6:7]
	v_lshl_add_u64 v[204:205], v[204:205], 0, s[66:67]
	global_load_lds_dwordx4 v[204:205], off
	v_mfma_f32_16x16x32_bf16 v[36:39], v[94:97], v[114:117], v[36:39]
	v_mfma_f32_16x16x32_bf16 v[32:35], v[94:97], v[118:121], v[32:35]
	ds_read_b128 v[94:97], v122 offset:2048
	s_add_i32 m0, s101, 0x5000
	v_lshl_add_u64 v[204:205], v[64:65], 0, s[6:7]
	v_lshl_add_u64 v[204:205], v[204:205], 0, s[70:71]
	global_load_lds_dwordx4 v[204:205], off
	s_waitcnt lgkmcnt(7)
	v_mfma_f32_16x16x32_bf16 v[28:31], v[98:101], v[106:109], v[28:31]
	v_mfma_f32_16x16x32_bf16 v[24:27], v[98:101], v[110:113], v[24:27]
	s_add_i32 m0, s101, 0x6000
	v_lshl_add_u64 v[204:205], v[64:65], 0, s[6:7]
	v_lshl_add_u64 v[204:205], v[204:205], 0, s[94:95]
	global_load_lds_dwordx4 v[204:205], off
	v_mfma_f32_16x16x32_bf16 v[20:23], v[98:101], v[114:117], v[20:23]
	v_mfma_f32_16x16x32_bf16 v[16:19], v[98:101], v[118:121], v[16:19]
	ds_read_b128 v[98:101], v122 offset:4096
	s_add_i32 m0, s101, 0x7000
	v_lshl_add_u64 v[204:205], v[64:65], 0, s[6:7]
	v_lshl_add_u64 v[204:205], v[204:205], 0, s[68:69]
	global_load_lds_dwordx4 v[204:205], off
	s_waitcnt lgkmcnt(7)
	v_mfma_f32_16x16x32_bf16 v[12:15], v[102:105], v[106:109], v[12:15]
	v_mfma_f32_16x16x32_bf16 v[8:11], v[102:105], v[110:113], v[8:11]
	v_mfma_f32_16x16x32_bf16 v[4:7], v[102:105], v[114:117], v[4:7]
	v_mfma_f32_16x16x32_bf16 v[0:3], v[102:105], v[118:121], v[0:3]
	ds_read_b128 v[102:105], v122 offset:6144
	s_waitcnt lgkmcnt(3)
	v_mfma_f32_16x16x32_bf16 v[60:63], v[90:93], v[190:193], v[60:63]
	v_mfma_f32_16x16x32_bf16 v[56:59], v[90:93], v[196:199], v[56:59]
	v_mfma_f32_16x16x32_bf16 v[52:55], v[90:93], v[200:203], v[52:55]
	v_mfma_f32_16x16x32_bf16 v[48:51], v[90:93], v[208:211], v[48:51]
	s_waitcnt lgkmcnt(2)
	v_mfma_f32_16x16x32_bf16 v[44:47], v[94:97], v[190:193], v[44:47]
	v_mfma_f32_16x16x32_bf16 v[40:43], v[94:97], v[196:199], v[40:43]
	v_mfma_f32_16x16x32_bf16 v[36:39], v[94:97], v[200:203], v[36:39]
	v_mfma_f32_16x16x32_bf16 v[32:35], v[94:97], v[208:211], v[32:35]
	s_waitcnt lgkmcnt(1)
	v_mfma_f32_16x16x32_bf16 v[28:31], v[98:101], v[190:193], v[28:31]
	v_mfma_f32_16x16x32_bf16 v[24:27], v[98:101], v[196:199], v[24:27]
	v_mfma_f32_16x16x32_bf16 v[20:23], v[98:101], v[200:203], v[20:23]
	v_mfma_f32_16x16x32_bf16 v[16:19], v[98:101], v[208:211], v[16:19]
	s_waitcnt lgkmcnt(0)
	s_add_u32 s6, s6, 0x80
	s_addc_u32 s7, s7, 0
	s_add_i32 s8, s8, 0x8000
	s_cmpk_eq_i32 s6, 0x780
	v_mfma_f32_16x16x32_bf16 v[12:15], v[102:105], v[190:193], v[12:15]
	v_mfma_f32_16x16x32_bf16 v[8:11], v[102:105], v[196:199], v[8:11]
	v_mfma_f32_16x16x32_bf16 v[4:7], v[102:105], v[200:203], v[4:7]
	v_mfma_f32_16x16x32_bf16 v[0:3], v[102:105], v[208:211], v[0:3]
	s_cbranch_scc0 .LBB0_495
	v_add_u32_e32 v64, v87, v88
	v_add_u32_e32 v65, v71, v86
	s_waitcnt vmcnt(0)
	s_waitcnt vmcnt(0)
	s_barrier
; DEVI uint32_t pack2(float lo, float hi) { f32x2_t v = {lo, hi}; bf16x2_t b = __builtin_convertvector(v, bf16x2_t); return __builtin_bit_cast(uint32_t, b); }
; DEVI f32x4 mfma16(bf16x8 a, bf16x8 b, f32x4 c) { return __builtin_amdgcn_mfma_f32_16x16x32_bf16(a, b, c, 0, 0, 0); }
; template <bool SWAP, class RP>
; DEVI void gemm_main(const int TIDX, const int BIDX, const int GDIM, f32x4 (&acc)[4][4], RP rowoff, const bf16_t* __restrict__ Bt, int ldb, int K, unsigned char* smem) {
;     ...
;     for (int ks = 0; ks < 2; ++ks) {
;       const int po = (px ^ (ks * 4)) * 16;
;       bf16x8 af[4], bfr[4];
; #pragma unroll
;       for (int i = 0; i < 4; ++i) {
;         af[i] = *(const bf16x8*)(A + i * 2048 + po);
;         bfr[i] = *(const bf16x8*)(B + i * 2048 + po);
;       }
; #pragma unroll
;       for (int mi = 0; mi < 4; ++mi)
; #pragma unroll
;         for (int ni = 0; ni < 4; ++ni)
;           acc[mi][ni] = SWAP ? mfma16(bfr[ni], af[mi], acc[mi][ni]) : mfma16(af[mi], bfr[ni], acc[mi][ni]);
;     }
;   }
;   __syncthreads();
; DEVI void phase_p1(const int TIDX, const int BIDX, const int GDIM, KAP KA, unsigned char* WSB, float* OUTB, int l, unsigned char* smem) {
;     ...
;       gemm_main<false>(TIDX, BIDX, GDIM, acc, rp, W + (size_t)nt * 128 * 1024, 1024, 1024, smem);
;       const int h = nt - 14, lane = TIDX & 63, w = TIDX >> 6;
;       const int rb = m0 + (w >> 1) * 64 + 4 * (lane >> 4), cb = (w & 1) * 64 + (lane & 15);
; #pragma unroll
;       for (int mi = 0; mi < 4; ++mi) {
;         const int row = rb + mi * 16, ch = row >> 5, s = row & 31;
; #pragma unroll
;         for (int ni = 0; ni < 4; ++ni) {
;           const int dv = cb + ni * 16;
;           const f32x4 a = acc[mi][ni];
;           *(uint2*)(VT2 + ((size_t)(ch * 4 + h) * 128 + dv) * 32 + s) = make_uint2(pack2(a[0], a[1]), pack2(a[2], a[3]));
;         }
;       }
	v_add_u32_e32 v77, v64, v86
	ds_read_b128 v[78:81], v65 offset:32768
	ds_read_b128 v[82:85], v77 offset:49152
	ds_read_b128 v[86:89], v65 offset:34816
	ds_read_b128 v[90:93], v77 offset:51200
	ds_read_b128 v[94:97], v65 offset:36864
	ds_read_b128 v[98:101], v77 offset:53248
	ds_read_b128 v[102:105], v65 offset:38912
	ds_read_b128 v[106:109], v77 offset:55296
	v_add_u32_e32 v65, v71, v73
	s_waitcnt lgkmcnt(6)
	v_mfma_f32_16x16x32_bf16 v[60:63], v[78:81], v[82:85], v[60:63]
	v_add_u32_e32 v64, v64, v73
	v_add_u32_e32 v71, s10, v69
	v_mov_b32_e32 v77, v129
	s_waitcnt lgkmcnt(4)
	v_mfma_f32_16x16x32_bf16 v[56:59], v[78:81], v[90:93], v[56:59]
	s_waitcnt lgkmcnt(2)
	v_mfma_f32_16x16x32_bf16 v[52:55], v[78:81], v[98:101], v[52:55]
	s_waitcnt lgkmcnt(0)
	v_mfma_f32_16x16x32_bf16 v[48:51], v[78:81], v[106:109], v[48:51]
	v_mfma_f32_16x16x32_bf16 v[44:47], v[86:89], v[82:85], v[44:47]
	v_mfma_f32_16x16x32_bf16 v[40:43], v[86:89], v[90:93], v[40:43]
	v_mfma_f32_16x16x32_bf16 v[36:39], v[86:89], v[98:101], v[36:39]
	v_mfma_f32_16x16x32_bf16 v[32:35], v[86:89], v[106:109], v[32:35]
	v_mfma_f32_16x16x32_bf16 v[28:31], v[94:97], v[82:85], v[28:31]
	v_mfma_f32_16x16x32_bf16 v[24:27], v[94:97], v[90:93], v[24:27]
	v_mfma_f32_16x16x32_bf16 v[20:23], v[94:97], v[98:101], v[20:23]
	v_mfma_f32_16x16x32_bf16 v[16:19], v[94:97], v[106:109], v[16:19]
	v_mfma_f32_16x16x32_bf16 v[12:15], v[102:105], v[82:85], v[12:15]
	v_mfma_f32_16x16x32_bf16 v[8:11], v[102:105], v[90:93], v[8:11]
	v_mfma_f32_16x16x32_bf16 v[4:7], v[102:105], v[98:101], v[4:7]
	v_mfma_f32_16x16x32_bf16 v[0:3], v[102:105], v[106:109], v[0:3]
	ds_read_b128 v[78:81], v65 offset:32768
	ds_read_b128 v[82:85], v64 offset:49152
	ds_read_b128 v[86:89], v65 offset:34816
	ds_read_b128 v[90:93], v64 offset:51200
	ds_read_b128 v[94:97], v65 offset:36864
	ds_read_b128 v[98:101], v64 offset:53248
	ds_read_b128 v[102:105], v65 offset:38912
	ds_read_b128 v[106:109], v64 offset:55296
	v_ashrrev_i32_e32 v64, 3, v71
	v_and_or_b32 v64, v64, -8, s11
	s_waitcnt lgkmcnt(6)
	v_mfma_f32_16x16x32_bf16 v[60:63], v[78:81], v[82:85], v[60:63]
	v_ashrrev_i32_e32 v65, 31, v64
	s_waitcnt lgkmcnt(0)
	s_barrier
	v_mfma_f32_16x16x32_bf16 v[32:35], v[86:89], v[106:109], v[32:35]
	s_nop 3
	v_cvt_pk_bf16_f32 v60, v60, v61
	v_cvt_pk_bf16_f32 v61, v62, v63
	v_mfma_f32_16x16x32_bf16 v[56:59], v[78:81], v[90:93], v[56:59]
	v_mfma_f32_16x16x32_bf16 v[52:55], v[78:81], v[98:101], v[52:55]
	v_cvt_pk_bf16_f32 v32, v32, v33
	v_cvt_pk_bf16_f32 v33, v34, v35
	s_nop 4
	v_cvt_pk_bf16_f32 v56, v56, v57
	v_mfma_f32_16x16x32_bf16 v[48:51], v[78:81], v[106:109], v[48:51]
	v_lshlrev_b64 v[78:79], 13, v[64:65]
	v_lshl_add_u64 v[62:63], v[74:75], 0, v[78:79]
	global_store_dwordx2 v[62:63], v[32:33], off offset:3104
	v_mfma_f32_16x16x32_bf16 v[28:31], v[94:97], v[82:85], v[28:31]
	v_or_b32_e32 v32, 4, v64
	v_ashrrev_i32_e32 v33, 31, v32
	v_lshlrev_b64 v[32:33], 13, v[32:33]
	v_mfma_f32_16x16x32_bf16 v[16:19], v[94:97], v[106:109], v[16:19]
	v_cvt_pk_bf16_f32 v57, v58, v59
	s_nop 2
	v_cvt_pk_bf16_f32 v28, v28, v29
	v_cvt_pk_bf16_f32 v29, v30, v31
	v_lshl_add_u64 v[30:31], v[74:75], 0, v[32:33]
	v_mfma_f32_16x16x32_bf16 v[44:47], v[86:89], v[82:85], v[44:47]
	v_cvt_pk_bf16_f32 v16, v16, v17
	v_cvt_pk_bf16_f32 v17, v18, v19
	global_store_dwordx2 v[30:31], v[16:17], off offset:3072
	v_or_b32_e32 v16, 48, v71
	v_ashrrev_i32_e32 v16, 3, v16
	v_and_or_b32 v16, v16, -4, s11
	v_mfma_f32_16x16x32_bf16 v[40:43], v[86:89], v[90:93], v[40:43]
	v_ashrrev_i32_e32 v17, 31, v16
	v_bitop3_b32 v18, v71, 28, 48 bitop3:0xc8
	v_lshlrev_b64 v[16:17], 13, v[16:17]
	v_mfma_f32_16x16x32_bf16 v[36:39], v[86:89], v[98:101], v[36:39]
	v_lshl_add_u64 v[16:17], s[2:3], 0, v[16:17]
	v_lshlrev_b32_e32 v128, 1, v18
	v_lshl_add_u64 v[16:17], v[16:17], 0, v[128:129]
	v_mfma_f32_16x16x32_bf16 v[24:27], v[94:97], v[90:93], v[24:27]
	v_cvt_pk_bf16_f32 v52, v52, v53
	v_cvt_pk_bf16_f32 v53, v54, v55
	v_cvt_pk_bf16_f32 v48, v48, v49
	v_mfma_f32_16x16x32_bf16 v[20:23], v[94:97], v[98:101], v[20:23]
	v_cvt_pk_bf16_f32 v49, v50, v51
	v_cvt_pk_bf16_f32 v44, v44, v45
	v_cvt_pk_bf16_f32 v45, v46, v47
	v_mfma_f32_16x16x32_bf16 v[12:15], v[102:105], v[82:85], v[12:15]
	v_cvt_pk_bf16_f32 v40, v40, v41
	v_cvt_pk_bf16_f32 v41, v42, v43
	v_cvt_pk_bf16_f32 v36, v36, v37
	v_mfma_f32_16x16x32_bf16 v[8:11], v[102:105], v[90:93], v[8:11]
	v_cvt_pk_bf16_f32 v37, v38, v39
	v_cvt_pk_bf16_f32 v24, v24, v25
	v_cvt_pk_bf16_f32 v25, v26, v27
	v_mfma_f32_16x16x32_bf16 v[4:7], v[102:105], v[98:101], v[4:7]
	v_cvt_pk_bf16_f32 v20, v20, v21
	v_cvt_pk_bf16_f32 v21, v22, v23
	v_cvt_pk_bf16_f32 v12, v12, v13
	v_mfma_f32_16x16x32_bf16 v[0:3], v[102:105], v[106:109], v[0:3]
	v_cvt_pk_bf16_f32 v13, v14, v15
	v_lshl_add_u64 v[14:15], v[16:17], 0, v[76:77]
	v_cvt_pk_bf16_f32 v8, v8, v9
	v_cvt_pk_bf16_f32 v9, v10, v11
	v_cvt_pk_bf16_f32 v4, v4, v5
	v_cvt_pk_bf16_f32 v5, v6, v7
	s_nop 1
	v_cvt_pk_bf16_f32 v0, v0, v1
	v_cvt_pk_bf16_f32 v1, v2, v3
	global_store_dwordx2 v[62:63], v[60:61], off
	global_store_dwordx2 v[62:63], v[56:57], off offset:1024
	global_store_dwordx2 v[62:63], v[52:53], off offset:2048
	global_store_dwordx2 v[62:63], v[48:49], off offset:3072
	global_store_dwordx2 v[62:63], v[44:45], off offset:32
	global_store_dwordx2 v[62:63], v[40:41], off offset:1056
	global_store_dwordx2 v[62:63], v[36:37], off offset:2080
	global_store_dwordx2 v[30:31], v[28:29], off
	global_store_dwordx2 v[30:31], v[24:25], off offset:1024
	global_store_dwordx2 v[30:31], v[20:21], off offset:2048
	global_store_dwordx2 v[14:15], v[12:13], off
	global_store_dwordx2 v[14:15], v[8:9], off offset:1024
	global_store_dwordx2 v[14:15], v[4:5], off offset:2048
	global_store_dwordx2 v[14:15], v[0:1], off offset:3072
	s_branch .LBB0_436
